# branch A unit body rewritten by hand: sink+q loads before the K/V prefetch with fixed 14-load prefetch and counted vmcnt; per 16-query block ALiBi bias computed into MFMA accumulators, 17 key tiles, s
# speedup vs baseline: 1.0357x; 1.0081x over previous
; #define LAS __attribute__((address_space(3)))
; __device__ __forceinline__ void attn_a_prefetch(const bf16* Z, int unit, v4u (&kr)[7], v4u (&vr)[7]) {
;     const int tid = threadIdx.x; const int ib = unit & 63, kvh = (unit >> 6) & 1, b = unit >> 7;
;     const size_t tok0 = (size_t)b * SEQ; const int kstart = (ib - 1) * 128;
; #pragma unroll
;     for (int k = 0; k < 7; ++k) { const int it = tid + k * NTHREADS; const int row = it >> 3, ch = it & 7, pos = kstart + row;
;         kr[k] = (v4u){0u, 0u, 0u, 0u}; vr[k] = (v4u){0u, 0u, 0u, 0u};
;         if (it < A_ROWS * 8 && row < 384 && pos >= 0 && pos < SEQ) { const int t = (int)tok0 + pos; kr[k] = *(const v4u*)((const unsigned char*)Z + tmo(t, Z_KA / 64 + kvh, ZLD / 64) + ch * 16); vr[k] = *(const v4u*)((const unsigned char*)Z + tmo(t, Z_VA / 64 + kvh, ZLD / 64) + ch * 16); } }
; }
; __device__ __forceinline__ void attn_a_commit(LAS unsigned char* lds, const v4u (&kr)[7], const v4u (&vr)[7]) {
;     const int tid = threadIdx.x; LAS unsigned char* Kl = lds + A_KOFF; LAS unsigned char* Vl = lds + A_VOFF;
; #pragma unroll
;     for (int k = 0; k < 7; ++k) { const int it = tid + k * NTHREADS; const int row = it >> 3, ch = it & 7;
;         if (it < A_ROWS * 8) { *(LAS v4u*)(Kl + swz(row, ch)) = kr[k]; *(LAS v4u*)(Vl + swz(row, ch)) = vr[k]; } }
; }
; __device__ __forceinline__ void attn_a_unit(LAS unsigned char* lds, const bf16* Z, bf16* Y, const float* sink, int unit) {
;     const int tid = threadIdx.x, lane = tid & 63, wid = tid >> 6, lq = lane & 15, g = lane >> 4;
;     const int ib = unit & 63, kvh = (unit >> 6) & 1, b = unit >> 7;
;     const size_t tok0 = (size_t)b * SEQ; const int kstart = (ib - 1) * 128;
;     LAS unsigned char* Kl = lds + A_KOFF; LAS unsigned char* Vl = lds + A_VOFF;
;     const int hq = kvh * 4 + (wid >> 1);
;     const float slope2 = __builtin_amdgcn_exp2f(-(float)(hq + 1)) * LOG2E, sink2 = sink[hq] * LOG2E, c1 = 0.125f * LOG2E;
;     const bool edge = (ib == 0) || (ib == 63);
;     for (int bp = 0; bp < 2; ++bp) {
;         const int qoffA = (wid & 1) * 64 + bp * 32, qoffB = qoffA + 16;
;         const size_t qtokA = tok0 + ib * 128 + qoffA + lq, qtokB = qtokA + 16;
;         const unsigned char* qpA = (const unsigned char*)Z + tmo((int)qtokA, Z_QA / 64 + hq, ZLD / 64) + 16 * g; const unsigned char* qpB = qpA + 16 * 128;
.LBB0_245:
	s_or_b64 exec, exec, s[16:17]
	v_readlane_b32 s72, v246, 7
	s_nop 3
	s_lshr_b32 s73, s20, 6
	s_and_b32 s73, s73, 1
	s_lshl_b32 s73, s73, 2
	s_lshr_b32 s74, s72, 1
	s_add_i32 s73, s73, s74
	s_lshl_b32 s75, s73, 2
	s_load_dword s76, s[44:45], s75
	s_and_b32 s77, s20, 63
	s_lshr_b32 s78, s20, 7
	s_lshl_b32 s78, s78, 5
	s_lshr_b32 s79, s77, 1
	s_add_i32 s78, s78, s79
	s_mul_i32 s80, s78, 0x44
	s_add_i32 s80, s80, s73
	s_mov_b32 s81, 0
	s_lshl_b64 s[80:81], s[80:81], 15
	s_add_u32 s80, s80, s38
	s_addc_u32 s81, s81, s39
	s_lshl_b32 s82, s78, 4
	s_add_i32 s82, s82, s73
	s_lshl_b32 s82, s82, 15
	s_add_u32 s82, s40, s82
	s_addc_u32 s83, s41, 0
	s_add_i32 s84, s73, 1
	s_lshl_b32 s84, s84, 23
	s_sub_i32 s84, 0x3fb8aa3b, s84
	s_and_b32 s85, s72, 1
	s_lshl_b32 s85, s85, 6
	s_and_b32 s86, s77, 1
	s_lshl_b32 s86, s86, 7
	s_add_i32 s86, s86, s85
	v_and_b32_e32 v219, 15, v218
	v_bfe_u32 v244, v218, 4, 2
	v_add_u32_e32 v219, s86, v219
	v_lshlrev_b32_e32 v219, 7, v219
	v_lshl_add_u32 v128, v244, 5, v219
	v_lshl_add_u32 v219, v244, 4, v219
	v_add_u32_e32 v245, 0x1000, v219
	global_load_dwordx4 v[146:149], v219, s[80:81] offset:0
	global_load_dwordx4 v[150:153], v219, s[80:81] offset:64
	global_load_dwordx4 v[154:157], v219, s[80:81] offset:2048
	global_load_dwordx4 v[158:161], v219, s[80:81] offset:2112
	global_load_dwordx4 v[162:165], v245, s[80:81] offset:0
	global_load_dwordx4 v[166:169], v245, s[80:81] offset:64
	global_load_dwordx4 v[170:173], v245, s[80:81] offset:2048
	global_load_dwordx4 v[174:177], v245, s[80:81] offset:2112
	s_add_i32 s97, s20, s33
	s_cmpk_gt_i32 s97, 0x3ff
	s_cselect_b64 s[70:71], -1, 0
	s_and_b64 vcc, exec, s[70:71]
	s_waitcnt lgkmcnt(0)
	s_barrier
	s_cbranch_vccnz .La_nonext
	s_lshl_b32 s1, s97, 7
	s_bfe_u32 s16, s97, 0x10006
	s_lshl_b32 s0, s97, 6
	s_and_b32 s1, s1, 0x1f80
	s_and_b32 s0, s0, 0xffffe000
	s_addk_i32 s1, 0xff80
	s_or_b32 s50, s16, 8
	s_or_b32 s16, s16, 10
	s_mov_b32 s17, s51
	v_mov_b32_e32 v2, 0
	s_cmpk_gt_u32 s1, 0x1fff
	v_mov_b32_e32 v10, 0
	v_mov_b32_e32 v11, 0
	v_mov_b32_e32 v12, 0
	v_mov_b32_e32 v13, 0
	v_mov_b32_e32 v6, 0
	v_mov_b32_e32 v7, 0
	v_mov_b32_e32 v8, 0
	v_mov_b32_e32 v9, 0
	s_mov_b64 s[90:91], exec
	s_cselect_b64 exec, 0, exec
	s_or_b32 s18, s1, s0
	s_ashr_i32 s18, s18, 8
	s_mul_i32 s21, s18, 0x44
	s_ashr_i32 s22, s21, 31
	s_add_u32 s18, s21, s50
	s_addc_u32 s19, s22, 0
	v_or_b32_e32 v3, s1, v138
	s_lshl_b64 s[18:19], s[18:19], 15
	v_lshlrev_b32_e32 v3, 7, v3
	s_add_u32 s18, s38, s18
	v_and_b32_e32 v120, 0x7f80, v3
	s_addc_u32 s19, s39, s19
	v_lshl_add_u64 v[4:5], s[18:19], 0, v[120:121]
	s_add_u32 s18, s21, s16
	s_addc_u32 s19, s22, 0
	s_lshl_b64 s[18:19], s[18:19], 15
	s_add_u32 s18, s38, s18
	s_addc_u32 s19, s39, s19
	v_lshl_add_u64 v[6:7], s[18:19], 0, v[120:121]
	v_lshl_add_u64 v[4:5], v[4:5], 0, v[118:119]
	v_lshl_add_u64 v[10:11], v[6:7], 0, v[118:119]
	global_load_dwordx4 v[6:9], v[4:5], off
	s_nop 0
	global_load_dwordx4 v[10:13], v[10:11], off
.LBB0_248:
	s_mov_b64 exec, s[90:91]
	v_add_u32_e32 v18, s1, v140
	v_cmp_gt_u32_e32 vcc, s3, v18
	v_mov_b32_e32 v3, 0
	v_mov_b32_e32 v4, 0
	v_mov_b32_e32 v5, 0
	v_mov_b32_e32 v14, 0
	v_mov_b32_e32 v15, 0
	v_mov_b32_e32 v16, 0
	v_mov_b32_e32 v17, 0
	s_and_saveexec_b64 s[18:19], vcc
	v_or_b32_e32 v2, s0, v18
	v_lshrrev_b32_e32 v2, 8, v2
	v_mul_i32_i24_e32 v2, 0x44, v2
	v_ashrrev_i32_e32 v3, 31, v2
	v_lshl_add_u64 v[4:5], v[2:3], 0, s[50:51]
	v_lshl_add_u64 v[2:3], v[2:3], 0, s[16:17]
	v_lshlrev_b64 v[4:5], 15, v[4:5]
	v_lshlrev_b32_e32 v14, 7, v18
	v_lshlrev_b64 v[2:3], 15, v[2:3]
	v_and_b32_e32 v120, 0x7f80, v14
	v_lshl_add_u64 v[4:5], s[38:39], 0, v[4:5]
	v_lshl_add_u64 v[2:3], s[38:39], 0, v[2:3]
	v_lshl_add_u64 v[4:5], v[4:5], 0, v[120:121]
	v_lshl_add_u64 v[2:3], v[2:3], 0, v[120:121]
	v_lshl_add_u64 v[4:5], v[4:5], 0, v[118:119]
	v_lshl_add_u64 v[2:3], v[2:3], 0, v[118:119]
	global_load_dwordx4 v[14:17], v[4:5], off
	s_nop 0
	global_load_dwordx4 v[2:5], v[2:3], off
; __device__ __forceinline__ size_t tmo(int row, int ct, int nct) { return ((size_t)(row >> 8) * nct + ct) * 32768 + (size_t)(row & 255) * 128; }
; __device__ __forceinline__ void attn_a_prefetch(const bf16* Z, int unit, v4u (&kr)[7], v4u (&vr)[7]) {
;     const int tid = threadIdx.x; const int ib = unit & 63, kvh = (unit >> 6) & 1, b = unit >> 7;
;     const size_t tok0 = (size_t)b * SEQ; const int kstart = (ib - 1) * 128;
; #pragma unroll
;     for (int k = 0; k < 7; ++k) { const int it = tid + k * NTHREADS; const int row = it >> 3, ch = it & 7, pos = kstart + row;
;         kr[k] = (v4u){0u, 0u, 0u, 0u}; vr[k] = (v4u){0u, 0u, 0u, 0u};
;         if (it < A_ROWS * 8 && row < 384 && pos >= 0 && pos < SEQ) { const int t = (int)tok0 + pos; kr[k] = *(const v4u*)((const unsigned char*)Z + tmo(t, Z_KA / 64 + kvh, ZLD / 64) + ch * 16); vr[k] = *(const v4u*)((const unsigned char*)Z + tmo(t, Z_VA / 64 + kvh, ZLD / 64) + ch * 16); } }
; }
.LBB0_250:
	s_or_b64 exec, exec, s[18:19]
	v_add_u32_e32 v22, s1, v143
	v_or_b32_e32 v18, s0, v22
	v_lshrrev_b32_e32 v18, 8, v18
	v_mul_i32_i24_e32 v18, 0x44, v18
	v_ashrrev_i32_e32 v19, 31, v18
	v_lshl_add_u64 v[20:21], v[18:19], 0, s[50:51]
	v_lshl_add_u64 v[18:19], v[18:19], 0, s[16:17]
	v_lshlrev_b64 v[20:21], 15, v[20:21]
	v_lshlrev_b32_e32 v22, 7, v22
	v_lshlrev_b64 v[18:19], 15, v[18:19]
	v_and_b32_e32 v120, 0x7f80, v22
	v_lshl_add_u64 v[20:21], s[38:39], 0, v[20:21]
	v_lshl_add_u64 v[18:19], s[38:39], 0, v[18:19]
	v_lshl_add_u64 v[20:21], v[20:21], 0, v[120:121]
	v_lshl_add_u64 v[18:19], v[18:19], 0, v[120:121]
	v_lshl_add_u64 v[20:21], v[20:21], 0, v[118:119]
	v_lshl_add_u64 v[22:23], v[18:19], 0, v[118:119]
	global_load_dwordx4 v[18:21], v[20:21], off
	s_nop 0
	global_load_dwordx4 v[22:25], v[22:23], off
	v_add_u32_e32 v34, s1, v141
	v_cmp_gt_u32_e32 vcc, s3, v34
	v_mov_b32_e32 v38, 0
	v_mov_b32_e32 v30, 0
	v_mov_b32_e32 v31, 0
	v_mov_b32_e32 v32, 0
	v_mov_b32_e32 v33, 0
	v_mov_b32_e32 v26, 0
	v_mov_b32_e32 v27, 0
	v_mov_b32_e32 v28, 0
	v_mov_b32_e32 v29, 0
	s_and_saveexec_b64 s[18:19], vcc
	v_or_b32_e32 v26, s0, v34
	v_lshrrev_b32_e32 v26, 8, v26
	v_mul_i32_i24_e32 v26, 0x44, v26
	v_ashrrev_i32_e32 v27, 31, v26
	v_lshl_add_u64 v[28:29], v[26:27], 0, s[50:51]
	v_lshl_add_u64 v[26:27], v[26:27], 0, s[16:17]
	v_lshlrev_b64 v[28:29], 15, v[28:29]
	v_lshlrev_b32_e32 v30, 7, v34
	v_lshlrev_b64 v[26:27], 15, v[26:27]
	v_and_b32_e32 v120, 0x7f80, v30
	v_lshl_add_u64 v[28:29], s[38:39], 0, v[28:29]
	v_lshl_add_u64 v[26:27], s[38:39], 0, v[26:27]
	v_lshl_add_u64 v[28:29], v[28:29], 0, v[120:121]
	v_lshl_add_u64 v[26:27], v[26:27], 0, v[120:121]
	v_lshl_add_u64 v[28:29], v[28:29], 0, v[118:119]
	v_lshl_add_u64 v[30:31], v[26:27], 0, v[118:119]
	global_load_dwordx4 v[26:29], v[28:29], off
	s_nop 0
	global_load_dwordx4 v[30:33], v[30:31], off
.LBB0_252:
	s_or_b64 exec, exec, s[18:19]
	v_add_u32_e32 v39, s1, v144
	v_cmp_gt_u32_e32 vcc, s3, v39
	v_mov_b32_e32 v34, 0
	v_mov_b32_e32 v35, 0
	v_mov_b32_e32 v36, 0
	v_mov_b32_e32 v37, 0
	v_mov_b32_e32 v42, 0
	v_mov_b32_e32 v43, 0
	v_mov_b32_e32 v44, 0
	v_mov_b32_e32 v45, 0
	s_and_saveexec_b64 s[18:19], vcc
	v_or_b32_e32 v34, s0, v39
	v_lshrrev_b32_e32 v34, 8, v34
	v_mul_i32_i24_e32 v34, 0x44, v34
	v_ashrrev_i32_e32 v35, 31, v34
	v_lshl_add_u64 v[36:37], v[34:35], 0, s[50:51]
	v_lshl_add_u64 v[34:35], v[34:35], 0, s[16:17]
	v_lshlrev_b64 v[36:37], 15, v[36:37]
	v_lshlrev_b32_e32 v39, 7, v39
	v_lshlrev_b64 v[34:35], 15, v[34:35]
	v_and_b32_e32 v120, 0x7f80, v39
	v_lshl_add_u64 v[36:37], s[38:39], 0, v[36:37]
	v_lshl_add_u64 v[34:35], s[38:39], 0, v[34:35]
	v_lshl_add_u64 v[36:37], v[36:37], 0, v[120:121]
	v_lshl_add_u64 v[34:35], v[34:35], 0, v[120:121]
	v_lshl_add_u64 v[36:37], v[36:37], 0, v[118:119]
	v_lshl_add_u64 v[34:35], v[34:35], 0, v[118:119]
	global_load_dwordx4 v[42:45], v[36:37], off
	s_nop 0
	global_load_dwordx4 v[34:37], v[34:35], off
.LBB0_254:
	s_or_b64 exec, exec, s[18:19]
	v_add_u32_e32 v50, s1, v142
	v_cmp_gt_u32_e32 vcc, s3, v50
	s_and_b64 s[22:23], s[6:7], vcc
	v_mov_b32_e32 v39, 0
	v_mov_b32_e32 v40, 0
	v_mov_b32_e32 v41, 0
	v_mov_b32_e32 v46, 0
	v_mov_b32_e32 v47, 0
	v_mov_b32_e32 v48, 0
	v_mov_b32_e32 v49, 0
	s_and_saveexec_b64 s[18:19], s[22:23]
	v_or_b32_e32 v38, s0, v50
	v_lshrrev_b32_e32 v38, 8, v38
	v_mul_i32_i24_e32 v38, 0x44, v38
	v_ashrrev_i32_e32 v39, 31, v38
	v_lshl_add_u64 v[40:41], v[38:39], 0, s[50:51]
	v_lshl_add_u64 v[38:39], v[38:39], 0, s[16:17]
	v_lshlrev_b64 v[40:41], 15, v[40:41]
	v_lshlrev_b32_e32 v46, 7, v50
	v_lshlrev_b64 v[38:39], 15, v[38:39]
	v_and_b32_e32 v120, 0x7f80, v46
	v_lshl_add_u64 v[40:41], s[38:39], 0, v[40:41]
	v_lshl_add_u64 v[38:39], s[38:39], 0, v[38:39]
	v_lshl_add_u64 v[40:41], v[40:41], 0, v[120:121]
	v_lshl_add_u64 v[38:39], v[38:39], 0, v[120:121]
	v_lshl_add_u64 v[40:41], v[40:41], 0, v[118:119]
	v_lshl_add_u64 v[38:39], v[38:39], 0, v[118:119]
	global_load_dwordx4 v[46:49], v[40:41], off
	s_nop 0
	global_load_dwordx4 v[38:41], v[38:39], off

; #define LAS __attribute__((address_space(3)))
; template <bool MASK> __device__ __forceinline__ void a_scores(f32x4& S0, f32x4& S1, float basef, float c1, float slope2, int krow0, int kstart) {
; #pragma unroll
;     for (int r = 0; r < 4; ++r) {
;         const float d0 = fabsf(basef - (float)r), d1 = fabsf(basef - (float)(16 + r));
;         const float v0 = S0[r] - slope2 * d0, v1 = S1[r] - slope2 * d1;
;         if (MASK) { const int p0 = kstart + krow0 + r, p1 = p0 + 16;
;             S0[r] = (d0 <= 128.f && p0 >= 0 && p0 < SEQ) ? v0 : -INFINITY; S1[r] = (d1 <= 128.f && p1 >= 0 && p1 < SEQ) ? v1 : -INFINITY; }
;         else { S0[r] = v0; S1[r] = v1; }
;     }
; }
; __device__ __forceinline__ void attn_a_unit(LAS unsigned char* lds, const bf16* Z, bf16* Y, const float* sink, int unit) {
;     ...
;         const LAS unsigned char* kp0 = Kl + swz(qoffA + lq, g); const LAS unsigned char* kp1 = Kl + swz(qoffA + lq, 4 + g);
;         const LAS unsigned char* vp[4];
;         { const int i = lane & 15, rq4 = i >> 2, p = i & 3;
; #pragma unroll
;           for (int db = 0; db < 4; ++db) vp[db] = Vl + swz(qoffA + 4 * g + rq4, 2 * db + (p >> 1)) + 8 * (p & 1); }
;         float basef = (float)(128 + lq - 4 * g);
.LBB0_257:
	s_waitcnt vmcnt(14)
	v_and_b32_e32 v219, 15, v218
	v_bfe_u32 v244, v218, 4, 2
	v_add_u32_e32 v245, s85, v219
	v_lshlrev_b32_e32 v245, 7, v245
	v_bitop3_b32 v120, v219, v244, 7 bitop3:0x6c
	v_lshl_add_u32 v122, v120, 4, v245
	v_xor_b32_e32 v120, 4, v120
	v_lshl_add_u32 v123, v120, 4, v245
	v_lshlrev_b32_e32 v245, 2, v244
	v_sub_u32_e32 v120, v219, v245
	v_cmp_ge_i32_e64 s[16:17], 0, v120
	v_cmp_le_i32_e64 s[28:29], 0, v120
	v_cmp_ge_i32_e64 s[18:19], 1, v120
	v_cmp_le_i32_e64 s[52:53], 1, v120
	v_cmp_ge_i32_e64 s[22:23], 2, v120
	v_cmp_le_i32_e64 s[54:55], 2, v120
	v_cmp_ge_i32_e64 s[24:25], 3, v120
	v_cmp_le_i32_e64 s[88:89], 3, v120
	v_cmp_eq_u32_e64 s[74:75], 0, v244
	v_cvt_f32_i32_e32 v129, v120
	v_lshrrev_b32_e32 v120, 2, v219
	v_add_u32_e32 v245, v245, v120
	v_bfe_u32 v120, v219, 1, 1
	v_and_b32_e32 v219, 1, v219
	v_lshlrev_b32_e32 v219, 3, v219
	v_add_u32_e32 v244, s85, v245
	v_lshl_add_u32 v219, v244, 7, v219
	v_add_u32_e32 v219, 0xc800, v219
	v_or_b32_e32 v245, 0, v120
	v_bitop3_b32 v245, v244, v245, 7 bitop3:0x6c
	v_lshl_add_u32 v124, v245, 4, v219
	v_or_b32_e32 v245, 2, v120
	v_bitop3_b32 v245, v244, v245, 7 bitop3:0x6c
	v_lshl_add_u32 v125, v245, 4, v219
	v_or_b32_e32 v245, 4, v120
	v_bitop3_b32 v245, v244, v245, 7 bitop3:0x6c
	v_lshl_add_u32 v126, v245, 4, v219
	v_or_b32_e32 v245, 6, v120
	v_bitop3_b32 v245, v244, v245, 7 bitop3:0x6c
	v_lshl_add_u32 v127, v245, 4, v219
	v_mov_b32_e32 v131, s84
	v_xor_b32_e32 v130, 0x80000000, v131
	v_mov_b32_e32 v219, s76
	v_mul_f32_e32 v145, 0x3fb8aa3b, v219
	v_mul_f32_e32 v132, v130, v129
	v_mul_f32_e32 v133, v131, v129
	s_cmp_eq_u32 s77, 0
	s_cbranch_scc1 .La_edge_lo
	s_cmp_eq_u32 s77, 63
	s_cbranch_scc1 .La_edge_hi
	v_fmamk_f32 v50, v130, 0x43000000, v132
	v_fmamk_f32 v51, v130, 0x42fe0000, v132
	v_fmamk_f32 v52, v130, 0x42fc0000, v132
	v_fmamk_f32 v53, v130, 0x42fa0000, v132
	v_fmamk_f32 v54, v130, 0x42e00000, v132
	v_fmamk_f32 v55, v130, 0x42de0000, v132
	v_fmamk_f32 v56, v130, 0x42dc0000, v132
	v_fmamk_f32 v57, v130, 0x42da0000, v132
	v_fmamk_f32 v58, v130, 0x42c00000, v132
	v_fmamk_f32 v59, v130, 0x42be0000, v132
	v_fmamk_f32 v60, v130, 0x42bc0000, v132
	v_fmamk_f32 v61, v130, 0x42ba0000, v132
	v_fmamk_f32 v62, v130, 0x42a00000, v132
	v_fmamk_f32 v63, v130, 0x429e0000, v132
	v_fmamk_f32 v64, v130, 0x429c0000, v132
	v_fmamk_f32 v65, v130, 0x429a0000, v132
	v_fmamk_f32 v66, v130, 0x42800000, v132
	v_fmamk_f32 v67, v130, 0x427c0000, v132
	v_fmamk_f32 v68, v130, 0x42780000, v132
	v_fmamk_f32 v69, v130, 0x42740000, v132
	v_fmamk_f32 v70, v130, 0x42400000, v132
	v_fmamk_f32 v71, v130, 0x423c0000, v132
	v_fmamk_f32 v72, v130, 0x42380000, v132
	v_fmamk_f32 v73, v130, 0x42340000, v132
	v_fmamk_f32 v74, v130, 0x42000000, v132
	v_fmamk_f32 v75, v130, 0x41f80000, v132
	v_fmamk_f32 v76, v130, 0x41f00000, v132
	v_fmamk_f32 v77, v130, 0x41e80000, v132
	v_fmamk_f32 v78, v130, 0x41800000, v132
	v_fmamk_f32 v79, v130, 0x41700000, v132
	v_fmamk_f32 v80, v130, 0x41600000, v132
	v_fmamk_f32 v81, v130, 0x41500000, v132
	v_add_f32_e32 v219, 0, v129
	v_mul_f32_e64 v82, v130, |v219|
	v_add_f32_e32 v244, 0xbf800000, v129
	v_mul_f32_e64 v83, v130, |v244|
	v_add_f32_e32 v219, 0xc0000000, v129
	v_mul_f32_e64 v84, v130, |v219|
	v_add_f32_e32 v244, 0xc0400000, v129
	v_mul_f32_e64 v85, v130, |v244|
	v_fmamk_f32 v86, v131, 0xc1800000, v133
	v_fmamk_f32 v87, v131, 0xc1880000, v133
	v_fmamk_f32 v88, v131, 0xc1900000, v133
	v_fmamk_f32 v89, v131, 0xc1980000, v133
	v_fmamk_f32 v90, v131, 0xc2000000, v133
	v_fmamk_f32 v91, v131, 0xc2040000, v133
	v_fmamk_f32 v92, v131, 0xc2080000, v133
	v_fmamk_f32 v93, v131, 0xc20c0000, v133
	v_fmamk_f32 v94, v131, 0xc2400000, v133
	v_fmamk_f32 v95, v131, 0xc2440000, v133
	v_fmamk_f32 v96, v131, 0xc2480000, v133
	v_fmamk_f32 v97, v131, 0xc24c0000, v133
	v_fmamk_f32 v98, v131, 0xc2800000, v133
	v_fmamk_f32 v99, v131, 0xc2820000, v133
	v_fmamk_f32 v100, v131, 0xc2840000, v133
	v_fmamk_f32 v101, v131, 0xc2860000, v133
	v_fmamk_f32 v102, v131, 0xc2a00000, v133
	v_fmamk_f32 v103, v131, 0xc2a20000, v133
	v_fmamk_f32 v104, v131, 0xc2a40000, v133
	v_fmamk_f32 v105, v131, 0xc2a60000, v133
	v_fmamk_f32 v106, v131, 0xc2c00000, v133
	v_fmamk_f32 v107, v131, 0xc2c20000, v133
	v_fmamk_f32 v108, v131, 0xc2c40000, v133
	v_fmamk_f32 v109, v131, 0xc2c60000, v133
	v_fmamk_f32 v110, v131, 0xc2e00000, v133
	v_fmamk_f32 v111, v131, 0xc2e20000, v133
	v_fmamk_f32 v112, v131, 0xc2e40000, v133
	v_fmamk_f32 v113, v131, 0xc2e60000, v133
	v_fmamk_f32 v114, v131, 0xc3000000, v133
	v_fmamk_f32 v115, v131, 0xc3010000, v133
	v_fmamk_f32 v116, v131, 0xc3020000, v133
	v_fmamk_f32 v117, v131, 0xc3030000, v133
	v_mov_b32_e32 v245, 0xff800000
	v_cndmask_b32_e64 v50, v245, v50, s[16:17]
	v_cndmask_b32_e64 v51, v245, v51, s[18:19]
	v_cndmask_b32_e64 v52, v245, v52, s[22:23]
	v_cndmask_b32_e64 v53, v245, v53, s[24:25]
	v_cndmask_b32_e64 v114, v245, v114, s[28:29]
	v_cndmask_b32_e64 v115, v245, v115, s[52:53]
	v_cndmask_b32_e64 v116, v245, v116, s[54:55]
	v_cndmask_b32_e64 v117, v245, v117, s[88:89]
	ds_read_b128 v[186:189], v122 offset:0
	ds_read_b128 v[190:193], v123 offset:0
	ds_read_b128 v[194:197], v122 offset:2048
	ds_read_b128 v[198:201], v123 offset:2048
	ds_read_b128 v[202:205], v122 offset:4096
	ds_read_b128 v[206:209], v123 offset:4096
	s_waitcnt lgkmcnt(5)
	v_mfma_f32_16x16x32_bf16 v[50:53], v[186:189], v[146:149], v[50:53]
	s_waitcnt lgkmcnt(4)
	v_mfma_f32_16x16x32_bf16 v[50:53], v[190:193], v[150:153], v[50:53]
	ds_read_b128 v[186:189], v122 offset:6144
	ds_read_b128 v[190:193], v123 offset:6144
	s_waitcnt lgkmcnt(5)
	v_mfma_f32_16x16x32_bf16 v[54:57], v[194:197], v[146:149], v[54:57]
	s_waitcnt lgkmcnt(4)
; #define LAS __attribute__((address_space(3)))
; #define MFMA16(a, b, c) __builtin_amdgcn_mfma_f32_16x16x32_bf16((a), (b), (c), 0, 0, 0)
; __device__ __forceinline__ void qk_at(const LAS unsigned char* kp0, const LAS unsigned char* kp1, int off, bf16x8 qf0, bf16x8 qf1, f32x4& S0, f32x4& S1) {
;     const bf16x8 k00 = *(const LAS bf16x8*)(kp0 + off), k01 = *(const LAS bf16x8*)(kp1 + off);
;     const bf16x8 k10 = *(const LAS bf16x8*)(kp0 + off + 2048), k11 = *(const LAS bf16x8*)(kp1 + off + 2048);
;     const f32x4 z = {0.f, 0.f, 0.f, 0.f};
;     S0 = MFMA16(k00, qf0, z); S0 = MFMA16(k01, qf1, S0);
;     S1 = MFMA16(k10, qf0, z); S1 = MFMA16(k11, qf1, S1);
; }
; __device__ __forceinline__ void softmax_step(f32x4& s0, f32x4& s1, float& m, float& l, f32x4 (&O)[4]) {
;     float t = fmaxf(fmaxf(fmaxf(s0[0], s0[1]), fmaxf(s0[2], s0[3])), fmaxf(fmaxf(s1[0], s1[1]), fmaxf(s1[2], s1[3])));
;     t = xrow16_max(t);
;     const float mn = fmaxf(m, t), alpha = __builtin_amdgcn_exp2f(m - mn);
	v_mfma_f32_16x16x32_bf16 v[54:57], v[198:201], v[150:153], v[54:57]
	ds_read_b128 v[194:197], v122 offset:8192
	ds_read_b128 v[198:201], v123 offset:8192
	s_waitcnt lgkmcnt(5)
	v_mfma_f32_16x16x32_bf16 v[58:61], v[202:205], v[146:149], v[58:61]
	s_waitcnt lgkmcnt(4)
	v_mfma_f32_16x16x32_bf16 v[58:61], v[206:209], v[150:153], v[58:61]
	ds_read_b128 v[202:205], v122 offset:10240
	ds_read_b128 v[206:209], v123 offset:10240
	s_waitcnt lgkmcnt(5)
	v_mfma_f32_16x16x32_bf16 v[62:65], v[186:189], v[146:149], v[62:65]
	s_waitcnt lgkmcnt(4)
	v_mfma_f32_16x16x32_bf16 v[62:65], v[190:193], v[150:153], v[62:65]
	ds_read_b128 v[186:189], v122 offset:12288
	ds_read_b128 v[190:193], v123 offset:12288
	s_waitcnt lgkmcnt(5)
	v_mfma_f32_16x16x32_bf16 v[66:69], v[194:197], v[146:149], v[66:69]
	s_waitcnt lgkmcnt(4)
	v_mfma_f32_16x16x32_bf16 v[66:69], v[198:201], v[150:153], v[66:69]
	ds_read_b128 v[194:197], v122 offset:14336
	ds_read_b128 v[198:201], v123 offset:14336
	s_waitcnt lgkmcnt(5)
	v_mfma_f32_16x16x32_bf16 v[70:73], v[202:205], v[146:149], v[70:73]
	s_waitcnt lgkmcnt(4)
	v_mfma_f32_16x16x32_bf16 v[70:73], v[206:209], v[150:153], v[70:73]
	ds_read_b128 v[202:205], v122 offset:16384
	ds_read_b128 v[206:209], v123 offset:16384
	s_waitcnt lgkmcnt(5)
	v_mfma_f32_16x16x32_bf16 v[74:77], v[186:189], v[146:149], v[74:77]
	s_waitcnt lgkmcnt(4)
	v_mfma_f32_16x16x32_bf16 v[74:77], v[190:193], v[150:153], v[74:77]
	ds_read_b128 v[186:189], v122 offset:18432
	ds_read_b128 v[190:193], v123 offset:18432
	s_waitcnt lgkmcnt(5)
	v_mfma_f32_16x16x32_bf16 v[78:81], v[194:197], v[146:149], v[78:81]
	s_waitcnt lgkmcnt(4)
	v_mfma_f32_16x16x32_bf16 v[78:81], v[198:201], v[150:153], v[78:81]
	ds_read_b128 v[194:197], v122 offset:20480
	ds_read_b128 v[198:201], v123 offset:20480
	s_waitcnt lgkmcnt(5)
	v_mfma_f32_16x16x32_bf16 v[82:85], v[202:205], v[146:149], v[82:85]
	s_waitcnt lgkmcnt(4)
	v_mfma_f32_16x16x32_bf16 v[82:85], v[206:209], v[150:153], v[82:85]
	ds_read_b128 v[202:205], v122 offset:22528
	ds_read_b128 v[206:209], v123 offset:22528
	s_waitcnt lgkmcnt(5)
	v_mfma_f32_16x16x32_bf16 v[86:89], v[186:189], v[146:149], v[86:89]
	s_waitcnt lgkmcnt(4)
	v_mfma_f32_16x16x32_bf16 v[86:89], v[190:193], v[150:153], v[86:89]
	ds_read_b128 v[186:189], v122 offset:24576
	ds_read_b128 v[190:193], v123 offset:24576
	s_waitcnt lgkmcnt(5)
	v_mfma_f32_16x16x32_bf16 v[90:93], v[194:197], v[146:149], v[90:93]
	s_waitcnt lgkmcnt(4)
	v_mfma_f32_16x16x32_bf16 v[90:93], v[198:201], v[150:153], v[90:93]
	ds_read_b128 v[194:197], v122 offset:26624
	ds_read_b128 v[198:201], v123 offset:26624
	s_waitcnt lgkmcnt(5)
	v_mfma_f32_16x16x32_bf16 v[94:97], v[202:205], v[146:149], v[94:97]
	s_waitcnt lgkmcnt(4)
	v_mfma_f32_16x16x32_bf16 v[94:97], v[206:209], v[150:153], v[94:97]
	ds_read_b128 v[202:205], v122 offset:28672
	ds_read_b128 v[206:209], v123 offset:28672
	s_waitcnt lgkmcnt(5)
	v_mfma_f32_16x16x32_bf16 v[98:101], v[186:189], v[146:149], v[98:101]
	s_waitcnt lgkmcnt(4)
	v_mfma_f32_16x16x32_bf16 v[98:101], v[190:193], v[150:153], v[98:101]
	ds_read_b128 v[186:189], v122 offset:30720
	ds_read_b128 v[190:193], v123 offset:30720
	s_waitcnt lgkmcnt(5)
	v_mfma_f32_16x16x32_bf16 v[102:105], v[194:197], v[146:149], v[102:105]
	s_waitcnt lgkmcnt(4)
	v_mfma_f32_16x16x32_bf16 v[102:105], v[198:201], v[150:153], v[102:105]
	ds_read_b128 v[194:197], v122 offset:32768
	ds_read_b128 v[198:201], v123 offset:32768
	s_waitcnt lgkmcnt(5)
	v_mfma_f32_16x16x32_bf16 v[106:109], v[202:205], v[146:149], v[106:109]
	s_waitcnt lgkmcnt(4)
	v_mfma_f32_16x16x32_bf16 v[106:109], v[206:209], v[150:153], v[106:109]
	s_waitcnt lgkmcnt(3)
	v_mfma_f32_16x16x32_bf16 v[110:113], v[186:189], v[146:149], v[110:113]
	s_waitcnt lgkmcnt(2)
	v_mfma_f32_16x16x32_bf16 v[110:113], v[190:193], v[150:153], v[110:113]
	s_waitcnt lgkmcnt(1)
	v_mfma_f32_16x16x32_bf16 v[114:117], v[194:197], v[146:149], v[114:117]
	s_waitcnt lgkmcnt(0)
	v_mfma_f32_16x16x32_bf16 v[114:117], v[198:201], v[150:153], v[114:117]
	v_max3_f32 v219, v50, v51, v52
	v_max3_f32 v244, v54, v55, v56
	v_max3_f32 v245, v58, v59, v60
	v_max3_f32 v120, v62, v63, v64
	v_max3_f32 v219, v219, v53, v66
	v_max3_f32 v244, v244, v57, v70
	v_max3_f32 v245, v245, v61, v74
	v_max3_f32 v120, v120, v65, v78
	v_max3_f32 v219, v219, v67, v68
	v_max3_f32 v244, v244, v71, v72
	v_max3_f32 v245, v245, v75, v76
	v_max3_f32 v120, v120, v79, v80
	ds_read_b64_tr_b16 v[186:187], v124 offset:0
	ds_read_b64_tr_b16 v[188:189], v124 offset:2048
	ds_read_b64_tr_b16 v[190:191], v125 offset:0
	ds_read_b64_tr_b16 v[192:193], v125 offset:2048
	ds_read_b64_tr_b16 v[194:195], v126 offset:0
	ds_read_b64_tr_b16 v[196:197], v126 offset:2048
	ds_read_b64_tr_b16 v[198:199], v127 offset:0
	ds_read_b64_tr_b16 v[200:201], v127 offset:2048
	v_max3_f32 v219, v219, v69, v82
	v_max3_f32 v244, v244, v73, v86
	v_max3_f32 v245, v245, v77, v90
	v_max3_f32 v120, v120, v81, v94
	v_max3_f32 v219, v219, v83, v84
	v_max3_f32 v244, v244, v87, v88
	v_max3_f32 v245, v245, v91, v92
	v_max3_f32 v120, v120, v95, v96
	v_max3_f32 v219, v219, v85, v98
	v_max3_f32 v244, v244, v89, v102
	v_max3_f32 v245, v245, v93, v106
	v_max3_f32 v120, v120, v97, v110
	v_max3_f32 v219, v219, v99, v100
	v_max3_f32 v244, v244, v103, v104
	v_max3_f32 v245, v245, v107, v108
	v_max3_f32 v120, v120, v111, v112
	v_max3_f32 v219, v219, v101, v114
	v_max3_f32 v219, v219, v115, v116
	v_max_f32_e32 v219, v219, v117
	v_max_f32_e32 v244, v244, v105
	v_max_f32_e32 v245, v245, v109
	v_max_f32_e32 v120, v120, v113
	v_max3_f32 v178, v219, v244, v245
	v_max_f32_e32 v178, v178, v120
	v_mov_b32_e32 v219, v178
	s_nop 1
	v_permlane16_swap_b32_e32 v178, v219
	v_max_f32_e32 v178, v178, v219
	v_mov_b32_e32 v219, v178
	s_nop 1
	v_permlane32_swap_b32_e32 v178, v219
	v_max3_f32 v178, v178, v219, v145
	s_waitcnt lgkmcnt(7)
; __device__ __forceinline__ void softmax_step(f32x4& s0, f32x4& s1, float& m, float& l, f32x4 (&O)[4]) {
;     float t = fmaxf(fmaxf(fmaxf(s0[0], s0[1]), fmaxf(s0[2], s0[3])), fmaxf(fmaxf(s1[0], s1[1]), fmaxf(s1[2], s1[3])));
;     t = xrow16_max(t);
;     const float mn = fmaxf(m, t), alpha = __builtin_amdgcn_exp2f(m - mn);
;     m = mn;
; #pragma unroll
;     for (int k = 0; k < 4; ++k) { s0[k] = __builtin_amdgcn_exp2f(s0[k] - mn); s1[k] = __builtin_amdgcn_exp2f(s1[k] - mn); }
;     l = l * alpha + ((s0[0] + s0[1]) + (s0[2] + s0[3])) + ((s1[0] + s1[1]) + (s1[2] + s1[3]));
; #pragma unroll
;     for (int db = 0; db < 4; ++db) O[db] *= alpha;
; }
	ds_read_b64_tr_b16 v[202:203], v124 offset:4096
	ds_read_b64_tr_b16 v[204:205], v124 offset:6144
	ds_read_b64_tr_b16 v[206:207], v125 offset:4096
	ds_read_b64_tr_b16 v[208:209], v125 offset:6144
	ds_read_b64_tr_b16 v[228:229], v126 offset:4096
	ds_read_b64_tr_b16 v[230:231], v126 offset:6144
	ds_read_b64_tr_b16 v[232:233], v127 offset:4096
	ds_read_b64_tr_b16 v[234:235], v127 offset:6144
	v_mov_b32_e32 v244, v178
	v_pk_add_f32 v[50:51], v[50:51], v[244:245] op_sel_hi:[1,0] neg_lo:[0,1] neg_hi:[0,1]
	v_pk_add_f32 v[52:53], v[52:53], v[244:245] op_sel_hi:[1,0] neg_lo:[0,1] neg_hi:[0,1]
	v_pk_add_f32 v[54:55], v[54:55], v[244:245] op_sel_hi:[1,0] neg_lo:[0,1] neg_hi:[0,1]
	v_pk_add_f32 v[56:57], v[56:57], v[244:245] op_sel_hi:[1,0] neg_lo:[0,1] neg_hi:[0,1]
	v_pk_add_f32 v[58:59], v[58:59], v[244:245] op_sel_hi:[1,0] neg_lo:[0,1] neg_hi:[0,1]
	v_pk_add_f32 v[60:61], v[60:61], v[244:245] op_sel_hi:[1,0] neg_lo:[0,1] neg_hi:[0,1]
	v_pk_add_f32 v[62:63], v[62:63], v[244:245] op_sel_hi:[1,0] neg_lo:[0,1] neg_hi:[0,1]
	v_pk_add_f32 v[64:65], v[64:65], v[244:245] op_sel_hi:[1,0] neg_lo:[0,1] neg_hi:[0,1]
	v_pk_add_f32 v[66:67], v[66:67], v[244:245] op_sel_hi:[1,0] neg_lo:[0,1] neg_hi:[0,1]
	v_pk_add_f32 v[68:69], v[68:69], v[244:245] op_sel_hi:[1,0] neg_lo:[0,1] neg_hi:[0,1]
	v_pk_add_f32 v[70:71], v[70:71], v[244:245] op_sel_hi:[1,0] neg_lo:[0,1] neg_hi:[0,1]
	v_pk_add_f32 v[72:73], v[72:73], v[244:245] op_sel_hi:[1,0] neg_lo:[0,1] neg_hi:[0,1]
	v_pk_add_f32 v[74:75], v[74:75], v[244:245] op_sel_hi:[1,0] neg_lo:[0,1] neg_hi:[0,1]
	v_pk_add_f32 v[76:77], v[76:77], v[244:245] op_sel_hi:[1,0] neg_lo:[0,1] neg_hi:[0,1]
	v_pk_add_f32 v[78:79], v[78:79], v[244:245] op_sel_hi:[1,0] neg_lo:[0,1] neg_hi:[0,1]
	v_pk_add_f32 v[80:81], v[80:81], v[244:245] op_sel_hi:[1,0] neg_lo:[0,1] neg_hi:[0,1]
	v_pk_add_f32 v[82:83], v[82:83], v[244:245] op_sel_hi:[1,0] neg_lo:[0,1] neg_hi:[0,1]
	v_pk_add_f32 v[84:85], v[84:85], v[244:245] op_sel_hi:[1,0] neg_lo:[0,1] neg_hi:[0,1]
	v_pk_add_f32 v[86:87], v[86:87], v[244:245] op_sel_hi:[1,0] neg_lo:[0,1] neg_hi:[0,1]
	v_pk_add_f32 v[88:89], v[88:89], v[244:245] op_sel_hi:[1,0] neg_lo:[0,1] neg_hi:[0,1]
	v_pk_add_f32 v[90:91], v[90:91], v[244:245] op_sel_hi:[1,0] neg_lo:[0,1] neg_hi:[0,1]
	v_pk_add_f32 v[92:93], v[92:93], v[244:245] op_sel_hi:[1,0] neg_lo:[0,1] neg_hi:[0,1]
	v_pk_add_f32 v[94:95], v[94:95], v[244:245] op_sel_hi:[1,0] neg_lo:[0,1] neg_hi:[0,1]
	v_pk_add_f32 v[96:97], v[96:97], v[244:245] op_sel_hi:[1,0] neg_lo:[0,1] neg_hi:[0,1]
	v_pk_add_f32 v[98:99], v[98:99], v[244:245] op_sel_hi:[1,0] neg_lo:[0,1] neg_hi:[0,1]
	v_pk_add_f32 v[100:101], v[100:101], v[244:245] op_sel_hi:[1,0] neg_lo:[0,1] neg_hi:[0,1]
	v_pk_add_f32 v[102:103], v[102:103], v[244:245] op_sel_hi:[1,0] neg_lo:[0,1] neg_hi:[0,1]
	v_pk_add_f32 v[104:105], v[104:105], v[244:245] op_sel_hi:[1,0] neg_lo:[0,1] neg_hi:[0,1]
	v_pk_add_f32 v[106:107], v[106:107], v[244:245] op_sel_hi:[1,0] neg_lo:[0,1] neg_hi:[0,1]
	v_pk_add_f32 v[108:109], v[108:109], v[244:245] op_sel_hi:[1,0] neg_lo:[0,1] neg_hi:[0,1]
	v_pk_add_f32 v[110:111], v[110:111], v[244:245] op_sel_hi:[1,0] neg_lo:[0,1] neg_hi:[0,1]
	v_pk_add_f32 v[112:113], v[112:113], v[244:245] op_sel_hi:[1,0] neg_lo:[0,1] neg_hi:[0,1]
	v_pk_add_f32 v[114:115], v[114:115], v[244:245] op_sel_hi:[1,0] neg_lo:[0,1] neg_hi:[0,1]
	v_pk_add_f32 v[116:117], v[116:117], v[244:245] op_sel_hi:[1,0] neg_lo:[0,1] neg_hi:[0,1]
	v_sub_f32_e32 v219, v145, v178
	v_exp_f32_e32 v50, v50
	v_exp_f32_e32 v51, v51
	v_exp_f32_e32 v52, v52
	v_exp_f32_e32 v53, v53
	v_exp_f32_e32 v54, v54
	v_exp_f32_e32 v55, v55
	v_exp_f32_e32 v56, v56
	v_exp_f32_e32 v57, v57
	v_exp_f32_e32 v58, v58
	v_exp_f32_e32 v59, v59
	v_exp_f32_e32 v60, v60
	v_exp_f32_e32 v61, v61
	v_exp_f32_e32 v62, v62
	v_exp_f32_e32 v63, v63
	v_exp_f32_e32 v64, v64
	v_exp_f32_e32 v65, v65
	v_exp_f32_e32 v66, v66
	v_exp_f32_e32 v67, v67
	v_exp_f32_e32 v68, v68
	v_exp_f32_e32 v69, v69
	v_exp_f32_e32 v70, v70
	v_exp_f32_e32 v71, v71
	v_exp_f32_e32 v72, v72
	v_exp_f32_e32 v73, v73
	v_exp_f32_e32 v74, v74
	v_exp_f32_e32 v75, v75
	v_exp_f32_e32 v76, v76
	v_exp_f32_e32 v77, v77
	v_exp_f32_e32 v78, v78
	v_exp_f32_e32 v79, v79
	v_exp_f32_e32 v80, v80
	v_exp_f32_e32 v81, v81
	v_exp_f32_e32 v82, v82
	v_exp_f32_e32 v83, v83
	v_exp_f32_e32 v84, v84
	v_exp_f32_e32 v85, v85
	v_exp_f32_e32 v86, v86
	v_exp_f32_e32 v87, v87
	v_exp_f32_e32 v88, v88
	v_exp_f32_e32 v89, v89
	v_exp_f32_e32 v90, v90
	v_exp_f32_e32 v91, v91
	v_exp_f32_e32 v92, v92
	v_exp_f32_e32 v93, v93
	v_exp_f32_e32 v94, v94
	v_exp_f32_e32 v95, v95
	v_exp_f32_e32 v96, v96
	v_exp_f32_e32 v97, v97
	v_exp_f32_e32 v98, v98
	v_exp_f32_e32 v99, v99
	v_exp_f32_e32 v100, v100
	v_exp_f32_e32 v101, v101
	v_exp_f32_e32 v102, v102
	v_exp_f32_e32 v103, v103
	v_exp_f32_e32 v104, v104
	v_exp_f32_e32 v105, v105
	v_exp_f32_e32 v106, v106
	v_exp_f32_e32 v107, v107
	v_exp_f32_e32 v108, v108
	v_exp_f32_e32 v109, v109
	v_exp_f32_e32 v110, v110
	v_exp_f32_e32 v111, v111
	v_exp_f32_e32 v112, v112
	v_exp_f32_e32 v113, v113
	v_exp_f32_e32 v114, v114
	v_exp_f32_e32 v115, v115
	v_exp_f32_e32 v116, v116
	v_exp_f32_e32 v117, v117
	v_exp_f32_e32 v219, v219
	v_pk_add_f32 v[236:237], v[50:51], v[52:53]
	v_pk_add_f32 v[238:239], v[54:55], v[56:57]
	v_pk_add_f32 v[240:241], v[58:59], v[60:61]
	v_pk_add_f32 v[242:243], v[62:63], v[64:65]
	v_pk_add_f32 v[236:237], v[236:237], v[66:67]
	v_pk_add_f32 v[238:239], v[238:239], v[70:71]
	v_pk_add_f32 v[240:241], v[240:241], v[74:75]
	v_pk_add_f32 v[242:243], v[242:243], v[78:79]
	v_pk_add_f32 v[236:237], v[236:237], v[68:69]
	v_pk_add_f32 v[238:239], v[238:239], v[72:73]
	v_pk_add_f32 v[240:241], v[240:241], v[76:77]
	v_pk_add_f32 v[242:243], v[242:243], v[80:81]
	v_pk_add_f32 v[236:237], v[236:237], v[82:83]
	v_pk_add_f32 v[238:239], v[238:239], v[86:87]
	v_pk_add_f32 v[240:241], v[240:241], v[90:91]
	v_pk_add_f32 v[242:243], v[242:243], v[94:95]
	v_pk_add_f32 v[236:237], v[236:237], v[84:85]
	v_pk_add_f32 v[238:239], v[238:239], v[88:89]
	v_pk_add_f32 v[240:241], v[240:241], v[92:93]
	v_pk_add_f32 v[242:243], v[242:243], v[96:97]
	v_pk_add_f32 v[236:237], v[236:237], v[98:99]
	v_pk_add_f32 v[238:239], v[238:239], v[102:103]
	v_pk_add_f32 v[240:241], v[240:241], v[106:107]
	v_pk_add_f32 v[242:243], v[242:243], v[110:111]
	v_pk_add_f32 v[236:237], v[236:237], v[100:101]
	v_pk_add_f32 v[238:239], v[238:239], v[104:105]
	v_pk_add_f32 v[240:241], v[240:241], v[108:109]
	v_pk_add_f32 v[242:243], v[242:243], v[112:113]
	v_pk_add_f32 v[236:237], v[236:237], v[114:115]
	v_pk_add_f32 v[236:237], v[236:237], v[116:117]
	v_pk_add_f32 v[236:237], v[236:237], v[238:239]
	v_pk_add_f32 v[240:241], v[240:241], v[242:243]
	v_cndmask_b32_e64 v219, 0, v219, s[74:75]
	v_pk_add_f32 v[236:237], v[236:237], v[240:241]
	v_add_f32_e32 v185, v236, v237
	v_add_f32_e32 v185, v185, v219
	v_cvt_pk_bf16_f32 v236, v50, v51
	v_cvt_pk_bf16_f32 v237, v52, v53
	v_cvt_pk_bf16_f32 v238, v54, v55
	v_cvt_pk_bf16_f32 v239, v56, v57
	s_nop 1
	s_waitcnt lgkmcnt(14)
; #define LAS __attribute__((address_space(3)))
; __device__ __forceinline__ unsigned pk2(float lo, float hi) { return pg8::cvt_pk_bf16(lo, hi); }
; __device__ __forceinline__ s16x4 vtr(const LAS unsigned char* p) { return __builtin_bit_cast(s16x4, __builtin_amdgcn_ds_read_tr16_b64_v4i16((LAS s16x4*)p)); }
; #define MFMA16(a, b, c) __builtin_amdgcn_mfma_f32_16x16x32_bf16((a), (b), (c), 0, 0, 0)
; __device__ __forceinline__ void pv_at(const LAS unsigned char* const (&vp)[4], int off, const f32x4& P0, const f32x4& P1, f32x4 (&O)[4]) {
;     v4u pw; pw.x = pk2(P0[0], P0[1]); pw.y = pk2(P0[2], P0[3]); pw.z = pk2(P1[0], P1[1]); pw.w = pk2(P1[2], P1[3]);
;     const bf16x8 pb = __builtin_bit_cast(bf16x8, pw);
; #pragma unroll
;     for (int db = 0; db < 4; ++db) {
;         const s16x4 lo = vtr(vp[db] + off), hi = vtr(vp[db] + off + 2048);
;         const bf16x8 vt = (bf16x8){lo[0], lo[1], lo[2], lo[3], hi[0], hi[1], hi[2], hi[3]};
;         O[db] = MFMA16(vt, pb, O[db]);
;     }
; }
	v_mfma_f32_16x16x32_bf16 v[210:213], v[186:189], v[236:239], 0
	s_waitcnt lgkmcnt(12)
	v_mfma_f32_16x16x32_bf16 v[214:217], v[190:193], v[236:239], 0
	s_waitcnt lgkmcnt(10)
	v_mfma_f32_16x16x32_bf16 v[220:223], v[194:197], v[236:239], 0
	s_waitcnt lgkmcnt(8)
	v_mfma_f32_16x16x32_bf16 v[224:227], v[198:201], v[236:239], 0
	v_cvt_pk_bf16_f32 v240, v58, v59
	v_cvt_pk_bf16_f32 v241, v60, v61
	v_cvt_pk_bf16_f32 v242, v62, v63
	v_cvt_pk_bf16_f32 v243, v64, v65
	s_waitcnt lgkmcnt(7)
	ds_read_b64_tr_b16 v[186:187], v124 offset:8192
	ds_read_b64_tr_b16 v[188:189], v124 offset:10240
	ds_read_b64_tr_b16 v[190:191], v125 offset:8192
	ds_read_b64_tr_b16 v[192:193], v125 offset:10240
	ds_read_b64_tr_b16 v[194:195], v126 offset:8192
	ds_read_b64_tr_b16 v[196:197], v126 offset:10240
	ds_read_b64_tr_b16 v[198:199], v127 offset:8192
	ds_read_b64_tr_b16 v[200:201], v127 offset:10240
	s_waitcnt lgkmcnt(14)
	v_mfma_f32_16x16x32_bf16 v[210:213], v[202:205], v[240:243], v[210:213]
	s_waitcnt lgkmcnt(12)
	v_mfma_f32_16x16x32_bf16 v[214:217], v[206:209], v[240:243], v[214:217]
	s_waitcnt lgkmcnt(10)
	v_mfma_f32_16x16x32_bf16 v[220:223], v[228:231], v[240:243], v[220:223]
	s_waitcnt lgkmcnt(8)
	v_mfma_f32_16x16x32_bf16 v[224:227], v[232:235], v[240:243], v[224:227]
	v_cvt_pk_bf16_f32 v236, v66, v67
	v_cvt_pk_bf16_f32 v237, v68, v69
	v_cvt_pk_bf16_f32 v238, v70, v71
	v_cvt_pk_bf16_f32 v239, v72, v73
	s_waitcnt lgkmcnt(7)
	ds_read_b64_tr_b16 v[202:203], v124 offset:12288
	ds_read_b64_tr_b16 v[204:205], v124 offset:14336
	ds_read_b64_tr_b16 v[206:207], v125 offset:12288
	ds_read_b64_tr_b16 v[208:209], v125 offset:14336
	ds_read_b64_tr_b16 v[228:229], v126 offset:12288
	ds_read_b64_tr_b16 v[230:231], v126 offset:14336
	ds_read_b64_tr_b16 v[232:233], v127 offset:12288
	ds_read_b64_tr_b16 v[234:235], v127 offset:14336
	s_waitcnt lgkmcnt(14)
	v_mfma_f32_16x16x32_bf16 v[210:213], v[186:189], v[236:239], v[210:213]
	s_waitcnt lgkmcnt(12)
	v_mfma_f32_16x16x32_bf16 v[214:217], v[190:193], v[236:239], v[214:217]
	s_waitcnt lgkmcnt(10)
	v_mfma_f32_16x16x32_bf16 v[220:223], v[194:197], v[236:239], v[220:223]
	s_waitcnt lgkmcnt(8)
	v_mfma_f32_16x16x32_bf16 v[224:227], v[198:201], v[236:239], v[224:227]
	v_cvt_pk_bf16_f32 v240, v74, v75
	v_cvt_pk_bf16_f32 v241, v76, v77
	v_cvt_pk_bf16_f32 v242, v78, v79
	v_cvt_pk_bf16_f32 v243, v80, v81
	s_waitcnt lgkmcnt(7)
	ds_read_b64_tr_b16 v[186:187], v124 offset:16384
	ds_read_b64_tr_b16 v[188:189], v124 offset:18432
	ds_read_b64_tr_b16 v[190:191], v125 offset:16384
	ds_read_b64_tr_b16 v[192:193], v125 offset:18432
	ds_read_b64_tr_b16 v[194:195], v126 offset:16384
	ds_read_b64_tr_b16 v[196:197], v126 offset:18432
	ds_read_b64_tr_b16 v[198:199], v127 offset:16384
	ds_read_b64_tr_b16 v[200:201], v127 offset:18432
	s_waitcnt lgkmcnt(14)
	v_mfma_f32_16x16x32_bf16 v[210:213], v[202:205], v[240:243], v[210:213]
	s_waitcnt lgkmcnt(12)
	v_mfma_f32_16x16x32_bf16 v[214:217], v[206:209], v[240:243], v[214:217]
	s_waitcnt lgkmcnt(10)
	v_mfma_f32_16x16x32_bf16 v[220:223], v[228:231], v[240:243], v[220:223]
	s_waitcnt lgkmcnt(8)
	v_mfma_f32_16x16x32_bf16 v[224:227], v[232:235], v[240:243], v[224:227]
	v_cvt_pk_bf16_f32 v236, v82, v83
	v_cvt_pk_bf16_f32 v237, v84, v85
	v_cvt_pk_bf16_f32 v238, v86, v87
	v_cvt_pk_bf16_f32 v239, v88, v89
	s_waitcnt lgkmcnt(7)
	ds_read_b64_tr_b16 v[202:203], v124 offset:20480
	ds_read_b64_tr_b16 v[204:205], v124 offset:22528
	ds_read_b64_tr_b16 v[206:207], v125 offset:20480
	ds_read_b64_tr_b16 v[208:209], v125 offset:22528
	ds_read_b64_tr_b16 v[228:229], v126 offset:20480
	ds_read_b64_tr_b16 v[230:231], v126 offset:22528
	ds_read_b64_tr_b16 v[232:233], v127 offset:20480
	ds_read_b64_tr_b16 v[234:235], v127 offset:22528
	s_waitcnt lgkmcnt(14)
	v_mfma_f32_16x16x32_bf16 v[210:213], v[186:189], v[236:239], v[210:213]
	s_waitcnt lgkmcnt(12)
	v_mfma_f32_16x16x32_bf16 v[214:217], v[190:193], v[236:239], v[214:217]
	s_waitcnt lgkmcnt(10)
	v_mfma_f32_16x16x32_bf16 v[220:223], v[194:197], v[236:239], v[220:223]
	s_waitcnt lgkmcnt(8)
	v_mfma_f32_16x16x32_bf16 v[224:227], v[198:201], v[236:239], v[224:227]
	v_cvt_pk_bf16_f32 v240, v90, v91
	v_cvt_pk_bf16_f32 v241, v92, v93
	v_cvt_pk_bf16_f32 v242, v94, v95
	v_cvt_pk_bf16_f32 v243, v96, v97
	s_waitcnt lgkmcnt(7)
	ds_read_b64_tr_b16 v[186:187], v124 offset:24576
	ds_read_b64_tr_b16 v[188:189], v124 offset:26624
	ds_read_b64_tr_b16 v[190:191], v125 offset:24576
	ds_read_b64_tr_b16 v[192:193], v125 offset:26624
	ds_read_b64_tr_b16 v[194:195], v126 offset:24576
	ds_read_b64_tr_b16 v[196:197], v126 offset:26624
	ds_read_b64_tr_b16 v[198:199], v127 offset:24576
	ds_read_b64_tr_b16 v[200:201], v127 offset:26624
	s_waitcnt lgkmcnt(14)
	v_mfma_f32_16x16x32_bf16 v[210:213], v[202:205], v[240:243], v[210:213]
	s_waitcnt lgkmcnt(12)
	v_mfma_f32_16x16x32_bf16 v[214:217], v[206:209], v[240:243], v[214:217]
	s_waitcnt lgkmcnt(10)
	v_mfma_f32_16x16x32_bf16 v[220:223], v[228:231], v[240:243], v[220:223]
	s_waitcnt lgkmcnt(8)
	v_mfma_f32_16x16x32_bf16 v[224:227], v[232:235], v[240:243], v[224:227]
	v_cvt_pk_bf16_f32 v236, v98, v99
	v_cvt_pk_bf16_f32 v237, v100, v101
	v_cvt_pk_bf16_f32 v238, v102, v103
	v_cvt_pk_bf16_f32 v239, v104, v105
	s_waitcnt lgkmcnt(7)
	ds_read_b64_tr_b16 v[202:203], v124 offset:28672
	ds_read_b64_tr_b16 v[204:205], v124 offset:30720
	ds_read_b64_tr_b16 v[206:207], v125 offset:28672
	ds_read_b64_tr_b16 v[208:209], v125 offset:30720
	ds_read_b64_tr_b16 v[228:229], v126 offset:28672
	ds_read_b64_tr_b16 v[230:231], v126 offset:30720
	ds_read_b64_tr_b16 v[232:233], v127 offset:28672
	ds_read_b64_tr_b16 v[234:235], v127 offset:30720
	s_waitcnt lgkmcnt(14)
; __device__ __forceinline__ unsigned pk2(float lo, float hi) { return pg8::cvt_pk_bf16(lo, hi); }
; __device__ __forceinline__ void store_o(bf16* yrow, int g, float l, const f32x4 (&O)[4]) {
;     const float inv = 1.0f / xrow16_sum(l);
;     unsigned wx[4], wy[4];
; #pragma unroll
;     for (int db = 0; db < 4; ++db) { wx[db] = pk2(O[db][0] * inv, O[db][1] * inv); wy[db] = pk2(O[db][2] * inv, O[db][3] * inv); }
; #pragma unroll
;     for (int p = 0; p < 2; ++p) {
;         auto rx = __builtin_amdgcn_permlane16_swap(wx[2 * p], wx[2 * p + 1], false, false); wx[2 * p] = rx[0]; wx[2 * p + 1] = rx[1];
;         auto ry = __builtin_amdgcn_permlane16_swap(wy[2 * p], wy[2 * p + 1], false, false); wy[2 * p] = ry[0]; wy[2 * p + 1] = ry[1]; }
; #pragma unroll
;     for (int p = 0; p < 2; ++p) {
;         auto rx = __builtin_amdgcn_permlane32_swap(wx[p], wx[p + 2], false, false); wx[p] = rx[0]; wx[p + 2] = rx[1];
;         auto ry = __builtin_amdgcn_permlane32_swap(wy[p], wy[p + 2], false, false); wy[p] = ry[0]; wy[p + 2] = ry[1]; }
;     v4u lo = {wx[0], wy[0], wx[1], wy[1]}, hi = {wx[2], wy[2], wx[3], wy[3]};
;     *(v4u*)(yrow + 16 * g) = lo; *(v4u*)(yrow + 16 * g + 8) = hi;
; }
; template <bool MASK> __device__ __forceinline__ void a_scores(f32x4& S0, f32x4& S1, float basef, float c1, float slope2, int krow0, int kstart) {
; #pragma unroll
;     for (int r = 0; r < 4; ++r) {
;         const float d0 = fabsf(basef - (float)r), d1 = fabsf(basef - (float)(16 + r));
;         const float v0 = S0[r] - slope2 * d0, v1 = S1[r] - slope2 * d1;
;         if (MASK) { const int p0 = kstart + krow0 + r, p1 = p0 + 16;
;             S0[r] = (d0 <= 128.f && p0 >= 0 && p0 < SEQ) ? v0 : -INFINITY; S1[r] = (d1 <= 128.f && p1 >= 0 && p1 < SEQ) ? v1 : -INFINITY; }
;         else { S0[r] = v0; S1[r] = v1; }
;     }
; }
	v_mfma_f32_16x16x32_bf16 v[210:213], v[186:189], v[236:239], v[210:213]
	s_waitcnt lgkmcnt(12)
	v_mfma_f32_16x16x32_bf16 v[214:217], v[190:193], v[236:239], v[214:217]
	s_waitcnt lgkmcnt(10)
	v_mfma_f32_16x16x32_bf16 v[220:223], v[194:197], v[236:239], v[220:223]
	s_waitcnt lgkmcnt(8)
	v_mfma_f32_16x16x32_bf16 v[224:227], v[198:201], v[236:239], v[224:227]
	v_cvt_pk_bf16_f32 v240, v106, v107
	v_cvt_pk_bf16_f32 v241, v108, v109
	v_cvt_pk_bf16_f32 v242, v110, v111
	v_cvt_pk_bf16_f32 v243, v112, v113
	s_waitcnt lgkmcnt(7)
	ds_read_b64_tr_b16 v[186:187], v124 offset:32768
	ds_read_b64_tr_b16 v[188:189], v124 offset:34816
	ds_read_b64_tr_b16 v[190:191], v125 offset:32768
	ds_read_b64_tr_b16 v[192:193], v125 offset:34816
	ds_read_b64_tr_b16 v[194:195], v126 offset:32768
	ds_read_b64_tr_b16 v[196:197], v126 offset:34816
	ds_read_b64_tr_b16 v[198:199], v127 offset:32768
	ds_read_b64_tr_b16 v[200:201], v127 offset:34816
	s_waitcnt lgkmcnt(14)
	v_mfma_f32_16x16x32_bf16 v[210:213], v[202:205], v[240:243], v[210:213]
	s_waitcnt lgkmcnt(12)
	v_mfma_f32_16x16x32_bf16 v[214:217], v[206:209], v[240:243], v[214:217]
	s_waitcnt lgkmcnt(10)
	v_mfma_f32_16x16x32_bf16 v[220:223], v[228:231], v[240:243], v[220:223]
	s_waitcnt lgkmcnt(8)
	v_mfma_f32_16x16x32_bf16 v[224:227], v[232:235], v[240:243], v[224:227]
	v_cvt_pk_bf16_f32 v236, v114, v115
	v_cvt_pk_bf16_f32 v237, v116, v117
	v_mov_b32_e32 v238, 0
	v_mov_b32_e32 v239, 0
	s_nop 1
	s_waitcnt lgkmcnt(6)
	v_mfma_f32_16x16x32_bf16 v[210:213], v[186:189], v[236:239], v[210:213]
	s_waitcnt lgkmcnt(4)
	v_mfma_f32_16x16x32_bf16 v[214:217], v[190:193], v[236:239], v[214:217]
	s_waitcnt lgkmcnt(2)
	v_mfma_f32_16x16x32_bf16 v[220:223], v[194:197], v[236:239], v[220:223]
	s_waitcnt lgkmcnt(0)
	v_mfma_f32_16x16x32_bf16 v[224:227], v[198:201], v[236:239], v[224:227]
	v_mov_b32_e32 v219, v185
	s_nop 1
	v_permlane16_swap_b32_e32 v185, v219
	v_add_f32_e32 v185, v185, v219
	v_mov_b32_e32 v219, v185
	s_nop 1
	v_permlane32_swap_b32_e32 v185, v219
	v_add_f32_e32 v185, v185, v219
	v_div_scale_f32 v236, s[78:79], v185, v185, 1.0
	v_div_scale_f32 v237, vcc, 1.0, v185, 1.0
	v_rcp_f32_e32 v238, v236
	s_nop 0
	v_fma_f32 v239, -v236, v238, 1.0
	v_fmac_f32_e32 v238, v239, v238
	v_mul_f32_e32 v240, v237, v238
	v_fma_f32 v241, -v236, v240, v237
	v_fmac_f32_e32 v240, v241, v238
	v_fma_f32 v237, -v236, v240, v237
	v_div_fmas_f32 v237, v237, v238, v240
	v_div_fixup_f32 v244, v237, v185, 1.0
	v_mul_f32_e32 v240, v210, v244
	v_mul_f32_e32 v241, v211, v244
	v_mul_f32_e32 v242, v212, v244
	v_mul_f32_e32 v243, v213, v244
	v_cvt_pk_bf16_f32 v186, v240, v241
	v_cvt_pk_bf16_f32 v187, v242, v243
	v_mul_f32_e32 v240, v214, v244
	v_mul_f32_e32 v241, v215, v244
	v_mul_f32_e32 v242, v216, v244
	v_mul_f32_e32 v243, v217, v244
	v_cvt_pk_bf16_f32 v188, v240, v241
	v_cvt_pk_bf16_f32 v189, v242, v243
	v_mul_f32_e32 v240, v220, v244
	v_mul_f32_e32 v241, v221, v244
	v_mul_f32_e32 v242, v222, v244
	v_mul_f32_e32 v243, v223, v244
	v_cvt_pk_bf16_f32 v190, v240, v241
	v_cvt_pk_bf16_f32 v191, v242, v243
	v_mul_f32_e32 v240, v224, v244
	v_mul_f32_e32 v241, v225, v244
	v_mul_f32_e32 v242, v226, v244
	v_mul_f32_e32 v243, v227, v244
	v_cvt_pk_bf16_f32 v192, v240, v241
	v_cvt_pk_bf16_f32 v193, v242, v243
	s_nop 1
	v_permlane16_swap_b32_e32 v186, v188
	v_permlane16_swap_b32_e32 v187, v189
	v_permlane16_swap_b32_e32 v190, v192
	v_permlane16_swap_b32_e32 v191, v193
	s_nop 0
	v_permlane32_swap_b32_e32 v186, v190
	v_permlane32_swap_b32_e32 v187, v191
	v_permlane32_swap_b32_e32 v188, v192
	v_permlane32_swap_b32_e32 v189, v193
	global_store_dwordx4 v128, v[186:189], s[82:83] offset:0
	global_store_dwordx4 v128, v[190:193], s[82:83] offset:16
	s_nop 1
	v_fmamk_f32 v50, v130, 0x43000000, v132
	v_fmamk_f32 v51, v130, 0x42fe0000, v132
	v_fmamk_f32 v52, v130, 0x42fc0000, v132
	v_fmamk_f32 v53, v130, 0x42fa0000, v132
	v_fmamk_f32 v54, v130, 0x42e00000, v132
	v_fmamk_f32 v55, v130, 0x42de0000, v132
	v_fmamk_f32 v56, v130, 0x42dc0000, v132
	v_fmamk_f32 v57, v130, 0x42da0000, v132
	v_fmamk_f32 v58, v130, 0x42c00000, v132
	v_fmamk_f32 v59, v130, 0x42be0000, v132
	v_fmamk_f32 v60, v130, 0x42bc0000, v132
	v_fmamk_f32 v61, v130, 0x42ba0000, v132
	v_fmamk_f32 v62, v130, 0x42a00000, v132
	v_fmamk_f32 v63, v130, 0x429e0000, v132
	v_fmamk_f32 v64, v130, 0x429c0000, v132
	v_fmamk_f32 v65, v130, 0x429a0000, v132
	v_fmamk_f32 v66, v130, 0x42800000, v132
	v_fmamk_f32 v67, v130, 0x427c0000, v132
	v_fmamk_f32 v68, v130, 0x42780000, v132
	v_fmamk_f32 v69, v130, 0x42740000, v132
	v_fmamk_f32 v70, v130, 0x42400000, v132
	v_fmamk_f32 v71, v130, 0x423c0000, v132
	v_fmamk_f32 v72, v130, 0x42380000, v132
	v_fmamk_f32 v73, v130, 0x42340000, v132
	v_fmamk_f32 v74, v130, 0x42000000, v132
	v_fmamk_f32 v75, v130, 0x41f80000, v132
	v_fmamk_f32 v76, v130, 0x41f00000, v132
	v_fmamk_f32 v77, v130, 0x41e80000, v132
	v_fmamk_f32 v78, v130, 0x41800000, v132
	v_fmamk_f32 v79, v130, 0x41700000, v132
	v_fmamk_f32 v80, v130, 0x41600000, v132
	v_fmamk_f32 v81, v130, 0x41500000, v132
	v_add_f32_e32 v219, 0, v129
	v_mul_f32_e64 v82, v130, |v219|
	v_add_f32_e32 v244, 0xbf800000, v129
	v_mul_f32_e64 v83, v130, |v244|
	v_add_f32_e32 v219, 0xc0000000, v129
	v_mul_f32_e64 v84, v130, |v219|
	v_add_f32_e32 v244, 0xc0400000, v129
	v_mul_f32_e64 v85, v130, |v244|
	v_fmamk_f32 v86, v131, 0xc1800000, v133
	v_fmamk_f32 v87, v131, 0xc1880000, v133
	v_fmamk_f32 v88, v131, 0xc1900000, v133
	v_fmamk_f32 v89, v131, 0xc1980000, v133
	v_fmamk_f32 v90, v131, 0xc2000000, v133
	v_fmamk_f32 v91, v131, 0xc2040000, v133
	v_fmamk_f32 v92, v131, 0xc2080000, v133
	v_fmamk_f32 v93, v131, 0xc20c0000, v133
	v_fmamk_f32 v94, v131, 0xc2400000, v133
; #define LAS __attribute__((address_space(3)))
; #define MFMA16(a, b, c) __builtin_amdgcn_mfma_f32_16x16x32_bf16((a), (b), (c), 0, 0, 0)
; __device__ __forceinline__ void qk_at(const LAS unsigned char* kp0, const LAS unsigned char* kp1, int off, bf16x8 qf0, bf16x8 qf1, f32x4& S0, f32x4& S1) {
;     const bf16x8 k00 = *(const LAS bf16x8*)(kp0 + off), k01 = *(const LAS bf16x8*)(kp1 + off);
;     const bf16x8 k10 = *(const LAS bf16x8*)(kp0 + off + 2048), k11 = *(const LAS bf16x8*)(kp1 + off + 2048);
;     const f32x4 z = {0.f, 0.f, 0.f, 0.f};
;     S0 = MFMA16(k00, qf0, z); S0 = MFMA16(k01, qf1, S0);
;     S1 = MFMA16(k10, qf0, z); S1 = MFMA16(k11, qf1, S1);
; }
; template <bool MASK> __device__ __forceinline__ void a_scores(f32x4& S0, f32x4& S1, float basef, float c1, float slope2, int krow0, int kstart) {
; #pragma unroll
;     for (int r = 0; r < 4; ++r) {
;         const float d0 = fabsf(basef - (float)r), d1 = fabsf(basef - (float)(16 + r));
;         const float v0 = S0[r] - slope2 * d0, v1 = S1[r] - slope2 * d1;
;         if (MASK) { const int p0 = kstart + krow0 + r, p1 = p0 + 16;
;             S0[r] = (d0 <= 128.f && p0 >= 0 && p0 < SEQ) ? v0 : -INFINITY; S1[r] = (d1 <= 128.f && p1 >= 0 && p1 < SEQ) ? v1 : -INFINITY; }
;         else { S0[r] = v0; S1[r] = v1; }
;     }
; }
	v_fmamk_f32 v95, v131, 0xc2440000, v133
	v_fmamk_f32 v96, v131, 0xc2480000, v133
	v_fmamk_f32 v97, v131, 0xc24c0000, v133
	v_fmamk_f32 v98, v131, 0xc2800000, v133
	v_fmamk_f32 v99, v131, 0xc2820000, v133
	v_fmamk_f32 v100, v131, 0xc2840000, v133
	v_fmamk_f32 v101, v131, 0xc2860000, v133
	v_fmamk_f32 v102, v131, 0xc2a00000, v133
	v_fmamk_f32 v103, v131, 0xc2a20000, v133
	v_fmamk_f32 v104, v131, 0xc2a40000, v133
	v_fmamk_f32 v105, v131, 0xc2a60000, v133
	v_fmamk_f32 v106, v131, 0xc2c00000, v133
	v_fmamk_f32 v107, v131, 0xc2c20000, v133
	v_fmamk_f32 v108, v131, 0xc2c40000, v133
	v_fmamk_f32 v109, v131, 0xc2c60000, v133
	v_fmamk_f32 v110, v131, 0xc2e00000, v133
	v_fmamk_f32 v111, v131, 0xc2e20000, v133
	v_fmamk_f32 v112, v131, 0xc2e40000, v133
	v_fmamk_f32 v113, v131, 0xc2e60000, v133
	v_fmamk_f32 v114, v131, 0xc3000000, v133
	v_fmamk_f32 v115, v131, 0xc3010000, v133
	v_fmamk_f32 v116, v131, 0xc3020000, v133
	v_fmamk_f32 v117, v131, 0xc3030000, v133
	v_mov_b32_e32 v245, 0xff800000
	v_cndmask_b32_e64 v50, v245, v50, s[16:17]
	v_cndmask_b32_e64 v51, v245, v51, s[18:19]
	v_cndmask_b32_e64 v52, v245, v52, s[22:23]
	v_cndmask_b32_e64 v53, v245, v53, s[24:25]
	v_cndmask_b32_e64 v114, v245, v114, s[28:29]
	v_cndmask_b32_e64 v115, v245, v115, s[52:53]
	v_cndmask_b32_e64 v116, v245, v116, s[54:55]
	v_cndmask_b32_e64 v117, v245, v117, s[88:89]
	ds_read_b128 v[186:189], v122 offset:2048
	ds_read_b128 v[190:193], v123 offset:2048
	ds_read_b128 v[194:197], v122 offset:4096
	ds_read_b128 v[198:201], v123 offset:4096
	ds_read_b128 v[202:205], v122 offset:6144
	ds_read_b128 v[206:209], v123 offset:6144
	s_waitcnt lgkmcnt(5)
	v_mfma_f32_16x16x32_bf16 v[50:53], v[186:189], v[154:157], v[50:53]
	s_waitcnt lgkmcnt(4)
	v_mfma_f32_16x16x32_bf16 v[50:53], v[190:193], v[158:161], v[50:53]
	ds_read_b128 v[186:189], v122 offset:8192
	ds_read_b128 v[190:193], v123 offset:8192
	s_waitcnt lgkmcnt(5)
	v_mfma_f32_16x16x32_bf16 v[54:57], v[194:197], v[154:157], v[54:57]
	s_waitcnt lgkmcnt(4)
	v_mfma_f32_16x16x32_bf16 v[54:57], v[198:201], v[158:161], v[54:57]
	ds_read_b128 v[194:197], v122 offset:10240
	ds_read_b128 v[198:201], v123 offset:10240
	s_waitcnt lgkmcnt(5)
	v_mfma_f32_16x16x32_bf16 v[58:61], v[202:205], v[154:157], v[58:61]
	s_waitcnt lgkmcnt(4)
	v_mfma_f32_16x16x32_bf16 v[58:61], v[206:209], v[158:161], v[58:61]
	ds_read_b128 v[202:205], v122 offset:12288
	ds_read_b128 v[206:209], v123 offset:12288
	s_waitcnt lgkmcnt(5)
	v_mfma_f32_16x16x32_bf16 v[62:65], v[186:189], v[154:157], v[62:65]
	s_waitcnt lgkmcnt(4)
	v_mfma_f32_16x16x32_bf16 v[62:65], v[190:193], v[158:161], v[62:65]
	ds_read_b128 v[186:189], v122 offset:14336
	ds_read_b128 v[190:193], v123 offset:14336
	s_waitcnt lgkmcnt(5)
	v_mfma_f32_16x16x32_bf16 v[66:69], v[194:197], v[154:157], v[66:69]
	s_waitcnt lgkmcnt(4)
	v_mfma_f32_16x16x32_bf16 v[66:69], v[198:201], v[158:161], v[66:69]
	ds_read_b128 v[194:197], v122 offset:16384
	ds_read_b128 v[198:201], v123 offset:16384
	s_waitcnt lgkmcnt(5)
	v_mfma_f32_16x16x32_bf16 v[70:73], v[202:205], v[154:157], v[70:73]
	s_waitcnt lgkmcnt(4)
	v_mfma_f32_16x16x32_bf16 v[70:73], v[206:209], v[158:161], v[70:73]
	ds_read_b128 v[202:205], v122 offset:18432
	ds_read_b128 v[206:209], v123 offset:18432
	s_waitcnt lgkmcnt(5)
	v_mfma_f32_16x16x32_bf16 v[74:77], v[186:189], v[154:157], v[74:77]
	s_waitcnt lgkmcnt(4)
	v_mfma_f32_16x16x32_bf16 v[74:77], v[190:193], v[158:161], v[74:77]
	ds_read_b128 v[186:189], v122 offset:20480
	ds_read_b128 v[190:193], v123 offset:20480
	s_waitcnt lgkmcnt(5)
	v_mfma_f32_16x16x32_bf16 v[78:81], v[194:197], v[154:157], v[78:81]
	s_waitcnt lgkmcnt(4)
	v_mfma_f32_16x16x32_bf16 v[78:81], v[198:201], v[158:161], v[78:81]
	ds_read_b128 v[194:197], v122 offset:22528
	ds_read_b128 v[198:201], v123 offset:22528
	s_waitcnt lgkmcnt(5)
	v_mfma_f32_16x16x32_bf16 v[82:85], v[202:205], v[154:157], v[82:85]
	s_waitcnt lgkmcnt(4)
	v_mfma_f32_16x16x32_bf16 v[82:85], v[206:209], v[158:161], v[82:85]
	ds_read_b128 v[202:205], v122 offset:24576
	ds_read_b128 v[206:209], v123 offset:24576
	s_waitcnt lgkmcnt(5)
	v_mfma_f32_16x16x32_bf16 v[86:89], v[186:189], v[154:157], v[86:89]
	s_waitcnt lgkmcnt(4)
	v_mfma_f32_16x16x32_bf16 v[86:89], v[190:193], v[158:161], v[86:89]
	ds_read_b128 v[186:189], v122 offset:26624
	ds_read_b128 v[190:193], v123 offset:26624
	s_waitcnt lgkmcnt(5)
	v_mfma_f32_16x16x32_bf16 v[90:93], v[194:197], v[154:157], v[90:93]
	s_waitcnt lgkmcnt(4)
	v_mfma_f32_16x16x32_bf16 v[90:93], v[198:201], v[158:161], v[90:93]
	ds_read_b128 v[194:197], v122 offset:28672
	ds_read_b128 v[198:201], v123 offset:28672
	s_waitcnt lgkmcnt(5)
	v_mfma_f32_16x16x32_bf16 v[94:97], v[202:205], v[154:157], v[94:97]
	s_waitcnt lgkmcnt(4)
	v_mfma_f32_16x16x32_bf16 v[94:97], v[206:209], v[158:161], v[94:97]
	ds_read_b128 v[202:205], v122 offset:30720
	ds_read_b128 v[206:209], v123 offset:30720
	s_waitcnt lgkmcnt(5)
	v_mfma_f32_16x16x32_bf16 v[98:101], v[186:189], v[154:157], v[98:101]
	s_waitcnt lgkmcnt(4)
	v_mfma_f32_16x16x32_bf16 v[98:101], v[190:193], v[158:161], v[98:101]
	ds_read_b128 v[186:189], v122 offset:32768
	ds_read_b128 v[190:193], v123 offset:32768
	s_waitcnt lgkmcnt(5)
	v_mfma_f32_16x16x32_bf16 v[102:105], v[194:197], v[154:157], v[102:105]
	s_waitcnt lgkmcnt(4)
	v_mfma_f32_16x16x32_bf16 v[102:105], v[198:201], v[158:161], v[102:105]
	ds_read_b128 v[194:197], v122 offset:34816
	ds_read_b128 v[198:201], v123 offset:34816
	s_waitcnt lgkmcnt(5)
	v_mfma_f32_16x16x32_bf16 v[106:109], v[202:205], v[154:157], v[106:109]
	s_waitcnt lgkmcnt(4)
	v_mfma_f32_16x16x32_bf16 v[106:109], v[206:209], v[158:161], v[106:109]
	s_waitcnt lgkmcnt(3)
; #define LAS __attribute__((address_space(3)))
; #define MFMA16(a, b, c) __builtin_amdgcn_mfma_f32_16x16x32_bf16((a), (b), (c), 0, 0, 0)
; __device__ __forceinline__ void qk_at(const LAS unsigned char* kp0, const LAS unsigned char* kp1, int off, bf16x8 qf0, bf16x8 qf1, f32x4& S0, f32x4& S1) {
;     const bf16x8 k00 = *(const LAS bf16x8*)(kp0 + off), k01 = *(const LAS bf16x8*)(kp1 + off);
;     const bf16x8 k10 = *(const LAS bf16x8*)(kp0 + off + 2048), k11 = *(const LAS bf16x8*)(kp1 + off + 2048);
;     const f32x4 z = {0.f, 0.f, 0.f, 0.f};
;     S0 = MFMA16(k00, qf0, z); S0 = MFMA16(k01, qf1, S0);
;     S1 = MFMA16(k10, qf0, z); S1 = MFMA16(k11, qf1, S1);
; }
; __device__ __forceinline__ void softmax_step(f32x4& s0, f32x4& s1, float& m, float& l, f32x4 (&O)[4]) {
;     float t = fmaxf(fmaxf(fmaxf(s0[0], s0[1]), fmaxf(s0[2], s0[3])), fmaxf(fmaxf(s1[0], s1[1]), fmaxf(s1[2], s1[3])));
;     t = xrow16_max(t);
;     const float mn = fmaxf(m, t), alpha = __builtin_amdgcn_exp2f(m - mn);
	v_mfma_f32_16x16x32_bf16 v[110:113], v[186:189], v[154:157], v[110:113]
	s_waitcnt lgkmcnt(2)
	v_mfma_f32_16x16x32_bf16 v[110:113], v[190:193], v[158:161], v[110:113]
	s_waitcnt lgkmcnt(1)
	v_mfma_f32_16x16x32_bf16 v[114:117], v[194:197], v[154:157], v[114:117]
	s_waitcnt lgkmcnt(0)
	v_mfma_f32_16x16x32_bf16 v[114:117], v[198:201], v[158:161], v[114:117]
	v_max3_f32 v219, v50, v51, v52
	v_max3_f32 v244, v54, v55, v56
	v_max3_f32 v245, v58, v59, v60
	v_max3_f32 v120, v62, v63, v64
	v_max3_f32 v219, v219, v53, v66
	v_max3_f32 v244, v244, v57, v70
	v_max3_f32 v245, v245, v61, v74
	v_max3_f32 v120, v120, v65, v78
	v_max3_f32 v219, v219, v67, v68
	v_max3_f32 v244, v244, v71, v72
	v_max3_f32 v245, v245, v75, v76
	v_max3_f32 v120, v120, v79, v80
	ds_read_b64_tr_b16 v[186:187], v124 offset:2048
	ds_read_b64_tr_b16 v[188:189], v124 offset:4096
	ds_read_b64_tr_b16 v[190:191], v125 offset:2048
	ds_read_b64_tr_b16 v[192:193], v125 offset:4096
	ds_read_b64_tr_b16 v[194:195], v126 offset:2048
	ds_read_b64_tr_b16 v[196:197], v126 offset:4096
	ds_read_b64_tr_b16 v[198:199], v127 offset:2048
	ds_read_b64_tr_b16 v[200:201], v127 offset:4096
	v_max3_f32 v219, v219, v69, v82
	v_max3_f32 v244, v244, v73, v86
	v_max3_f32 v245, v245, v77, v90
	v_max3_f32 v120, v120, v81, v94
	v_max3_f32 v219, v219, v83, v84
	v_max3_f32 v244, v244, v87, v88
	v_max3_f32 v245, v245, v91, v92
	v_max3_f32 v120, v120, v95, v96
	v_max3_f32 v219, v219, v85, v98
	v_max3_f32 v244, v244, v89, v102
	v_max3_f32 v245, v245, v93, v106
	v_max3_f32 v120, v120, v97, v110
	v_max3_f32 v219, v219, v99, v100
	v_max3_f32 v244, v244, v103, v104
	v_max3_f32 v245, v245, v107, v108
	v_max3_f32 v120, v120, v111, v112
	v_max3_f32 v219, v219, v101, v114
	v_max3_f32 v219, v219, v115, v116
	v_max_f32_e32 v219, v219, v117
	v_max_f32_e32 v244, v244, v105
	v_max_f32_e32 v245, v245, v109
	v_max_f32_e32 v120, v120, v113
	v_max3_f32 v178, v219, v244, v245
	v_max_f32_e32 v178, v178, v120
	v_mov_b32_e32 v219, v178
	s_nop 1
	v_permlane16_swap_b32_e32 v178, v219
	v_max_f32_e32 v178, v178, v219
	v_mov_b32_e32 v219, v178
	s_nop 1
	v_permlane32_swap_b32_e32 v178, v219
	v_max3_f32 v178, v178, v219, v145
	s_waitcnt lgkmcnt(7)
	ds_read_b64_tr_b16 v[202:203], v124 offset:6144
	ds_read_b64_tr_b16 v[204:205], v124 offset:8192
	ds_read_b64_tr_b16 v[206:207], v125 offset:6144
	ds_read_b64_tr_b16 v[208:209], v125 offset:8192
	ds_read_b64_tr_b16 v[228:229], v126 offset:6144
	ds_read_b64_tr_b16 v[230:231], v126 offset:8192
	ds_read_b64_tr_b16 v[232:233], v127 offset:6144
	ds_read_b64_tr_b16 v[234:235], v127 offset:8192
	v_mov_b32_e32 v244, v178
	v_pk_add_f32 v[50:51], v[50:51], v[244:245] op_sel_hi:[1,0] neg_lo:[0,1] neg_hi:[0,1]
	v_pk_add_f32 v[52:53], v[52:53], v[244:245] op_sel_hi:[1,0] neg_lo:[0,1] neg_hi:[0,1]
	v_pk_add_f32 v[54:55], v[54:55], v[244:245] op_sel_hi:[1,0] neg_lo:[0,1] neg_hi:[0,1]
	v_pk_add_f32 v[56:57], v[56:57], v[244:245] op_sel_hi:[1,0] neg_lo:[0,1] neg_hi:[0,1]
	v_pk_add_f32 v[58:59], v[58:59], v[244:245] op_sel_hi:[1,0] neg_lo:[0,1] neg_hi:[0,1]
	v_pk_add_f32 v[60:61], v[60:61], v[244:245] op_sel_hi:[1,0] neg_lo:[0,1] neg_hi:[0,1]
	v_pk_add_f32 v[62:63], v[62:63], v[244:245] op_sel_hi:[1,0] neg_lo:[0,1] neg_hi:[0,1]
	v_pk_add_f32 v[64:65], v[64:65], v[244:245] op_sel_hi:[1,0] neg_lo:[0,1] neg_hi:[0,1]
	v_pk_add_f32 v[66:67], v[66:67], v[244:245] op_sel_hi:[1,0] neg_lo:[0,1] neg_hi:[0,1]
	v_pk_add_f32 v[68:69], v[68:69], v[244:245] op_sel_hi:[1,0] neg_lo:[0,1] neg_hi:[0,1]
	v_pk_add_f32 v[70:71], v[70:71], v[244:245] op_sel_hi:[1,0] neg_lo:[0,1] neg_hi:[0,1]
	v_pk_add_f32 v[72:73], v[72:73], v[244:245] op_sel_hi:[1,0] neg_lo:[0,1] neg_hi:[0,1]
	v_pk_add_f32 v[74:75], v[74:75], v[244:245] op_sel_hi:[1,0] neg_lo:[0,1] neg_hi:[0,1]
	v_pk_add_f32 v[76:77], v[76:77], v[244:245] op_sel_hi:[1,0] neg_lo:[0,1] neg_hi:[0,1]
	v_pk_add_f32 v[78:79], v[78:79], v[244:245] op_sel_hi:[1,0] neg_lo:[0,1] neg_hi:[0,1]
	v_pk_add_f32 v[80:81], v[80:81], v[244:245] op_sel_hi:[1,0] neg_lo:[0,1] neg_hi:[0,1]
	v_pk_add_f32 v[82:83], v[82:83], v[244:245] op_sel_hi:[1,0] neg_lo:[0,1] neg_hi:[0,1]
	v_pk_add_f32 v[84:85], v[84:85], v[244:245] op_sel_hi:[1,0] neg_lo:[0,1] neg_hi:[0,1]
	v_pk_add_f32 v[86:87], v[86:87], v[244:245] op_sel_hi:[1,0] neg_lo:[0,1] neg_hi:[0,1]
	v_pk_add_f32 v[88:89], v[88:89], v[244:245] op_sel_hi:[1,0] neg_lo:[0,1] neg_hi:[0,1]
	v_pk_add_f32 v[90:91], v[90:91], v[244:245] op_sel_hi:[1,0] neg_lo:[0,1] neg_hi:[0,1]
	v_pk_add_f32 v[92:93], v[92:93], v[244:245] op_sel_hi:[1,0] neg_lo:[0,1] neg_hi:[0,1]
	v_pk_add_f32 v[94:95], v[94:95], v[244:245] op_sel_hi:[1,0] neg_lo:[0,1] neg_hi:[0,1]
	v_pk_add_f32 v[96:97], v[96:97], v[244:245] op_sel_hi:[1,0] neg_lo:[0,1] neg_hi:[0,1]
	v_pk_add_f32 v[98:99], v[98:99], v[244:245] op_sel_hi:[1,0] neg_lo:[0,1] neg_hi:[0,1]
	v_pk_add_f32 v[100:101], v[100:101], v[244:245] op_sel_hi:[1,0] neg_lo:[0,1] neg_hi:[0,1]
	v_pk_add_f32 v[102:103], v[102:103], v[244:245] op_sel_hi:[1,0] neg_lo:[0,1] neg_hi:[0,1]
	v_pk_add_f32 v[104:105], v[104:105], v[244:245] op_sel_hi:[1,0] neg_lo:[0,1] neg_hi:[0,1]
	v_pk_add_f32 v[106:107], v[106:107], v[244:245] op_sel_hi:[1,0] neg_lo:[0,1] neg_hi:[0,1]
	v_pk_add_f32 v[108:109], v[108:109], v[244:245] op_sel_hi:[1,0] neg_lo:[0,1] neg_hi:[0,1]
	v_pk_add_f32 v[110:111], v[110:111], v[244:245] op_sel_hi:[1,0] neg_lo:[0,1] neg_hi:[0,1]
	v_pk_add_f32 v[112:113], v[112:113], v[244:245] op_sel_hi:[1,0] neg_lo:[0,1] neg_hi:[0,1]
	v_pk_add_f32 v[114:115], v[114:115], v[244:245] op_sel_hi:[1,0] neg_lo:[0,1] neg_hi:[0,1]
	v_pk_add_f32 v[116:117], v[116:117], v[244:245] op_sel_hi:[1,0] neg_lo:[0,1] neg_hi:[0,1]
	v_sub_f32_e32 v219, v145, v178
	v_exp_f32_e32 v50, v50
; #define LAS __attribute__((address_space(3)))
; __device__ __forceinline__ unsigned pk2(float lo, float hi) { return pg8::cvt_pk_bf16(lo, hi); }
; __device__ __forceinline__ s16x4 vtr(const LAS unsigned char* p) { return __builtin_bit_cast(s16x4, __builtin_amdgcn_ds_read_tr16_b64_v4i16((LAS s16x4*)p)); }
; #define MFMA16(a, b, c) __builtin_amdgcn_mfma_f32_16x16x32_bf16((a), (b), (c), 0, 0, 0)
; __device__ __forceinline__ void pv_at(const LAS unsigned char* const (&vp)[4], int off, const f32x4& P0, const f32x4& P1, f32x4 (&O)[4]) {
;     v4u pw; pw.x = pk2(P0[0], P0[1]); pw.y = pk2(P0[2], P0[3]); pw.z = pk2(P1[0], P1[1]); pw.w = pk2(P1[2], P1[3]);
;     const bf16x8 pb = __builtin_bit_cast(bf16x8, pw);
; #pragma unroll
;     for (int db = 0; db < 4; ++db) {
;         const s16x4 lo = vtr(vp[db] + off), hi = vtr(vp[db] + off + 2048);
;         const bf16x8 vt = (bf16x8){lo[0], lo[1], lo[2], lo[3], hi[0], hi[1], hi[2], hi[3]};
;         O[db] = MFMA16(vt, pb, O[db]);
;     }
; }
; __device__ __forceinline__ void softmax_step(f32x4& s0, f32x4& s1, float& m, float& l, f32x4 (&O)[4]) {
;     float t = fmaxf(fmaxf(fmaxf(s0[0], s0[1]), fmaxf(s0[2], s0[3])), fmaxf(fmaxf(s1[0], s1[1]), fmaxf(s1[2], s1[3])));
;     t = xrow16_max(t);
;     const float mn = fmaxf(m, t), alpha = __builtin_amdgcn_exp2f(m - mn);
;     m = mn;
; #pragma unroll
;     for (int k = 0; k < 4; ++k) { s0[k] = __builtin_amdgcn_exp2f(s0[k] - mn); s1[k] = __builtin_amdgcn_exp2f(s1[k] - mn); }
;     l = l * alpha + ((s0[0] + s0[1]) + (s0[2] + s0[3])) + ((s1[0] + s1[1]) + (s1[2] + s1[3]));
; #pragma unroll
;     for (int db = 0; db < 4; ++db) O[db] *= alpha;
; }
	v_exp_f32_e32 v51, v51
	v_exp_f32_e32 v52, v52
	v_exp_f32_e32 v53, v53
	v_exp_f32_e32 v54, v54
	v_exp_f32_e32 v55, v55
	v_exp_f32_e32 v56, v56
	v_exp_f32_e32 v57, v57
	v_exp_f32_e32 v58, v58
	v_exp_f32_e32 v59, v59
	v_exp_f32_e32 v60, v60
	v_exp_f32_e32 v61, v61
	v_exp_f32_e32 v62, v62
	v_exp_f32_e32 v63, v63
	v_exp_f32_e32 v64, v64
	v_exp_f32_e32 v65, v65
	v_exp_f32_e32 v66, v66
	v_exp_f32_e32 v67, v67
	v_exp_f32_e32 v68, v68
	v_exp_f32_e32 v69, v69
	v_exp_f32_e32 v70, v70
	v_exp_f32_e32 v71, v71
	v_exp_f32_e32 v72, v72
	v_exp_f32_e32 v73, v73
	v_exp_f32_e32 v74, v74
	v_exp_f32_e32 v75, v75
	v_exp_f32_e32 v76, v76
	v_exp_f32_e32 v77, v77
	v_exp_f32_e32 v78, v78
	v_exp_f32_e32 v79, v79
	v_exp_f32_e32 v80, v80
	v_exp_f32_e32 v81, v81
	v_exp_f32_e32 v82, v82
	v_exp_f32_e32 v83, v83
	v_exp_f32_e32 v84, v84
	v_exp_f32_e32 v85, v85
	v_exp_f32_e32 v86, v86
	v_exp_f32_e32 v87, v87
	v_exp_f32_e32 v88, v88
	v_exp_f32_e32 v89, v89
	v_exp_f32_e32 v90, v90
	v_exp_f32_e32 v91, v91
	v_exp_f32_e32 v92, v92
	v_exp_f32_e32 v93, v93
	v_exp_f32_e32 v94, v94
	v_exp_f32_e32 v95, v95
	v_exp_f32_e32 v96, v96
	v_exp_f32_e32 v97, v97
	v_exp_f32_e32 v98, v98
	v_exp_f32_e32 v99, v99
	v_exp_f32_e32 v100, v100
	v_exp_f32_e32 v101, v101
	v_exp_f32_e32 v102, v102
	v_exp_f32_e32 v103, v103
	v_exp_f32_e32 v104, v104
	v_exp_f32_e32 v105, v105
	v_exp_f32_e32 v106, v106
	v_exp_f32_e32 v107, v107
	v_exp_f32_e32 v108, v108
	v_exp_f32_e32 v109, v109
	v_exp_f32_e32 v110, v110
	v_exp_f32_e32 v111, v111
	v_exp_f32_e32 v112, v112
	v_exp_f32_e32 v113, v113
	v_exp_f32_e32 v114, v114
	v_exp_f32_e32 v115, v115
	v_exp_f32_e32 v116, v116
	v_exp_f32_e32 v117, v117
	v_exp_f32_e32 v219, v219
	v_pk_add_f32 v[236:237], v[50:51], v[52:53]
	v_pk_add_f32 v[238:239], v[54:55], v[56:57]
	v_pk_add_f32 v[240:241], v[58:59], v[60:61]
	v_pk_add_f32 v[242:243], v[62:63], v[64:65]
	v_pk_add_f32 v[236:237], v[236:237], v[66:67]
	v_pk_add_f32 v[238:239], v[238:239], v[70:71]
	v_pk_add_f32 v[240:241], v[240:241], v[74:75]
	v_pk_add_f32 v[242:243], v[242:243], v[78:79]
	v_pk_add_f32 v[236:237], v[236:237], v[68:69]
	v_pk_add_f32 v[238:239], v[238:239], v[72:73]
	v_pk_add_f32 v[240:241], v[240:241], v[76:77]
	v_pk_add_f32 v[242:243], v[242:243], v[80:81]
	v_pk_add_f32 v[236:237], v[236:237], v[82:83]
	v_pk_add_f32 v[238:239], v[238:239], v[86:87]
	v_pk_add_f32 v[240:241], v[240:241], v[90:91]
	v_pk_add_f32 v[242:243], v[242:243], v[94:95]
	v_pk_add_f32 v[236:237], v[236:237], v[84:85]
	v_pk_add_f32 v[238:239], v[238:239], v[88:89]
	v_pk_add_f32 v[240:241], v[240:241], v[92:93]
	v_pk_add_f32 v[242:243], v[242:243], v[96:97]
	v_pk_add_f32 v[236:237], v[236:237], v[98:99]
	v_pk_add_f32 v[238:239], v[238:239], v[102:103]
	v_pk_add_f32 v[240:241], v[240:241], v[106:107]
	v_pk_add_f32 v[242:243], v[242:243], v[110:111]
	v_pk_add_f32 v[236:237], v[236:237], v[100:101]
	v_pk_add_f32 v[238:239], v[238:239], v[104:105]
	v_pk_add_f32 v[240:241], v[240:241], v[108:109]
	v_pk_add_f32 v[242:243], v[242:243], v[112:113]
	v_pk_add_f32 v[236:237], v[236:237], v[114:115]
	v_pk_add_f32 v[236:237], v[236:237], v[116:117]
	v_pk_add_f32 v[236:237], v[236:237], v[238:239]
	v_pk_add_f32 v[240:241], v[240:241], v[242:243]
	v_cndmask_b32_e64 v219, 0, v219, s[74:75]
	v_pk_add_f32 v[236:237], v[236:237], v[240:241]
	v_add_f32_e32 v185, v236, v237
	v_add_f32_e32 v185, v185, v219
	v_cvt_pk_bf16_f32 v236, v50, v51
	v_cvt_pk_bf16_f32 v237, v52, v53
	v_cvt_pk_bf16_f32 v238, v54, v55
	v_cvt_pk_bf16_f32 v239, v56, v57
	s_nop 1
	s_waitcnt lgkmcnt(14)
	v_mfma_f32_16x16x32_bf16 v[210:213], v[186:189], v[236:239], 0
	s_waitcnt lgkmcnt(12)
	v_mfma_f32_16x16x32_bf16 v[214:217], v[190:193], v[236:239], 0
	s_waitcnt lgkmcnt(10)
	v_mfma_f32_16x16x32_bf16 v[220:223], v[194:197], v[236:239], 0
	s_waitcnt lgkmcnt(8)
	v_mfma_f32_16x16x32_bf16 v[224:227], v[198:201], v[236:239], 0
	v_cvt_pk_bf16_f32 v240, v58, v59
	v_cvt_pk_bf16_f32 v241, v60, v61
	v_cvt_pk_bf16_f32 v242, v62, v63
	v_cvt_pk_bf16_f32 v243, v64, v65
	s_waitcnt lgkmcnt(7)
	ds_read_b64_tr_b16 v[186:187], v124 offset:10240
	ds_read_b64_tr_b16 v[188:189], v124 offset:12288
	ds_read_b64_tr_b16 v[190:191], v125 offset:10240
	ds_read_b64_tr_b16 v[192:193], v125 offset:12288
	ds_read_b64_tr_b16 v[194:195], v126 offset:10240
	ds_read_b64_tr_b16 v[196:197], v126 offset:12288
	ds_read_b64_tr_b16 v[198:199], v127 offset:10240
	ds_read_b64_tr_b16 v[200:201], v127 offset:12288
	s_waitcnt lgkmcnt(14)
	v_mfma_f32_16x16x32_bf16 v[210:213], v[202:205], v[240:243], v[210:213]
	s_waitcnt lgkmcnt(12)
	v_mfma_f32_16x16x32_bf16 v[214:217], v[206:209], v[240:243], v[214:217]
	s_waitcnt lgkmcnt(10)
	v_mfma_f32_16x16x32_bf16 v[220:223], v[228:231], v[240:243], v[220:223]
	s_waitcnt lgkmcnt(8)
	v_mfma_f32_16x16x32_bf16 v[224:227], v[232:235], v[240:243], v[224:227]
	v_cvt_pk_bf16_f32 v236, v66, v67
	v_cvt_pk_bf16_f32 v237, v68, v69
	v_cvt_pk_bf16_f32 v238, v70, v71
	v_cvt_pk_bf16_f32 v239, v72, v73
	s_waitcnt lgkmcnt(7)
	ds_read_b64_tr_b16 v[202:203], v124 offset:14336
	ds_read_b64_tr_b16 v[204:205], v124 offset:16384
	ds_read_b64_tr_b16 v[206:207], v125 offset:14336
	ds_read_b64_tr_b16 v[208:209], v125 offset:16384
	ds_read_b64_tr_b16 v[228:229], v126 offset:14336
	ds_read_b64_tr_b16 v[230:231], v126 offset:16384
	ds_read_b64_tr_b16 v[232:233], v127 offset:14336
	ds_read_b64_tr_b16 v[234:235], v127 offset:16384
	s_waitcnt lgkmcnt(14)
	v_mfma_f32_16x16x32_bf16 v[210:213], v[186:189], v[236:239], v[210:213]
	s_waitcnt lgkmcnt(12)
	v_mfma_f32_16x16x32_bf16 v[214:217], v[190:193], v[236:239], v[214:217]
	s_waitcnt lgkmcnt(10)
	v_mfma_f32_16x16x32_bf16 v[220:223], v[194:197], v[236:239], v[220:223]
	s_waitcnt lgkmcnt(8)
; #define LAS __attribute__((address_space(3)))
; __device__ __forceinline__ unsigned pk2(float lo, float hi) { return pg8::cvt_pk_bf16(lo, hi); }
; __device__ __forceinline__ s16x4 vtr(const LAS unsigned char* p) { return __builtin_bit_cast(s16x4, __builtin_amdgcn_ds_read_tr16_b64_v4i16((LAS s16x4*)p)); }
; #define MFMA16(a, b, c) __builtin_amdgcn_mfma_f32_16x16x32_bf16((a), (b), (c), 0, 0, 0)
; __device__ __forceinline__ void pv_at(const LAS unsigned char* const (&vp)[4], int off, const f32x4& P0, const f32x4& P1, f32x4 (&O)[4]) {
;     v4u pw; pw.x = pk2(P0[0], P0[1]); pw.y = pk2(P0[2], P0[3]); pw.z = pk2(P1[0], P1[1]); pw.w = pk2(P1[2], P1[3]);
;     const bf16x8 pb = __builtin_bit_cast(bf16x8, pw);
; #pragma unroll
;     for (int db = 0; db < 4; ++db) {
;         const s16x4 lo = vtr(vp[db] + off), hi = vtr(vp[db] + off + 2048);
;         const bf16x8 vt = (bf16x8){lo[0], lo[1], lo[2], lo[3], hi[0], hi[1], hi[2], hi[3]};
;         O[db] = MFMA16(vt, pb, O[db]);
;     }
; }
	v_mfma_f32_16x16x32_bf16 v[224:227], v[198:201], v[236:239], v[224:227]
	v_cvt_pk_bf16_f32 v240, v74, v75
	v_cvt_pk_bf16_f32 v241, v76, v77
	v_cvt_pk_bf16_f32 v242, v78, v79
	v_cvt_pk_bf16_f32 v243, v80, v81
	s_waitcnt lgkmcnt(7)
	ds_read_b64_tr_b16 v[186:187], v124 offset:18432
	ds_read_b64_tr_b16 v[188:189], v124 offset:20480
	ds_read_b64_tr_b16 v[190:191], v125 offset:18432
	ds_read_b64_tr_b16 v[192:193], v125 offset:20480
	ds_read_b64_tr_b16 v[194:195], v126 offset:18432
	ds_read_b64_tr_b16 v[196:197], v126 offset:20480
	ds_read_b64_tr_b16 v[198:199], v127 offset:18432
	ds_read_b64_tr_b16 v[200:201], v127 offset:20480
	s_waitcnt lgkmcnt(14)
	v_mfma_f32_16x16x32_bf16 v[210:213], v[202:205], v[240:243], v[210:213]
	s_waitcnt lgkmcnt(12)
	v_mfma_f32_16x16x32_bf16 v[214:217], v[206:209], v[240:243], v[214:217]
	s_waitcnt lgkmcnt(10)
	v_mfma_f32_16x16x32_bf16 v[220:223], v[228:231], v[240:243], v[220:223]
	s_waitcnt lgkmcnt(8)
	v_mfma_f32_16x16x32_bf16 v[224:227], v[232:235], v[240:243], v[224:227]
	v_cvt_pk_bf16_f32 v236, v82, v83
	v_cvt_pk_bf16_f32 v237, v84, v85
	v_cvt_pk_bf16_f32 v238, v86, v87
	v_cvt_pk_bf16_f32 v239, v88, v89
	s_waitcnt lgkmcnt(7)
	ds_read_b64_tr_b16 v[202:203], v124 offset:22528
	ds_read_b64_tr_b16 v[204:205], v124 offset:24576
	ds_read_b64_tr_b16 v[206:207], v125 offset:22528
	ds_read_b64_tr_b16 v[208:209], v125 offset:24576
	ds_read_b64_tr_b16 v[228:229], v126 offset:22528
	ds_read_b64_tr_b16 v[230:231], v126 offset:24576
	ds_read_b64_tr_b16 v[232:233], v127 offset:22528
	ds_read_b64_tr_b16 v[234:235], v127 offset:24576
	s_waitcnt lgkmcnt(14)
	v_mfma_f32_16x16x32_bf16 v[210:213], v[186:189], v[236:239], v[210:213]
	s_waitcnt lgkmcnt(12)
	v_mfma_f32_16x16x32_bf16 v[214:217], v[190:193], v[236:239], v[214:217]
	s_waitcnt lgkmcnt(10)
	v_mfma_f32_16x16x32_bf16 v[220:223], v[194:197], v[236:239], v[220:223]
	s_waitcnt lgkmcnt(8)
	v_mfma_f32_16x16x32_bf16 v[224:227], v[198:201], v[236:239], v[224:227]
	v_cvt_pk_bf16_f32 v240, v90, v91
	v_cvt_pk_bf16_f32 v241, v92, v93
	v_cvt_pk_bf16_f32 v242, v94, v95
	v_cvt_pk_bf16_f32 v243, v96, v97
	s_waitcnt lgkmcnt(7)
	ds_read_b64_tr_b16 v[186:187], v124 offset:26624
	ds_read_b64_tr_b16 v[188:189], v124 offset:28672
	ds_read_b64_tr_b16 v[190:191], v125 offset:26624
	ds_read_b64_tr_b16 v[192:193], v125 offset:28672
	ds_read_b64_tr_b16 v[194:195], v126 offset:26624
	ds_read_b64_tr_b16 v[196:197], v126 offset:28672
	ds_read_b64_tr_b16 v[198:199], v127 offset:26624
	ds_read_b64_tr_b16 v[200:201], v127 offset:28672
	s_waitcnt lgkmcnt(14)
	v_mfma_f32_16x16x32_bf16 v[210:213], v[202:205], v[240:243], v[210:213]
	s_waitcnt lgkmcnt(12)
	v_mfma_f32_16x16x32_bf16 v[214:217], v[206:209], v[240:243], v[214:217]
	s_waitcnt lgkmcnt(10)
	v_mfma_f32_16x16x32_bf16 v[220:223], v[228:231], v[240:243], v[220:223]
	s_waitcnt lgkmcnt(8)
	v_mfma_f32_16x16x32_bf16 v[224:227], v[232:235], v[240:243], v[224:227]
	v_cvt_pk_bf16_f32 v236, v98, v99
	v_cvt_pk_bf16_f32 v237, v100, v101
	v_cvt_pk_bf16_f32 v238, v102, v103
	v_cvt_pk_bf16_f32 v239, v104, v105
	s_waitcnt lgkmcnt(7)
	ds_read_b64_tr_b16 v[202:203], v124 offset:30720
	ds_read_b64_tr_b16 v[204:205], v124 offset:32768
	ds_read_b64_tr_b16 v[206:207], v125 offset:30720
	ds_read_b64_tr_b16 v[208:209], v125 offset:32768
	ds_read_b64_tr_b16 v[228:229], v126 offset:30720
	ds_read_b64_tr_b16 v[230:231], v126 offset:32768
	ds_read_b64_tr_b16 v[232:233], v127 offset:30720
	ds_read_b64_tr_b16 v[234:235], v127 offset:32768
	s_waitcnt lgkmcnt(14)
	v_mfma_f32_16x16x32_bf16 v[210:213], v[186:189], v[236:239], v[210:213]
	s_waitcnt lgkmcnt(12)
	v_mfma_f32_16x16x32_bf16 v[214:217], v[190:193], v[236:239], v[214:217]
	s_waitcnt lgkmcnt(10)
	v_mfma_f32_16x16x32_bf16 v[220:223], v[194:197], v[236:239], v[220:223]
	s_waitcnt lgkmcnt(8)
	v_mfma_f32_16x16x32_bf16 v[224:227], v[198:201], v[236:239], v[224:227]
	v_cvt_pk_bf16_f32 v240, v106, v107
	v_cvt_pk_bf16_f32 v241, v108, v109
	v_cvt_pk_bf16_f32 v242, v110, v111
	v_cvt_pk_bf16_f32 v243, v112, v113
	s_waitcnt lgkmcnt(7)
	ds_read_b64_tr_b16 v[186:187], v124 offset:34816
	ds_read_b64_tr_b16 v[188:189], v124 offset:36864
	ds_read_b64_tr_b16 v[190:191], v125 offset:34816
	ds_read_b64_tr_b16 v[192:193], v125 offset:36864
	ds_read_b64_tr_b16 v[194:195], v126 offset:34816
	ds_read_b64_tr_b16 v[196:197], v126 offset:36864
	ds_read_b64_tr_b16 v[198:199], v127 offset:34816
	ds_read_b64_tr_b16 v[200:201], v127 offset:36864
	s_waitcnt lgkmcnt(14)
	v_mfma_f32_16x16x32_bf16 v[210:213], v[202:205], v[240:243], v[210:213]
	s_waitcnt lgkmcnt(12)
	v_mfma_f32_16x16x32_bf16 v[214:217], v[206:209], v[240:243], v[214:217]
	s_waitcnt lgkmcnt(10)
	v_mfma_f32_16x16x32_bf16 v[220:223], v[228:231], v[240:243], v[220:223]
	s_waitcnt lgkmcnt(8)
	v_mfma_f32_16x16x32_bf16 v[224:227], v[232:235], v[240:243], v[224:227]
	v_cvt_pk_bf16_f32 v236, v114, v115
	v_cvt_pk_bf16_f32 v237, v116, v117
	v_mov_b32_e32 v238, 0
	v_mov_b32_e32 v239, 0
	s_nop 1
	s_waitcnt lgkmcnt(6)
	v_mfma_f32_16x16x32_bf16 v[210:213], v[186:189], v[236:239], v[210:213]
	s_waitcnt lgkmcnt(4)
	v_mfma_f32_16x16x32_bf16 v[214:217], v[190:193], v[236:239], v[214:217]
	s_waitcnt lgkmcnt(2)
	v_mfma_f32_16x16x32_bf16 v[220:223], v[194:197], v[236:239], v[220:223]
	s_waitcnt lgkmcnt(0)
; __device__ __forceinline__ unsigned pk2(float lo, float hi) { return pg8::cvt_pk_bf16(lo, hi); }
; __device__ __forceinline__ void store_o(bf16* yrow, int g, float l, const f32x4 (&O)[4]) {
;     const float inv = 1.0f / xrow16_sum(l);
;     unsigned wx[4], wy[4];
; #pragma unroll
;     for (int db = 0; db < 4; ++db) { wx[db] = pk2(O[db][0] * inv, O[db][1] * inv); wy[db] = pk2(O[db][2] * inv, O[db][3] * inv); }
; #pragma unroll
;     for (int p = 0; p < 2; ++p) {
;         auto rx = __builtin_amdgcn_permlane16_swap(wx[2 * p], wx[2 * p + 1], false, false); wx[2 * p] = rx[0]; wx[2 * p + 1] = rx[1];
;         auto ry = __builtin_amdgcn_permlane16_swap(wy[2 * p], wy[2 * p + 1], false, false); wy[2 * p] = ry[0]; wy[2 * p + 1] = ry[1]; }
; #pragma unroll
;     for (int p = 0; p < 2; ++p) {
;         auto rx = __builtin_amdgcn_permlane32_swap(wx[p], wx[p + 2], false, false); wx[p] = rx[0]; wx[p + 2] = rx[1];
;         auto ry = __builtin_amdgcn_permlane32_swap(wy[p], wy[p + 2], false, false); wy[p] = ry[0]; wy[p + 2] = ry[1]; }
;     v4u lo = {wx[0], wy[0], wx[1], wy[1]}, hi = {wx[2], wy[2], wx[3], wy[3]};
;     *(v4u*)(yrow + 16 * g) = lo; *(v4u*)(yrow + 16 * g + 8) = hi;
; }
; template <bool MASK> __device__ __forceinline__ void a_scores(f32x4& S0, f32x4& S1, float basef, float c1, float slope2, int krow0, int kstart) {
; #pragma unroll
;     for (int r = 0; r < 4; ++r) {
;         const float d0 = fabsf(basef - (float)r), d1 = fabsf(basef - (float)(16 + r));
;         const float v0 = S0[r] - slope2 * d0, v1 = S1[r] - slope2 * d1;
;         if (MASK) { const int p0 = kstart + krow0 + r, p1 = p0 + 16;
;             S0[r] = (d0 <= 128.f && p0 >= 0 && p0 < SEQ) ? v0 : -INFINITY; S1[r] = (d1 <= 128.f && p1 >= 0 && p1 < SEQ) ? v1 : -INFINITY; }
;         else { S0[r] = v0; S1[r] = v1; }
;     }
; }
	v_mfma_f32_16x16x32_bf16 v[224:227], v[198:201], v[236:239], v[224:227]
	v_mov_b32_e32 v219, v185
	s_nop 1
	v_permlane16_swap_b32_e32 v185, v219
	v_add_f32_e32 v185, v185, v219
	v_mov_b32_e32 v219, v185
	s_nop 1
	v_permlane32_swap_b32_e32 v185, v219
	v_add_f32_e32 v185, v185, v219
	v_div_scale_f32 v236, s[78:79], v185, v185, 1.0
	v_div_scale_f32 v237, vcc, 1.0, v185, 1.0
	v_rcp_f32_e32 v238, v236
	s_nop 0
	v_fma_f32 v239, -v236, v238, 1.0
	v_fmac_f32_e32 v238, v239, v238
	v_mul_f32_e32 v240, v237, v238
	v_fma_f32 v241, -v236, v240, v237
	v_fmac_f32_e32 v240, v241, v238
	v_fma_f32 v237, -v236, v240, v237
	v_div_fmas_f32 v237, v237, v238, v240
	v_div_fixup_f32 v244, v237, v185, 1.0
	v_mul_f32_e32 v240, v210, v244
	v_mul_f32_e32 v241, v211, v244
	v_mul_f32_e32 v242, v212, v244
	v_mul_f32_e32 v243, v213, v244
	v_cvt_pk_bf16_f32 v186, v240, v241
	v_cvt_pk_bf16_f32 v187, v242, v243
	v_mul_f32_e32 v240, v214, v244
	v_mul_f32_e32 v241, v215, v244
	v_mul_f32_e32 v242, v216, v244
	v_mul_f32_e32 v243, v217, v244
	v_cvt_pk_bf16_f32 v188, v240, v241
	v_cvt_pk_bf16_f32 v189, v242, v243
	v_mul_f32_e32 v240, v220, v244
	v_mul_f32_e32 v241, v221, v244
	v_mul_f32_e32 v242, v222, v244
	v_mul_f32_e32 v243, v223, v244
	v_cvt_pk_bf16_f32 v190, v240, v241
	v_cvt_pk_bf16_f32 v191, v242, v243
	v_mul_f32_e32 v240, v224, v244
	v_mul_f32_e32 v241, v225, v244
	v_mul_f32_e32 v242, v226, v244
	v_mul_f32_e32 v243, v227, v244
	v_cvt_pk_bf16_f32 v192, v240, v241
	v_cvt_pk_bf16_f32 v193, v242, v243
	s_nop 1
	v_permlane16_swap_b32_e32 v186, v188
	v_permlane16_swap_b32_e32 v187, v189
	v_permlane16_swap_b32_e32 v190, v192
	v_permlane16_swap_b32_e32 v191, v193
	s_nop 0
	v_permlane32_swap_b32_e32 v186, v190
	v_permlane32_swap_b32_e32 v187, v191
	v_permlane32_swap_b32_e32 v188, v192
	v_permlane32_swap_b32_e32 v189, v193
	global_store_dwordx4 v128, v[186:189], s[82:83] offset:2048
	global_store_dwordx4 v128, v[190:193], s[82:83] offset:2064
	s_nop 1
	v_fmamk_f32 v50, v130, 0x43000000, v132
	v_fmamk_f32 v51, v130, 0x42fe0000, v132
	v_fmamk_f32 v52, v130, 0x42fc0000, v132
	v_fmamk_f32 v53, v130, 0x42fa0000, v132
	v_fmamk_f32 v54, v130, 0x42e00000, v132
	v_fmamk_f32 v55, v130, 0x42de0000, v132
	v_fmamk_f32 v56, v130, 0x42dc0000, v132
	v_fmamk_f32 v57, v130, 0x42da0000, v132
	v_fmamk_f32 v58, v130, 0x42c00000, v132
	v_fmamk_f32 v59, v130, 0x42be0000, v132
	v_fmamk_f32 v60, v130, 0x42bc0000, v132
	v_fmamk_f32 v61, v130, 0x42ba0000, v132
	v_fmamk_f32 v62, v130, 0x42a00000, v132
	v_fmamk_f32 v63, v130, 0x429e0000, v132
	v_fmamk_f32 v64, v130, 0x429c0000, v132
	v_fmamk_f32 v65, v130, 0x429a0000, v132
	v_fmamk_f32 v66, v130, 0x42800000, v132
	v_fmamk_f32 v67, v130, 0x427c0000, v132
	v_fmamk_f32 v68, v130, 0x42780000, v132
	v_fmamk_f32 v69, v130, 0x42740000, v132
	v_fmamk_f32 v70, v130, 0x42400000, v132
	v_fmamk_f32 v71, v130, 0x423c0000, v132
	v_fmamk_f32 v72, v130, 0x42380000, v132
	v_fmamk_f32 v73, v130, 0x42340000, v132
	v_fmamk_f32 v74, v130, 0x42000000, v132
	v_fmamk_f32 v75, v130, 0x41f80000, v132
	v_fmamk_f32 v76, v130, 0x41f00000, v132
	v_fmamk_f32 v77, v130, 0x41e80000, v132
	v_fmamk_f32 v78, v130, 0x41800000, v132
	v_fmamk_f32 v79, v130, 0x41700000, v132
	v_fmamk_f32 v80, v130, 0x41600000, v132
	v_fmamk_f32 v81, v130, 0x41500000, v132
	v_add_f32_e32 v219, 0, v129
	v_mul_f32_e64 v82, v130, |v219|
	v_add_f32_e32 v244, 0xbf800000, v129
	v_mul_f32_e64 v83, v130, |v244|
	v_add_f32_e32 v219, 0xc0000000, v129
	v_mul_f32_e64 v84, v130, |v219|
	v_add_f32_e32 v244, 0xc0400000, v129
	v_mul_f32_e64 v85, v130, |v244|
	v_fmamk_f32 v86, v131, 0xc1800000, v133
	v_fmamk_f32 v87, v131, 0xc1880000, v133
	v_fmamk_f32 v88, v131, 0xc1900000, v133
	v_fmamk_f32 v89, v131, 0xc1980000, v133
	v_fmamk_f32 v90, v131, 0xc2000000, v133
	v_fmamk_f32 v91, v131, 0xc2040000, v133
	v_fmamk_f32 v92, v131, 0xc2080000, v133
	v_fmamk_f32 v93, v131, 0xc20c0000, v133
	v_fmamk_f32 v94, v131, 0xc2400000, v133
	v_fmamk_f32 v95, v131, 0xc2440000, v133
	v_fmamk_f32 v96, v131, 0xc2480000, v133
	v_fmamk_f32 v97, v131, 0xc24c0000, v133
	v_fmamk_f32 v98, v131, 0xc2800000, v133
	v_fmamk_f32 v99, v131, 0xc2820000, v133
	v_fmamk_f32 v100, v131, 0xc2840000, v133
	v_fmamk_f32 v101, v131, 0xc2860000, v133
	v_fmamk_f32 v102, v131, 0xc2a00000, v133
	v_fmamk_f32 v103, v131, 0xc2a20000, v133
	v_fmamk_f32 v104, v131, 0xc2a40000, v133
	v_fmamk_f32 v105, v131, 0xc2a60000, v133
	v_fmamk_f32 v106, v131, 0xc2c00000, v133
	v_fmamk_f32 v107, v131, 0xc2c20000, v133
	v_fmamk_f32 v108, v131, 0xc2c40000, v133
	v_fmamk_f32 v109, v131, 0xc2c60000, v133
	v_fmamk_f32 v110, v131, 0xc2e00000, v133
	v_fmamk_f32 v111, v131, 0xc2e20000, v133
	v_fmamk_f32 v112, v131, 0xc2e40000, v133
	v_fmamk_f32 v113, v131, 0xc2e60000, v133
	v_fmamk_f32 v114, v131, 0xc3000000, v133
	v_fmamk_f32 v115, v131, 0xc3010000, v133
	v_fmamk_f32 v116, v131, 0xc3020000, v133
	v_fmamk_f32 v117, v131, 0xc3030000, v133
	v_mov_b32_e32 v245, 0xff800000
	v_cndmask_b32_e64 v50, v245, v50, s[16:17]
	v_cndmask_b32_e64 v51, v245, v51, s[18:19]
	v_cndmask_b32_e64 v52, v245, v52, s[22:23]
	v_cndmask_b32_e64 v53, v245, v53, s[24:25]
	v_cndmask_b32_e64 v114, v245, v114, s[28:29]
	v_cndmask_b32_e64 v115, v245, v115, s[52:53]
	v_cndmask_b32_e64 v116, v245, v116, s[54:55]
	v_cndmask_b32_e64 v117, v245, v117, s[88:89]
	ds_read_b128 v[186:189], v122 offset:4096
	ds_read_b128 v[190:193], v123 offset:4096
	ds_read_b128 v[194:197], v122 offset:6144
	ds_read_b128 v[198:201], v123 offset:6144
	ds_read_b128 v[202:205], v122 offset:8192
	ds_read_b128 v[206:209], v123 offset:8192
	s_waitcnt lgkmcnt(5)
	v_mfma_f32_16x16x32_bf16 v[50:53], v[186:189], v[162:165], v[50:53]
	s_waitcnt lgkmcnt(4)
; #define LAS __attribute__((address_space(3)))
; #define MFMA16(a, b, c) __builtin_amdgcn_mfma_f32_16x16x32_bf16((a), (b), (c), 0, 0, 0)
; __device__ __forceinline__ void qk_at(const LAS unsigned char* kp0, const LAS unsigned char* kp1, int off, bf16x8 qf0, bf16x8 qf1, f32x4& S0, f32x4& S1) {
;     const bf16x8 k00 = *(const LAS bf16x8*)(kp0 + off), k01 = *(const LAS bf16x8*)(kp1 + off);
;     const bf16x8 k10 = *(const LAS bf16x8*)(kp0 + off + 2048), k11 = *(const LAS bf16x8*)(kp1 + off + 2048);
;     const f32x4 z = {0.f, 0.f, 0.f, 0.f};
;     S0 = MFMA16(k00, qf0, z); S0 = MFMA16(k01, qf1, S0);
;     S1 = MFMA16(k10, qf0, z); S1 = MFMA16(k11, qf1, S1);
; }
; __device__ __forceinline__ void softmax_step(f32x4& s0, f32x4& s1, float& m, float& l, f32x4 (&O)[4]) {
;     float t = fmaxf(fmaxf(fmaxf(s0[0], s0[1]), fmaxf(s0[2], s0[3])), fmaxf(fmaxf(s1[0], s1[1]), fmaxf(s1[2], s1[3])));
;     t = xrow16_max(t);
	v_mfma_f32_16x16x32_bf16 v[50:53], v[190:193], v[166:169], v[50:53]
	ds_read_b128 v[186:189], v122 offset:10240
	ds_read_b128 v[190:193], v123 offset:10240
	s_waitcnt lgkmcnt(5)
	v_mfma_f32_16x16x32_bf16 v[54:57], v[194:197], v[162:165], v[54:57]
	s_waitcnt lgkmcnt(4)
	v_mfma_f32_16x16x32_bf16 v[54:57], v[198:201], v[166:169], v[54:57]
	ds_read_b128 v[194:197], v122 offset:12288
	ds_read_b128 v[198:201], v123 offset:12288
	s_waitcnt lgkmcnt(5)
	v_mfma_f32_16x16x32_bf16 v[58:61], v[202:205], v[162:165], v[58:61]
	s_waitcnt lgkmcnt(4)
	v_mfma_f32_16x16x32_bf16 v[58:61], v[206:209], v[166:169], v[58:61]
	ds_read_b128 v[202:205], v122 offset:14336
	ds_read_b128 v[206:209], v123 offset:14336
	s_waitcnt lgkmcnt(5)
	v_mfma_f32_16x16x32_bf16 v[62:65], v[186:189], v[162:165], v[62:65]
	s_waitcnt lgkmcnt(4)
	v_mfma_f32_16x16x32_bf16 v[62:65], v[190:193], v[166:169], v[62:65]
	ds_read_b128 v[186:189], v122 offset:16384
	ds_read_b128 v[190:193], v123 offset:16384
	s_waitcnt lgkmcnt(5)
	v_mfma_f32_16x16x32_bf16 v[66:69], v[194:197], v[162:165], v[66:69]
	s_waitcnt lgkmcnt(4)
	v_mfma_f32_16x16x32_bf16 v[66:69], v[198:201], v[166:169], v[66:69]
	ds_read_b128 v[194:197], v122 offset:18432
	ds_read_b128 v[198:201], v123 offset:18432
	s_waitcnt lgkmcnt(5)
	v_mfma_f32_16x16x32_bf16 v[70:73], v[202:205], v[162:165], v[70:73]
	s_waitcnt lgkmcnt(4)
	v_mfma_f32_16x16x32_bf16 v[70:73], v[206:209], v[166:169], v[70:73]
	ds_read_b128 v[202:205], v122 offset:20480
	ds_read_b128 v[206:209], v123 offset:20480
	s_waitcnt lgkmcnt(5)
	v_mfma_f32_16x16x32_bf16 v[74:77], v[186:189], v[162:165], v[74:77]
	s_waitcnt lgkmcnt(4)
	v_mfma_f32_16x16x32_bf16 v[74:77], v[190:193], v[166:169], v[74:77]
	ds_read_b128 v[186:189], v122 offset:22528
	ds_read_b128 v[190:193], v123 offset:22528
	s_waitcnt lgkmcnt(5)
	v_mfma_f32_16x16x32_bf16 v[78:81], v[194:197], v[162:165], v[78:81]
	s_waitcnt lgkmcnt(4)
	v_mfma_f32_16x16x32_bf16 v[78:81], v[198:201], v[166:169], v[78:81]
	ds_read_b128 v[194:197], v122 offset:24576
	ds_read_b128 v[198:201], v123 offset:24576
	s_waitcnt lgkmcnt(5)
	v_mfma_f32_16x16x32_bf16 v[82:85], v[202:205], v[162:165], v[82:85]
	s_waitcnt lgkmcnt(4)
	v_mfma_f32_16x16x32_bf16 v[82:85], v[206:209], v[166:169], v[82:85]
	ds_read_b128 v[202:205], v122 offset:26624
	ds_read_b128 v[206:209], v123 offset:26624
	s_waitcnt lgkmcnt(5)
	v_mfma_f32_16x16x32_bf16 v[86:89], v[186:189], v[162:165], v[86:89]
	s_waitcnt lgkmcnt(4)
	v_mfma_f32_16x16x32_bf16 v[86:89], v[190:193], v[166:169], v[86:89]
	ds_read_b128 v[186:189], v122 offset:28672
	ds_read_b128 v[190:193], v123 offset:28672
	s_waitcnt lgkmcnt(5)
	v_mfma_f32_16x16x32_bf16 v[90:93], v[194:197], v[162:165], v[90:93]
	s_waitcnt lgkmcnt(4)
	v_mfma_f32_16x16x32_bf16 v[90:93], v[198:201], v[166:169], v[90:93]
	ds_read_b128 v[194:197], v122 offset:30720
	ds_read_b128 v[198:201], v123 offset:30720
	s_waitcnt lgkmcnt(5)
	v_mfma_f32_16x16x32_bf16 v[94:97], v[202:205], v[162:165], v[94:97]
	s_waitcnt lgkmcnt(4)
	v_mfma_f32_16x16x32_bf16 v[94:97], v[206:209], v[166:169], v[94:97]
	ds_read_b128 v[202:205], v122 offset:32768
	ds_read_b128 v[206:209], v123 offset:32768
	s_waitcnt lgkmcnt(5)
	v_mfma_f32_16x16x32_bf16 v[98:101], v[186:189], v[162:165], v[98:101]
	s_waitcnt lgkmcnt(4)
	v_mfma_f32_16x16x32_bf16 v[98:101], v[190:193], v[166:169], v[98:101]
	ds_read_b128 v[186:189], v122 offset:34816
	ds_read_b128 v[190:193], v123 offset:34816
	s_waitcnt lgkmcnt(5)
	v_mfma_f32_16x16x32_bf16 v[102:105], v[194:197], v[162:165], v[102:105]
	s_waitcnt lgkmcnt(4)
	v_mfma_f32_16x16x32_bf16 v[102:105], v[198:201], v[166:169], v[102:105]
	ds_read_b128 v[194:197], v122 offset:36864
	ds_read_b128 v[198:201], v123 offset:36864
	s_waitcnt lgkmcnt(5)
	v_mfma_f32_16x16x32_bf16 v[106:109], v[202:205], v[162:165], v[106:109]
	s_waitcnt lgkmcnt(4)
	v_mfma_f32_16x16x32_bf16 v[106:109], v[206:209], v[166:169], v[106:109]
	s_waitcnt lgkmcnt(3)
	v_mfma_f32_16x16x32_bf16 v[110:113], v[186:189], v[162:165], v[110:113]
	s_waitcnt lgkmcnt(2)
	v_mfma_f32_16x16x32_bf16 v[110:113], v[190:193], v[166:169], v[110:113]
	s_waitcnt lgkmcnt(1)
	v_mfma_f32_16x16x32_bf16 v[114:117], v[194:197], v[162:165], v[114:117]
	s_waitcnt lgkmcnt(0)
	v_mfma_f32_16x16x32_bf16 v[114:117], v[198:201], v[166:169], v[114:117]
	v_max3_f32 v219, v50, v51, v52
	v_max3_f32 v244, v54, v55, v56
	v_max3_f32 v245, v58, v59, v60
	v_max3_f32 v120, v62, v63, v64
	v_max3_f32 v219, v219, v53, v66
	v_max3_f32 v244, v244, v57, v70
	v_max3_f32 v245, v245, v61, v74
	v_max3_f32 v120, v120, v65, v78
	v_max3_f32 v219, v219, v67, v68
	v_max3_f32 v244, v244, v71, v72
	v_max3_f32 v245, v245, v75, v76
	v_max3_f32 v120, v120, v79, v80
	ds_read_b64_tr_b16 v[186:187], v124 offset:4096
	ds_read_b64_tr_b16 v[188:189], v124 offset:6144
	ds_read_b64_tr_b16 v[190:191], v125 offset:4096
	ds_read_b64_tr_b16 v[192:193], v125 offset:6144
	ds_read_b64_tr_b16 v[194:195], v126 offset:4096
	ds_read_b64_tr_b16 v[196:197], v126 offset:6144
	ds_read_b64_tr_b16 v[198:199], v127 offset:4096
	ds_read_b64_tr_b16 v[200:201], v127 offset:6144
	v_max3_f32 v219, v219, v69, v82
	v_max3_f32 v244, v244, v73, v86
	v_max3_f32 v245, v245, v77, v90
	v_max3_f32 v120, v120, v81, v94
	v_max3_f32 v219, v219, v83, v84
	v_max3_f32 v244, v244, v87, v88
	v_max3_f32 v245, v245, v91, v92
	v_max3_f32 v120, v120, v95, v96
	v_max3_f32 v219, v219, v85, v98
	v_max3_f32 v244, v244, v89, v102
	v_max3_f32 v245, v245, v93, v106
	v_max3_f32 v120, v120, v97, v110
	v_max3_f32 v219, v219, v99, v100
	v_max3_f32 v244, v244, v103, v104
	v_max3_f32 v245, v245, v107, v108
	v_max3_f32 v120, v120, v111, v112
	v_max3_f32 v219, v219, v101, v114
	v_max3_f32 v219, v219, v115, v116
	v_max_f32_e32 v219, v219, v117
	v_max_f32_e32 v244, v244, v105
	v_max_f32_e32 v245, v245, v109
	v_max_f32_e32 v120, v120, v113
	v_max3_f32 v178, v219, v244, v245
	v_max_f32_e32 v178, v178, v120
	v_mov_b32_e32 v219, v178
	s_nop 1
	v_permlane16_swap_b32_e32 v178, v219
	v_max_f32_e32 v178, v178, v219
	v_mov_b32_e32 v219, v178
	s_nop 1
	v_permlane32_swap_b32_e32 v178, v219
	v_max3_f32 v178, v178, v219, v145
	s_waitcnt lgkmcnt(7)
; __device__ __forceinline__ void softmax_step(f32x4& s0, f32x4& s1, float& m, float& l, f32x4 (&O)[4]) {
;     float t = fmaxf(fmaxf(fmaxf(s0[0], s0[1]), fmaxf(s0[2], s0[3])), fmaxf(fmaxf(s1[0], s1[1]), fmaxf(s1[2], s1[3])));
;     t = xrow16_max(t);
;     const float mn = fmaxf(m, t), alpha = __builtin_amdgcn_exp2f(m - mn);
;     m = mn;
; #pragma unroll
;     for (int k = 0; k < 4; ++k) { s0[k] = __builtin_amdgcn_exp2f(s0[k] - mn); s1[k] = __builtin_amdgcn_exp2f(s1[k] - mn); }
;     l = l * alpha + ((s0[0] + s0[1]) + (s0[2] + s0[3])) + ((s1[0] + s1[1]) + (s1[2] + s1[3]));
; #pragma unroll
;     for (int db = 0; db < 4; ++db) O[db] *= alpha;
; }
	ds_read_b64_tr_b16 v[202:203], v124 offset:8192
	ds_read_b64_tr_b16 v[204:205], v124 offset:10240
	ds_read_b64_tr_b16 v[206:207], v125 offset:8192
	ds_read_b64_tr_b16 v[208:209], v125 offset:10240
	ds_read_b64_tr_b16 v[228:229], v126 offset:8192
	ds_read_b64_tr_b16 v[230:231], v126 offset:10240
	ds_read_b64_tr_b16 v[232:233], v127 offset:8192
	ds_read_b64_tr_b16 v[234:235], v127 offset:10240
	v_mov_b32_e32 v244, v178
	v_pk_add_f32 v[50:51], v[50:51], v[244:245] op_sel_hi:[1,0] neg_lo:[0,1] neg_hi:[0,1]
	v_pk_add_f32 v[52:53], v[52:53], v[244:245] op_sel_hi:[1,0] neg_lo:[0,1] neg_hi:[0,1]
	v_pk_add_f32 v[54:55], v[54:55], v[244:245] op_sel_hi:[1,0] neg_lo:[0,1] neg_hi:[0,1]
	v_pk_add_f32 v[56:57], v[56:57], v[244:245] op_sel_hi:[1,0] neg_lo:[0,1] neg_hi:[0,1]
	v_pk_add_f32 v[58:59], v[58:59], v[244:245] op_sel_hi:[1,0] neg_lo:[0,1] neg_hi:[0,1]
	v_pk_add_f32 v[60:61], v[60:61], v[244:245] op_sel_hi:[1,0] neg_lo:[0,1] neg_hi:[0,1]
	v_pk_add_f32 v[62:63], v[62:63], v[244:245] op_sel_hi:[1,0] neg_lo:[0,1] neg_hi:[0,1]
	v_pk_add_f32 v[64:65], v[64:65], v[244:245] op_sel_hi:[1,0] neg_lo:[0,1] neg_hi:[0,1]
	v_pk_add_f32 v[66:67], v[66:67], v[244:245] op_sel_hi:[1,0] neg_lo:[0,1] neg_hi:[0,1]
	v_pk_add_f32 v[68:69], v[68:69], v[244:245] op_sel_hi:[1,0] neg_lo:[0,1] neg_hi:[0,1]
	v_pk_add_f32 v[70:71], v[70:71], v[244:245] op_sel_hi:[1,0] neg_lo:[0,1] neg_hi:[0,1]
	v_pk_add_f32 v[72:73], v[72:73], v[244:245] op_sel_hi:[1,0] neg_lo:[0,1] neg_hi:[0,1]
	v_pk_add_f32 v[74:75], v[74:75], v[244:245] op_sel_hi:[1,0] neg_lo:[0,1] neg_hi:[0,1]
	v_pk_add_f32 v[76:77], v[76:77], v[244:245] op_sel_hi:[1,0] neg_lo:[0,1] neg_hi:[0,1]
	v_pk_add_f32 v[78:79], v[78:79], v[244:245] op_sel_hi:[1,0] neg_lo:[0,1] neg_hi:[0,1]
	v_pk_add_f32 v[80:81], v[80:81], v[244:245] op_sel_hi:[1,0] neg_lo:[0,1] neg_hi:[0,1]
	v_pk_add_f32 v[82:83], v[82:83], v[244:245] op_sel_hi:[1,0] neg_lo:[0,1] neg_hi:[0,1]
	v_pk_add_f32 v[84:85], v[84:85], v[244:245] op_sel_hi:[1,0] neg_lo:[0,1] neg_hi:[0,1]
	v_pk_add_f32 v[86:87], v[86:87], v[244:245] op_sel_hi:[1,0] neg_lo:[0,1] neg_hi:[0,1]
	v_pk_add_f32 v[88:89], v[88:89], v[244:245] op_sel_hi:[1,0] neg_lo:[0,1] neg_hi:[0,1]
	v_pk_add_f32 v[90:91], v[90:91], v[244:245] op_sel_hi:[1,0] neg_lo:[0,1] neg_hi:[0,1]
	v_pk_add_f32 v[92:93], v[92:93], v[244:245] op_sel_hi:[1,0] neg_lo:[0,1] neg_hi:[0,1]
	v_pk_add_f32 v[94:95], v[94:95], v[244:245] op_sel_hi:[1,0] neg_lo:[0,1] neg_hi:[0,1]
	v_pk_add_f32 v[96:97], v[96:97], v[244:245] op_sel_hi:[1,0] neg_lo:[0,1] neg_hi:[0,1]
	v_pk_add_f32 v[98:99], v[98:99], v[244:245] op_sel_hi:[1,0] neg_lo:[0,1] neg_hi:[0,1]
	v_pk_add_f32 v[100:101], v[100:101], v[244:245] op_sel_hi:[1,0] neg_lo:[0,1] neg_hi:[0,1]
	v_pk_add_f32 v[102:103], v[102:103], v[244:245] op_sel_hi:[1,0] neg_lo:[0,1] neg_hi:[0,1]
	v_pk_add_f32 v[104:105], v[104:105], v[244:245] op_sel_hi:[1,0] neg_lo:[0,1] neg_hi:[0,1]
	v_pk_add_f32 v[106:107], v[106:107], v[244:245] op_sel_hi:[1,0] neg_lo:[0,1] neg_hi:[0,1]
	v_pk_add_f32 v[108:109], v[108:109], v[244:245] op_sel_hi:[1,0] neg_lo:[0,1] neg_hi:[0,1]
	v_pk_add_f32 v[110:111], v[110:111], v[244:245] op_sel_hi:[1,0] neg_lo:[0,1] neg_hi:[0,1]
	v_pk_add_f32 v[112:113], v[112:113], v[244:245] op_sel_hi:[1,0] neg_lo:[0,1] neg_hi:[0,1]
	v_pk_add_f32 v[114:115], v[114:115], v[244:245] op_sel_hi:[1,0] neg_lo:[0,1] neg_hi:[0,1]
	v_pk_add_f32 v[116:117], v[116:117], v[244:245] op_sel_hi:[1,0] neg_lo:[0,1] neg_hi:[0,1]
	v_sub_f32_e32 v219, v145, v178
	v_exp_f32_e32 v50, v50
	v_exp_f32_e32 v51, v51
	v_exp_f32_e32 v52, v52
	v_exp_f32_e32 v53, v53
	v_exp_f32_e32 v54, v54
	v_exp_f32_e32 v55, v55
	v_exp_f32_e32 v56, v56
	v_exp_f32_e32 v57, v57
	v_exp_f32_e32 v58, v58
	v_exp_f32_e32 v59, v59
	v_exp_f32_e32 v60, v60
	v_exp_f32_e32 v61, v61
	v_exp_f32_e32 v62, v62
	v_exp_f32_e32 v63, v63
	v_exp_f32_e32 v64, v64
	v_exp_f32_e32 v65, v65
	v_exp_f32_e32 v66, v66
	v_exp_f32_e32 v67, v67
	v_exp_f32_e32 v68, v68
	v_exp_f32_e32 v69, v69
	v_exp_f32_e32 v70, v70
	v_exp_f32_e32 v71, v71
	v_exp_f32_e32 v72, v72
	v_exp_f32_e32 v73, v73
	v_exp_f32_e32 v74, v74
	v_exp_f32_e32 v75, v75
	v_exp_f32_e32 v76, v76
	v_exp_f32_e32 v77, v77
	v_exp_f32_e32 v78, v78
	v_exp_f32_e32 v79, v79
	v_exp_f32_e32 v80, v80
	v_exp_f32_e32 v81, v81
	v_exp_f32_e32 v82, v82
	v_exp_f32_e32 v83, v83
	v_exp_f32_e32 v84, v84
	v_exp_f32_e32 v85, v85
	v_exp_f32_e32 v86, v86
	v_exp_f32_e32 v87, v87
	v_exp_f32_e32 v88, v88
	v_exp_f32_e32 v89, v89
	v_exp_f32_e32 v90, v90
	v_exp_f32_e32 v91, v91
	v_exp_f32_e32 v92, v92
	v_exp_f32_e32 v93, v93
	v_exp_f32_e32 v94, v94
	v_exp_f32_e32 v95, v95
	v_exp_f32_e32 v96, v96
	v_exp_f32_e32 v97, v97
	v_exp_f32_e32 v98, v98
	v_exp_f32_e32 v99, v99
	v_exp_f32_e32 v100, v100
	v_exp_f32_e32 v101, v101
	v_exp_f32_e32 v102, v102
	v_exp_f32_e32 v103, v103
	v_exp_f32_e32 v104, v104
	v_exp_f32_e32 v105, v105
	v_exp_f32_e32 v106, v106
	v_exp_f32_e32 v107, v107
	v_exp_f32_e32 v108, v108
	v_exp_f32_e32 v109, v109
	v_exp_f32_e32 v110, v110
	v_exp_f32_e32 v111, v111
	v_exp_f32_e32 v112, v112
	v_exp_f32_e32 v113, v113
	v_exp_f32_e32 v114, v114
	v_exp_f32_e32 v115, v115
	v_exp_f32_e32 v116, v116
	v_exp_f32_e32 v117, v117
	v_exp_f32_e32 v219, v219
	v_pk_add_f32 v[236:237], v[50:51], v[52:53]
	v_pk_add_f32 v[238:239], v[54:55], v[56:57]
	v_pk_add_f32 v[240:241], v[58:59], v[60:61]
	v_pk_add_f32 v[242:243], v[62:63], v[64:65]
	v_pk_add_f32 v[236:237], v[236:237], v[66:67]
	v_pk_add_f32 v[238:239], v[238:239], v[70:71]
	v_pk_add_f32 v[240:241], v[240:241], v[74:75]
	v_pk_add_f32 v[242:243], v[242:243], v[78:79]
	v_pk_add_f32 v[236:237], v[236:237], v[68:69]
	v_pk_add_f32 v[238:239], v[238:239], v[72:73]
	v_pk_add_f32 v[240:241], v[240:241], v[76:77]
	v_pk_add_f32 v[242:243], v[242:243], v[80:81]
	v_pk_add_f32 v[236:237], v[236:237], v[82:83]
	v_pk_add_f32 v[238:239], v[238:239], v[86:87]
	v_pk_add_f32 v[240:241], v[240:241], v[90:91]
	v_pk_add_f32 v[242:243], v[242:243], v[94:95]
	v_pk_add_f32 v[236:237], v[236:237], v[84:85]
	v_pk_add_f32 v[238:239], v[238:239], v[88:89]
	v_pk_add_f32 v[240:241], v[240:241], v[92:93]
	v_pk_add_f32 v[242:243], v[242:243], v[96:97]
	v_pk_add_f32 v[236:237], v[236:237], v[98:99]
	v_pk_add_f32 v[238:239], v[238:239], v[102:103]
	v_pk_add_f32 v[240:241], v[240:241], v[106:107]
	v_pk_add_f32 v[242:243], v[242:243], v[110:111]
	v_pk_add_f32 v[236:237], v[236:237], v[100:101]
	v_pk_add_f32 v[238:239], v[238:239], v[104:105]
	v_pk_add_f32 v[240:241], v[240:241], v[108:109]
	v_pk_add_f32 v[242:243], v[242:243], v[112:113]
	v_pk_add_f32 v[236:237], v[236:237], v[114:115]
	v_pk_add_f32 v[236:237], v[236:237], v[116:117]
	v_pk_add_f32 v[236:237], v[236:237], v[238:239]
	v_pk_add_f32 v[240:241], v[240:241], v[242:243]
	v_cndmask_b32_e64 v219, 0, v219, s[74:75]
	v_pk_add_f32 v[236:237], v[236:237], v[240:241]
	v_add_f32_e32 v185, v236, v237
	v_add_f32_e32 v185, v185, v219
	v_cvt_pk_bf16_f32 v236, v50, v51
	v_cvt_pk_bf16_f32 v237, v52, v53
	v_cvt_pk_bf16_f32 v238, v54, v55
	v_cvt_pk_bf16_f32 v239, v56, v57
	s_nop 1
	s_waitcnt lgkmcnt(14)
; #define LAS __attribute__((address_space(3)))
; __device__ __forceinline__ unsigned pk2(float lo, float hi) { return pg8::cvt_pk_bf16(lo, hi); }
; __device__ __forceinline__ s16x4 vtr(const LAS unsigned char* p) { return __builtin_bit_cast(s16x4, __builtin_amdgcn_ds_read_tr16_b64_v4i16((LAS s16x4*)p)); }
; #define MFMA16(a, b, c) __builtin_amdgcn_mfma_f32_16x16x32_bf16((a), (b), (c), 0, 0, 0)
; __device__ __forceinline__ void pv_at(const LAS unsigned char* const (&vp)[4], int off, const f32x4& P0, const f32x4& P1, f32x4 (&O)[4]) {
;     v4u pw; pw.x = pk2(P0[0], P0[1]); pw.y = pk2(P0[2], P0[3]); pw.z = pk2(P1[0], P1[1]); pw.w = pk2(P1[2], P1[3]);
;     const bf16x8 pb = __builtin_bit_cast(bf16x8, pw);
; #pragma unroll
;     for (int db = 0; db < 4; ++db) {
;         const s16x4 lo = vtr(vp[db] + off), hi = vtr(vp[db] + off + 2048);
;         const bf16x8 vt = (bf16x8){lo[0], lo[1], lo[2], lo[3], hi[0], hi[1], hi[2], hi[3]};
;         O[db] = MFMA16(vt, pb, O[db]);
;     }
; }
	v_mfma_f32_16x16x32_bf16 v[210:213], v[186:189], v[236:239], 0
	s_waitcnt lgkmcnt(12)
	v_mfma_f32_16x16x32_bf16 v[214:217], v[190:193], v[236:239], 0
	s_waitcnt lgkmcnt(10)
	v_mfma_f32_16x16x32_bf16 v[220:223], v[194:197], v[236:239], 0
	s_waitcnt lgkmcnt(8)
	v_mfma_f32_16x16x32_bf16 v[224:227], v[198:201], v[236:239], 0
	v_cvt_pk_bf16_f32 v240, v58, v59
	v_cvt_pk_bf16_f32 v241, v60, v61
	v_cvt_pk_bf16_f32 v242, v62, v63
	v_cvt_pk_bf16_f32 v243, v64, v65
	s_waitcnt lgkmcnt(7)
	ds_read_b64_tr_b16 v[186:187], v124 offset:12288
	ds_read_b64_tr_b16 v[188:189], v124 offset:14336
	ds_read_b64_tr_b16 v[190:191], v125 offset:12288
	ds_read_b64_tr_b16 v[192:193], v125 offset:14336
	ds_read_b64_tr_b16 v[194:195], v126 offset:12288
	ds_read_b64_tr_b16 v[196:197], v126 offset:14336
	ds_read_b64_tr_b16 v[198:199], v127 offset:12288
	ds_read_b64_tr_b16 v[200:201], v127 offset:14336
	s_waitcnt lgkmcnt(14)
	v_mfma_f32_16x16x32_bf16 v[210:213], v[202:205], v[240:243], v[210:213]
	s_waitcnt lgkmcnt(12)
	v_mfma_f32_16x16x32_bf16 v[214:217], v[206:209], v[240:243], v[214:217]
	s_waitcnt lgkmcnt(10)
	v_mfma_f32_16x16x32_bf16 v[220:223], v[228:231], v[240:243], v[220:223]
	s_waitcnt lgkmcnt(8)
	v_mfma_f32_16x16x32_bf16 v[224:227], v[232:235], v[240:243], v[224:227]
	v_cvt_pk_bf16_f32 v236, v66, v67
	v_cvt_pk_bf16_f32 v237, v68, v69
	v_cvt_pk_bf16_f32 v238, v70, v71
	v_cvt_pk_bf16_f32 v239, v72, v73
	s_waitcnt lgkmcnt(7)
	ds_read_b64_tr_b16 v[202:203], v124 offset:16384
	ds_read_b64_tr_b16 v[204:205], v124 offset:18432
	ds_read_b64_tr_b16 v[206:207], v125 offset:16384
	ds_read_b64_tr_b16 v[208:209], v125 offset:18432
	ds_read_b64_tr_b16 v[228:229], v126 offset:16384
	ds_read_b64_tr_b16 v[230:231], v126 offset:18432
	ds_read_b64_tr_b16 v[232:233], v127 offset:16384
	ds_read_b64_tr_b16 v[234:235], v127 offset:18432
	s_waitcnt lgkmcnt(14)
	v_mfma_f32_16x16x32_bf16 v[210:213], v[186:189], v[236:239], v[210:213]
	s_waitcnt lgkmcnt(12)
	v_mfma_f32_16x16x32_bf16 v[214:217], v[190:193], v[236:239], v[214:217]
	s_waitcnt lgkmcnt(10)
	v_mfma_f32_16x16x32_bf16 v[220:223], v[194:197], v[236:239], v[220:223]
	s_waitcnt lgkmcnt(8)
	v_mfma_f32_16x16x32_bf16 v[224:227], v[198:201], v[236:239], v[224:227]
	v_cvt_pk_bf16_f32 v240, v74, v75
	v_cvt_pk_bf16_f32 v241, v76, v77
	v_cvt_pk_bf16_f32 v242, v78, v79
	v_cvt_pk_bf16_f32 v243, v80, v81
	s_waitcnt lgkmcnt(7)
	ds_read_b64_tr_b16 v[186:187], v124 offset:20480
	ds_read_b64_tr_b16 v[188:189], v124 offset:22528
	ds_read_b64_tr_b16 v[190:191], v125 offset:20480
	ds_read_b64_tr_b16 v[192:193], v125 offset:22528
	ds_read_b64_tr_b16 v[194:195], v126 offset:20480
	ds_read_b64_tr_b16 v[196:197], v126 offset:22528
	ds_read_b64_tr_b16 v[198:199], v127 offset:20480
	ds_read_b64_tr_b16 v[200:201], v127 offset:22528
	s_waitcnt lgkmcnt(14)
	v_mfma_f32_16x16x32_bf16 v[210:213], v[202:205], v[240:243], v[210:213]
	s_waitcnt lgkmcnt(12)
	v_mfma_f32_16x16x32_bf16 v[214:217], v[206:209], v[240:243], v[214:217]
	s_waitcnt lgkmcnt(10)
	v_mfma_f32_16x16x32_bf16 v[220:223], v[228:231], v[240:243], v[220:223]
	s_waitcnt lgkmcnt(8)
	v_mfma_f32_16x16x32_bf16 v[224:227], v[232:235], v[240:243], v[224:227]
	v_cvt_pk_bf16_f32 v236, v82, v83
	v_cvt_pk_bf16_f32 v237, v84, v85
	v_cvt_pk_bf16_f32 v238, v86, v87
	v_cvt_pk_bf16_f32 v239, v88, v89
	s_waitcnt lgkmcnt(7)
	ds_read_b64_tr_b16 v[202:203], v124 offset:24576
	ds_read_b64_tr_b16 v[204:205], v124 offset:26624
	ds_read_b64_tr_b16 v[206:207], v125 offset:24576
	ds_read_b64_tr_b16 v[208:209], v125 offset:26624
	ds_read_b64_tr_b16 v[228:229], v126 offset:24576
	ds_read_b64_tr_b16 v[230:231], v126 offset:26624
	ds_read_b64_tr_b16 v[232:233], v127 offset:24576
	ds_read_b64_tr_b16 v[234:235], v127 offset:26624
	s_waitcnt lgkmcnt(14)
	v_mfma_f32_16x16x32_bf16 v[210:213], v[186:189], v[236:239], v[210:213]
	s_waitcnt lgkmcnt(12)
	v_mfma_f32_16x16x32_bf16 v[214:217], v[190:193], v[236:239], v[214:217]
	s_waitcnt lgkmcnt(10)
	v_mfma_f32_16x16x32_bf16 v[220:223], v[194:197], v[236:239], v[220:223]
	s_waitcnt lgkmcnt(8)
	v_mfma_f32_16x16x32_bf16 v[224:227], v[198:201], v[236:239], v[224:227]
	v_cvt_pk_bf16_f32 v240, v90, v91
	v_cvt_pk_bf16_f32 v241, v92, v93
	v_cvt_pk_bf16_f32 v242, v94, v95
	v_cvt_pk_bf16_f32 v243, v96, v97
	s_waitcnt lgkmcnt(7)
	ds_read_b64_tr_b16 v[186:187], v124 offset:28672
	ds_read_b64_tr_b16 v[188:189], v124 offset:30720
	ds_read_b64_tr_b16 v[190:191], v125 offset:28672
	ds_read_b64_tr_b16 v[192:193], v125 offset:30720
	ds_read_b64_tr_b16 v[194:195], v126 offset:28672
	ds_read_b64_tr_b16 v[196:197], v126 offset:30720
	ds_read_b64_tr_b16 v[198:199], v127 offset:28672
	ds_read_b64_tr_b16 v[200:201], v127 offset:30720
	s_waitcnt lgkmcnt(14)
	v_mfma_f32_16x16x32_bf16 v[210:213], v[202:205], v[240:243], v[210:213]
	s_waitcnt lgkmcnt(12)
	v_mfma_f32_16x16x32_bf16 v[214:217], v[206:209], v[240:243], v[214:217]
	s_waitcnt lgkmcnt(10)
	v_mfma_f32_16x16x32_bf16 v[220:223], v[228:231], v[240:243], v[220:223]
	s_waitcnt lgkmcnt(8)
	v_mfma_f32_16x16x32_bf16 v[224:227], v[232:235], v[240:243], v[224:227]
	v_cvt_pk_bf16_f32 v236, v98, v99
	v_cvt_pk_bf16_f32 v237, v100, v101
	v_cvt_pk_bf16_f32 v238, v102, v103
	v_cvt_pk_bf16_f32 v239, v104, v105
	s_waitcnt lgkmcnt(7)
	ds_read_b64_tr_b16 v[202:203], v124 offset:32768
	ds_read_b64_tr_b16 v[204:205], v124 offset:34816
	ds_read_b64_tr_b16 v[206:207], v125 offset:32768
	ds_read_b64_tr_b16 v[208:209], v125 offset:34816
	ds_read_b64_tr_b16 v[228:229], v126 offset:32768
	ds_read_b64_tr_b16 v[230:231], v126 offset:34816
	ds_read_b64_tr_b16 v[232:233], v127 offset:32768
	ds_read_b64_tr_b16 v[234:235], v127 offset:34816
	s_waitcnt lgkmcnt(14)
; __device__ __forceinline__ unsigned pk2(float lo, float hi) { return pg8::cvt_pk_bf16(lo, hi); }
; __device__ __forceinline__ void store_o(bf16* yrow, int g, float l, const f32x4 (&O)[4]) {
;     const float inv = 1.0f / xrow16_sum(l);
;     unsigned wx[4], wy[4];
; #pragma unroll
;     for (int db = 0; db < 4; ++db) { wx[db] = pk2(O[db][0] * inv, O[db][1] * inv); wy[db] = pk2(O[db][2] * inv, O[db][3] * inv); }
; #pragma unroll
;     for (int p = 0; p < 2; ++p) {
;         auto rx = __builtin_amdgcn_permlane16_swap(wx[2 * p], wx[2 * p + 1], false, false); wx[2 * p] = rx[0]; wx[2 * p + 1] = rx[1];
;         auto ry = __builtin_amdgcn_permlane16_swap(wy[2 * p], wy[2 * p + 1], false, false); wy[2 * p] = ry[0]; wy[2 * p + 1] = ry[1]; }
; #pragma unroll
;     for (int p = 0; p < 2; ++p) {
;         auto rx = __builtin_amdgcn_permlane32_swap(wx[p], wx[p + 2], false, false); wx[p] = rx[0]; wx[p + 2] = rx[1];
;         auto ry = __builtin_amdgcn_permlane32_swap(wy[p], wy[p + 2], false, false); wy[p] = ry[0]; wy[p + 2] = ry[1]; }
;     v4u lo = {wx[0], wy[0], wx[1], wy[1]}, hi = {wx[2], wy[2], wx[3], wy[3]};
;     *(v4u*)(yrow + 16 * g) = lo; *(v4u*)(yrow + 16 * g + 8) = hi;
; }
; template <bool MASK> __device__ __forceinline__ void a_scores(f32x4& S0, f32x4& S1, float basef, float c1, float slope2, int krow0, int kstart) {
; #pragma unroll
;     for (int r = 0; r < 4; ++r) {
;         const float d0 = fabsf(basef - (float)r), d1 = fabsf(basef - (float)(16 + r));
;         const float v0 = S0[r] - slope2 * d0, v1 = S1[r] - slope2 * d1;
;         if (MASK) { const int p0 = kstart + krow0 + r, p1 = p0 + 16;
;             S0[r] = (d0 <= 128.f && p0 >= 0 && p0 < SEQ) ? v0 : -INFINITY; S1[r] = (d1 <= 128.f && p1 >= 0 && p1 < SEQ) ? v1 : -INFINITY; }
;         else { S0[r] = v0; S1[r] = v1; }
;     }
; }
	v_mfma_f32_16x16x32_bf16 v[210:213], v[186:189], v[236:239], v[210:213]
	s_waitcnt lgkmcnt(12)
	v_mfma_f32_16x16x32_bf16 v[214:217], v[190:193], v[236:239], v[214:217]
	s_waitcnt lgkmcnt(10)
	v_mfma_f32_16x16x32_bf16 v[220:223], v[194:197], v[236:239], v[220:223]
	s_waitcnt lgkmcnt(8)
	v_mfma_f32_16x16x32_bf16 v[224:227], v[198:201], v[236:239], v[224:227]
	v_cvt_pk_bf16_f32 v240, v106, v107
	v_cvt_pk_bf16_f32 v241, v108, v109
	v_cvt_pk_bf16_f32 v242, v110, v111
	v_cvt_pk_bf16_f32 v243, v112, v113
	s_waitcnt lgkmcnt(7)
	ds_read_b64_tr_b16 v[186:187], v124 offset:36864
	ds_read_b64_tr_b16 v[188:189], v124 offset:38912
	ds_read_b64_tr_b16 v[190:191], v125 offset:36864
	ds_read_b64_tr_b16 v[192:193], v125 offset:38912
	ds_read_b64_tr_b16 v[194:195], v126 offset:36864
	ds_read_b64_tr_b16 v[196:197], v126 offset:38912
	ds_read_b64_tr_b16 v[198:199], v127 offset:36864
	ds_read_b64_tr_b16 v[200:201], v127 offset:38912
	s_waitcnt lgkmcnt(14)
	v_mfma_f32_16x16x32_bf16 v[210:213], v[202:205], v[240:243], v[210:213]
	s_waitcnt lgkmcnt(12)
	v_mfma_f32_16x16x32_bf16 v[214:217], v[206:209], v[240:243], v[214:217]
	s_waitcnt lgkmcnt(10)
	v_mfma_f32_16x16x32_bf16 v[220:223], v[228:231], v[240:243], v[220:223]
	s_waitcnt lgkmcnt(8)
	v_mfma_f32_16x16x32_bf16 v[224:227], v[232:235], v[240:243], v[224:227]
	v_cvt_pk_bf16_f32 v236, v114, v115
	v_cvt_pk_bf16_f32 v237, v116, v117
	v_mov_b32_e32 v238, 0
	v_mov_b32_e32 v239, 0
	s_nop 1
	s_waitcnt lgkmcnt(6)
	v_mfma_f32_16x16x32_bf16 v[210:213], v[186:189], v[236:239], v[210:213]
	s_waitcnt lgkmcnt(4)
	v_mfma_f32_16x16x32_bf16 v[214:217], v[190:193], v[236:239], v[214:217]
	s_waitcnt lgkmcnt(2)
	v_mfma_f32_16x16x32_bf16 v[220:223], v[194:197], v[236:239], v[220:223]
	s_waitcnt lgkmcnt(0)
	v_mfma_f32_16x16x32_bf16 v[224:227], v[198:201], v[236:239], v[224:227]
	v_mov_b32_e32 v219, v185
	s_nop 1
	v_permlane16_swap_b32_e32 v185, v219
	v_add_f32_e32 v185, v185, v219
	v_mov_b32_e32 v219, v185
	s_nop 1
	v_permlane32_swap_b32_e32 v185, v219
	v_add_f32_e32 v185, v185, v219
	v_div_scale_f32 v236, s[78:79], v185, v185, 1.0
	v_div_scale_f32 v237, vcc, 1.0, v185, 1.0
	v_rcp_f32_e32 v238, v236
	s_nop 0
	v_fma_f32 v239, -v236, v238, 1.0
	v_fmac_f32_e32 v238, v239, v238
	v_mul_f32_e32 v240, v237, v238
	v_fma_f32 v241, -v236, v240, v237
	v_fmac_f32_e32 v240, v241, v238
	v_fma_f32 v237, -v236, v240, v237
	v_div_fmas_f32 v237, v237, v238, v240
	v_div_fixup_f32 v244, v237, v185, 1.0
	v_mul_f32_e32 v240, v210, v244
	v_mul_f32_e32 v241, v211, v244
	v_mul_f32_e32 v242, v212, v244
	v_mul_f32_e32 v243, v213, v244
	v_cvt_pk_bf16_f32 v186, v240, v241
	v_cvt_pk_bf16_f32 v187, v242, v243
	v_mul_f32_e32 v240, v214, v244
	v_mul_f32_e32 v241, v215, v244
	v_mul_f32_e32 v242, v216, v244
	v_mul_f32_e32 v243, v217, v244
	v_cvt_pk_bf16_f32 v188, v240, v241
	v_cvt_pk_bf16_f32 v189, v242, v243
	v_mul_f32_e32 v240, v220, v244
	v_mul_f32_e32 v241, v221, v244
	v_mul_f32_e32 v242, v222, v244
	v_mul_f32_e32 v243, v223, v244
	v_cvt_pk_bf16_f32 v190, v240, v241
	v_cvt_pk_bf16_f32 v191, v242, v243
	v_mul_f32_e32 v240, v224, v244
	v_mul_f32_e32 v241, v225, v244
	v_mul_f32_e32 v242, v226, v244
	v_mul_f32_e32 v243, v227, v244
	v_cvt_pk_bf16_f32 v192, v240, v241
	v_cvt_pk_bf16_f32 v193, v242, v243
	s_nop 1
	v_permlane16_swap_b32_e32 v186, v188
	v_permlane16_swap_b32_e32 v187, v189
	v_permlane16_swap_b32_e32 v190, v192
	v_permlane16_swap_b32_e32 v191, v193
	s_nop 0
	v_permlane32_swap_b32_e32 v186, v190
	v_permlane32_swap_b32_e32 v187, v191
	v_permlane32_swap_b32_e32 v188, v192
	v_permlane32_swap_b32_e32 v189, v193
	v_add_u32_e32 v219, 0x1000, v128
	global_store_dwordx4 v219, v[186:189], s[82:83] offset:0
	global_store_dwordx4 v219, v[190:193], s[82:83] offset:16
	s_nop 1
	v_fmamk_f32 v50, v130, 0x43000000, v132
	v_fmamk_f32 v51, v130, 0x42fe0000, v132
	v_fmamk_f32 v52, v130, 0x42fc0000, v132
	v_fmamk_f32 v53, v130, 0x42fa0000, v132
	v_fmamk_f32 v54, v130, 0x42e00000, v132
	v_fmamk_f32 v55, v130, 0x42de0000, v132
	v_fmamk_f32 v56, v130, 0x42dc0000, v132
	v_fmamk_f32 v57, v130, 0x42da0000, v132
	v_fmamk_f32 v58, v130, 0x42c00000, v132
	v_fmamk_f32 v59, v130, 0x42be0000, v132
	v_fmamk_f32 v60, v130, 0x42bc0000, v132
	v_fmamk_f32 v61, v130, 0x42ba0000, v132
	v_fmamk_f32 v62, v130, 0x42a00000, v132
	v_fmamk_f32 v63, v130, 0x429e0000, v132
	v_fmamk_f32 v64, v130, 0x429c0000, v132
	v_fmamk_f32 v65, v130, 0x429a0000, v132
	v_fmamk_f32 v66, v130, 0x42800000, v132
	v_fmamk_f32 v67, v130, 0x427c0000, v132
	v_fmamk_f32 v68, v130, 0x42780000, v132
	v_fmamk_f32 v69, v130, 0x42740000, v132
	v_fmamk_f32 v70, v130, 0x42400000, v132
	v_fmamk_f32 v71, v130, 0x423c0000, v132
	v_fmamk_f32 v72, v130, 0x42380000, v132
	v_fmamk_f32 v73, v130, 0x42340000, v132
	v_fmamk_f32 v74, v130, 0x42000000, v132
	v_fmamk_f32 v75, v130, 0x41f80000, v132
	v_fmamk_f32 v76, v130, 0x41f00000, v132
	v_fmamk_f32 v77, v130, 0x41e80000, v132
	v_fmamk_f32 v78, v130, 0x41800000, v132
	v_fmamk_f32 v79, v130, 0x41700000, v132
	v_fmamk_f32 v80, v130, 0x41600000, v132
	v_fmamk_f32 v81, v130, 0x41500000, v132
	v_add_f32_e32 v219, 0, v129
	v_mul_f32_e64 v82, v130, |v219|
	v_add_f32_e32 v244, 0xbf800000, v129
	v_mul_f32_e64 v83, v130, |v244|
	v_add_f32_e32 v219, 0xc0000000, v129
	v_mul_f32_e64 v84, v130, |v219|
	v_add_f32_e32 v244, 0xc0400000, v129
	v_mul_f32_e64 v85, v130, |v244|
	v_fmamk_f32 v86, v131, 0xc1800000, v133
	v_fmamk_f32 v87, v131, 0xc1880000, v133
	v_fmamk_f32 v88, v131, 0xc1900000, v133
	v_fmamk_f32 v89, v131, 0xc1980000, v133
	v_fmamk_f32 v90, v131, 0xc2000000, v133
	v_fmamk_f32 v91, v131, 0xc2040000, v133
	v_fmamk_f32 v92, v131, 0xc2080000, v133
	v_fmamk_f32 v93, v131, 0xc20c0000, v133
; #define LAS __attribute__((address_space(3)))
; #define MFMA16(a, b, c) __builtin_amdgcn_mfma_f32_16x16x32_bf16((a), (b), (c), 0, 0, 0)
; __device__ __forceinline__ void qk_at(const LAS unsigned char* kp0, const LAS unsigned char* kp1, int off, bf16x8 qf0, bf16x8 qf1, f32x4& S0, f32x4& S1) {
;     const bf16x8 k00 = *(const LAS bf16x8*)(kp0 + off), k01 = *(const LAS bf16x8*)(kp1 + off);
;     const bf16x8 k10 = *(const LAS bf16x8*)(kp0 + off + 2048), k11 = *(const LAS bf16x8*)(kp1 + off + 2048);
;     const f32x4 z = {0.f, 0.f, 0.f, 0.f};
;     S0 = MFMA16(k00, qf0, z); S0 = MFMA16(k01, qf1, S0);
;     S1 = MFMA16(k10, qf0, z); S1 = MFMA16(k11, qf1, S1);
; }
; template <bool MASK> __device__ __forceinline__ void a_scores(f32x4& S0, f32x4& S1, float basef, float c1, float slope2, int krow0, int kstart) {
; #pragma unroll
;     for (int r = 0; r < 4; ++r) {
;         const float d0 = fabsf(basef - (float)r), d1 = fabsf(basef - (float)(16 + r));
;         const float v0 = S0[r] - slope2 * d0, v1 = S1[r] - slope2 * d1;
;         if (MASK) { const int p0 = kstart + krow0 + r, p1 = p0 + 16;
;             S0[r] = (d0 <= 128.f && p0 >= 0 && p0 < SEQ) ? v0 : -INFINITY; S1[r] = (d1 <= 128.f && p1 >= 0 && p1 < SEQ) ? v1 : -INFINITY; }
;         else { S0[r] = v0; S1[r] = v1; }
;     }
; }
	v_fmamk_f32 v94, v131, 0xc2400000, v133
	v_fmamk_f32 v95, v131, 0xc2440000, v133
	v_fmamk_f32 v96, v131, 0xc2480000, v133
	v_fmamk_f32 v97, v131, 0xc24c0000, v133
	v_fmamk_f32 v98, v131, 0xc2800000, v133
	v_fmamk_f32 v99, v131, 0xc2820000, v133
	v_fmamk_f32 v100, v131, 0xc2840000, v133
	v_fmamk_f32 v101, v131, 0xc2860000, v133
	v_fmamk_f32 v102, v131, 0xc2a00000, v133
	v_fmamk_f32 v103, v131, 0xc2a20000, v133
	v_fmamk_f32 v104, v131, 0xc2a40000, v133
	v_fmamk_f32 v105, v131, 0xc2a60000, v133
	v_fmamk_f32 v106, v131, 0xc2c00000, v133
	v_fmamk_f32 v107, v131, 0xc2c20000, v133
	v_fmamk_f32 v108, v131, 0xc2c40000, v133
	v_fmamk_f32 v109, v131, 0xc2c60000, v133
	v_fmamk_f32 v110, v131, 0xc2e00000, v133
	v_fmamk_f32 v111, v131, 0xc2e20000, v133
	v_fmamk_f32 v112, v131, 0xc2e40000, v133
	v_fmamk_f32 v113, v131, 0xc2e60000, v133
	v_fmamk_f32 v114, v131, 0xc3000000, v133
	v_fmamk_f32 v115, v131, 0xc3010000, v133
	v_fmamk_f32 v116, v131, 0xc3020000, v133
	v_fmamk_f32 v117, v131, 0xc3030000, v133
	v_mov_b32_e32 v245, 0xff800000
	v_cndmask_b32_e64 v50, v245, v50, s[16:17]
	v_cndmask_b32_e64 v51, v245, v51, s[18:19]
	v_cndmask_b32_e64 v52, v245, v52, s[22:23]
	v_cndmask_b32_e64 v53, v245, v53, s[24:25]
	v_cndmask_b32_e64 v114, v245, v114, s[28:29]
	v_cndmask_b32_e64 v115, v245, v115, s[52:53]
	v_cndmask_b32_e64 v116, v245, v116, s[54:55]
	v_cndmask_b32_e64 v117, v245, v117, s[88:89]
	ds_read_b128 v[186:189], v122 offset:6144
	ds_read_b128 v[190:193], v123 offset:6144
	ds_read_b128 v[194:197], v122 offset:8192
	ds_read_b128 v[198:201], v123 offset:8192
	ds_read_b128 v[202:205], v122 offset:10240
	ds_read_b128 v[206:209], v123 offset:10240
	s_waitcnt lgkmcnt(5)
	v_mfma_f32_16x16x32_bf16 v[50:53], v[186:189], v[170:173], v[50:53]
	s_waitcnt lgkmcnt(4)
	v_mfma_f32_16x16x32_bf16 v[50:53], v[190:193], v[174:177], v[50:53]
	ds_read_b128 v[186:189], v122 offset:12288
	ds_read_b128 v[190:193], v123 offset:12288
	s_waitcnt lgkmcnt(5)
	v_mfma_f32_16x16x32_bf16 v[54:57], v[194:197], v[170:173], v[54:57]
	s_waitcnt lgkmcnt(4)
	v_mfma_f32_16x16x32_bf16 v[54:57], v[198:201], v[174:177], v[54:57]
	ds_read_b128 v[194:197], v122 offset:14336
	ds_read_b128 v[198:201], v123 offset:14336
	s_waitcnt lgkmcnt(5)
	v_mfma_f32_16x16x32_bf16 v[58:61], v[202:205], v[170:173], v[58:61]
	s_waitcnt lgkmcnt(4)
	v_mfma_f32_16x16x32_bf16 v[58:61], v[206:209], v[174:177], v[58:61]
	ds_read_b128 v[202:205], v122 offset:16384
	ds_read_b128 v[206:209], v123 offset:16384
	s_waitcnt lgkmcnt(5)
	v_mfma_f32_16x16x32_bf16 v[62:65], v[186:189], v[170:173], v[62:65]
	s_waitcnt lgkmcnt(4)
	v_mfma_f32_16x16x32_bf16 v[62:65], v[190:193], v[174:177], v[62:65]
	ds_read_b128 v[186:189], v122 offset:18432
	ds_read_b128 v[190:193], v123 offset:18432
	s_waitcnt lgkmcnt(5)
	v_mfma_f32_16x16x32_bf16 v[66:69], v[194:197], v[170:173], v[66:69]
	s_waitcnt lgkmcnt(4)
	v_mfma_f32_16x16x32_bf16 v[66:69], v[198:201], v[174:177], v[66:69]
	ds_read_b128 v[194:197], v122 offset:20480
	ds_read_b128 v[198:201], v123 offset:20480
	s_waitcnt lgkmcnt(5)
	v_mfma_f32_16x16x32_bf16 v[70:73], v[202:205], v[170:173], v[70:73]
	s_waitcnt lgkmcnt(4)
	v_mfma_f32_16x16x32_bf16 v[70:73], v[206:209], v[174:177], v[70:73]
	ds_read_b128 v[202:205], v122 offset:22528
	ds_read_b128 v[206:209], v123 offset:22528
	s_waitcnt lgkmcnt(5)
	v_mfma_f32_16x16x32_bf16 v[74:77], v[186:189], v[170:173], v[74:77]
	s_waitcnt lgkmcnt(4)
	v_mfma_f32_16x16x32_bf16 v[74:77], v[190:193], v[174:177], v[74:77]
	ds_read_b128 v[186:189], v122 offset:24576
	ds_read_b128 v[190:193], v123 offset:24576
	s_waitcnt lgkmcnt(5)
	v_mfma_f32_16x16x32_bf16 v[78:81], v[194:197], v[170:173], v[78:81]
	s_waitcnt lgkmcnt(4)
	v_mfma_f32_16x16x32_bf16 v[78:81], v[198:201], v[174:177], v[78:81]
	ds_read_b128 v[194:197], v122 offset:26624
	ds_read_b128 v[198:201], v123 offset:26624
	s_waitcnt lgkmcnt(5)
	v_mfma_f32_16x16x32_bf16 v[82:85], v[202:205], v[170:173], v[82:85]
	s_waitcnt lgkmcnt(4)
	v_mfma_f32_16x16x32_bf16 v[82:85], v[206:209], v[174:177], v[82:85]
	ds_read_b128 v[202:205], v122 offset:28672
	ds_read_b128 v[206:209], v123 offset:28672
	s_waitcnt lgkmcnt(5)
	v_mfma_f32_16x16x32_bf16 v[86:89], v[186:189], v[170:173], v[86:89]
	s_waitcnt lgkmcnt(4)
	v_mfma_f32_16x16x32_bf16 v[86:89], v[190:193], v[174:177], v[86:89]
	ds_read_b128 v[186:189], v122 offset:30720
	ds_read_b128 v[190:193], v123 offset:30720
	s_waitcnt lgkmcnt(5)
	v_mfma_f32_16x16x32_bf16 v[90:93], v[194:197], v[170:173], v[90:93]
	s_waitcnt lgkmcnt(4)
	v_mfma_f32_16x16x32_bf16 v[90:93], v[198:201], v[174:177], v[90:93]
	ds_read_b128 v[194:197], v122 offset:32768
	ds_read_b128 v[198:201], v123 offset:32768
	s_waitcnt lgkmcnt(5)
	v_mfma_f32_16x16x32_bf16 v[94:97], v[202:205], v[170:173], v[94:97]
	s_waitcnt lgkmcnt(4)
	v_mfma_f32_16x16x32_bf16 v[94:97], v[206:209], v[174:177], v[94:97]
	ds_read_b128 v[202:205], v122 offset:34816
	ds_read_b128 v[206:209], v123 offset:34816
	s_waitcnt lgkmcnt(5)
	v_mfma_f32_16x16x32_bf16 v[98:101], v[186:189], v[170:173], v[98:101]
	s_waitcnt lgkmcnt(4)
	v_mfma_f32_16x16x32_bf16 v[98:101], v[190:193], v[174:177], v[98:101]
	ds_read_b128 v[186:189], v122 offset:36864
	ds_read_b128 v[190:193], v123 offset:36864
	s_waitcnt lgkmcnt(5)
	v_mfma_f32_16x16x32_bf16 v[102:105], v[194:197], v[170:173], v[102:105]
	s_waitcnt lgkmcnt(4)
	v_mfma_f32_16x16x32_bf16 v[102:105], v[198:201], v[174:177], v[102:105]
	ds_read_b128 v[194:197], v122 offset:38912
	ds_read_b128 v[198:201], v123 offset:38912
	s_waitcnt lgkmcnt(5)
	v_mfma_f32_16x16x32_bf16 v[106:109], v[202:205], v[170:173], v[106:109]
	s_waitcnt lgkmcnt(4)
	v_mfma_f32_16x16x32_bf16 v[106:109], v[206:209], v[174:177], v[106:109]
	s_waitcnt lgkmcnt(3)
; __device__ __forceinline__ void softmax_step(f32x4& s0, f32x4& s1, float& m, float& l, f32x4 (&O)[4]) {
;     float t = fmaxf(fmaxf(fmaxf(s0[0], s0[1]), fmaxf(s0[2], s0[3])), fmaxf(fmaxf(s1[0], s1[1]), fmaxf(s1[2], s1[3])));
;     t = xrow16_max(t);
;     const float mn = fmaxf(m, t), alpha = __builtin_amdgcn_exp2f(m - mn);
;     m = mn;
; #pragma unroll
;     for (int k = 0; k < 4; ++k) { s0[k] = __builtin_amdgcn_exp2f(s0[k] - mn); s1[k] = __builtin_amdgcn_exp2f(s1[k] - mn); }
;     l = l * alpha + ((s0[0] + s0[1]) + (s0[2] + s0[3])) + ((s1[0] + s1[1]) + (s1[2] + s1[3]));
	v_mfma_f32_16x16x32_bf16 v[110:113], v[186:189], v[170:173], v[110:113]
	s_waitcnt lgkmcnt(2)
	v_mfma_f32_16x16x32_bf16 v[110:113], v[190:193], v[174:177], v[110:113]
	s_waitcnt lgkmcnt(1)
	v_mfma_f32_16x16x32_bf16 v[114:117], v[194:197], v[170:173], v[114:117]
	s_waitcnt lgkmcnt(0)
	v_mfma_f32_16x16x32_bf16 v[114:117], v[198:201], v[174:177], v[114:117]
	v_max3_f32 v219, v50, v51, v52
	v_max3_f32 v244, v54, v55, v56
	v_max3_f32 v245, v58, v59, v60
	v_max3_f32 v120, v62, v63, v64
	v_max3_f32 v219, v219, v53, v66
	v_max3_f32 v244, v244, v57, v70
	v_max3_f32 v245, v245, v61, v74
	v_max3_f32 v120, v120, v65, v78
	v_max3_f32 v219, v219, v67, v68
	v_max3_f32 v244, v244, v71, v72
	v_max3_f32 v245, v245, v75, v76
	v_max3_f32 v120, v120, v79, v80
	ds_read_b64_tr_b16 v[186:187], v124 offset:6144
	ds_read_b64_tr_b16 v[188:189], v124 offset:8192
	ds_read_b64_tr_b16 v[190:191], v125 offset:6144
	ds_read_b64_tr_b16 v[192:193], v125 offset:8192
	ds_read_b64_tr_b16 v[194:195], v126 offset:6144
	ds_read_b64_tr_b16 v[196:197], v126 offset:8192
	ds_read_b64_tr_b16 v[198:199], v127 offset:6144
	ds_read_b64_tr_b16 v[200:201], v127 offset:8192
	v_max3_f32 v219, v219, v69, v82
	v_max3_f32 v244, v244, v73, v86
	v_max3_f32 v245, v245, v77, v90
	v_max3_f32 v120, v120, v81, v94
	v_max3_f32 v219, v219, v83, v84
	v_max3_f32 v244, v244, v87, v88
	v_max3_f32 v245, v245, v91, v92
	v_max3_f32 v120, v120, v95, v96
	v_max3_f32 v219, v219, v85, v98
	v_max3_f32 v244, v244, v89, v102
	v_max3_f32 v245, v245, v93, v106
	v_max3_f32 v120, v120, v97, v110
	v_max3_f32 v219, v219, v99, v100
	v_max3_f32 v244, v244, v103, v104
	v_max3_f32 v245, v245, v107, v108
	v_max3_f32 v120, v120, v111, v112
	v_max3_f32 v219, v219, v101, v114
	v_max3_f32 v219, v219, v115, v116
	v_max_f32_e32 v219, v219, v117
	v_max_f32_e32 v244, v244, v105
	v_max_f32_e32 v245, v245, v109
	v_max_f32_e32 v120, v120, v113
	v_max3_f32 v178, v219, v244, v245
	v_max_f32_e32 v178, v178, v120
	v_mov_b32_e32 v219, v178
	s_nop 1
	v_permlane16_swap_b32_e32 v178, v219
	v_max_f32_e32 v178, v178, v219
	v_mov_b32_e32 v219, v178
	s_nop 1
	v_permlane32_swap_b32_e32 v178, v219
	v_max3_f32 v178, v178, v219, v145
	s_waitcnt lgkmcnt(7)
	ds_read_b64_tr_b16 v[202:203], v124 offset:10240
	ds_read_b64_tr_b16 v[204:205], v124 offset:12288
	ds_read_b64_tr_b16 v[206:207], v125 offset:10240
	ds_read_b64_tr_b16 v[208:209], v125 offset:12288
	ds_read_b64_tr_b16 v[228:229], v126 offset:10240
	ds_read_b64_tr_b16 v[230:231], v126 offset:12288
	ds_read_b64_tr_b16 v[232:233], v127 offset:10240
	ds_read_b64_tr_b16 v[234:235], v127 offset:12288
	v_mov_b32_e32 v244, v178
	v_pk_add_f32 v[50:51], v[50:51], v[244:245] op_sel_hi:[1,0] neg_lo:[0,1] neg_hi:[0,1]
	v_pk_add_f32 v[52:53], v[52:53], v[244:245] op_sel_hi:[1,0] neg_lo:[0,1] neg_hi:[0,1]
	v_pk_add_f32 v[54:55], v[54:55], v[244:245] op_sel_hi:[1,0] neg_lo:[0,1] neg_hi:[0,1]
	v_pk_add_f32 v[56:57], v[56:57], v[244:245] op_sel_hi:[1,0] neg_lo:[0,1] neg_hi:[0,1]
	v_pk_add_f32 v[58:59], v[58:59], v[244:245] op_sel_hi:[1,0] neg_lo:[0,1] neg_hi:[0,1]
	v_pk_add_f32 v[60:61], v[60:61], v[244:245] op_sel_hi:[1,0] neg_lo:[0,1] neg_hi:[0,1]
	v_pk_add_f32 v[62:63], v[62:63], v[244:245] op_sel_hi:[1,0] neg_lo:[0,1] neg_hi:[0,1]
	v_pk_add_f32 v[64:65], v[64:65], v[244:245] op_sel_hi:[1,0] neg_lo:[0,1] neg_hi:[0,1]
	v_pk_add_f32 v[66:67], v[66:67], v[244:245] op_sel_hi:[1,0] neg_lo:[0,1] neg_hi:[0,1]
	v_pk_add_f32 v[68:69], v[68:69], v[244:245] op_sel_hi:[1,0] neg_lo:[0,1] neg_hi:[0,1]
	v_pk_add_f32 v[70:71], v[70:71], v[244:245] op_sel_hi:[1,0] neg_lo:[0,1] neg_hi:[0,1]
	v_pk_add_f32 v[72:73], v[72:73], v[244:245] op_sel_hi:[1,0] neg_lo:[0,1] neg_hi:[0,1]
	v_pk_add_f32 v[74:75], v[74:75], v[244:245] op_sel_hi:[1,0] neg_lo:[0,1] neg_hi:[0,1]
	v_pk_add_f32 v[76:77], v[76:77], v[244:245] op_sel_hi:[1,0] neg_lo:[0,1] neg_hi:[0,1]
	v_pk_add_f32 v[78:79], v[78:79], v[244:245] op_sel_hi:[1,0] neg_lo:[0,1] neg_hi:[0,1]
	v_pk_add_f32 v[80:81], v[80:81], v[244:245] op_sel_hi:[1,0] neg_lo:[0,1] neg_hi:[0,1]
	v_pk_add_f32 v[82:83], v[82:83], v[244:245] op_sel_hi:[1,0] neg_lo:[0,1] neg_hi:[0,1]
	v_pk_add_f32 v[84:85], v[84:85], v[244:245] op_sel_hi:[1,0] neg_lo:[0,1] neg_hi:[0,1]
	v_pk_add_f32 v[86:87], v[86:87], v[244:245] op_sel_hi:[1,0] neg_lo:[0,1] neg_hi:[0,1]
	v_pk_add_f32 v[88:89], v[88:89], v[244:245] op_sel_hi:[1,0] neg_lo:[0,1] neg_hi:[0,1]
	v_pk_add_f32 v[90:91], v[90:91], v[244:245] op_sel_hi:[1,0] neg_lo:[0,1] neg_hi:[0,1]
	v_pk_add_f32 v[92:93], v[92:93], v[244:245] op_sel_hi:[1,0] neg_lo:[0,1] neg_hi:[0,1]
	v_pk_add_f32 v[94:95], v[94:95], v[244:245] op_sel_hi:[1,0] neg_lo:[0,1] neg_hi:[0,1]
	v_pk_add_f32 v[96:97], v[96:97], v[244:245] op_sel_hi:[1,0] neg_lo:[0,1] neg_hi:[0,1]
	v_pk_add_f32 v[98:99], v[98:99], v[244:245] op_sel_hi:[1,0] neg_lo:[0,1] neg_hi:[0,1]
	v_pk_add_f32 v[100:101], v[100:101], v[244:245] op_sel_hi:[1,0] neg_lo:[0,1] neg_hi:[0,1]
	v_pk_add_f32 v[102:103], v[102:103], v[244:245] op_sel_hi:[1,0] neg_lo:[0,1] neg_hi:[0,1]
	v_pk_add_f32 v[104:105], v[104:105], v[244:245] op_sel_hi:[1,0] neg_lo:[0,1] neg_hi:[0,1]
	v_pk_add_f32 v[106:107], v[106:107], v[244:245] op_sel_hi:[1,0] neg_lo:[0,1] neg_hi:[0,1]
	v_pk_add_f32 v[108:109], v[108:109], v[244:245] op_sel_hi:[1,0] neg_lo:[0,1] neg_hi:[0,1]
	v_pk_add_f32 v[110:111], v[110:111], v[244:245] op_sel_hi:[1,0] neg_lo:[0,1] neg_hi:[0,1]
	v_pk_add_f32 v[112:113], v[112:113], v[244:245] op_sel_hi:[1,0] neg_lo:[0,1] neg_hi:[0,1]
	v_pk_add_f32 v[114:115], v[114:115], v[244:245] op_sel_hi:[1,0] neg_lo:[0,1] neg_hi:[0,1]
	v_pk_add_f32 v[116:117], v[116:117], v[244:245] op_sel_hi:[1,0] neg_lo:[0,1] neg_hi:[0,1]
	v_sub_f32_e32 v219, v145, v178
; #define LAS __attribute__((address_space(3)))
; __device__ __forceinline__ unsigned pk2(float lo, float hi) { return pg8::cvt_pk_bf16(lo, hi); }
; __device__ __forceinline__ s16x4 vtr(const LAS unsigned char* p) { return __builtin_bit_cast(s16x4, __builtin_amdgcn_ds_read_tr16_b64_v4i16((LAS s16x4*)p)); }
; #define MFMA16(a, b, c) __builtin_amdgcn_mfma_f32_16x16x32_bf16((a), (b), (c), 0, 0, 0)
; __device__ __forceinline__ void pv_at(const LAS unsigned char* const (&vp)[4], int off, const f32x4& P0, const f32x4& P1, f32x4 (&O)[4]) {
;     v4u pw; pw.x = pk2(P0[0], P0[1]); pw.y = pk2(P0[2], P0[3]); pw.z = pk2(P1[0], P1[1]); pw.w = pk2(P1[2], P1[3]);
;     const bf16x8 pb = __builtin_bit_cast(bf16x8, pw);
; #pragma unroll
;     for (int db = 0; db < 4; ++db) {
;         const s16x4 lo = vtr(vp[db] + off), hi = vtr(vp[db] + off + 2048);
;         const bf16x8 vt = (bf16x8){lo[0], lo[1], lo[2], lo[3], hi[0], hi[1], hi[2], hi[3]};
;         O[db] = MFMA16(vt, pb, O[db]);
;     }
; }
; __device__ __forceinline__ void softmax_step(f32x4& s0, f32x4& s1, float& m, float& l, f32x4 (&O)[4]) {
;     float t = fmaxf(fmaxf(fmaxf(s0[0], s0[1]), fmaxf(s0[2], s0[3])), fmaxf(fmaxf(s1[0], s1[1]), fmaxf(s1[2], s1[3])));
;     t = xrow16_max(t);
;     const float mn = fmaxf(m, t), alpha = __builtin_amdgcn_exp2f(m - mn);
;     m = mn;
; #pragma unroll
;     for (int k = 0; k < 4; ++k) { s0[k] = __builtin_amdgcn_exp2f(s0[k] - mn); s1[k] = __builtin_amdgcn_exp2f(s1[k] - mn); }
;     l = l * alpha + ((s0[0] + s0[1]) + (s0[2] + s0[3])) + ((s1[0] + s1[1]) + (s1[2] + s1[3]));
; #pragma unroll
;     for (int db = 0; db < 4; ++db) O[db] *= alpha;
; }
	v_exp_f32_e32 v50, v50
	v_exp_f32_e32 v51, v51
	v_exp_f32_e32 v52, v52
	v_exp_f32_e32 v53, v53
	v_exp_f32_e32 v54, v54
	v_exp_f32_e32 v55, v55
	v_exp_f32_e32 v56, v56
	v_exp_f32_e32 v57, v57
	v_exp_f32_e32 v58, v58
	v_exp_f32_e32 v59, v59
	v_exp_f32_e32 v60, v60
	v_exp_f32_e32 v61, v61
	v_exp_f32_e32 v62, v62
	v_exp_f32_e32 v63, v63
	v_exp_f32_e32 v64, v64
	v_exp_f32_e32 v65, v65
	v_exp_f32_e32 v66, v66
	v_exp_f32_e32 v67, v67
	v_exp_f32_e32 v68, v68
	v_exp_f32_e32 v69, v69
	v_exp_f32_e32 v70, v70
	v_exp_f32_e32 v71, v71
	v_exp_f32_e32 v72, v72
	v_exp_f32_e32 v73, v73
	v_exp_f32_e32 v74, v74
	v_exp_f32_e32 v75, v75
	v_exp_f32_e32 v76, v76
	v_exp_f32_e32 v77, v77
	v_exp_f32_e32 v78, v78
	v_exp_f32_e32 v79, v79
	v_exp_f32_e32 v80, v80
	v_exp_f32_e32 v81, v81
	v_exp_f32_e32 v82, v82
	v_exp_f32_e32 v83, v83
	v_exp_f32_e32 v84, v84
	v_exp_f32_e32 v85, v85
	v_exp_f32_e32 v86, v86
	v_exp_f32_e32 v87, v87
	v_exp_f32_e32 v88, v88
	v_exp_f32_e32 v89, v89
	v_exp_f32_e32 v90, v90
	v_exp_f32_e32 v91, v91
	v_exp_f32_e32 v92, v92
	v_exp_f32_e32 v93, v93
	v_exp_f32_e32 v94, v94
	v_exp_f32_e32 v95, v95
	v_exp_f32_e32 v96, v96
	v_exp_f32_e32 v97, v97
	v_exp_f32_e32 v98, v98
	v_exp_f32_e32 v99, v99
	v_exp_f32_e32 v100, v100
	v_exp_f32_e32 v101, v101
	v_exp_f32_e32 v102, v102
	v_exp_f32_e32 v103, v103
	v_exp_f32_e32 v104, v104
	v_exp_f32_e32 v105, v105
	v_exp_f32_e32 v106, v106
	v_exp_f32_e32 v107, v107
	v_exp_f32_e32 v108, v108
	v_exp_f32_e32 v109, v109
	v_exp_f32_e32 v110, v110
	v_exp_f32_e32 v111, v111
	v_exp_f32_e32 v112, v112
	v_exp_f32_e32 v113, v113
	v_exp_f32_e32 v114, v114
	v_exp_f32_e32 v115, v115
	v_exp_f32_e32 v116, v116
	v_exp_f32_e32 v117, v117
	v_exp_f32_e32 v219, v219
	v_pk_add_f32 v[236:237], v[50:51], v[52:53]
	v_pk_add_f32 v[238:239], v[54:55], v[56:57]
	v_pk_add_f32 v[240:241], v[58:59], v[60:61]
	v_pk_add_f32 v[242:243], v[62:63], v[64:65]
	v_pk_add_f32 v[236:237], v[236:237], v[66:67]
	v_pk_add_f32 v[238:239], v[238:239], v[70:71]
	v_pk_add_f32 v[240:241], v[240:241], v[74:75]
	v_pk_add_f32 v[242:243], v[242:243], v[78:79]
	v_pk_add_f32 v[236:237], v[236:237], v[68:69]
	v_pk_add_f32 v[238:239], v[238:239], v[72:73]
	v_pk_add_f32 v[240:241], v[240:241], v[76:77]
	v_pk_add_f32 v[242:243], v[242:243], v[80:81]
	v_pk_add_f32 v[236:237], v[236:237], v[82:83]
	v_pk_add_f32 v[238:239], v[238:239], v[86:87]
	v_pk_add_f32 v[240:241], v[240:241], v[90:91]
	v_pk_add_f32 v[242:243], v[242:243], v[94:95]
	v_pk_add_f32 v[236:237], v[236:237], v[84:85]
	v_pk_add_f32 v[238:239], v[238:239], v[88:89]
	v_pk_add_f32 v[240:241], v[240:241], v[92:93]
	v_pk_add_f32 v[242:243], v[242:243], v[96:97]
	v_pk_add_f32 v[236:237], v[236:237], v[98:99]
	v_pk_add_f32 v[238:239], v[238:239], v[102:103]
	v_pk_add_f32 v[240:241], v[240:241], v[106:107]
	v_pk_add_f32 v[242:243], v[242:243], v[110:111]
	v_pk_add_f32 v[236:237], v[236:237], v[100:101]
	v_pk_add_f32 v[238:239], v[238:239], v[104:105]
	v_pk_add_f32 v[240:241], v[240:241], v[108:109]
	v_pk_add_f32 v[242:243], v[242:243], v[112:113]
	v_pk_add_f32 v[236:237], v[236:237], v[114:115]
	v_pk_add_f32 v[236:237], v[236:237], v[116:117]
	v_pk_add_f32 v[236:237], v[236:237], v[238:239]
	v_pk_add_f32 v[240:241], v[240:241], v[242:243]
	v_cndmask_b32_e64 v219, 0, v219, s[74:75]
	v_pk_add_f32 v[236:237], v[236:237], v[240:241]
	v_add_f32_e32 v185, v236, v237
	v_add_f32_e32 v185, v185, v219
	v_cvt_pk_bf16_f32 v236, v50, v51
	v_cvt_pk_bf16_f32 v237, v52, v53
	v_cvt_pk_bf16_f32 v238, v54, v55
	v_cvt_pk_bf16_f32 v239, v56, v57
	s_nop 1
	s_waitcnt lgkmcnt(14)
	v_mfma_f32_16x16x32_bf16 v[210:213], v[186:189], v[236:239], 0
	s_waitcnt lgkmcnt(12)
	v_mfma_f32_16x16x32_bf16 v[214:217], v[190:193], v[236:239], 0
	s_waitcnt lgkmcnt(10)
	v_mfma_f32_16x16x32_bf16 v[220:223], v[194:197], v[236:239], 0
	s_waitcnt lgkmcnt(8)
	v_mfma_f32_16x16x32_bf16 v[224:227], v[198:201], v[236:239], 0
	v_cvt_pk_bf16_f32 v240, v58, v59
	v_cvt_pk_bf16_f32 v241, v60, v61
	v_cvt_pk_bf16_f32 v242, v62, v63
	v_cvt_pk_bf16_f32 v243, v64, v65
	s_waitcnt lgkmcnt(7)
	ds_read_b64_tr_b16 v[186:187], v124 offset:14336
	ds_read_b64_tr_b16 v[188:189], v124 offset:16384
	ds_read_b64_tr_b16 v[190:191], v125 offset:14336
	ds_read_b64_tr_b16 v[192:193], v125 offset:16384
	ds_read_b64_tr_b16 v[194:195], v126 offset:14336
	ds_read_b64_tr_b16 v[196:197], v126 offset:16384
	ds_read_b64_tr_b16 v[198:199], v127 offset:14336
	ds_read_b64_tr_b16 v[200:201], v127 offset:16384
	s_waitcnt lgkmcnt(14)
	v_mfma_f32_16x16x32_bf16 v[210:213], v[202:205], v[240:243], v[210:213]
	s_waitcnt lgkmcnt(12)
	v_mfma_f32_16x16x32_bf16 v[214:217], v[206:209], v[240:243], v[214:217]
	s_waitcnt lgkmcnt(10)
	v_mfma_f32_16x16x32_bf16 v[220:223], v[228:231], v[240:243], v[220:223]
	s_waitcnt lgkmcnt(8)
	v_mfma_f32_16x16x32_bf16 v[224:227], v[232:235], v[240:243], v[224:227]
	v_cvt_pk_bf16_f32 v236, v66, v67
	v_cvt_pk_bf16_f32 v237, v68, v69
	v_cvt_pk_bf16_f32 v238, v70, v71
	v_cvt_pk_bf16_f32 v239, v72, v73
	s_waitcnt lgkmcnt(7)
	ds_read_b64_tr_b16 v[202:203], v124 offset:18432
	ds_read_b64_tr_b16 v[204:205], v124 offset:20480
	ds_read_b64_tr_b16 v[206:207], v125 offset:18432
	ds_read_b64_tr_b16 v[208:209], v125 offset:20480
	ds_read_b64_tr_b16 v[228:229], v126 offset:18432
	ds_read_b64_tr_b16 v[230:231], v126 offset:20480
	ds_read_b64_tr_b16 v[232:233], v127 offset:18432
	ds_read_b64_tr_b16 v[234:235], v127 offset:20480
	s_waitcnt lgkmcnt(14)
	v_mfma_f32_16x16x32_bf16 v[210:213], v[186:189], v[236:239], v[210:213]
	s_waitcnt lgkmcnt(12)
	v_mfma_f32_16x16x32_bf16 v[214:217], v[190:193], v[236:239], v[214:217]
	s_waitcnt lgkmcnt(10)
	v_mfma_f32_16x16x32_bf16 v[220:223], v[194:197], v[236:239], v[220:223]
	s_waitcnt lgkmcnt(8)
; #define LAS __attribute__((address_space(3)))
; __device__ __forceinline__ unsigned pk2(float lo, float hi) { return pg8::cvt_pk_bf16(lo, hi); }
; __device__ __forceinline__ s16x4 vtr(const LAS unsigned char* p) { return __builtin_bit_cast(s16x4, __builtin_amdgcn_ds_read_tr16_b64_v4i16((LAS s16x4*)p)); }
; #define MFMA16(a, b, c) __builtin_amdgcn_mfma_f32_16x16x32_bf16((a), (b), (c), 0, 0, 0)
; __device__ __forceinline__ void pv_at(const LAS unsigned char* const (&vp)[4], int off, const f32x4& P0, const f32x4& P1, f32x4 (&O)[4]) {
;     v4u pw; pw.x = pk2(P0[0], P0[1]); pw.y = pk2(P0[2], P0[3]); pw.z = pk2(P1[0], P1[1]); pw.w = pk2(P1[2], P1[3]);
;     const bf16x8 pb = __builtin_bit_cast(bf16x8, pw);
; #pragma unroll
;     for (int db = 0; db < 4; ++db) {
;         const s16x4 lo = vtr(vp[db] + off), hi = vtr(vp[db] + off + 2048);
;         const bf16x8 vt = (bf16x8){lo[0], lo[1], lo[2], lo[3], hi[0], hi[1], hi[2], hi[3]};
;         O[db] = MFMA16(vt, pb, O[db]);
;     }
; }
	v_mfma_f32_16x16x32_bf16 v[224:227], v[198:201], v[236:239], v[224:227]
	v_cvt_pk_bf16_f32 v240, v74, v75
	v_cvt_pk_bf16_f32 v241, v76, v77
	v_cvt_pk_bf16_f32 v242, v78, v79
	v_cvt_pk_bf16_f32 v243, v80, v81
	s_waitcnt lgkmcnt(7)
	ds_read_b64_tr_b16 v[186:187], v124 offset:22528
	ds_read_b64_tr_b16 v[188:189], v124 offset:24576
	ds_read_b64_tr_b16 v[190:191], v125 offset:22528
	ds_read_b64_tr_b16 v[192:193], v125 offset:24576
	ds_read_b64_tr_b16 v[194:195], v126 offset:22528
	ds_read_b64_tr_b16 v[196:197], v126 offset:24576
	ds_read_b64_tr_b16 v[198:199], v127 offset:22528
	ds_read_b64_tr_b16 v[200:201], v127 offset:24576
	s_waitcnt lgkmcnt(14)
	v_mfma_f32_16x16x32_bf16 v[210:213], v[202:205], v[240:243], v[210:213]
	s_waitcnt lgkmcnt(12)
	v_mfma_f32_16x16x32_bf16 v[214:217], v[206:209], v[240:243], v[214:217]
	s_waitcnt lgkmcnt(10)
	v_mfma_f32_16x16x32_bf16 v[220:223], v[228:231], v[240:243], v[220:223]
	s_waitcnt lgkmcnt(8)
	v_mfma_f32_16x16x32_bf16 v[224:227], v[232:235], v[240:243], v[224:227]
	v_cvt_pk_bf16_f32 v236, v82, v83
	v_cvt_pk_bf16_f32 v237, v84, v85
	v_cvt_pk_bf16_f32 v238, v86, v87
	v_cvt_pk_bf16_f32 v239, v88, v89
	s_waitcnt lgkmcnt(7)
	ds_read_b64_tr_b16 v[202:203], v124 offset:26624
	ds_read_b64_tr_b16 v[204:205], v124 offset:28672
	ds_read_b64_tr_b16 v[206:207], v125 offset:26624
	ds_read_b64_tr_b16 v[208:209], v125 offset:28672
	ds_read_b64_tr_b16 v[228:229], v126 offset:26624
	ds_read_b64_tr_b16 v[230:231], v126 offset:28672
	ds_read_b64_tr_b16 v[232:233], v127 offset:26624
	ds_read_b64_tr_b16 v[234:235], v127 offset:28672
	s_waitcnt lgkmcnt(14)
	v_mfma_f32_16x16x32_bf16 v[210:213], v[186:189], v[236:239], v[210:213]
	s_waitcnt lgkmcnt(12)
	v_mfma_f32_16x16x32_bf16 v[214:217], v[190:193], v[236:239], v[214:217]
	s_waitcnt lgkmcnt(10)
	v_mfma_f32_16x16x32_bf16 v[220:223], v[194:197], v[236:239], v[220:223]
	s_waitcnt lgkmcnt(8)
	v_mfma_f32_16x16x32_bf16 v[224:227], v[198:201], v[236:239], v[224:227]
	v_cvt_pk_bf16_f32 v240, v90, v91
	v_cvt_pk_bf16_f32 v241, v92, v93
	v_cvt_pk_bf16_f32 v242, v94, v95
	v_cvt_pk_bf16_f32 v243, v96, v97
	s_waitcnt lgkmcnt(7)
	ds_read_b64_tr_b16 v[186:187], v124 offset:30720
	ds_read_b64_tr_b16 v[188:189], v124 offset:32768
	ds_read_b64_tr_b16 v[190:191], v125 offset:30720
	ds_read_b64_tr_b16 v[192:193], v125 offset:32768
	ds_read_b64_tr_b16 v[194:195], v126 offset:30720
	ds_read_b64_tr_b16 v[196:197], v126 offset:32768
	ds_read_b64_tr_b16 v[198:199], v127 offset:30720
	ds_read_b64_tr_b16 v[200:201], v127 offset:32768
	s_waitcnt lgkmcnt(14)
	v_mfma_f32_16x16x32_bf16 v[210:213], v[202:205], v[240:243], v[210:213]
	s_waitcnt lgkmcnt(12)
	v_mfma_f32_16x16x32_bf16 v[214:217], v[206:209], v[240:243], v[214:217]
	s_waitcnt lgkmcnt(10)
	v_mfma_f32_16x16x32_bf16 v[220:223], v[228:231], v[240:243], v[220:223]
	s_waitcnt lgkmcnt(8)
	v_mfma_f32_16x16x32_bf16 v[224:227], v[232:235], v[240:243], v[224:227]
	v_cvt_pk_bf16_f32 v236, v98, v99
	v_cvt_pk_bf16_f32 v237, v100, v101
	v_cvt_pk_bf16_f32 v238, v102, v103
	v_cvt_pk_bf16_f32 v239, v104, v105
	s_waitcnt lgkmcnt(7)
	ds_read_b64_tr_b16 v[202:203], v124 offset:34816
	ds_read_b64_tr_b16 v[204:205], v124 offset:36864
	ds_read_b64_tr_b16 v[206:207], v125 offset:34816
	ds_read_b64_tr_b16 v[208:209], v125 offset:36864
	ds_read_b64_tr_b16 v[228:229], v126 offset:34816
	ds_read_b64_tr_b16 v[230:231], v126 offset:36864
	ds_read_b64_tr_b16 v[232:233], v127 offset:34816
	ds_read_b64_tr_b16 v[234:235], v127 offset:36864
	s_waitcnt lgkmcnt(14)
	v_mfma_f32_16x16x32_bf16 v[210:213], v[186:189], v[236:239], v[210:213]
	s_waitcnt lgkmcnt(12)
	v_mfma_f32_16x16x32_bf16 v[214:217], v[190:193], v[236:239], v[214:217]
	s_waitcnt lgkmcnt(10)
	v_mfma_f32_16x16x32_bf16 v[220:223], v[194:197], v[236:239], v[220:223]
	s_waitcnt lgkmcnt(8)
	v_mfma_f32_16x16x32_bf16 v[224:227], v[198:201], v[236:239], v[224:227]
	v_cvt_pk_bf16_f32 v240, v106, v107
	v_cvt_pk_bf16_f32 v241, v108, v109
	v_cvt_pk_bf16_f32 v242, v110, v111
	v_cvt_pk_bf16_f32 v243, v112, v113
	s_waitcnt lgkmcnt(7)
	ds_read_b64_tr_b16 v[186:187], v124 offset:38912
	ds_read_b64_tr_b16 v[188:189], v124 offset:40960
	ds_read_b64_tr_b16 v[190:191], v125 offset:38912
	ds_read_b64_tr_b16 v[192:193], v125 offset:40960
	ds_read_b64_tr_b16 v[194:195], v126 offset:38912
	ds_read_b64_tr_b16 v[196:197], v126 offset:40960
	ds_read_b64_tr_b16 v[198:199], v127 offset:38912
	ds_read_b64_tr_b16 v[200:201], v127 offset:40960
	s_waitcnt lgkmcnt(14)
	v_mfma_f32_16x16x32_bf16 v[210:213], v[202:205], v[240:243], v[210:213]
	s_waitcnt lgkmcnt(12)
	v_mfma_f32_16x16x32_bf16 v[214:217], v[206:209], v[240:243], v[214:217]
	s_waitcnt lgkmcnt(10)
	v_mfma_f32_16x16x32_bf16 v[220:223], v[228:231], v[240:243], v[220:223]
	s_waitcnt lgkmcnt(8)
	v_mfma_f32_16x16x32_bf16 v[224:227], v[232:235], v[240:243], v[224:227]
	v_cvt_pk_bf16_f32 v236, v114, v115
	v_cvt_pk_bf16_f32 v237, v116, v117
	v_mov_b32_e32 v238, 0
	v_mov_b32_e32 v239, 0
	s_nop 1
	s_waitcnt lgkmcnt(6)
	v_mfma_f32_16x16x32_bf16 v[210:213], v[186:189], v[236:239], v[210:213]
	s_waitcnt lgkmcnt(4)
	v_mfma_f32_16x16x32_bf16 v[214:217], v[190:193], v[236:239], v[214:217]
	s_waitcnt lgkmcnt(2)
	v_mfma_f32_16x16x32_bf16 v[220:223], v[194:197], v[236:239], v[220:223]
	s_waitcnt lgkmcnt(0)
; __device__ __forceinline__ unsigned pk2(float lo, float hi) { return pg8::cvt_pk_bf16(lo, hi); }
; __device__ __forceinline__ void store_o(bf16* yrow, int g, float l, const f32x4 (&O)[4]) {
;     const float inv = 1.0f / xrow16_sum(l);
;     unsigned wx[4], wy[4];
; #pragma unroll
;     for (int db = 0; db < 4; ++db) { wx[db] = pk2(O[db][0] * inv, O[db][1] * inv); wy[db] = pk2(O[db][2] * inv, O[db][3] * inv); }
; #pragma unroll
;     for (int p = 0; p < 2; ++p) {
;         auto rx = __builtin_amdgcn_permlane16_swap(wx[2 * p], wx[2 * p + 1], false, false); wx[2 * p] = rx[0]; wx[2 * p + 1] = rx[1];
;         auto ry = __builtin_amdgcn_permlane16_swap(wy[2 * p], wy[2 * p + 1], false, false); wy[2 * p] = ry[0]; wy[2 * p + 1] = ry[1]; }
; #pragma unroll
;     for (int p = 0; p < 2; ++p) {
;         auto rx = __builtin_amdgcn_permlane32_swap(wx[p], wx[p + 2], false, false); wx[p] = rx[0]; wx[p + 2] = rx[1];
;         auto ry = __builtin_amdgcn_permlane32_swap(wy[p], wy[p + 2], false, false); wy[p] = ry[0]; wy[p + 2] = ry[1]; }
;     v4u lo = {wx[0], wy[0], wx[1], wy[1]}, hi = {wx[2], wy[2], wx[3], wy[3]};
;     *(v4u*)(yrow + 16 * g) = lo; *(v4u*)(yrow + 16 * g + 8) = hi;
; }
; template <bool MASK> __device__ __forceinline__ void a_scores(f32x4& S0, f32x4& S1, float basef, float c1, float slope2, int krow0, int kstart) {
; #pragma unroll
;     for (int r = 0; r < 4; ++r) {
;         const float d0 = fabsf(basef - (float)r), d1 = fabsf(basef - (float)(16 + r));
;         const float v0 = S0[r] - slope2 * d0, v1 = S1[r] - slope2 * d1;
;         if (MASK) { const int p0 = kstart + krow0 + r, p1 = p0 + 16;
;             S0[r] = (d0 <= 128.f && p0 >= 0 && p0 < SEQ) ? v0 : -INFINITY; S1[r] = (d1 <= 128.f && p1 >= 0 && p1 < SEQ) ? v1 : -INFINITY; }
;         else { S0[r] = v0; S1[r] = v1; }
;     }
; }
	v_mfma_f32_16x16x32_bf16 v[224:227], v[198:201], v[236:239], v[224:227]
	v_mov_b32_e32 v219, v185
	s_nop 1
	v_permlane16_swap_b32_e32 v185, v219
	v_add_f32_e32 v185, v185, v219
	v_mov_b32_e32 v219, v185
	s_nop 1
	v_permlane32_swap_b32_e32 v185, v219
	v_add_f32_e32 v185, v185, v219
	v_div_scale_f32 v236, s[78:79], v185, v185, 1.0
	v_div_scale_f32 v237, vcc, 1.0, v185, 1.0
	v_rcp_f32_e32 v238, v236
	s_nop 0
	v_fma_f32 v239, -v236, v238, 1.0
	v_fmac_f32_e32 v238, v239, v238
	v_mul_f32_e32 v240, v237, v238
	v_fma_f32 v241, -v236, v240, v237
	v_fmac_f32_e32 v240, v241, v238
	v_fma_f32 v237, -v236, v240, v237
	v_div_fmas_f32 v237, v237, v238, v240
	v_div_fixup_f32 v244, v237, v185, 1.0
	v_mul_f32_e32 v240, v210, v244
	v_mul_f32_e32 v241, v211, v244
	v_mul_f32_e32 v242, v212, v244
	v_mul_f32_e32 v243, v213, v244
	v_cvt_pk_bf16_f32 v186, v240, v241
	v_cvt_pk_bf16_f32 v187, v242, v243
	v_mul_f32_e32 v240, v214, v244
	v_mul_f32_e32 v241, v215, v244
	v_mul_f32_e32 v242, v216, v244
	v_mul_f32_e32 v243, v217, v244
	v_cvt_pk_bf16_f32 v188, v240, v241
	v_cvt_pk_bf16_f32 v189, v242, v243
	v_mul_f32_e32 v240, v220, v244
	v_mul_f32_e32 v241, v221, v244
	v_mul_f32_e32 v242, v222, v244
	v_mul_f32_e32 v243, v223, v244
	v_cvt_pk_bf16_f32 v190, v240, v241
	v_cvt_pk_bf16_f32 v191, v242, v243
	v_mul_f32_e32 v240, v224, v244
	v_mul_f32_e32 v241, v225, v244
	v_mul_f32_e32 v242, v226, v244
	v_mul_f32_e32 v243, v227, v244
	v_cvt_pk_bf16_f32 v192, v240, v241
	v_cvt_pk_bf16_f32 v193, v242, v243
	s_nop 1
	v_permlane16_swap_b32_e32 v186, v188
	v_permlane16_swap_b32_e32 v187, v189
	v_permlane16_swap_b32_e32 v190, v192
	v_permlane16_swap_b32_e32 v191, v193
	s_nop 0
	v_permlane32_swap_b32_e32 v186, v190
	v_permlane32_swap_b32_e32 v187, v191
	v_permlane32_swap_b32_e32 v188, v192
	v_permlane32_swap_b32_e32 v189, v193
	v_add_u32_e32 v219, 0x1000, v128
	global_store_dwordx4 v219, v[186:189], s[82:83] offset:2048
	global_store_dwordx4 v219, v[190:193], s[82:83] offset:2064
	s_nop 1
	s_branch .LBB0_240
.La_edge_lo:
	s_lshr_b32 s21, s85, 4
	s_sub_i32 s21, 8, s21
	s_lshl_b32 s87, 1, s21
	s_sub_i32 s87, 0, s87
	s_branch .La_edge_go
.La_edge_hi:
	s_lshr_b32 s21, s85, 4
	s_sub_i32 s21, 16, s21
	s_lshl_b32 s87, 1, s21
	s_sub_i32 s87, s87, 1
.La_edge_go:
	s_bitcmp1_b32 s87, 0
	s_cselect_b32 s21, 0, 0xff800000
	v_add_f32_e32 v120, s21, v132
	v_fmamk_f32 v50, v130, 0x43000000, v120
	v_fmamk_f32 v51, v130, 0x42fe0000, v120
	v_fmamk_f32 v52, v130, 0x42fc0000, v120
	v_fmamk_f32 v53, v130, 0x42fa0000, v120
	s_bitcmp1_b32 s87, 1
	s_cselect_b32 s21, 0, 0xff800000
	v_add_f32_e32 v120, s21, v132
	v_fmamk_f32 v54, v130, 0x42e00000, v120
	v_fmamk_f32 v55, v130, 0x42de0000, v120
	v_fmamk_f32 v56, v130, 0x42dc0000, v120
	v_fmamk_f32 v57, v130, 0x42da0000, v120
	s_bitcmp1_b32 s87, 2
	s_cselect_b32 s21, 0, 0xff800000
	v_add_f32_e32 v120, s21, v132
	v_fmamk_f32 v58, v130, 0x42c00000, v120
	v_fmamk_f32 v59, v130, 0x42be0000, v120
	v_fmamk_f32 v60, v130, 0x42bc0000, v120
	v_fmamk_f32 v61, v130, 0x42ba0000, v120
	s_bitcmp1_b32 s87, 3
	s_cselect_b32 s21, 0, 0xff800000
	v_add_f32_e32 v120, s21, v132
	v_fmamk_f32 v62, v130, 0x42a00000, v120
	v_fmamk_f32 v63, v130, 0x429e0000, v120
	v_fmamk_f32 v64, v130, 0x429c0000, v120
	v_fmamk_f32 v65, v130, 0x429a0000, v120
	s_bitcmp1_b32 s87, 4
	s_cselect_b32 s21, 0, 0xff800000
	v_add_f32_e32 v120, s21, v132
	v_fmamk_f32 v66, v130, 0x42800000, v120
	v_fmamk_f32 v67, v130, 0x427c0000, v120
	v_fmamk_f32 v68, v130, 0x42780000, v120
	v_fmamk_f32 v69, v130, 0x42740000, v120
	s_bitcmp1_b32 s87, 5
	s_cselect_b32 s21, 0, 0xff800000
	v_add_f32_e32 v120, s21, v132
	v_fmamk_f32 v70, v130, 0x42400000, v120
	v_fmamk_f32 v71, v130, 0x423c0000, v120
	v_fmamk_f32 v72, v130, 0x42380000, v120
	v_fmamk_f32 v73, v130, 0x42340000, v120
	s_bitcmp1_b32 s87, 6
	s_cselect_b32 s21, 0, 0xff800000
	v_add_f32_e32 v120, s21, v132
	v_fmamk_f32 v74, v130, 0x42000000, v120
	v_fmamk_f32 v75, v130, 0x41f80000, v120
	v_fmamk_f32 v76, v130, 0x41f00000, v120
	v_fmamk_f32 v77, v130, 0x41e80000, v120
	s_bitcmp1_b32 s87, 7
	s_cselect_b32 s21, 0, 0xff800000
	v_add_f32_e32 v120, s21, v132
	v_fmamk_f32 v78, v130, 0x41800000, v120
	v_fmamk_f32 v79, v130, 0x41700000, v120
	v_fmamk_f32 v80, v130, 0x41600000, v120
	v_fmamk_f32 v81, v130, 0x41500000, v120
	s_bitcmp1_b32 s87, 8
	s_cselect_b32 s21, 0, 0xff800000
	v_add_f32_e32 v219, 0, v129
	v_fma_f32 v82, v130, |v219|, s21
	v_add_f32_e32 v244, 0xbf800000, v129
	v_fma_f32 v83, v130, |v244|, s21
	v_add_f32_e32 v219, 0xc0000000, v129
	v_fma_f32 v84, v130, |v219|, s21
	v_add_f32_e32 v244, 0xc0400000, v129
	v_fma_f32 v85, v130, |v244|, s21
	s_bitcmp1_b32 s87, 9
	s_cselect_b32 s21, 0, 0xff800000
	v_add_f32_e32 v120, s21, v133
	v_fmamk_f32 v86, v131, 0xc1800000, v120
	v_fmamk_f32 v87, v131, 0xc1880000, v120
	v_fmamk_f32 v88, v131, 0xc1900000, v120
	v_fmamk_f32 v89, v131, 0xc1980000, v120
	s_bitcmp1_b32 s87, 10
	s_cselect_b32 s21, 0, 0xff800000
	v_add_f32_e32 v120, s21, v133
	v_fmamk_f32 v90, v131, 0xc2000000, v120
	v_fmamk_f32 v91, v131, 0xc2040000, v120
	v_fmamk_f32 v92, v131, 0xc2080000, v120
	v_fmamk_f32 v93, v131, 0xc20c0000, v120
	s_bitcmp1_b32 s87, 11
	s_cselect_b32 s21, 0, 0xff800000
	v_add_f32_e32 v120, s21, v133
	v_fmamk_f32 v94, v131, 0xc2400000, v120
	v_fmamk_f32 v95, v131, 0xc2440000, v120
	v_fmamk_f32 v96, v131, 0xc2480000, v120
	v_fmamk_f32 v97, v131, 0xc24c0000, v120
	s_bitcmp1_b32 s87, 12
	s_cselect_b32 s21, 0, 0xff800000
	v_add_f32_e32 v120, s21, v133
	v_fmamk_f32 v98, v131, 0xc2800000, v120
	v_fmamk_f32 v99, v131, 0xc2820000, v120
	v_fmamk_f32 v100, v131, 0xc2840000, v120
	v_fmamk_f32 v101, v131, 0xc2860000, v120
	s_bitcmp1_b32 s87, 13
	s_cselect_b32 s21, 0, 0xff800000
; #define LAS __attribute__((address_space(3)))
; #define MFMA16(a, b, c) __builtin_amdgcn_mfma_f32_16x16x32_bf16((a), (b), (c), 0, 0, 0)
; __device__ __forceinline__ void qk_at(const LAS unsigned char* kp0, const LAS unsigned char* kp1, int off, bf16x8 qf0, bf16x8 qf1, f32x4& S0, f32x4& S1) {
;     const bf16x8 k00 = *(const LAS bf16x8*)(kp0 + off), k01 = *(const LAS bf16x8*)(kp1 + off);
;     const bf16x8 k10 = *(const LAS bf16x8*)(kp0 + off + 2048), k11 = *(const LAS bf16x8*)(kp1 + off + 2048);
;     const f32x4 z = {0.f, 0.f, 0.f, 0.f};
;     S0 = MFMA16(k00, qf0, z); S0 = MFMA16(k01, qf1, S0);
;     S1 = MFMA16(k10, qf0, z); S1 = MFMA16(k11, qf1, S1);
; }
; template <bool MASK> __device__ __forceinline__ void a_scores(f32x4& S0, f32x4& S1, float basef, float c1, float slope2, int krow0, int kstart) {
; #pragma unroll
;     for (int r = 0; r < 4; ++r) {
;         const float d0 = fabsf(basef - (float)r), d1 = fabsf(basef - (float)(16 + r));
;         const float v0 = S0[r] - slope2 * d0, v1 = S1[r] - slope2 * d1;
;         if (MASK) { const int p0 = kstart + krow0 + r, p1 = p0 + 16;
;             S0[r] = (d0 <= 128.f && p0 >= 0 && p0 < SEQ) ? v0 : -INFINITY; S1[r] = (d1 <= 128.f && p1 >= 0 && p1 < SEQ) ? v1 : -INFINITY; }
;         else { S0[r] = v0; S1[r] = v1; }
;     }
; }
	v_add_f32_e32 v120, s21, v133
	v_fmamk_f32 v102, v131, 0xc2a00000, v120
	v_fmamk_f32 v103, v131, 0xc2a20000, v120
	v_fmamk_f32 v104, v131, 0xc2a40000, v120
	v_fmamk_f32 v105, v131, 0xc2a60000, v120
	s_bitcmp1_b32 s87, 14
	s_cselect_b32 s21, 0, 0xff800000
	v_add_f32_e32 v120, s21, v133
	v_fmamk_f32 v106, v131, 0xc2c00000, v120
	v_fmamk_f32 v107, v131, 0xc2c20000, v120
	v_fmamk_f32 v108, v131, 0xc2c40000, v120
	v_fmamk_f32 v109, v131, 0xc2c60000, v120
	s_bitcmp1_b32 s87, 15
	s_cselect_b32 s21, 0, 0xff800000
	v_add_f32_e32 v120, s21, v133
	v_fmamk_f32 v110, v131, 0xc2e00000, v120
	v_fmamk_f32 v111, v131, 0xc2e20000, v120
	v_fmamk_f32 v112, v131, 0xc2e40000, v120
	v_fmamk_f32 v113, v131, 0xc2e60000, v120
	s_bitcmp1_b32 s87, 16
	s_cselect_b32 s21, 0, 0xff800000
	v_add_f32_e32 v120, s21, v133
	v_fmamk_f32 v114, v131, 0xc3000000, v120
	v_fmamk_f32 v115, v131, 0xc3010000, v120
	v_fmamk_f32 v116, v131, 0xc3020000, v120
	v_fmamk_f32 v117, v131, 0xc3030000, v120
	v_mov_b32_e32 v245, 0xff800000
	v_cndmask_b32_e64 v50, v245, v50, s[16:17]
	v_cndmask_b32_e64 v51, v245, v51, s[18:19]
	v_cndmask_b32_e64 v52, v245, v52, s[22:23]
	v_cndmask_b32_e64 v53, v245, v53, s[24:25]
	v_cndmask_b32_e64 v114, v245, v114, s[28:29]
	v_cndmask_b32_e64 v115, v245, v115, s[52:53]
	v_cndmask_b32_e64 v116, v245, v116, s[54:55]
	v_cndmask_b32_e64 v117, v245, v117, s[88:89]
	ds_read_b128 v[186:189], v122 offset:0
	ds_read_b128 v[190:193], v123 offset:0
	ds_read_b128 v[194:197], v122 offset:2048
	ds_read_b128 v[198:201], v123 offset:2048
	ds_read_b128 v[202:205], v122 offset:4096
	ds_read_b128 v[206:209], v123 offset:4096
	s_waitcnt lgkmcnt(5)
	v_mfma_f32_16x16x32_bf16 v[50:53], v[186:189], v[146:149], v[50:53]
	s_waitcnt lgkmcnt(4)
	v_mfma_f32_16x16x32_bf16 v[50:53], v[190:193], v[150:153], v[50:53]
	ds_read_b128 v[186:189], v122 offset:6144
	ds_read_b128 v[190:193], v123 offset:6144
	s_waitcnt lgkmcnt(5)
	v_mfma_f32_16x16x32_bf16 v[54:57], v[194:197], v[146:149], v[54:57]
	s_waitcnt lgkmcnt(4)
	v_mfma_f32_16x16x32_bf16 v[54:57], v[198:201], v[150:153], v[54:57]
	ds_read_b128 v[194:197], v122 offset:8192
	ds_read_b128 v[198:201], v123 offset:8192
	s_waitcnt lgkmcnt(5)
	v_mfma_f32_16x16x32_bf16 v[58:61], v[202:205], v[146:149], v[58:61]
	s_waitcnt lgkmcnt(4)
	v_mfma_f32_16x16x32_bf16 v[58:61], v[206:209], v[150:153], v[58:61]
	ds_read_b128 v[202:205], v122 offset:10240
	ds_read_b128 v[206:209], v123 offset:10240
	s_waitcnt lgkmcnt(5)
	v_mfma_f32_16x16x32_bf16 v[62:65], v[186:189], v[146:149], v[62:65]
	s_waitcnt lgkmcnt(4)
	v_mfma_f32_16x16x32_bf16 v[62:65], v[190:193], v[150:153], v[62:65]
	ds_read_b128 v[186:189], v122 offset:12288
	ds_read_b128 v[190:193], v123 offset:12288
	s_waitcnt lgkmcnt(5)
	v_mfma_f32_16x16x32_bf16 v[66:69], v[194:197], v[146:149], v[66:69]
	s_waitcnt lgkmcnt(4)
	v_mfma_f32_16x16x32_bf16 v[66:69], v[198:201], v[150:153], v[66:69]
	ds_read_b128 v[194:197], v122 offset:14336
	ds_read_b128 v[198:201], v123 offset:14336
	s_waitcnt lgkmcnt(5)
	v_mfma_f32_16x16x32_bf16 v[70:73], v[202:205], v[146:149], v[70:73]
	s_waitcnt lgkmcnt(4)
	v_mfma_f32_16x16x32_bf16 v[70:73], v[206:209], v[150:153], v[70:73]
	ds_read_b128 v[202:205], v122 offset:16384
	ds_read_b128 v[206:209], v123 offset:16384
	s_waitcnt lgkmcnt(5)
	v_mfma_f32_16x16x32_bf16 v[74:77], v[186:189], v[146:149], v[74:77]
	s_waitcnt lgkmcnt(4)
	v_mfma_f32_16x16x32_bf16 v[74:77], v[190:193], v[150:153], v[74:77]
	ds_read_b128 v[186:189], v122 offset:18432
	ds_read_b128 v[190:193], v123 offset:18432
	s_waitcnt lgkmcnt(5)
	v_mfma_f32_16x16x32_bf16 v[78:81], v[194:197], v[146:149], v[78:81]
	s_waitcnt lgkmcnt(4)
	v_mfma_f32_16x16x32_bf16 v[78:81], v[198:201], v[150:153], v[78:81]
	ds_read_b128 v[194:197], v122 offset:20480
	ds_read_b128 v[198:201], v123 offset:20480
	s_waitcnt lgkmcnt(5)
	v_mfma_f32_16x16x32_bf16 v[82:85], v[202:205], v[146:149], v[82:85]
	s_waitcnt lgkmcnt(4)
	v_mfma_f32_16x16x32_bf16 v[82:85], v[206:209], v[150:153], v[82:85]
	ds_read_b128 v[202:205], v122 offset:22528
	ds_read_b128 v[206:209], v123 offset:22528
	s_waitcnt lgkmcnt(5)
	v_mfma_f32_16x16x32_bf16 v[86:89], v[186:189], v[146:149], v[86:89]
	s_waitcnt lgkmcnt(4)
	v_mfma_f32_16x16x32_bf16 v[86:89], v[190:193], v[150:153], v[86:89]
	ds_read_b128 v[186:189], v122 offset:24576
	ds_read_b128 v[190:193], v123 offset:24576
	s_waitcnt lgkmcnt(5)
	v_mfma_f32_16x16x32_bf16 v[90:93], v[194:197], v[146:149], v[90:93]
	s_waitcnt lgkmcnt(4)
	v_mfma_f32_16x16x32_bf16 v[90:93], v[198:201], v[150:153], v[90:93]
	ds_read_b128 v[194:197], v122 offset:26624
	ds_read_b128 v[198:201], v123 offset:26624
	s_waitcnt lgkmcnt(5)
	v_mfma_f32_16x16x32_bf16 v[94:97], v[202:205], v[146:149], v[94:97]
	s_waitcnt lgkmcnt(4)
	v_mfma_f32_16x16x32_bf16 v[94:97], v[206:209], v[150:153], v[94:97]
	ds_read_b128 v[202:205], v122 offset:28672
	ds_read_b128 v[206:209], v123 offset:28672
	s_waitcnt lgkmcnt(5)
	v_mfma_f32_16x16x32_bf16 v[98:101], v[186:189], v[146:149], v[98:101]
	s_waitcnt lgkmcnt(4)
	v_mfma_f32_16x16x32_bf16 v[98:101], v[190:193], v[150:153], v[98:101]
	ds_read_b128 v[186:189], v122 offset:30720
	ds_read_b128 v[190:193], v123 offset:30720
	s_waitcnt lgkmcnt(5)
	v_mfma_f32_16x16x32_bf16 v[102:105], v[194:197], v[146:149], v[102:105]
	s_waitcnt lgkmcnt(4)
	v_mfma_f32_16x16x32_bf16 v[102:105], v[198:201], v[150:153], v[102:105]
	ds_read_b128 v[194:197], v122 offset:32768
	ds_read_b128 v[198:201], v123 offset:32768
	s_waitcnt lgkmcnt(5)
	v_mfma_f32_16x16x32_bf16 v[106:109], v[202:205], v[146:149], v[106:109]
	s_waitcnt lgkmcnt(4)
	v_mfma_f32_16x16x32_bf16 v[106:109], v[206:209], v[150:153], v[106:109]
	s_waitcnt lgkmcnt(3)
; __device__ __forceinline__ void softmax_step(f32x4& s0, f32x4& s1, float& m, float& l, f32x4 (&O)[4]) {
;     float t = fmaxf(fmaxf(fmaxf(s0[0], s0[1]), fmaxf(s0[2], s0[3])), fmaxf(fmaxf(s1[0], s1[1]), fmaxf(s1[2], s1[3])));
;     t = xrow16_max(t);
;     const float mn = fmaxf(m, t), alpha = __builtin_amdgcn_exp2f(m - mn);
;     m = mn;
; #pragma unroll
;     for (int k = 0; k < 4; ++k) { s0[k] = __builtin_amdgcn_exp2f(s0[k] - mn); s1[k] = __builtin_amdgcn_exp2f(s1[k] - mn); }
;     l = l * alpha + ((s0[0] + s0[1]) + (s0[2] + s0[3])) + ((s1[0] + s1[1]) + (s1[2] + s1[3]));
	v_mfma_f32_16x16x32_bf16 v[110:113], v[186:189], v[146:149], v[110:113]
	s_waitcnt lgkmcnt(2)
	v_mfma_f32_16x16x32_bf16 v[110:113], v[190:193], v[150:153], v[110:113]
	s_waitcnt lgkmcnt(1)
	v_mfma_f32_16x16x32_bf16 v[114:117], v[194:197], v[146:149], v[114:117]
	s_waitcnt lgkmcnt(0)
	v_mfma_f32_16x16x32_bf16 v[114:117], v[198:201], v[150:153], v[114:117]
	v_max3_f32 v219, v50, v51, v52
	v_max3_f32 v244, v54, v55, v56
	v_max3_f32 v245, v58, v59, v60
	v_max3_f32 v120, v62, v63, v64
	v_max3_f32 v219, v219, v53, v66
	v_max3_f32 v244, v244, v57, v70
	v_max3_f32 v245, v245, v61, v74
	v_max3_f32 v120, v120, v65, v78
	v_max3_f32 v219, v219, v67, v68
	v_max3_f32 v244, v244, v71, v72
	v_max3_f32 v245, v245, v75, v76
	v_max3_f32 v120, v120, v79, v80
	ds_read_b64_tr_b16 v[186:187], v124 offset:0
	ds_read_b64_tr_b16 v[188:189], v124 offset:2048
	ds_read_b64_tr_b16 v[190:191], v125 offset:0
	ds_read_b64_tr_b16 v[192:193], v125 offset:2048
	ds_read_b64_tr_b16 v[194:195], v126 offset:0
	ds_read_b64_tr_b16 v[196:197], v126 offset:2048
	ds_read_b64_tr_b16 v[198:199], v127 offset:0
	ds_read_b64_tr_b16 v[200:201], v127 offset:2048
	v_max3_f32 v219, v219, v69, v82
	v_max3_f32 v244, v244, v73, v86
	v_max3_f32 v245, v245, v77, v90
	v_max3_f32 v120, v120, v81, v94
	v_max3_f32 v219, v219, v83, v84
	v_max3_f32 v244, v244, v87, v88
	v_max3_f32 v245, v245, v91, v92
	v_max3_f32 v120, v120, v95, v96
	v_max3_f32 v219, v219, v85, v98
	v_max3_f32 v244, v244, v89, v102
	v_max3_f32 v245, v245, v93, v106
	v_max3_f32 v120, v120, v97, v110
	v_max3_f32 v219, v219, v99, v100
	v_max3_f32 v244, v244, v103, v104
	v_max3_f32 v245, v245, v107, v108
	v_max3_f32 v120, v120, v111, v112
	v_max3_f32 v219, v219, v101, v114
	v_max3_f32 v219, v219, v115, v116
	v_max_f32_e32 v219, v219, v117
	v_max_f32_e32 v244, v244, v105
	v_max_f32_e32 v245, v245, v109
	v_max_f32_e32 v120, v120, v113
	v_max3_f32 v178, v219, v244, v245
	v_max_f32_e32 v178, v178, v120
	v_mov_b32_e32 v219, v178
	s_nop 1
	v_permlane16_swap_b32_e32 v178, v219
	v_max_f32_e32 v178, v178, v219
	v_mov_b32_e32 v219, v178
	s_nop 1
	v_permlane32_swap_b32_e32 v178, v219
	v_max3_f32 v178, v178, v219, v145
	s_waitcnt lgkmcnt(7)
	ds_read_b64_tr_b16 v[202:203], v124 offset:4096
	ds_read_b64_tr_b16 v[204:205], v124 offset:6144
	ds_read_b64_tr_b16 v[206:207], v125 offset:4096
	ds_read_b64_tr_b16 v[208:209], v125 offset:6144
	ds_read_b64_tr_b16 v[228:229], v126 offset:4096
	ds_read_b64_tr_b16 v[230:231], v126 offset:6144
	ds_read_b64_tr_b16 v[232:233], v127 offset:4096
	ds_read_b64_tr_b16 v[234:235], v127 offset:6144
	v_mov_b32_e32 v244, v178
	v_pk_add_f32 v[50:51], v[50:51], v[244:245] op_sel_hi:[1,0] neg_lo:[0,1] neg_hi:[0,1]
	v_pk_add_f32 v[52:53], v[52:53], v[244:245] op_sel_hi:[1,0] neg_lo:[0,1] neg_hi:[0,1]
	v_pk_add_f32 v[54:55], v[54:55], v[244:245] op_sel_hi:[1,0] neg_lo:[0,1] neg_hi:[0,1]
	v_pk_add_f32 v[56:57], v[56:57], v[244:245] op_sel_hi:[1,0] neg_lo:[0,1] neg_hi:[0,1]
	v_pk_add_f32 v[58:59], v[58:59], v[244:245] op_sel_hi:[1,0] neg_lo:[0,1] neg_hi:[0,1]
	v_pk_add_f32 v[60:61], v[60:61], v[244:245] op_sel_hi:[1,0] neg_lo:[0,1] neg_hi:[0,1]
	v_pk_add_f32 v[62:63], v[62:63], v[244:245] op_sel_hi:[1,0] neg_lo:[0,1] neg_hi:[0,1]
	v_pk_add_f32 v[64:65], v[64:65], v[244:245] op_sel_hi:[1,0] neg_lo:[0,1] neg_hi:[0,1]
	v_pk_add_f32 v[66:67], v[66:67], v[244:245] op_sel_hi:[1,0] neg_lo:[0,1] neg_hi:[0,1]
	v_pk_add_f32 v[68:69], v[68:69], v[244:245] op_sel_hi:[1,0] neg_lo:[0,1] neg_hi:[0,1]
	v_pk_add_f32 v[70:71], v[70:71], v[244:245] op_sel_hi:[1,0] neg_lo:[0,1] neg_hi:[0,1]
	v_pk_add_f32 v[72:73], v[72:73], v[244:245] op_sel_hi:[1,0] neg_lo:[0,1] neg_hi:[0,1]
	v_pk_add_f32 v[74:75], v[74:75], v[244:245] op_sel_hi:[1,0] neg_lo:[0,1] neg_hi:[0,1]
	v_pk_add_f32 v[76:77], v[76:77], v[244:245] op_sel_hi:[1,0] neg_lo:[0,1] neg_hi:[0,1]
	v_pk_add_f32 v[78:79], v[78:79], v[244:245] op_sel_hi:[1,0] neg_lo:[0,1] neg_hi:[0,1]
	v_pk_add_f32 v[80:81], v[80:81], v[244:245] op_sel_hi:[1,0] neg_lo:[0,1] neg_hi:[0,1]
	v_pk_add_f32 v[82:83], v[82:83], v[244:245] op_sel_hi:[1,0] neg_lo:[0,1] neg_hi:[0,1]
	v_pk_add_f32 v[84:85], v[84:85], v[244:245] op_sel_hi:[1,0] neg_lo:[0,1] neg_hi:[0,1]
	v_pk_add_f32 v[86:87], v[86:87], v[244:245] op_sel_hi:[1,0] neg_lo:[0,1] neg_hi:[0,1]
	v_pk_add_f32 v[88:89], v[88:89], v[244:245] op_sel_hi:[1,0] neg_lo:[0,1] neg_hi:[0,1]
	v_pk_add_f32 v[90:91], v[90:91], v[244:245] op_sel_hi:[1,0] neg_lo:[0,1] neg_hi:[0,1]
	v_pk_add_f32 v[92:93], v[92:93], v[244:245] op_sel_hi:[1,0] neg_lo:[0,1] neg_hi:[0,1]
	v_pk_add_f32 v[94:95], v[94:95], v[244:245] op_sel_hi:[1,0] neg_lo:[0,1] neg_hi:[0,1]
	v_pk_add_f32 v[96:97], v[96:97], v[244:245] op_sel_hi:[1,0] neg_lo:[0,1] neg_hi:[0,1]
	v_pk_add_f32 v[98:99], v[98:99], v[244:245] op_sel_hi:[1,0] neg_lo:[0,1] neg_hi:[0,1]
	v_pk_add_f32 v[100:101], v[100:101], v[244:245] op_sel_hi:[1,0] neg_lo:[0,1] neg_hi:[0,1]
	v_pk_add_f32 v[102:103], v[102:103], v[244:245] op_sel_hi:[1,0] neg_lo:[0,1] neg_hi:[0,1]
	v_pk_add_f32 v[104:105], v[104:105], v[244:245] op_sel_hi:[1,0] neg_lo:[0,1] neg_hi:[0,1]
	v_pk_add_f32 v[106:107], v[106:107], v[244:245] op_sel_hi:[1,0] neg_lo:[0,1] neg_hi:[0,1]
	v_pk_add_f32 v[108:109], v[108:109], v[244:245] op_sel_hi:[1,0] neg_lo:[0,1] neg_hi:[0,1]
	v_pk_add_f32 v[110:111], v[110:111], v[244:245] op_sel_hi:[1,0] neg_lo:[0,1] neg_hi:[0,1]
	v_pk_add_f32 v[112:113], v[112:113], v[244:245] op_sel_hi:[1,0] neg_lo:[0,1] neg_hi:[0,1]
	v_pk_add_f32 v[114:115], v[114:115], v[244:245] op_sel_hi:[1,0] neg_lo:[0,1] neg_hi:[0,1]
	v_pk_add_f32 v[116:117], v[116:117], v[244:245] op_sel_hi:[1,0] neg_lo:[0,1] neg_hi:[0,1]
	v_sub_f32_e32 v219, v145, v178
	v_exp_f32_e32 v50, v50
; #define LAS __attribute__((address_space(3)))
; __device__ __forceinline__ unsigned pk2(float lo, float hi) { return pg8::cvt_pk_bf16(lo, hi); }
; __device__ __forceinline__ s16x4 vtr(const LAS unsigned char* p) { return __builtin_bit_cast(s16x4, __builtin_amdgcn_ds_read_tr16_b64_v4i16((LAS s16x4*)p)); }
; #define MFMA16(a, b, c) __builtin_amdgcn_mfma_f32_16x16x32_bf16((a), (b), (c), 0, 0, 0)
; __device__ __forceinline__ void pv_at(const LAS unsigned char* const (&vp)[4], int off, const f32x4& P0, const f32x4& P1, f32x4 (&O)[4]) {
;     v4u pw; pw.x = pk2(P0[0], P0[1]); pw.y = pk2(P0[2], P0[3]); pw.z = pk2(P1[0], P1[1]); pw.w = pk2(P1[2], P1[3]);
;     const bf16x8 pb = __builtin_bit_cast(bf16x8, pw);
; #pragma unroll
;     for (int db = 0; db < 4; ++db) {
;         const s16x4 lo = vtr(vp[db] + off), hi = vtr(vp[db] + off + 2048);
;         const bf16x8 vt = (bf16x8){lo[0], lo[1], lo[2], lo[3], hi[0], hi[1], hi[2], hi[3]};
;         O[db] = MFMA16(vt, pb, O[db]);
;     }
; }
; __device__ __forceinline__ void softmax_step(f32x4& s0, f32x4& s1, float& m, float& l, f32x4 (&O)[4]) {
;     float t = fmaxf(fmaxf(fmaxf(s0[0], s0[1]), fmaxf(s0[2], s0[3])), fmaxf(fmaxf(s1[0], s1[1]), fmaxf(s1[2], s1[3])));
;     t = xrow16_max(t);
;     const float mn = fmaxf(m, t), alpha = __builtin_amdgcn_exp2f(m - mn);
;     m = mn;
; #pragma unroll
;     for (int k = 0; k < 4; ++k) { s0[k] = __builtin_amdgcn_exp2f(s0[k] - mn); s1[k] = __builtin_amdgcn_exp2f(s1[k] - mn); }
;     l = l * alpha + ((s0[0] + s0[1]) + (s0[2] + s0[3])) + ((s1[0] + s1[1]) + (s1[2] + s1[3]));
; #pragma unroll
;     for (int db = 0; db < 4; ++db) O[db] *= alpha;
; }
	v_exp_f32_e32 v51, v51
	v_exp_f32_e32 v52, v52
	v_exp_f32_e32 v53, v53
	v_exp_f32_e32 v54, v54
	v_exp_f32_e32 v55, v55
	v_exp_f32_e32 v56, v56
	v_exp_f32_e32 v57, v57
	v_exp_f32_e32 v58, v58
	v_exp_f32_e32 v59, v59
	v_exp_f32_e32 v60, v60
	v_exp_f32_e32 v61, v61
	v_exp_f32_e32 v62, v62
	v_exp_f32_e32 v63, v63
	v_exp_f32_e32 v64, v64
	v_exp_f32_e32 v65, v65
	v_exp_f32_e32 v66, v66
	v_exp_f32_e32 v67, v67
	v_exp_f32_e32 v68, v68
	v_exp_f32_e32 v69, v69
	v_exp_f32_e32 v70, v70
	v_exp_f32_e32 v71, v71
	v_exp_f32_e32 v72, v72
	v_exp_f32_e32 v73, v73
	v_exp_f32_e32 v74, v74
	v_exp_f32_e32 v75, v75
	v_exp_f32_e32 v76, v76
	v_exp_f32_e32 v77, v77
	v_exp_f32_e32 v78, v78
	v_exp_f32_e32 v79, v79
	v_exp_f32_e32 v80, v80
	v_exp_f32_e32 v81, v81
	v_exp_f32_e32 v82, v82
	v_exp_f32_e32 v83, v83
	v_exp_f32_e32 v84, v84
	v_exp_f32_e32 v85, v85
	v_exp_f32_e32 v86, v86
	v_exp_f32_e32 v87, v87
	v_exp_f32_e32 v88, v88
	v_exp_f32_e32 v89, v89
	v_exp_f32_e32 v90, v90
	v_exp_f32_e32 v91, v91
	v_exp_f32_e32 v92, v92
	v_exp_f32_e32 v93, v93
	v_exp_f32_e32 v94, v94
	v_exp_f32_e32 v95, v95
	v_exp_f32_e32 v96, v96
	v_exp_f32_e32 v97, v97
	v_exp_f32_e32 v98, v98
	v_exp_f32_e32 v99, v99
	v_exp_f32_e32 v100, v100
	v_exp_f32_e32 v101, v101
	v_exp_f32_e32 v102, v102
	v_exp_f32_e32 v103, v103
	v_exp_f32_e32 v104, v104
	v_exp_f32_e32 v105, v105
	v_exp_f32_e32 v106, v106
	v_exp_f32_e32 v107, v107
	v_exp_f32_e32 v108, v108
	v_exp_f32_e32 v109, v109
	v_exp_f32_e32 v110, v110
	v_exp_f32_e32 v111, v111
	v_exp_f32_e32 v112, v112
	v_exp_f32_e32 v113, v113
	v_exp_f32_e32 v114, v114
	v_exp_f32_e32 v115, v115
	v_exp_f32_e32 v116, v116
	v_exp_f32_e32 v117, v117
	v_exp_f32_e32 v219, v219
	v_pk_add_f32 v[236:237], v[50:51], v[52:53]
	v_pk_add_f32 v[238:239], v[54:55], v[56:57]
	v_pk_add_f32 v[240:241], v[58:59], v[60:61]
	v_pk_add_f32 v[242:243], v[62:63], v[64:65]
	v_pk_add_f32 v[236:237], v[236:237], v[66:67]
	v_pk_add_f32 v[238:239], v[238:239], v[70:71]
	v_pk_add_f32 v[240:241], v[240:241], v[74:75]
	v_pk_add_f32 v[242:243], v[242:243], v[78:79]
	v_pk_add_f32 v[236:237], v[236:237], v[68:69]
	v_pk_add_f32 v[238:239], v[238:239], v[72:73]
	v_pk_add_f32 v[240:241], v[240:241], v[76:77]
	v_pk_add_f32 v[242:243], v[242:243], v[80:81]
	v_pk_add_f32 v[236:237], v[236:237], v[82:83]
	v_pk_add_f32 v[238:239], v[238:239], v[86:87]
	v_pk_add_f32 v[240:241], v[240:241], v[90:91]
	v_pk_add_f32 v[242:243], v[242:243], v[94:95]
	v_pk_add_f32 v[236:237], v[236:237], v[84:85]
	v_pk_add_f32 v[238:239], v[238:239], v[88:89]
	v_pk_add_f32 v[240:241], v[240:241], v[92:93]
	v_pk_add_f32 v[242:243], v[242:243], v[96:97]
	v_pk_add_f32 v[236:237], v[236:237], v[98:99]
	v_pk_add_f32 v[238:239], v[238:239], v[102:103]
	v_pk_add_f32 v[240:241], v[240:241], v[106:107]
	v_pk_add_f32 v[242:243], v[242:243], v[110:111]
	v_pk_add_f32 v[236:237], v[236:237], v[100:101]
	v_pk_add_f32 v[238:239], v[238:239], v[104:105]
	v_pk_add_f32 v[240:241], v[240:241], v[108:109]
	v_pk_add_f32 v[242:243], v[242:243], v[112:113]
	v_pk_add_f32 v[236:237], v[236:237], v[114:115]
	v_pk_add_f32 v[236:237], v[236:237], v[116:117]
	v_pk_add_f32 v[236:237], v[236:237], v[238:239]
	v_pk_add_f32 v[240:241], v[240:241], v[242:243]
	v_cndmask_b32_e64 v219, 0, v219, s[74:75]
	v_pk_add_f32 v[236:237], v[236:237], v[240:241]
	v_add_f32_e32 v185, v236, v237
	v_add_f32_e32 v185, v185, v219
	v_cvt_pk_bf16_f32 v236, v50, v51
	v_cvt_pk_bf16_f32 v237, v52, v53
	v_cvt_pk_bf16_f32 v238, v54, v55
	v_cvt_pk_bf16_f32 v239, v56, v57
	s_nop 1
	s_waitcnt lgkmcnt(14)
	v_mfma_f32_16x16x32_bf16 v[210:213], v[186:189], v[236:239], 0
	s_waitcnt lgkmcnt(12)
	v_mfma_f32_16x16x32_bf16 v[214:217], v[190:193], v[236:239], 0
	s_waitcnt lgkmcnt(10)
	v_mfma_f32_16x16x32_bf16 v[220:223], v[194:197], v[236:239], 0
	s_waitcnt lgkmcnt(8)
	v_mfma_f32_16x16x32_bf16 v[224:227], v[198:201], v[236:239], 0
	v_cvt_pk_bf16_f32 v240, v58, v59
	v_cvt_pk_bf16_f32 v241, v60, v61
	v_cvt_pk_bf16_f32 v242, v62, v63
	v_cvt_pk_bf16_f32 v243, v64, v65
	s_waitcnt lgkmcnt(7)
	ds_read_b64_tr_b16 v[186:187], v124 offset:8192
	ds_read_b64_tr_b16 v[188:189], v124 offset:10240
	ds_read_b64_tr_b16 v[190:191], v125 offset:8192
	ds_read_b64_tr_b16 v[192:193], v125 offset:10240
	ds_read_b64_tr_b16 v[194:195], v126 offset:8192
	ds_read_b64_tr_b16 v[196:197], v126 offset:10240
	ds_read_b64_tr_b16 v[198:199], v127 offset:8192
	ds_read_b64_tr_b16 v[200:201], v127 offset:10240
	s_waitcnt lgkmcnt(14)
	v_mfma_f32_16x16x32_bf16 v[210:213], v[202:205], v[240:243], v[210:213]
	s_waitcnt lgkmcnt(12)
	v_mfma_f32_16x16x32_bf16 v[214:217], v[206:209], v[240:243], v[214:217]
	s_waitcnt lgkmcnt(10)
	v_mfma_f32_16x16x32_bf16 v[220:223], v[228:231], v[240:243], v[220:223]
	s_waitcnt lgkmcnt(8)
	v_mfma_f32_16x16x32_bf16 v[224:227], v[232:235], v[240:243], v[224:227]
	v_cvt_pk_bf16_f32 v236, v66, v67
	v_cvt_pk_bf16_f32 v237, v68, v69
	v_cvt_pk_bf16_f32 v238, v70, v71
	v_cvt_pk_bf16_f32 v239, v72, v73
	s_waitcnt lgkmcnt(7)
	ds_read_b64_tr_b16 v[202:203], v124 offset:12288
	ds_read_b64_tr_b16 v[204:205], v124 offset:14336
	ds_read_b64_tr_b16 v[206:207], v125 offset:12288
	ds_read_b64_tr_b16 v[208:209], v125 offset:14336
	ds_read_b64_tr_b16 v[228:229], v126 offset:12288
	ds_read_b64_tr_b16 v[230:231], v126 offset:14336
	ds_read_b64_tr_b16 v[232:233], v127 offset:12288
	ds_read_b64_tr_b16 v[234:235], v127 offset:14336
	s_waitcnt lgkmcnt(14)
	v_mfma_f32_16x16x32_bf16 v[210:213], v[186:189], v[236:239], v[210:213]
	s_waitcnt lgkmcnt(12)
	v_mfma_f32_16x16x32_bf16 v[214:217], v[190:193], v[236:239], v[214:217]
	s_waitcnt lgkmcnt(10)
	v_mfma_f32_16x16x32_bf16 v[220:223], v[194:197], v[236:239], v[220:223]
	s_waitcnt lgkmcnt(8)
; #define LAS __attribute__((address_space(3)))
; __device__ __forceinline__ unsigned pk2(float lo, float hi) { return pg8::cvt_pk_bf16(lo, hi); }
; __device__ __forceinline__ s16x4 vtr(const LAS unsigned char* p) { return __builtin_bit_cast(s16x4, __builtin_amdgcn_ds_read_tr16_b64_v4i16((LAS s16x4*)p)); }
; #define MFMA16(a, b, c) __builtin_amdgcn_mfma_f32_16x16x32_bf16((a), (b), (c), 0, 0, 0)
; __device__ __forceinline__ void pv_at(const LAS unsigned char* const (&vp)[4], int off, const f32x4& P0, const f32x4& P1, f32x4 (&O)[4]) {
;     v4u pw; pw.x = pk2(P0[0], P0[1]); pw.y = pk2(P0[2], P0[3]); pw.z = pk2(P1[0], P1[1]); pw.w = pk2(P1[2], P1[3]);
;     const bf16x8 pb = __builtin_bit_cast(bf16x8, pw);
; #pragma unroll
;     for (int db = 0; db < 4; ++db) {
;         const s16x4 lo = vtr(vp[db] + off), hi = vtr(vp[db] + off + 2048);
;         const bf16x8 vt = (bf16x8){lo[0], lo[1], lo[2], lo[3], hi[0], hi[1], hi[2], hi[3]};
;         O[db] = MFMA16(vt, pb, O[db]);
;     }
; }
	v_mfma_f32_16x16x32_bf16 v[224:227], v[198:201], v[236:239], v[224:227]
	v_cvt_pk_bf16_f32 v240, v74, v75
	v_cvt_pk_bf16_f32 v241, v76, v77
	v_cvt_pk_bf16_f32 v242, v78, v79
	v_cvt_pk_bf16_f32 v243, v80, v81
	s_waitcnt lgkmcnt(7)
	ds_read_b64_tr_b16 v[186:187], v124 offset:16384
	ds_read_b64_tr_b16 v[188:189], v124 offset:18432
	ds_read_b64_tr_b16 v[190:191], v125 offset:16384
	ds_read_b64_tr_b16 v[192:193], v125 offset:18432
	ds_read_b64_tr_b16 v[194:195], v126 offset:16384
	ds_read_b64_tr_b16 v[196:197], v126 offset:18432
	ds_read_b64_tr_b16 v[198:199], v127 offset:16384
	ds_read_b64_tr_b16 v[200:201], v127 offset:18432
	s_waitcnt lgkmcnt(14)
	v_mfma_f32_16x16x32_bf16 v[210:213], v[202:205], v[240:243], v[210:213]
	s_waitcnt lgkmcnt(12)
	v_mfma_f32_16x16x32_bf16 v[214:217], v[206:209], v[240:243], v[214:217]
	s_waitcnt lgkmcnt(10)
	v_mfma_f32_16x16x32_bf16 v[220:223], v[228:231], v[240:243], v[220:223]
	s_waitcnt lgkmcnt(8)
	v_mfma_f32_16x16x32_bf16 v[224:227], v[232:235], v[240:243], v[224:227]
	v_cvt_pk_bf16_f32 v236, v82, v83
	v_cvt_pk_bf16_f32 v237, v84, v85
	v_cvt_pk_bf16_f32 v238, v86, v87
	v_cvt_pk_bf16_f32 v239, v88, v89
	s_waitcnt lgkmcnt(7)
	ds_read_b64_tr_b16 v[202:203], v124 offset:20480
	ds_read_b64_tr_b16 v[204:205], v124 offset:22528
	ds_read_b64_tr_b16 v[206:207], v125 offset:20480
	ds_read_b64_tr_b16 v[208:209], v125 offset:22528
	ds_read_b64_tr_b16 v[228:229], v126 offset:20480
	ds_read_b64_tr_b16 v[230:231], v126 offset:22528
	ds_read_b64_tr_b16 v[232:233], v127 offset:20480
	ds_read_b64_tr_b16 v[234:235], v127 offset:22528
	s_waitcnt lgkmcnt(14)
	v_mfma_f32_16x16x32_bf16 v[210:213], v[186:189], v[236:239], v[210:213]
	s_waitcnt lgkmcnt(12)
	v_mfma_f32_16x16x32_bf16 v[214:217], v[190:193], v[236:239], v[214:217]
	s_waitcnt lgkmcnt(10)
	v_mfma_f32_16x16x32_bf16 v[220:223], v[194:197], v[236:239], v[220:223]
	s_waitcnt lgkmcnt(8)
	v_mfma_f32_16x16x32_bf16 v[224:227], v[198:201], v[236:239], v[224:227]
	v_cvt_pk_bf16_f32 v240, v90, v91
	v_cvt_pk_bf16_f32 v241, v92, v93
	v_cvt_pk_bf16_f32 v242, v94, v95
	v_cvt_pk_bf16_f32 v243, v96, v97
	s_waitcnt lgkmcnt(7)
	ds_read_b64_tr_b16 v[186:187], v124 offset:24576
	ds_read_b64_tr_b16 v[188:189], v124 offset:26624
	ds_read_b64_tr_b16 v[190:191], v125 offset:24576
	ds_read_b64_tr_b16 v[192:193], v125 offset:26624
	ds_read_b64_tr_b16 v[194:195], v126 offset:24576
	ds_read_b64_tr_b16 v[196:197], v126 offset:26624
	ds_read_b64_tr_b16 v[198:199], v127 offset:24576
	ds_read_b64_tr_b16 v[200:201], v127 offset:26624
	s_waitcnt lgkmcnt(14)
	v_mfma_f32_16x16x32_bf16 v[210:213], v[202:205], v[240:243], v[210:213]
	s_waitcnt lgkmcnt(12)
	v_mfma_f32_16x16x32_bf16 v[214:217], v[206:209], v[240:243], v[214:217]
	s_waitcnt lgkmcnt(10)
	v_mfma_f32_16x16x32_bf16 v[220:223], v[228:231], v[240:243], v[220:223]
	s_waitcnt lgkmcnt(8)
	v_mfma_f32_16x16x32_bf16 v[224:227], v[232:235], v[240:243], v[224:227]
	v_cvt_pk_bf16_f32 v236, v98, v99
	v_cvt_pk_bf16_f32 v237, v100, v101
	v_cvt_pk_bf16_f32 v238, v102, v103
	v_cvt_pk_bf16_f32 v239, v104, v105
	s_waitcnt lgkmcnt(7)
	ds_read_b64_tr_b16 v[202:203], v124 offset:28672
	ds_read_b64_tr_b16 v[204:205], v124 offset:30720
	ds_read_b64_tr_b16 v[206:207], v125 offset:28672
	ds_read_b64_tr_b16 v[208:209], v125 offset:30720
	ds_read_b64_tr_b16 v[228:229], v126 offset:28672
	ds_read_b64_tr_b16 v[230:231], v126 offset:30720
	ds_read_b64_tr_b16 v[232:233], v127 offset:28672
	ds_read_b64_tr_b16 v[234:235], v127 offset:30720
	s_waitcnt lgkmcnt(14)
	v_mfma_f32_16x16x32_bf16 v[210:213], v[186:189], v[236:239], v[210:213]
	s_waitcnt lgkmcnt(12)
	v_mfma_f32_16x16x32_bf16 v[214:217], v[190:193], v[236:239], v[214:217]
	s_waitcnt lgkmcnt(10)
	v_mfma_f32_16x16x32_bf16 v[220:223], v[194:197], v[236:239], v[220:223]
	s_waitcnt lgkmcnt(8)
	v_mfma_f32_16x16x32_bf16 v[224:227], v[198:201], v[236:239], v[224:227]
	v_cvt_pk_bf16_f32 v240, v106, v107
	v_cvt_pk_bf16_f32 v241, v108, v109
	v_cvt_pk_bf16_f32 v242, v110, v111
	v_cvt_pk_bf16_f32 v243, v112, v113
	s_waitcnt lgkmcnt(7)
	ds_read_b64_tr_b16 v[186:187], v124 offset:32768
	ds_read_b64_tr_b16 v[188:189], v124 offset:34816
	ds_read_b64_tr_b16 v[190:191], v125 offset:32768
	ds_read_b64_tr_b16 v[192:193], v125 offset:34816
	ds_read_b64_tr_b16 v[194:195], v126 offset:32768
	ds_read_b64_tr_b16 v[196:197], v126 offset:34816
	ds_read_b64_tr_b16 v[198:199], v127 offset:32768
	ds_read_b64_tr_b16 v[200:201], v127 offset:34816
	s_waitcnt lgkmcnt(14)
	v_mfma_f32_16x16x32_bf16 v[210:213], v[202:205], v[240:243], v[210:213]
	s_waitcnt lgkmcnt(12)
	v_mfma_f32_16x16x32_bf16 v[214:217], v[206:209], v[240:243], v[214:217]
	s_waitcnt lgkmcnt(10)
	v_mfma_f32_16x16x32_bf16 v[220:223], v[228:231], v[240:243], v[220:223]
	s_waitcnt lgkmcnt(8)
	v_mfma_f32_16x16x32_bf16 v[224:227], v[232:235], v[240:243], v[224:227]
	v_cvt_pk_bf16_f32 v236, v114, v115
	v_cvt_pk_bf16_f32 v237, v116, v117
	v_mov_b32_e32 v238, 0
	v_mov_b32_e32 v239, 0
	s_nop 1
	s_waitcnt lgkmcnt(6)
	v_mfma_f32_16x16x32_bf16 v[210:213], v[186:189], v[236:239], v[210:213]
	s_waitcnt lgkmcnt(4)
	v_mfma_f32_16x16x32_bf16 v[214:217], v[190:193], v[236:239], v[214:217]
	s_waitcnt lgkmcnt(2)
	v_mfma_f32_16x16x32_bf16 v[220:223], v[194:197], v[236:239], v[220:223]
	s_waitcnt lgkmcnt(0)
; __device__ __forceinline__ unsigned pk2(float lo, float hi) { return pg8::cvt_pk_bf16(lo, hi); }
; __device__ __forceinline__ void store_o(bf16* yrow, int g, float l, const f32x4 (&O)[4]) {
;     const float inv = 1.0f / xrow16_sum(l);
;     unsigned wx[4], wy[4];
; #pragma unroll
;     for (int db = 0; db < 4; ++db) { wx[db] = pk2(O[db][0] * inv, O[db][1] * inv); wy[db] = pk2(O[db][2] * inv, O[db][3] * inv); }
; #pragma unroll
;     for (int p = 0; p < 2; ++p) {
;         auto rx = __builtin_amdgcn_permlane16_swap(wx[2 * p], wx[2 * p + 1], false, false); wx[2 * p] = rx[0]; wx[2 * p + 1] = rx[1];
;         auto ry = __builtin_amdgcn_permlane16_swap(wy[2 * p], wy[2 * p + 1], false, false); wy[2 * p] = ry[0]; wy[2 * p + 1] = ry[1]; }
; #pragma unroll
;     for (int p = 0; p < 2; ++p) {
;         auto rx = __builtin_amdgcn_permlane32_swap(wx[p], wx[p + 2], false, false); wx[p] = rx[0]; wx[p + 2] = rx[1];
;         auto ry = __builtin_amdgcn_permlane32_swap(wy[p], wy[p + 2], false, false); wy[p] = ry[0]; wy[p + 2] = ry[1]; }
;     v4u lo = {wx[0], wy[0], wx[1], wy[1]}, hi = {wx[2], wy[2], wx[3], wy[3]};
;     *(v4u*)(yrow + 16 * g) = lo; *(v4u*)(yrow + 16 * g + 8) = hi;
; }
; template <bool MASK> __device__ __forceinline__ void a_scores(f32x4& S0, f32x4& S1, float basef, float c1, float slope2, int krow0, int kstart) {
; #pragma unroll
;     for (int r = 0; r < 4; ++r) {
;         const float d0 = fabsf(basef - (float)r), d1 = fabsf(basef - (float)(16 + r));
;         const float v0 = S0[r] - slope2 * d0, v1 = S1[r] - slope2 * d1;
;         if (MASK) { const int p0 = kstart + krow0 + r, p1 = p0 + 16;
;             S0[r] = (d0 <= 128.f && p0 >= 0 && p0 < SEQ) ? v0 : -INFINITY; S1[r] = (d1 <= 128.f && p1 >= 0 && p1 < SEQ) ? v1 : -INFINITY; }
;         else { S0[r] = v0; S1[r] = v1; }
;     }
; }
	v_mfma_f32_16x16x32_bf16 v[224:227], v[198:201], v[236:239], v[224:227]
	v_mov_b32_e32 v219, v185
	s_nop 1
	v_permlane16_swap_b32_e32 v185, v219
	v_add_f32_e32 v185, v185, v219
	v_mov_b32_e32 v219, v185
	s_nop 1
	v_permlane32_swap_b32_e32 v185, v219
	v_add_f32_e32 v185, v185, v219
	v_div_scale_f32 v236, s[78:79], v185, v185, 1.0
	v_div_scale_f32 v237, vcc, 1.0, v185, 1.0
	v_rcp_f32_e32 v238, v236
	s_nop 0
	v_fma_f32 v239, -v236, v238, 1.0
	v_fmac_f32_e32 v238, v239, v238
	v_mul_f32_e32 v240, v237, v238
	v_fma_f32 v241, -v236, v240, v237
	v_fmac_f32_e32 v240, v241, v238
	v_fma_f32 v237, -v236, v240, v237
	v_div_fmas_f32 v237, v237, v238, v240
	v_div_fixup_f32 v244, v237, v185, 1.0
	v_mul_f32_e32 v240, v210, v244
	v_mul_f32_e32 v241, v211, v244
	v_mul_f32_e32 v242, v212, v244
	v_mul_f32_e32 v243, v213, v244
	v_cvt_pk_bf16_f32 v186, v240, v241
	v_cvt_pk_bf16_f32 v187, v242, v243
	v_mul_f32_e32 v240, v214, v244
	v_mul_f32_e32 v241, v215, v244
	v_mul_f32_e32 v242, v216, v244
	v_mul_f32_e32 v243, v217, v244
	v_cvt_pk_bf16_f32 v188, v240, v241
	v_cvt_pk_bf16_f32 v189, v242, v243
	v_mul_f32_e32 v240, v220, v244
	v_mul_f32_e32 v241, v221, v244
	v_mul_f32_e32 v242, v222, v244
	v_mul_f32_e32 v243, v223, v244
	v_cvt_pk_bf16_f32 v190, v240, v241
	v_cvt_pk_bf16_f32 v191, v242, v243
	v_mul_f32_e32 v240, v224, v244
	v_mul_f32_e32 v241, v225, v244
	v_mul_f32_e32 v242, v226, v244
	v_mul_f32_e32 v243, v227, v244
	v_cvt_pk_bf16_f32 v192, v240, v241
	v_cvt_pk_bf16_f32 v193, v242, v243
	s_nop 1
	v_permlane16_swap_b32_e32 v186, v188
	v_permlane16_swap_b32_e32 v187, v189
	v_permlane16_swap_b32_e32 v190, v192
	v_permlane16_swap_b32_e32 v191, v193
	s_nop 0
	v_permlane32_swap_b32_e32 v186, v190
	v_permlane32_swap_b32_e32 v187, v191
	v_permlane32_swap_b32_e32 v188, v192
	v_permlane32_swap_b32_e32 v189, v193
	global_store_dwordx4 v128, v[186:189], s[82:83] offset:0
	global_store_dwordx4 v128, v[190:193], s[82:83] offset:16
	s_nop 1
	s_bitcmp1_b32 s87, 1
	s_cselect_b32 s21, 0, 0xff800000
	v_add_f32_e32 v120, s21, v132
	v_fmamk_f32 v50, v130, 0x43000000, v120
	v_fmamk_f32 v51, v130, 0x42fe0000, v120
	v_fmamk_f32 v52, v130, 0x42fc0000, v120
	v_fmamk_f32 v53, v130, 0x42fa0000, v120
	s_bitcmp1_b32 s87, 2
	s_cselect_b32 s21, 0, 0xff800000
	v_add_f32_e32 v120, s21, v132
	v_fmamk_f32 v54, v130, 0x42e00000, v120
	v_fmamk_f32 v55, v130, 0x42de0000, v120
	v_fmamk_f32 v56, v130, 0x42dc0000, v120
	v_fmamk_f32 v57, v130, 0x42da0000, v120
	s_bitcmp1_b32 s87, 3
	s_cselect_b32 s21, 0, 0xff800000
	v_add_f32_e32 v120, s21, v132
	v_fmamk_f32 v58, v130, 0x42c00000, v120
	v_fmamk_f32 v59, v130, 0x42be0000, v120
	v_fmamk_f32 v60, v130, 0x42bc0000, v120
	v_fmamk_f32 v61, v130, 0x42ba0000, v120
	s_bitcmp1_b32 s87, 4
	s_cselect_b32 s21, 0, 0xff800000
	v_add_f32_e32 v120, s21, v132
	v_fmamk_f32 v62, v130, 0x42a00000, v120
	v_fmamk_f32 v63, v130, 0x429e0000, v120
	v_fmamk_f32 v64, v130, 0x429c0000, v120
	v_fmamk_f32 v65, v130, 0x429a0000, v120
	s_bitcmp1_b32 s87, 5
	s_cselect_b32 s21, 0, 0xff800000
	v_add_f32_e32 v120, s21, v132
	v_fmamk_f32 v66, v130, 0x42800000, v120
	v_fmamk_f32 v67, v130, 0x427c0000, v120
	v_fmamk_f32 v68, v130, 0x42780000, v120
	v_fmamk_f32 v69, v130, 0x42740000, v120
	s_bitcmp1_b32 s87, 6
	s_cselect_b32 s21, 0, 0xff800000
	v_add_f32_e32 v120, s21, v132
	v_fmamk_f32 v70, v130, 0x42400000, v120
	v_fmamk_f32 v71, v130, 0x423c0000, v120
	v_fmamk_f32 v72, v130, 0x42380000, v120
	v_fmamk_f32 v73, v130, 0x42340000, v120
	s_bitcmp1_b32 s87, 7
	s_cselect_b32 s21, 0, 0xff800000
	v_add_f32_e32 v120, s21, v132
	v_fmamk_f32 v74, v130, 0x42000000, v120
	v_fmamk_f32 v75, v130, 0x41f80000, v120
	v_fmamk_f32 v76, v130, 0x41f00000, v120
	v_fmamk_f32 v77, v130, 0x41e80000, v120
	s_bitcmp1_b32 s87, 8
	s_cselect_b32 s21, 0, 0xff800000
	v_add_f32_e32 v120, s21, v132
	v_fmamk_f32 v78, v130, 0x41800000, v120
	v_fmamk_f32 v79, v130, 0x41700000, v120
	v_fmamk_f32 v80, v130, 0x41600000, v120
	v_fmamk_f32 v81, v130, 0x41500000, v120
	s_bitcmp1_b32 s87, 9
	s_cselect_b32 s21, 0, 0xff800000
	v_add_f32_e32 v219, 0, v129
	v_fma_f32 v82, v130, |v219|, s21
	v_add_f32_e32 v244, 0xbf800000, v129
	v_fma_f32 v83, v130, |v244|, s21
	v_add_f32_e32 v219, 0xc0000000, v129
	v_fma_f32 v84, v130, |v219|, s21
	v_add_f32_e32 v244, 0xc0400000, v129
	v_fma_f32 v85, v130, |v244|, s21
	s_bitcmp1_b32 s87, 10
	s_cselect_b32 s21, 0, 0xff800000
	v_add_f32_e32 v120, s21, v133
	v_fmamk_f32 v86, v131, 0xc1800000, v120
	v_fmamk_f32 v87, v131, 0xc1880000, v120
	v_fmamk_f32 v88, v131, 0xc1900000, v120
	v_fmamk_f32 v89, v131, 0xc1980000, v120
	s_bitcmp1_b32 s87, 11
	s_cselect_b32 s21, 0, 0xff800000
	v_add_f32_e32 v120, s21, v133
	v_fmamk_f32 v90, v131, 0xc2000000, v120
	v_fmamk_f32 v91, v131, 0xc2040000, v120
	v_fmamk_f32 v92, v131, 0xc2080000, v120
	v_fmamk_f32 v93, v131, 0xc20c0000, v120
	s_bitcmp1_b32 s87, 12
	s_cselect_b32 s21, 0, 0xff800000
	v_add_f32_e32 v120, s21, v133
	v_fmamk_f32 v94, v131, 0xc2400000, v120
	v_fmamk_f32 v95, v131, 0xc2440000, v120
	v_fmamk_f32 v96, v131, 0xc2480000, v120
	v_fmamk_f32 v97, v131, 0xc24c0000, v120
	s_bitcmp1_b32 s87, 13
	s_cselect_b32 s21, 0, 0xff800000
	v_add_f32_e32 v120, s21, v133
	v_fmamk_f32 v98, v131, 0xc2800000, v120
	v_fmamk_f32 v99, v131, 0xc2820000, v120
	v_fmamk_f32 v100, v131, 0xc2840000, v120
	v_fmamk_f32 v101, v131, 0xc2860000, v120
	s_bitcmp1_b32 s87, 14
	s_cselect_b32 s21, 0, 0xff800000
	v_add_f32_e32 v120, s21, v133
	v_fmamk_f32 v102, v131, 0xc2a00000, v120
	v_fmamk_f32 v103, v131, 0xc2a20000, v120
	v_fmamk_f32 v104, v131, 0xc2a40000, v120
	v_fmamk_f32 v105, v131, 0xc2a60000, v120
	s_bitcmp1_b32 s87, 15
	s_cselect_b32 s21, 0, 0xff800000
	v_add_f32_e32 v120, s21, v133
	v_fmamk_f32 v106, v131, 0xc2c00000, v120
	v_fmamk_f32 v107, v131, 0xc2c20000, v120
	v_fmamk_f32 v108, v131, 0xc2c40000, v120
	v_fmamk_f32 v109, v131, 0xc2c60000, v120
	s_bitcmp1_b32 s87, 16
	s_cselect_b32 s21, 0, 0xff800000
	v_add_f32_e32 v120, s21, v133
	v_fmamk_f32 v110, v131, 0xc2e00000, v120
	v_fmamk_f32 v111, v131, 0xc2e20000, v120
	v_fmamk_f32 v112, v131, 0xc2e40000, v120
	v_fmamk_f32 v113, v131, 0xc2e60000, v120
	s_bitcmp1_b32 s87, 17
	s_cselect_b32 s21, 0, 0xff800000
	v_add_f32_e32 v120, s21, v133
	v_fmamk_f32 v114, v131, 0xc3000000, v120
	v_fmamk_f32 v115, v131, 0xc3010000, v120
	v_fmamk_f32 v116, v131, 0xc3020000, v120
	v_fmamk_f32 v117, v131, 0xc3030000, v120
	v_mov_b32_e32 v245, 0xff800000
	v_cndmask_b32_e64 v50, v245, v50, s[16:17]
	v_cndmask_b32_e64 v51, v245, v51, s[18:19]
	v_cndmask_b32_e64 v52, v245, v52, s[22:23]
	v_cndmask_b32_e64 v53, v245, v53, s[24:25]
	v_cndmask_b32_e64 v114, v245, v114, s[28:29]
	v_cndmask_b32_e64 v115, v245, v115, s[52:53]
	v_cndmask_b32_e64 v116, v245, v116, s[54:55]
	v_cndmask_b32_e64 v117, v245, v117, s[88:89]
	ds_read_b128 v[186:189], v122 offset:2048
	ds_read_b128 v[190:193], v123 offset:2048
	ds_read_b128 v[194:197], v122 offset:4096
	ds_read_b128 v[198:201], v123 offset:4096
	ds_read_b128 v[202:205], v122 offset:6144
	ds_read_b128 v[206:209], v123 offset:6144
	s_waitcnt lgkmcnt(5)
; #define LAS __attribute__((address_space(3)))
; #define MFMA16(a, b, c) __builtin_amdgcn_mfma_f32_16x16x32_bf16((a), (b), (c), 0, 0, 0)
; __device__ __forceinline__ void qk_at(const LAS unsigned char* kp0, const LAS unsigned char* kp1, int off, bf16x8 qf0, bf16x8 qf1, f32x4& S0, f32x4& S1) {
;     const bf16x8 k00 = *(const LAS bf16x8*)(kp0 + off), k01 = *(const LAS bf16x8*)(kp1 + off);
;     const bf16x8 k10 = *(const LAS bf16x8*)(kp0 + off + 2048), k11 = *(const LAS bf16x8*)(kp1 + off + 2048);
;     const f32x4 z = {0.f, 0.f, 0.f, 0.f};
;     S0 = MFMA16(k00, qf0, z); S0 = MFMA16(k01, qf1, S0);
;     S1 = MFMA16(k10, qf0, z); S1 = MFMA16(k11, qf1, S1);
; }
; __device__ __forceinline__ void softmax_step(f32x4& s0, f32x4& s1, float& m, float& l, f32x4 (&O)[4]) {
;     float t = fmaxf(fmaxf(fmaxf(s0[0], s0[1]), fmaxf(s0[2], s0[3])), fmaxf(fmaxf(s1[0], s1[1]), fmaxf(s1[2], s1[3])));
;     t = xrow16_max(t);
	v_mfma_f32_16x16x32_bf16 v[50:53], v[186:189], v[154:157], v[50:53]
	s_waitcnt lgkmcnt(4)
	v_mfma_f32_16x16x32_bf16 v[50:53], v[190:193], v[158:161], v[50:53]
	ds_read_b128 v[186:189], v122 offset:8192
	ds_read_b128 v[190:193], v123 offset:8192
	s_waitcnt lgkmcnt(5)
	v_mfma_f32_16x16x32_bf16 v[54:57], v[194:197], v[154:157], v[54:57]
	s_waitcnt lgkmcnt(4)
	v_mfma_f32_16x16x32_bf16 v[54:57], v[198:201], v[158:161], v[54:57]
	ds_read_b128 v[194:197], v122 offset:10240
	ds_read_b128 v[198:201], v123 offset:10240
	s_waitcnt lgkmcnt(5)
	v_mfma_f32_16x16x32_bf16 v[58:61], v[202:205], v[154:157], v[58:61]
	s_waitcnt lgkmcnt(4)
	v_mfma_f32_16x16x32_bf16 v[58:61], v[206:209], v[158:161], v[58:61]
	ds_read_b128 v[202:205], v122 offset:12288
	ds_read_b128 v[206:209], v123 offset:12288
	s_waitcnt lgkmcnt(5)
	v_mfma_f32_16x16x32_bf16 v[62:65], v[186:189], v[154:157], v[62:65]
	s_waitcnt lgkmcnt(4)
	v_mfma_f32_16x16x32_bf16 v[62:65], v[190:193], v[158:161], v[62:65]
	ds_read_b128 v[186:189], v122 offset:14336
	ds_read_b128 v[190:193], v123 offset:14336
	s_waitcnt lgkmcnt(5)
	v_mfma_f32_16x16x32_bf16 v[66:69], v[194:197], v[154:157], v[66:69]
	s_waitcnt lgkmcnt(4)
	v_mfma_f32_16x16x32_bf16 v[66:69], v[198:201], v[158:161], v[66:69]
	ds_read_b128 v[194:197], v122 offset:16384
	ds_read_b128 v[198:201], v123 offset:16384
	s_waitcnt lgkmcnt(5)
	v_mfma_f32_16x16x32_bf16 v[70:73], v[202:205], v[154:157], v[70:73]
	s_waitcnt lgkmcnt(4)
	v_mfma_f32_16x16x32_bf16 v[70:73], v[206:209], v[158:161], v[70:73]
	ds_read_b128 v[202:205], v122 offset:18432
	ds_read_b128 v[206:209], v123 offset:18432
	s_waitcnt lgkmcnt(5)
	v_mfma_f32_16x16x32_bf16 v[74:77], v[186:189], v[154:157], v[74:77]
	s_waitcnt lgkmcnt(4)
	v_mfma_f32_16x16x32_bf16 v[74:77], v[190:193], v[158:161], v[74:77]
	ds_read_b128 v[186:189], v122 offset:20480
	ds_read_b128 v[190:193], v123 offset:20480
	s_waitcnt lgkmcnt(5)
	v_mfma_f32_16x16x32_bf16 v[78:81], v[194:197], v[154:157], v[78:81]
	s_waitcnt lgkmcnt(4)
	v_mfma_f32_16x16x32_bf16 v[78:81], v[198:201], v[158:161], v[78:81]
	ds_read_b128 v[194:197], v122 offset:22528
	ds_read_b128 v[198:201], v123 offset:22528
	s_waitcnt lgkmcnt(5)
	v_mfma_f32_16x16x32_bf16 v[82:85], v[202:205], v[154:157], v[82:85]
	s_waitcnt lgkmcnt(4)
	v_mfma_f32_16x16x32_bf16 v[82:85], v[206:209], v[158:161], v[82:85]
	ds_read_b128 v[202:205], v122 offset:24576
	ds_read_b128 v[206:209], v123 offset:24576
	s_waitcnt lgkmcnt(5)
	v_mfma_f32_16x16x32_bf16 v[86:89], v[186:189], v[154:157], v[86:89]
	s_waitcnt lgkmcnt(4)
	v_mfma_f32_16x16x32_bf16 v[86:89], v[190:193], v[158:161], v[86:89]
	ds_read_b128 v[186:189], v122 offset:26624
	ds_read_b128 v[190:193], v123 offset:26624
	s_waitcnt lgkmcnt(5)
	v_mfma_f32_16x16x32_bf16 v[90:93], v[194:197], v[154:157], v[90:93]
	s_waitcnt lgkmcnt(4)
	v_mfma_f32_16x16x32_bf16 v[90:93], v[198:201], v[158:161], v[90:93]
	ds_read_b128 v[194:197], v122 offset:28672
	ds_read_b128 v[198:201], v123 offset:28672
	s_waitcnt lgkmcnt(5)
	v_mfma_f32_16x16x32_bf16 v[94:97], v[202:205], v[154:157], v[94:97]
	s_waitcnt lgkmcnt(4)
	v_mfma_f32_16x16x32_bf16 v[94:97], v[206:209], v[158:161], v[94:97]
	ds_read_b128 v[202:205], v122 offset:30720
	ds_read_b128 v[206:209], v123 offset:30720
	s_waitcnt lgkmcnt(5)
	v_mfma_f32_16x16x32_bf16 v[98:101], v[186:189], v[154:157], v[98:101]
	s_waitcnt lgkmcnt(4)
	v_mfma_f32_16x16x32_bf16 v[98:101], v[190:193], v[158:161], v[98:101]
	ds_read_b128 v[186:189], v122 offset:32768
	ds_read_b128 v[190:193], v123 offset:32768
	s_waitcnt lgkmcnt(5)
	v_mfma_f32_16x16x32_bf16 v[102:105], v[194:197], v[154:157], v[102:105]
	s_waitcnt lgkmcnt(4)
	v_mfma_f32_16x16x32_bf16 v[102:105], v[198:201], v[158:161], v[102:105]
	ds_read_b128 v[194:197], v122 offset:34816
	ds_read_b128 v[198:201], v123 offset:34816
	s_waitcnt lgkmcnt(5)
	v_mfma_f32_16x16x32_bf16 v[106:109], v[202:205], v[154:157], v[106:109]
	s_waitcnt lgkmcnt(4)
	v_mfma_f32_16x16x32_bf16 v[106:109], v[206:209], v[158:161], v[106:109]
	s_waitcnt lgkmcnt(3)
	v_mfma_f32_16x16x32_bf16 v[110:113], v[186:189], v[154:157], v[110:113]
	s_waitcnt lgkmcnt(2)
	v_mfma_f32_16x16x32_bf16 v[110:113], v[190:193], v[158:161], v[110:113]
	s_waitcnt lgkmcnt(1)
	v_mfma_f32_16x16x32_bf16 v[114:117], v[194:197], v[154:157], v[114:117]
	s_waitcnt lgkmcnt(0)
	v_mfma_f32_16x16x32_bf16 v[114:117], v[198:201], v[158:161], v[114:117]
	v_max3_f32 v219, v50, v51, v52
	v_max3_f32 v244, v54, v55, v56
	v_max3_f32 v245, v58, v59, v60
	v_max3_f32 v120, v62, v63, v64
	v_max3_f32 v219, v219, v53, v66
	v_max3_f32 v244, v244, v57, v70
	v_max3_f32 v245, v245, v61, v74
	v_max3_f32 v120, v120, v65, v78
	v_max3_f32 v219, v219, v67, v68
	v_max3_f32 v244, v244, v71, v72
	v_max3_f32 v245, v245, v75, v76
	v_max3_f32 v120, v120, v79, v80
	ds_read_b64_tr_b16 v[186:187], v124 offset:2048
	ds_read_b64_tr_b16 v[188:189], v124 offset:4096
	ds_read_b64_tr_b16 v[190:191], v125 offset:2048
	ds_read_b64_tr_b16 v[192:193], v125 offset:4096
	ds_read_b64_tr_b16 v[194:195], v126 offset:2048
	ds_read_b64_tr_b16 v[196:197], v126 offset:4096
	ds_read_b64_tr_b16 v[198:199], v127 offset:2048
	ds_read_b64_tr_b16 v[200:201], v127 offset:4096
	v_max3_f32 v219, v219, v69, v82
	v_max3_f32 v244, v244, v73, v86
	v_max3_f32 v245, v245, v77, v90
	v_max3_f32 v120, v120, v81, v94
	v_max3_f32 v219, v219, v83, v84
	v_max3_f32 v244, v244, v87, v88
	v_max3_f32 v245, v245, v91, v92
	v_max3_f32 v120, v120, v95, v96
	v_max3_f32 v219, v219, v85, v98
	v_max3_f32 v244, v244, v89, v102
	v_max3_f32 v245, v245, v93, v106
	v_max3_f32 v120, v120, v97, v110
	v_max3_f32 v219, v219, v99, v100
	v_max3_f32 v244, v244, v103, v104
	v_max3_f32 v245, v245, v107, v108
	v_max3_f32 v120, v120, v111, v112
	v_max3_f32 v219, v219, v101, v114
	v_max3_f32 v219, v219, v115, v116
	v_max_f32_e32 v219, v219, v117
	v_max_f32_e32 v244, v244, v105
	v_max_f32_e32 v245, v245, v109
	v_max_f32_e32 v120, v120, v113
	v_max3_f32 v178, v219, v244, v245
	v_max_f32_e32 v178, v178, v120
	v_mov_b32_e32 v219, v178
	s_nop 1
	v_permlane16_swap_b32_e32 v178, v219
	v_max_f32_e32 v178, v178, v219
	v_mov_b32_e32 v219, v178
	s_nop 1
	v_permlane32_swap_b32_e32 v178, v219
	v_max3_f32 v178, v178, v219, v145
	s_waitcnt lgkmcnt(7)
; __device__ __forceinline__ void softmax_step(f32x4& s0, f32x4& s1, float& m, float& l, f32x4 (&O)[4]) {
;     float t = fmaxf(fmaxf(fmaxf(s0[0], s0[1]), fmaxf(s0[2], s0[3])), fmaxf(fmaxf(s1[0], s1[1]), fmaxf(s1[2], s1[3])));
;     t = xrow16_max(t);
;     const float mn = fmaxf(m, t), alpha = __builtin_amdgcn_exp2f(m - mn);
;     m = mn;
; #pragma unroll
;     for (int k = 0; k < 4; ++k) { s0[k] = __builtin_amdgcn_exp2f(s0[k] - mn); s1[k] = __builtin_amdgcn_exp2f(s1[k] - mn); }
;     l = l * alpha + ((s0[0] + s0[1]) + (s0[2] + s0[3])) + ((s1[0] + s1[1]) + (s1[2] + s1[3]));
; #pragma unroll
;     for (int db = 0; db < 4; ++db) O[db] *= alpha;
; }
	ds_read_b64_tr_b16 v[202:203], v124 offset:6144
	ds_read_b64_tr_b16 v[204:205], v124 offset:8192
	ds_read_b64_tr_b16 v[206:207], v125 offset:6144
	ds_read_b64_tr_b16 v[208:209], v125 offset:8192
	ds_read_b64_tr_b16 v[228:229], v126 offset:6144
	ds_read_b64_tr_b16 v[230:231], v126 offset:8192
	ds_read_b64_tr_b16 v[232:233], v127 offset:6144
	ds_read_b64_tr_b16 v[234:235], v127 offset:8192
	v_mov_b32_e32 v244, v178
	v_pk_add_f32 v[50:51], v[50:51], v[244:245] op_sel_hi:[1,0] neg_lo:[0,1] neg_hi:[0,1]
	v_pk_add_f32 v[52:53], v[52:53], v[244:245] op_sel_hi:[1,0] neg_lo:[0,1] neg_hi:[0,1]
	v_pk_add_f32 v[54:55], v[54:55], v[244:245] op_sel_hi:[1,0] neg_lo:[0,1] neg_hi:[0,1]
	v_pk_add_f32 v[56:57], v[56:57], v[244:245] op_sel_hi:[1,0] neg_lo:[0,1] neg_hi:[0,1]
	v_pk_add_f32 v[58:59], v[58:59], v[244:245] op_sel_hi:[1,0] neg_lo:[0,1] neg_hi:[0,1]
	v_pk_add_f32 v[60:61], v[60:61], v[244:245] op_sel_hi:[1,0] neg_lo:[0,1] neg_hi:[0,1]
	v_pk_add_f32 v[62:63], v[62:63], v[244:245] op_sel_hi:[1,0] neg_lo:[0,1] neg_hi:[0,1]
	v_pk_add_f32 v[64:65], v[64:65], v[244:245] op_sel_hi:[1,0] neg_lo:[0,1] neg_hi:[0,1]
	v_pk_add_f32 v[66:67], v[66:67], v[244:245] op_sel_hi:[1,0] neg_lo:[0,1] neg_hi:[0,1]
	v_pk_add_f32 v[68:69], v[68:69], v[244:245] op_sel_hi:[1,0] neg_lo:[0,1] neg_hi:[0,1]
	v_pk_add_f32 v[70:71], v[70:71], v[244:245] op_sel_hi:[1,0] neg_lo:[0,1] neg_hi:[0,1]
	v_pk_add_f32 v[72:73], v[72:73], v[244:245] op_sel_hi:[1,0] neg_lo:[0,1] neg_hi:[0,1]
	v_pk_add_f32 v[74:75], v[74:75], v[244:245] op_sel_hi:[1,0] neg_lo:[0,1] neg_hi:[0,1]
	v_pk_add_f32 v[76:77], v[76:77], v[244:245] op_sel_hi:[1,0] neg_lo:[0,1] neg_hi:[0,1]
	v_pk_add_f32 v[78:79], v[78:79], v[244:245] op_sel_hi:[1,0] neg_lo:[0,1] neg_hi:[0,1]
	v_pk_add_f32 v[80:81], v[80:81], v[244:245] op_sel_hi:[1,0] neg_lo:[0,1] neg_hi:[0,1]
	v_pk_add_f32 v[82:83], v[82:83], v[244:245] op_sel_hi:[1,0] neg_lo:[0,1] neg_hi:[0,1]
	v_pk_add_f32 v[84:85], v[84:85], v[244:245] op_sel_hi:[1,0] neg_lo:[0,1] neg_hi:[0,1]
	v_pk_add_f32 v[86:87], v[86:87], v[244:245] op_sel_hi:[1,0] neg_lo:[0,1] neg_hi:[0,1]
	v_pk_add_f32 v[88:89], v[88:89], v[244:245] op_sel_hi:[1,0] neg_lo:[0,1] neg_hi:[0,1]
	v_pk_add_f32 v[90:91], v[90:91], v[244:245] op_sel_hi:[1,0] neg_lo:[0,1] neg_hi:[0,1]
	v_pk_add_f32 v[92:93], v[92:93], v[244:245] op_sel_hi:[1,0] neg_lo:[0,1] neg_hi:[0,1]
	v_pk_add_f32 v[94:95], v[94:95], v[244:245] op_sel_hi:[1,0] neg_lo:[0,1] neg_hi:[0,1]
	v_pk_add_f32 v[96:97], v[96:97], v[244:245] op_sel_hi:[1,0] neg_lo:[0,1] neg_hi:[0,1]
	v_pk_add_f32 v[98:99], v[98:99], v[244:245] op_sel_hi:[1,0] neg_lo:[0,1] neg_hi:[0,1]
	v_pk_add_f32 v[100:101], v[100:101], v[244:245] op_sel_hi:[1,0] neg_lo:[0,1] neg_hi:[0,1]
	v_pk_add_f32 v[102:103], v[102:103], v[244:245] op_sel_hi:[1,0] neg_lo:[0,1] neg_hi:[0,1]
	v_pk_add_f32 v[104:105], v[104:105], v[244:245] op_sel_hi:[1,0] neg_lo:[0,1] neg_hi:[0,1]
	v_pk_add_f32 v[106:107], v[106:107], v[244:245] op_sel_hi:[1,0] neg_lo:[0,1] neg_hi:[0,1]
	v_pk_add_f32 v[108:109], v[108:109], v[244:245] op_sel_hi:[1,0] neg_lo:[0,1] neg_hi:[0,1]
	v_pk_add_f32 v[110:111], v[110:111], v[244:245] op_sel_hi:[1,0] neg_lo:[0,1] neg_hi:[0,1]
	v_pk_add_f32 v[112:113], v[112:113], v[244:245] op_sel_hi:[1,0] neg_lo:[0,1] neg_hi:[0,1]
	v_pk_add_f32 v[114:115], v[114:115], v[244:245] op_sel_hi:[1,0] neg_lo:[0,1] neg_hi:[0,1]
	v_pk_add_f32 v[116:117], v[116:117], v[244:245] op_sel_hi:[1,0] neg_lo:[0,1] neg_hi:[0,1]
	v_sub_f32_e32 v219, v145, v178
	v_exp_f32_e32 v50, v50
	v_exp_f32_e32 v51, v51
	v_exp_f32_e32 v52, v52
	v_exp_f32_e32 v53, v53
	v_exp_f32_e32 v54, v54
	v_exp_f32_e32 v55, v55
	v_exp_f32_e32 v56, v56
	v_exp_f32_e32 v57, v57
	v_exp_f32_e32 v58, v58
	v_exp_f32_e32 v59, v59
	v_exp_f32_e32 v60, v60
	v_exp_f32_e32 v61, v61
	v_exp_f32_e32 v62, v62
	v_exp_f32_e32 v63, v63
	v_exp_f32_e32 v64, v64
	v_exp_f32_e32 v65, v65
	v_exp_f32_e32 v66, v66
	v_exp_f32_e32 v67, v67
	v_exp_f32_e32 v68, v68
	v_exp_f32_e32 v69, v69
	v_exp_f32_e32 v70, v70
	v_exp_f32_e32 v71, v71
	v_exp_f32_e32 v72, v72
	v_exp_f32_e32 v73, v73
	v_exp_f32_e32 v74, v74
	v_exp_f32_e32 v75, v75
	v_exp_f32_e32 v76, v76
	v_exp_f32_e32 v77, v77
	v_exp_f32_e32 v78, v78
	v_exp_f32_e32 v79, v79
	v_exp_f32_e32 v80, v80
	v_exp_f32_e32 v81, v81
	v_exp_f32_e32 v82, v82
	v_exp_f32_e32 v83, v83
	v_exp_f32_e32 v84, v84
	v_exp_f32_e32 v85, v85
	v_exp_f32_e32 v86, v86
	v_exp_f32_e32 v87, v87
	v_exp_f32_e32 v88, v88
	v_exp_f32_e32 v89, v89
	v_exp_f32_e32 v90, v90
	v_exp_f32_e32 v91, v91
	v_exp_f32_e32 v92, v92
	v_exp_f32_e32 v93, v93
	v_exp_f32_e32 v94, v94
	v_exp_f32_e32 v95, v95
	v_exp_f32_e32 v96, v96
	v_exp_f32_e32 v97, v97
	v_exp_f32_e32 v98, v98
	v_exp_f32_e32 v99, v99
	v_exp_f32_e32 v100, v100
	v_exp_f32_e32 v101, v101
	v_exp_f32_e32 v102, v102
	v_exp_f32_e32 v103, v103
	v_exp_f32_e32 v104, v104
	v_exp_f32_e32 v105, v105
	v_exp_f32_e32 v106, v106
	v_exp_f32_e32 v107, v107
	v_exp_f32_e32 v108, v108
	v_exp_f32_e32 v109, v109
	v_exp_f32_e32 v110, v110
	v_exp_f32_e32 v111, v111
	v_exp_f32_e32 v112, v112
	v_exp_f32_e32 v113, v113
	v_exp_f32_e32 v114, v114
	v_exp_f32_e32 v115, v115
	v_exp_f32_e32 v116, v116
	v_exp_f32_e32 v117, v117
	v_exp_f32_e32 v219, v219
	v_pk_add_f32 v[236:237], v[50:51], v[52:53]
	v_pk_add_f32 v[238:239], v[54:55], v[56:57]
	v_pk_add_f32 v[240:241], v[58:59], v[60:61]
	v_pk_add_f32 v[242:243], v[62:63], v[64:65]
	v_pk_add_f32 v[236:237], v[236:237], v[66:67]
	v_pk_add_f32 v[238:239], v[238:239], v[70:71]
	v_pk_add_f32 v[240:241], v[240:241], v[74:75]
	v_pk_add_f32 v[242:243], v[242:243], v[78:79]
	v_pk_add_f32 v[236:237], v[236:237], v[68:69]
	v_pk_add_f32 v[238:239], v[238:239], v[72:73]
	v_pk_add_f32 v[240:241], v[240:241], v[76:77]
	v_pk_add_f32 v[242:243], v[242:243], v[80:81]
	v_pk_add_f32 v[236:237], v[236:237], v[82:83]
	v_pk_add_f32 v[238:239], v[238:239], v[86:87]
	v_pk_add_f32 v[240:241], v[240:241], v[90:91]
	v_pk_add_f32 v[242:243], v[242:243], v[94:95]
	v_pk_add_f32 v[236:237], v[236:237], v[84:85]
	v_pk_add_f32 v[238:239], v[238:239], v[88:89]
	v_pk_add_f32 v[240:241], v[240:241], v[92:93]
	v_pk_add_f32 v[242:243], v[242:243], v[96:97]
	v_pk_add_f32 v[236:237], v[236:237], v[98:99]
	v_pk_add_f32 v[238:239], v[238:239], v[102:103]
	v_pk_add_f32 v[240:241], v[240:241], v[106:107]
	v_pk_add_f32 v[242:243], v[242:243], v[110:111]
	v_pk_add_f32 v[236:237], v[236:237], v[100:101]
	v_pk_add_f32 v[238:239], v[238:239], v[104:105]
	v_pk_add_f32 v[240:241], v[240:241], v[108:109]
	v_pk_add_f32 v[242:243], v[242:243], v[112:113]
	v_pk_add_f32 v[236:237], v[236:237], v[114:115]
	v_pk_add_f32 v[236:237], v[236:237], v[116:117]
	v_pk_add_f32 v[236:237], v[236:237], v[238:239]
	v_pk_add_f32 v[240:241], v[240:241], v[242:243]
	v_cndmask_b32_e64 v219, 0, v219, s[74:75]
	v_pk_add_f32 v[236:237], v[236:237], v[240:241]
	v_add_f32_e32 v185, v236, v237
	v_add_f32_e32 v185, v185, v219
	v_cvt_pk_bf16_f32 v236, v50, v51
	v_cvt_pk_bf16_f32 v237, v52, v53
	v_cvt_pk_bf16_f32 v238, v54, v55
	v_cvt_pk_bf16_f32 v239, v56, v57
	s_nop 1
	s_waitcnt lgkmcnt(14)
; #define LAS __attribute__((address_space(3)))
; __device__ __forceinline__ unsigned pk2(float lo, float hi) { return pg8::cvt_pk_bf16(lo, hi); }
; __device__ __forceinline__ s16x4 vtr(const LAS unsigned char* p) { return __builtin_bit_cast(s16x4, __builtin_amdgcn_ds_read_tr16_b64_v4i16((LAS s16x4*)p)); }
; #define MFMA16(a, b, c) __builtin_amdgcn_mfma_f32_16x16x32_bf16((a), (b), (c), 0, 0, 0)
; __device__ __forceinline__ void pv_at(const LAS unsigned char* const (&vp)[4], int off, const f32x4& P0, const f32x4& P1, f32x4 (&O)[4]) {
;     v4u pw; pw.x = pk2(P0[0], P0[1]); pw.y = pk2(P0[2], P0[3]); pw.z = pk2(P1[0], P1[1]); pw.w = pk2(P1[2], P1[3]);
;     const bf16x8 pb = __builtin_bit_cast(bf16x8, pw);
; #pragma unroll
;     for (int db = 0; db < 4; ++db) {
;         const s16x4 lo = vtr(vp[db] + off), hi = vtr(vp[db] + off + 2048);
;         const bf16x8 vt = (bf16x8){lo[0], lo[1], lo[2], lo[3], hi[0], hi[1], hi[2], hi[3]};
;         O[db] = MFMA16(vt, pb, O[db]);
;     }
; }
	v_mfma_f32_16x16x32_bf16 v[210:213], v[186:189], v[236:239], 0
	s_waitcnt lgkmcnt(12)
	v_mfma_f32_16x16x32_bf16 v[214:217], v[190:193], v[236:239], 0
	s_waitcnt lgkmcnt(10)
	v_mfma_f32_16x16x32_bf16 v[220:223], v[194:197], v[236:239], 0
	s_waitcnt lgkmcnt(8)
	v_mfma_f32_16x16x32_bf16 v[224:227], v[198:201], v[236:239], 0
	v_cvt_pk_bf16_f32 v240, v58, v59
	v_cvt_pk_bf16_f32 v241, v60, v61
	v_cvt_pk_bf16_f32 v242, v62, v63
	v_cvt_pk_bf16_f32 v243, v64, v65
	s_waitcnt lgkmcnt(7)
	ds_read_b64_tr_b16 v[186:187], v124 offset:10240
	ds_read_b64_tr_b16 v[188:189], v124 offset:12288
	ds_read_b64_tr_b16 v[190:191], v125 offset:10240
	ds_read_b64_tr_b16 v[192:193], v125 offset:12288
	ds_read_b64_tr_b16 v[194:195], v126 offset:10240
	ds_read_b64_tr_b16 v[196:197], v126 offset:12288
	ds_read_b64_tr_b16 v[198:199], v127 offset:10240
	ds_read_b64_tr_b16 v[200:201], v127 offset:12288
	s_waitcnt lgkmcnt(14)
	v_mfma_f32_16x16x32_bf16 v[210:213], v[202:205], v[240:243], v[210:213]
	s_waitcnt lgkmcnt(12)
	v_mfma_f32_16x16x32_bf16 v[214:217], v[206:209], v[240:243], v[214:217]
	s_waitcnt lgkmcnt(10)
	v_mfma_f32_16x16x32_bf16 v[220:223], v[228:231], v[240:243], v[220:223]
	s_waitcnt lgkmcnt(8)
	v_mfma_f32_16x16x32_bf16 v[224:227], v[232:235], v[240:243], v[224:227]
	v_cvt_pk_bf16_f32 v236, v66, v67
	v_cvt_pk_bf16_f32 v237, v68, v69
	v_cvt_pk_bf16_f32 v238, v70, v71
	v_cvt_pk_bf16_f32 v239, v72, v73
	s_waitcnt lgkmcnt(7)
	ds_read_b64_tr_b16 v[202:203], v124 offset:14336
	ds_read_b64_tr_b16 v[204:205], v124 offset:16384
	ds_read_b64_tr_b16 v[206:207], v125 offset:14336
	ds_read_b64_tr_b16 v[208:209], v125 offset:16384
	ds_read_b64_tr_b16 v[228:229], v126 offset:14336
	ds_read_b64_tr_b16 v[230:231], v126 offset:16384
	ds_read_b64_tr_b16 v[232:233], v127 offset:14336
	ds_read_b64_tr_b16 v[234:235], v127 offset:16384
	s_waitcnt lgkmcnt(14)
	v_mfma_f32_16x16x32_bf16 v[210:213], v[186:189], v[236:239], v[210:213]
	s_waitcnt lgkmcnt(12)
	v_mfma_f32_16x16x32_bf16 v[214:217], v[190:193], v[236:239], v[214:217]
	s_waitcnt lgkmcnt(10)
	v_mfma_f32_16x16x32_bf16 v[220:223], v[194:197], v[236:239], v[220:223]
	s_waitcnt lgkmcnt(8)
	v_mfma_f32_16x16x32_bf16 v[224:227], v[198:201], v[236:239], v[224:227]
	v_cvt_pk_bf16_f32 v240, v74, v75
	v_cvt_pk_bf16_f32 v241, v76, v77
	v_cvt_pk_bf16_f32 v242, v78, v79
	v_cvt_pk_bf16_f32 v243, v80, v81
	s_waitcnt lgkmcnt(7)
	ds_read_b64_tr_b16 v[186:187], v124 offset:18432
	ds_read_b64_tr_b16 v[188:189], v124 offset:20480
	ds_read_b64_tr_b16 v[190:191], v125 offset:18432
	ds_read_b64_tr_b16 v[192:193], v125 offset:20480
	ds_read_b64_tr_b16 v[194:195], v126 offset:18432
	ds_read_b64_tr_b16 v[196:197], v126 offset:20480
	ds_read_b64_tr_b16 v[198:199], v127 offset:18432
	ds_read_b64_tr_b16 v[200:201], v127 offset:20480
	s_waitcnt lgkmcnt(14)
	v_mfma_f32_16x16x32_bf16 v[210:213], v[202:205], v[240:243], v[210:213]
	s_waitcnt lgkmcnt(12)
	v_mfma_f32_16x16x32_bf16 v[214:217], v[206:209], v[240:243], v[214:217]
	s_waitcnt lgkmcnt(10)
	v_mfma_f32_16x16x32_bf16 v[220:223], v[228:231], v[240:243], v[220:223]
	s_waitcnt lgkmcnt(8)
	v_mfma_f32_16x16x32_bf16 v[224:227], v[232:235], v[240:243], v[224:227]
	v_cvt_pk_bf16_f32 v236, v82, v83
	v_cvt_pk_bf16_f32 v237, v84, v85
	v_cvt_pk_bf16_f32 v238, v86, v87
	v_cvt_pk_bf16_f32 v239, v88, v89
	s_waitcnt lgkmcnt(7)
	ds_read_b64_tr_b16 v[202:203], v124 offset:22528
	ds_read_b64_tr_b16 v[204:205], v124 offset:24576
	ds_read_b64_tr_b16 v[206:207], v125 offset:22528
	ds_read_b64_tr_b16 v[208:209], v125 offset:24576
	ds_read_b64_tr_b16 v[228:229], v126 offset:22528
	ds_read_b64_tr_b16 v[230:231], v126 offset:24576
	ds_read_b64_tr_b16 v[232:233], v127 offset:22528
	ds_read_b64_tr_b16 v[234:235], v127 offset:24576
	s_waitcnt lgkmcnt(14)
	v_mfma_f32_16x16x32_bf16 v[210:213], v[186:189], v[236:239], v[210:213]
	s_waitcnt lgkmcnt(12)
	v_mfma_f32_16x16x32_bf16 v[214:217], v[190:193], v[236:239], v[214:217]
	s_waitcnt lgkmcnt(10)
	v_mfma_f32_16x16x32_bf16 v[220:223], v[194:197], v[236:239], v[220:223]
	s_waitcnt lgkmcnt(8)
	v_mfma_f32_16x16x32_bf16 v[224:227], v[198:201], v[236:239], v[224:227]
	v_cvt_pk_bf16_f32 v240, v90, v91
	v_cvt_pk_bf16_f32 v241, v92, v93
	v_cvt_pk_bf16_f32 v242, v94, v95
	v_cvt_pk_bf16_f32 v243, v96, v97
	s_waitcnt lgkmcnt(7)
	ds_read_b64_tr_b16 v[186:187], v124 offset:26624
	ds_read_b64_tr_b16 v[188:189], v124 offset:28672
	ds_read_b64_tr_b16 v[190:191], v125 offset:26624
	ds_read_b64_tr_b16 v[192:193], v125 offset:28672
	ds_read_b64_tr_b16 v[194:195], v126 offset:26624
	ds_read_b64_tr_b16 v[196:197], v126 offset:28672
	ds_read_b64_tr_b16 v[198:199], v127 offset:26624
	ds_read_b64_tr_b16 v[200:201], v127 offset:28672
	s_waitcnt lgkmcnt(14)
	v_mfma_f32_16x16x32_bf16 v[210:213], v[202:205], v[240:243], v[210:213]
	s_waitcnt lgkmcnt(12)
	v_mfma_f32_16x16x32_bf16 v[214:217], v[206:209], v[240:243], v[214:217]
	s_waitcnt lgkmcnt(10)
	v_mfma_f32_16x16x32_bf16 v[220:223], v[228:231], v[240:243], v[220:223]
	s_waitcnt lgkmcnt(8)
	v_mfma_f32_16x16x32_bf16 v[224:227], v[232:235], v[240:243], v[224:227]
	v_cvt_pk_bf16_f32 v236, v98, v99
	v_cvt_pk_bf16_f32 v237, v100, v101
	v_cvt_pk_bf16_f32 v238, v102, v103
	v_cvt_pk_bf16_f32 v239, v104, v105
	s_waitcnt lgkmcnt(7)
	ds_read_b64_tr_b16 v[202:203], v124 offset:30720
	ds_read_b64_tr_b16 v[204:205], v124 offset:32768
	ds_read_b64_tr_b16 v[206:207], v125 offset:30720
	ds_read_b64_tr_b16 v[208:209], v125 offset:32768
	ds_read_b64_tr_b16 v[228:229], v126 offset:30720
	ds_read_b64_tr_b16 v[230:231], v126 offset:32768
	ds_read_b64_tr_b16 v[232:233], v127 offset:30720
	ds_read_b64_tr_b16 v[234:235], v127 offset:32768
	s_waitcnt lgkmcnt(14)
; __device__ __forceinline__ unsigned pk2(float lo, float hi) { return pg8::cvt_pk_bf16(lo, hi); }
; __device__ __forceinline__ void store_o(bf16* yrow, int g, float l, const f32x4 (&O)[4]) {
;     const float inv = 1.0f / xrow16_sum(l);
;     unsigned wx[4], wy[4];
; #pragma unroll
;     for (int db = 0; db < 4; ++db) { wx[db] = pk2(O[db][0] * inv, O[db][1] * inv); wy[db] = pk2(O[db][2] * inv, O[db][3] * inv); }
; #pragma unroll
;     for (int p = 0; p < 2; ++p) {
;         auto rx = __builtin_amdgcn_permlane16_swap(wx[2 * p], wx[2 * p + 1], false, false); wx[2 * p] = rx[0]; wx[2 * p + 1] = rx[1];
;         auto ry = __builtin_amdgcn_permlane16_swap(wy[2 * p], wy[2 * p + 1], false, false); wy[2 * p] = ry[0]; wy[2 * p + 1] = ry[1]; }
; #pragma unroll
;     for (int p = 0; p < 2; ++p) {
;         auto rx = __builtin_amdgcn_permlane32_swap(wx[p], wx[p + 2], false, false); wx[p] = rx[0]; wx[p + 2] = rx[1];
;         auto ry = __builtin_amdgcn_permlane32_swap(wy[p], wy[p + 2], false, false); wy[p] = ry[0]; wy[p + 2] = ry[1]; }
;     v4u lo = {wx[0], wy[0], wx[1], wy[1]}, hi = {wx[2], wy[2], wx[3], wy[3]};
;     *(v4u*)(yrow + 16 * g) = lo; *(v4u*)(yrow + 16 * g + 8) = hi;
; }
; template <bool MASK> __device__ __forceinline__ void a_scores(f32x4& S0, f32x4& S1, float basef, float c1, float slope2, int krow0, int kstart) {
; #pragma unroll
;     for (int r = 0; r < 4; ++r) {
;         const float d0 = fabsf(basef - (float)r), d1 = fabsf(basef - (float)(16 + r));
;         const float v0 = S0[r] - slope2 * d0, v1 = S1[r] - slope2 * d1;
;         if (MASK) { const int p0 = kstart + krow0 + r, p1 = p0 + 16;
;             S0[r] = (d0 <= 128.f && p0 >= 0 && p0 < SEQ) ? v0 : -INFINITY; S1[r] = (d1 <= 128.f && p1 >= 0 && p1 < SEQ) ? v1 : -INFINITY; }
;         else { S0[r] = v0; S1[r] = v1; }
;     }
; }
	v_mfma_f32_16x16x32_bf16 v[210:213], v[186:189], v[236:239], v[210:213]
	s_waitcnt lgkmcnt(12)
	v_mfma_f32_16x16x32_bf16 v[214:217], v[190:193], v[236:239], v[214:217]
	s_waitcnt lgkmcnt(10)
	v_mfma_f32_16x16x32_bf16 v[220:223], v[194:197], v[236:239], v[220:223]
	s_waitcnt lgkmcnt(8)
	v_mfma_f32_16x16x32_bf16 v[224:227], v[198:201], v[236:239], v[224:227]
	v_cvt_pk_bf16_f32 v240, v106, v107
	v_cvt_pk_bf16_f32 v241, v108, v109
	v_cvt_pk_bf16_f32 v242, v110, v111
	v_cvt_pk_bf16_f32 v243, v112, v113
	s_waitcnt lgkmcnt(7)
	ds_read_b64_tr_b16 v[186:187], v124 offset:34816
	ds_read_b64_tr_b16 v[188:189], v124 offset:36864
	ds_read_b64_tr_b16 v[190:191], v125 offset:34816
	ds_read_b64_tr_b16 v[192:193], v125 offset:36864
	ds_read_b64_tr_b16 v[194:195], v126 offset:34816
	ds_read_b64_tr_b16 v[196:197], v126 offset:36864
	ds_read_b64_tr_b16 v[198:199], v127 offset:34816
	ds_read_b64_tr_b16 v[200:201], v127 offset:36864
	s_waitcnt lgkmcnt(14)
	v_mfma_f32_16x16x32_bf16 v[210:213], v[202:205], v[240:243], v[210:213]
	s_waitcnt lgkmcnt(12)
	v_mfma_f32_16x16x32_bf16 v[214:217], v[206:209], v[240:243], v[214:217]
	s_waitcnt lgkmcnt(10)
	v_mfma_f32_16x16x32_bf16 v[220:223], v[228:231], v[240:243], v[220:223]
	s_waitcnt lgkmcnt(8)
	v_mfma_f32_16x16x32_bf16 v[224:227], v[232:235], v[240:243], v[224:227]
	v_cvt_pk_bf16_f32 v236, v114, v115
	v_cvt_pk_bf16_f32 v237, v116, v117
	v_mov_b32_e32 v238, 0
	v_mov_b32_e32 v239, 0
	s_nop 1
	s_waitcnt lgkmcnt(6)
	v_mfma_f32_16x16x32_bf16 v[210:213], v[186:189], v[236:239], v[210:213]
	s_waitcnt lgkmcnt(4)
	v_mfma_f32_16x16x32_bf16 v[214:217], v[190:193], v[236:239], v[214:217]
	s_waitcnt lgkmcnt(2)
	v_mfma_f32_16x16x32_bf16 v[220:223], v[194:197], v[236:239], v[220:223]
	s_waitcnt lgkmcnt(0)
	v_mfma_f32_16x16x32_bf16 v[224:227], v[198:201], v[236:239], v[224:227]
	v_mov_b32_e32 v219, v185
	s_nop 1
	v_permlane16_swap_b32_e32 v185, v219
	v_add_f32_e32 v185, v185, v219
	v_mov_b32_e32 v219, v185
	s_nop 1
	v_permlane32_swap_b32_e32 v185, v219
	v_add_f32_e32 v185, v185, v219
	v_div_scale_f32 v236, s[78:79], v185, v185, 1.0
	v_div_scale_f32 v237, vcc, 1.0, v185, 1.0
	v_rcp_f32_e32 v238, v236
	s_nop 0
	v_fma_f32 v239, -v236, v238, 1.0
	v_fmac_f32_e32 v238, v239, v238
	v_mul_f32_e32 v240, v237, v238
	v_fma_f32 v241, -v236, v240, v237
	v_fmac_f32_e32 v240, v241, v238
	v_fma_f32 v237, -v236, v240, v237
	v_div_fmas_f32 v237, v237, v238, v240
	v_div_fixup_f32 v244, v237, v185, 1.0
	v_mul_f32_e32 v240, v210, v244
	v_mul_f32_e32 v241, v211, v244
	v_mul_f32_e32 v242, v212, v244
	v_mul_f32_e32 v243, v213, v244
	v_cvt_pk_bf16_f32 v186, v240, v241
	v_cvt_pk_bf16_f32 v187, v242, v243
	v_mul_f32_e32 v240, v214, v244
	v_mul_f32_e32 v241, v215, v244
	v_mul_f32_e32 v242, v216, v244
	v_mul_f32_e32 v243, v217, v244
	v_cvt_pk_bf16_f32 v188, v240, v241
	v_cvt_pk_bf16_f32 v189, v242, v243
	v_mul_f32_e32 v240, v220, v244
	v_mul_f32_e32 v241, v221, v244
	v_mul_f32_e32 v242, v222, v244
	v_mul_f32_e32 v243, v223, v244
	v_cvt_pk_bf16_f32 v190, v240, v241
	v_cvt_pk_bf16_f32 v191, v242, v243
	v_mul_f32_e32 v240, v224, v244
	v_mul_f32_e32 v241, v225, v244
	v_mul_f32_e32 v242, v226, v244
	v_mul_f32_e32 v243, v227, v244
	v_cvt_pk_bf16_f32 v192, v240, v241
	v_cvt_pk_bf16_f32 v193, v242, v243
	s_nop 1
	v_permlane16_swap_b32_e32 v186, v188
	v_permlane16_swap_b32_e32 v187, v189
	v_permlane16_swap_b32_e32 v190, v192
	v_permlane16_swap_b32_e32 v191, v193
	s_nop 0
	v_permlane32_swap_b32_e32 v186, v190
	v_permlane32_swap_b32_e32 v187, v191
	v_permlane32_swap_b32_e32 v188, v192
	v_permlane32_swap_b32_e32 v189, v193
	global_store_dwordx4 v128, v[186:189], s[82:83] offset:2048
	global_store_dwordx4 v128, v[190:193], s[82:83] offset:2064
	s_nop 1
	s_bitcmp1_b32 s87, 2
	s_cselect_b32 s21, 0, 0xff800000
	v_add_f32_e32 v120, s21, v132
	v_fmamk_f32 v50, v130, 0x43000000, v120
	v_fmamk_f32 v51, v130, 0x42fe0000, v120
	v_fmamk_f32 v52, v130, 0x42fc0000, v120
	v_fmamk_f32 v53, v130, 0x42fa0000, v120
	s_bitcmp1_b32 s87, 3
	s_cselect_b32 s21, 0, 0xff800000
	v_add_f32_e32 v120, s21, v132
	v_fmamk_f32 v54, v130, 0x42e00000, v120
	v_fmamk_f32 v55, v130, 0x42de0000, v120
	v_fmamk_f32 v56, v130, 0x42dc0000, v120
	v_fmamk_f32 v57, v130, 0x42da0000, v120
	s_bitcmp1_b32 s87, 4
	s_cselect_b32 s21, 0, 0xff800000
	v_add_f32_e32 v120, s21, v132
	v_fmamk_f32 v58, v130, 0x42c00000, v120
	v_fmamk_f32 v59, v130, 0x42be0000, v120
	v_fmamk_f32 v60, v130, 0x42bc0000, v120
	v_fmamk_f32 v61, v130, 0x42ba0000, v120
	s_bitcmp1_b32 s87, 5
	s_cselect_b32 s21, 0, 0xff800000
	v_add_f32_e32 v120, s21, v132
	v_fmamk_f32 v62, v130, 0x42a00000, v120
	v_fmamk_f32 v63, v130, 0x429e0000, v120
	v_fmamk_f32 v64, v130, 0x429c0000, v120
	v_fmamk_f32 v65, v130, 0x429a0000, v120
	s_bitcmp1_b32 s87, 6
	s_cselect_b32 s21, 0, 0xff800000
	v_add_f32_e32 v120, s21, v132
	v_fmamk_f32 v66, v130, 0x42800000, v120
	v_fmamk_f32 v67, v130, 0x427c0000, v120
	v_fmamk_f32 v68, v130, 0x42780000, v120
	v_fmamk_f32 v69, v130, 0x42740000, v120
	s_bitcmp1_b32 s87, 7
	s_cselect_b32 s21, 0, 0xff800000
	v_add_f32_e32 v120, s21, v132
	v_fmamk_f32 v70, v130, 0x42400000, v120
	v_fmamk_f32 v71, v130, 0x423c0000, v120
	v_fmamk_f32 v72, v130, 0x42380000, v120
	v_fmamk_f32 v73, v130, 0x42340000, v120
	s_bitcmp1_b32 s87, 8
	s_cselect_b32 s21, 0, 0xff800000
	v_add_f32_e32 v120, s21, v132
	v_fmamk_f32 v74, v130, 0x42000000, v120
	v_fmamk_f32 v75, v130, 0x41f80000, v120
	v_fmamk_f32 v76, v130, 0x41f00000, v120
	v_fmamk_f32 v77, v130, 0x41e80000, v120
	s_bitcmp1_b32 s87, 9
	s_cselect_b32 s21, 0, 0xff800000
	v_add_f32_e32 v120, s21, v132
	v_fmamk_f32 v78, v130, 0x41800000, v120
	v_fmamk_f32 v79, v130, 0x41700000, v120
	v_fmamk_f32 v80, v130, 0x41600000, v120
; #define LAS __attribute__((address_space(3)))
; #define MFMA16(a, b, c) __builtin_amdgcn_mfma_f32_16x16x32_bf16((a), (b), (c), 0, 0, 0)
; __device__ __forceinline__ void qk_at(const LAS unsigned char* kp0, const LAS unsigned char* kp1, int off, bf16x8 qf0, bf16x8 qf1, f32x4& S0, f32x4& S1) {
;     const bf16x8 k00 = *(const LAS bf16x8*)(kp0 + off), k01 = *(const LAS bf16x8*)(kp1 + off);
;     const bf16x8 k10 = *(const LAS bf16x8*)(kp0 + off + 2048), k11 = *(const LAS bf16x8*)(kp1 + off + 2048);
;     const f32x4 z = {0.f, 0.f, 0.f, 0.f};
;     S0 = MFMA16(k00, qf0, z); S0 = MFMA16(k01, qf1, S0);
;     S1 = MFMA16(k10, qf0, z); S1 = MFMA16(k11, qf1, S1);
; }
; template <bool MASK> __device__ __forceinline__ void a_scores(f32x4& S0, f32x4& S1, float basef, float c1, float slope2, int krow0, int kstart) {
; #pragma unroll
;     for (int r = 0; r < 4; ++r) {
;         const float d0 = fabsf(basef - (float)r), d1 = fabsf(basef - (float)(16 + r));
;         const float v0 = S0[r] - slope2 * d0, v1 = S1[r] - slope2 * d1;
;         if (MASK) { const int p0 = kstart + krow0 + r, p1 = p0 + 16;
;             S0[r] = (d0 <= 128.f && p0 >= 0 && p0 < SEQ) ? v0 : -INFINITY; S1[r] = (d1 <= 128.f && p1 >= 0 && p1 < SEQ) ? v1 : -INFINITY; }
;         else { S0[r] = v0; S1[r] = v1; }
;     }
; }
	v_fmamk_f32 v81, v130, 0x41500000, v120
	s_bitcmp1_b32 s87, 10
	s_cselect_b32 s21, 0, 0xff800000
	v_add_f32_e32 v219, 0, v129
	v_fma_f32 v82, v130, |v219|, s21
	v_add_f32_e32 v244, 0xbf800000, v129
	v_fma_f32 v83, v130, |v244|, s21
	v_add_f32_e32 v219, 0xc0000000, v129
	v_fma_f32 v84, v130, |v219|, s21
	v_add_f32_e32 v244, 0xc0400000, v129
	v_fma_f32 v85, v130, |v244|, s21
	s_bitcmp1_b32 s87, 11
	s_cselect_b32 s21, 0, 0xff800000
	v_add_f32_e32 v120, s21, v133
	v_fmamk_f32 v86, v131, 0xc1800000, v120
	v_fmamk_f32 v87, v131, 0xc1880000, v120
	v_fmamk_f32 v88, v131, 0xc1900000, v120
	v_fmamk_f32 v89, v131, 0xc1980000, v120
	s_bitcmp1_b32 s87, 12
	s_cselect_b32 s21, 0, 0xff800000
	v_add_f32_e32 v120, s21, v133
	v_fmamk_f32 v90, v131, 0xc2000000, v120
	v_fmamk_f32 v91, v131, 0xc2040000, v120
	v_fmamk_f32 v92, v131, 0xc2080000, v120
	v_fmamk_f32 v93, v131, 0xc20c0000, v120
	s_bitcmp1_b32 s87, 13
	s_cselect_b32 s21, 0, 0xff800000
	v_add_f32_e32 v120, s21, v133
	v_fmamk_f32 v94, v131, 0xc2400000, v120
	v_fmamk_f32 v95, v131, 0xc2440000, v120
	v_fmamk_f32 v96, v131, 0xc2480000, v120
	v_fmamk_f32 v97, v131, 0xc24c0000, v120
	s_bitcmp1_b32 s87, 14
	s_cselect_b32 s21, 0, 0xff800000
	v_add_f32_e32 v120, s21, v133
	v_fmamk_f32 v98, v131, 0xc2800000, v120
	v_fmamk_f32 v99, v131, 0xc2820000, v120
	v_fmamk_f32 v100, v131, 0xc2840000, v120
	v_fmamk_f32 v101, v131, 0xc2860000, v120
	s_bitcmp1_b32 s87, 15
	s_cselect_b32 s21, 0, 0xff800000
	v_add_f32_e32 v120, s21, v133
	v_fmamk_f32 v102, v131, 0xc2a00000, v120
	v_fmamk_f32 v103, v131, 0xc2a20000, v120
	v_fmamk_f32 v104, v131, 0xc2a40000, v120
	v_fmamk_f32 v105, v131, 0xc2a60000, v120
	s_bitcmp1_b32 s87, 16
	s_cselect_b32 s21, 0, 0xff800000
	v_add_f32_e32 v120, s21, v133
	v_fmamk_f32 v106, v131, 0xc2c00000, v120
	v_fmamk_f32 v107, v131, 0xc2c20000, v120
	v_fmamk_f32 v108, v131, 0xc2c40000, v120
	v_fmamk_f32 v109, v131, 0xc2c60000, v120
	s_bitcmp1_b32 s87, 17
	s_cselect_b32 s21, 0, 0xff800000
	v_add_f32_e32 v120, s21, v133
	v_fmamk_f32 v110, v131, 0xc2e00000, v120
	v_fmamk_f32 v111, v131, 0xc2e20000, v120
	v_fmamk_f32 v112, v131, 0xc2e40000, v120
	v_fmamk_f32 v113, v131, 0xc2e60000, v120
	s_bitcmp1_b32 s87, 18
	s_cselect_b32 s21, 0, 0xff800000
	v_add_f32_e32 v120, s21, v133
	v_fmamk_f32 v114, v131, 0xc3000000, v120
	v_fmamk_f32 v115, v131, 0xc3010000, v120
	v_fmamk_f32 v116, v131, 0xc3020000, v120
	v_fmamk_f32 v117, v131, 0xc3030000, v120
	v_mov_b32_e32 v245, 0xff800000
	v_cndmask_b32_e64 v50, v245, v50, s[16:17]
	v_cndmask_b32_e64 v51, v245, v51, s[18:19]
	v_cndmask_b32_e64 v52, v245, v52, s[22:23]
	v_cndmask_b32_e64 v53, v245, v53, s[24:25]
	v_cndmask_b32_e64 v114, v245, v114, s[28:29]
	v_cndmask_b32_e64 v115, v245, v115, s[52:53]
	v_cndmask_b32_e64 v116, v245, v116, s[54:55]
	v_cndmask_b32_e64 v117, v245, v117, s[88:89]
	ds_read_b128 v[186:189], v122 offset:4096
	ds_read_b128 v[190:193], v123 offset:4096
	ds_read_b128 v[194:197], v122 offset:6144
	ds_read_b128 v[198:201], v123 offset:6144
	ds_read_b128 v[202:205], v122 offset:8192
	ds_read_b128 v[206:209], v123 offset:8192
	s_waitcnt lgkmcnt(5)
	v_mfma_f32_16x16x32_bf16 v[50:53], v[186:189], v[162:165], v[50:53]
	s_waitcnt lgkmcnt(4)
	v_mfma_f32_16x16x32_bf16 v[50:53], v[190:193], v[166:169], v[50:53]
	ds_read_b128 v[186:189], v122 offset:10240
	ds_read_b128 v[190:193], v123 offset:10240
	s_waitcnt lgkmcnt(5)
	v_mfma_f32_16x16x32_bf16 v[54:57], v[194:197], v[162:165], v[54:57]
	s_waitcnt lgkmcnt(4)
	v_mfma_f32_16x16x32_bf16 v[54:57], v[198:201], v[166:169], v[54:57]
	ds_read_b128 v[194:197], v122 offset:12288
	ds_read_b128 v[198:201], v123 offset:12288
	s_waitcnt lgkmcnt(5)
	v_mfma_f32_16x16x32_bf16 v[58:61], v[202:205], v[162:165], v[58:61]
	s_waitcnt lgkmcnt(4)
	v_mfma_f32_16x16x32_bf16 v[58:61], v[206:209], v[166:169], v[58:61]
	ds_read_b128 v[202:205], v122 offset:14336
	ds_read_b128 v[206:209], v123 offset:14336
	s_waitcnt lgkmcnt(5)
	v_mfma_f32_16x16x32_bf16 v[62:65], v[186:189], v[162:165], v[62:65]
	s_waitcnt lgkmcnt(4)
	v_mfma_f32_16x16x32_bf16 v[62:65], v[190:193], v[166:169], v[62:65]
	ds_read_b128 v[186:189], v122 offset:16384
	ds_read_b128 v[190:193], v123 offset:16384
	s_waitcnt lgkmcnt(5)
	v_mfma_f32_16x16x32_bf16 v[66:69], v[194:197], v[162:165], v[66:69]
	s_waitcnt lgkmcnt(4)
	v_mfma_f32_16x16x32_bf16 v[66:69], v[198:201], v[166:169], v[66:69]
	ds_read_b128 v[194:197], v122 offset:18432
	ds_read_b128 v[198:201], v123 offset:18432
	s_waitcnt lgkmcnt(5)
	v_mfma_f32_16x16x32_bf16 v[70:73], v[202:205], v[162:165], v[70:73]
	s_waitcnt lgkmcnt(4)
	v_mfma_f32_16x16x32_bf16 v[70:73], v[206:209], v[166:169], v[70:73]
	ds_read_b128 v[202:205], v122 offset:20480
	ds_read_b128 v[206:209], v123 offset:20480
	s_waitcnt lgkmcnt(5)
	v_mfma_f32_16x16x32_bf16 v[74:77], v[186:189], v[162:165], v[74:77]
	s_waitcnt lgkmcnt(4)
	v_mfma_f32_16x16x32_bf16 v[74:77], v[190:193], v[166:169], v[74:77]
	ds_read_b128 v[186:189], v122 offset:22528
	ds_read_b128 v[190:193], v123 offset:22528
	s_waitcnt lgkmcnt(5)
	v_mfma_f32_16x16x32_bf16 v[78:81], v[194:197], v[162:165], v[78:81]
	s_waitcnt lgkmcnt(4)
	v_mfma_f32_16x16x32_bf16 v[78:81], v[198:201], v[166:169], v[78:81]
	ds_read_b128 v[194:197], v122 offset:24576
	ds_read_b128 v[198:201], v123 offset:24576
	s_waitcnt lgkmcnt(5)
	v_mfma_f32_16x16x32_bf16 v[82:85], v[202:205], v[162:165], v[82:85]
	s_waitcnt lgkmcnt(4)
	v_mfma_f32_16x16x32_bf16 v[82:85], v[206:209], v[166:169], v[82:85]
	ds_read_b128 v[202:205], v122 offset:26624
	ds_read_b128 v[206:209], v123 offset:26624
	s_waitcnt lgkmcnt(5)
	v_mfma_f32_16x16x32_bf16 v[86:89], v[186:189], v[162:165], v[86:89]
	s_waitcnt lgkmcnt(4)
; __device__ __forceinline__ void qk_at(const LAS unsigned char* kp0, const LAS unsigned char* kp1, int off, bf16x8 qf0, bf16x8 qf1, f32x4& S0, f32x4& S1) {
;     const bf16x8 k00 = *(const LAS bf16x8*)(kp0 + off), k01 = *(const LAS bf16x8*)(kp1 + off);
;     const bf16x8 k10 = *(const LAS bf16x8*)(kp0 + off + 2048), k11 = *(const LAS bf16x8*)(kp1 + off + 2048);
;     const f32x4 z = {0.f, 0.f, 0.f, 0.f};
;     S0 = MFMA16(k00, qf0, z); S0 = MFMA16(k01, qf1, S0);
;     S1 = MFMA16(k10, qf0, z); S1 = MFMA16(k11, qf1, S1);
; }
; __device__ __forceinline__ void pv_at(const LAS unsigned char* const (&vp)[4], int off, const f32x4& P0, const f32x4& P1, f32x4 (&O)[4]) {
;     v4u pw; pw.x = pk2(P0[0], P0[1]); pw.y = pk2(P0[2], P0[3]); pw.z = pk2(P1[0], P1[1]); pw.w = pk2(P1[2], P1[3]);
;     const bf16x8 pb = __builtin_bit_cast(bf16x8, pw);
; #pragma unroll
;     for (int db = 0; db < 4; ++db) {
;         const s16x4 lo = vtr(vp[db] + off), hi = vtr(vp[db] + off + 2048);
;         const bf16x8 vt = (bf16x8){lo[0], lo[1], lo[2], lo[3], hi[0], hi[1], hi[2], hi[3]};
;         O[db] = MFMA16(vt, pb, O[db]);
;     }
; }
; __device__ __forceinline__ float xrow16_max(float x) {
;     auto s = __builtin_amdgcn_permlane16_swap(__float_as_uint(x), __float_as_uint(x), false, false);
;     x = fmaxf(__uint_as_float(s[0]), __uint_as_float(s[1]));
;     auto t = __builtin_amdgcn_permlane32_swap(__float_as_uint(x), __float_as_uint(x), false, false);
;     return fmaxf(__uint_as_float(t[0]), __uint_as_float(t[1]));
; }
; __device__ __forceinline__ float xrow16_sum(float x) {
;     auto s = __builtin_amdgcn_permlane16_swap(__float_as_uint(x), __float_as_uint(x), false, false);
;     x = __uint_as_float(s[0]) + __uint_as_float(s[1]);
;     auto t = __builtin_amdgcn_permlane32_swap(__float_as_uint(x), __float_as_uint(x), false, false);
;     return __uint_as_float(t[0]) + __uint_as_float(t[1]);
; }
; __device__ __forceinline__ void softmax_step(f32x4& s0, f32x4& s1, float& m, float& l, f32x4 (&O)[4]) {
;     float t = fmaxf(fmaxf(fmaxf(s0[0], s0[1]), fmaxf(s0[2], s0[3])), fmaxf(fmaxf(s1[0], s1[1]), fmaxf(s1[2], s1[3])));
;     t = xrow16_max(t);
;     const float mn = fmaxf(m, t), alpha = __builtin_amdgcn_exp2f(m - mn);
;     m = mn;
; #pragma unroll
;     for (int k = 0; k < 4; ++k) { s0[k] = __builtin_amdgcn_exp2f(s0[k] - mn); s1[k] = __builtin_amdgcn_exp2f(s1[k] - mn); }
	v_mfma_f32_16x16x32_bf16 v[86:89], v[190:193], v[166:169], v[86:89]
	ds_read_b128 v[186:189], v122 offset:28672
	ds_read_b128 v[190:193], v123 offset:28672
	s_waitcnt lgkmcnt(5)
	v_mfma_f32_16x16x32_bf16 v[90:93], v[194:197], v[162:165], v[90:93]
	s_waitcnt lgkmcnt(4)
	v_mfma_f32_16x16x32_bf16 v[90:93], v[198:201], v[166:169], v[90:93]
	ds_read_b128 v[194:197], v122 offset:30720
	ds_read_b128 v[198:201], v123 offset:30720
	s_waitcnt lgkmcnt(5)
	v_mfma_f32_16x16x32_bf16 v[94:97], v[202:205], v[162:165], v[94:97]
	s_waitcnt lgkmcnt(4)
	v_mfma_f32_16x16x32_bf16 v[94:97], v[206:209], v[166:169], v[94:97]
	ds_read_b128 v[202:205], v122 offset:32768
	ds_read_b128 v[206:209], v123 offset:32768
	s_waitcnt lgkmcnt(5)
	v_mfma_f32_16x16x32_bf16 v[98:101], v[186:189], v[162:165], v[98:101]
	s_waitcnt lgkmcnt(4)
	v_mfma_f32_16x16x32_bf16 v[98:101], v[190:193], v[166:169], v[98:101]
	ds_read_b128 v[186:189], v122 offset:34816
	ds_read_b128 v[190:193], v123 offset:34816
	s_waitcnt lgkmcnt(5)
	v_mfma_f32_16x16x32_bf16 v[102:105], v[194:197], v[162:165], v[102:105]
	s_waitcnt lgkmcnt(4)
	v_mfma_f32_16x16x32_bf16 v[102:105], v[198:201], v[166:169], v[102:105]
	ds_read_b128 v[194:197], v122 offset:36864
	ds_read_b128 v[198:201], v123 offset:36864
	s_waitcnt lgkmcnt(5)
	v_mfma_f32_16x16x32_bf16 v[106:109], v[202:205], v[162:165], v[106:109]
	s_waitcnt lgkmcnt(4)
	v_mfma_f32_16x16x32_bf16 v[106:109], v[206:209], v[166:169], v[106:109]
	s_waitcnt lgkmcnt(3)
	v_mfma_f32_16x16x32_bf16 v[110:113], v[186:189], v[162:165], v[110:113]
	s_waitcnt lgkmcnt(2)
	v_mfma_f32_16x16x32_bf16 v[110:113], v[190:193], v[166:169], v[110:113]
	s_waitcnt lgkmcnt(1)
	v_mfma_f32_16x16x32_bf16 v[114:117], v[194:197], v[162:165], v[114:117]
	s_waitcnt lgkmcnt(0)
	v_mfma_f32_16x16x32_bf16 v[114:117], v[198:201], v[166:169], v[114:117]
	v_max3_f32 v219, v50, v51, v52
	v_max3_f32 v244, v54, v55, v56
	v_max3_f32 v245, v58, v59, v60
	v_max3_f32 v120, v62, v63, v64
	v_max3_f32 v219, v219, v53, v66
	v_max3_f32 v244, v244, v57, v70
	v_max3_f32 v245, v245, v61, v74
	v_max3_f32 v120, v120, v65, v78
	v_max3_f32 v219, v219, v67, v68
	v_max3_f32 v244, v244, v71, v72
	v_max3_f32 v245, v245, v75, v76
	v_max3_f32 v120, v120, v79, v80
	ds_read_b64_tr_b16 v[186:187], v124 offset:4096
	ds_read_b64_tr_b16 v[188:189], v124 offset:6144
	ds_read_b64_tr_b16 v[190:191], v125 offset:4096
	ds_read_b64_tr_b16 v[192:193], v125 offset:6144
	ds_read_b64_tr_b16 v[194:195], v126 offset:4096
	ds_read_b64_tr_b16 v[196:197], v126 offset:6144
	ds_read_b64_tr_b16 v[198:199], v127 offset:4096
	ds_read_b64_tr_b16 v[200:201], v127 offset:6144
	v_max3_f32 v219, v219, v69, v82
	v_max3_f32 v244, v244, v73, v86
	v_max3_f32 v245, v245, v77, v90
	v_max3_f32 v120, v120, v81, v94
	v_max3_f32 v219, v219, v83, v84
	v_max3_f32 v244, v244, v87, v88
	v_max3_f32 v245, v245, v91, v92
	v_max3_f32 v120, v120, v95, v96
	v_max3_f32 v219, v219, v85, v98
	v_max3_f32 v244, v244, v89, v102
	v_max3_f32 v245, v245, v93, v106
	v_max3_f32 v120, v120, v97, v110
	v_max3_f32 v219, v219, v99, v100
	v_max3_f32 v244, v244, v103, v104
	v_max3_f32 v245, v245, v107, v108
	v_max3_f32 v120, v120, v111, v112
	v_max3_f32 v219, v219, v101, v114
	v_max3_f32 v219, v219, v115, v116
	v_max_f32_e32 v219, v219, v117
	v_max_f32_e32 v244, v244, v105
	v_max_f32_e32 v245, v245, v109
	v_max_f32_e32 v120, v120, v113
	v_max3_f32 v178, v219, v244, v245
	v_max_f32_e32 v178, v178, v120
	v_mov_b32_e32 v219, v178
	s_nop 1
	v_permlane16_swap_b32_e32 v178, v219
	v_max_f32_e32 v178, v178, v219
	v_mov_b32_e32 v219, v178
	s_nop 1
	v_permlane32_swap_b32_e32 v178, v219
	v_max3_f32 v178, v178, v219, v145
	s_waitcnt lgkmcnt(7)
	ds_read_b64_tr_b16 v[202:203], v124 offset:8192
	ds_read_b64_tr_b16 v[204:205], v124 offset:10240
	ds_read_b64_tr_b16 v[206:207], v125 offset:8192
	ds_read_b64_tr_b16 v[208:209], v125 offset:10240
	ds_read_b64_tr_b16 v[228:229], v126 offset:8192
	ds_read_b64_tr_b16 v[230:231], v126 offset:10240
	ds_read_b64_tr_b16 v[232:233], v127 offset:8192
	ds_read_b64_tr_b16 v[234:235], v127 offset:10240
	v_mov_b32_e32 v244, v178
	v_pk_add_f32 v[50:51], v[50:51], v[244:245] op_sel_hi:[1,0] neg_lo:[0,1] neg_hi:[0,1]
	v_pk_add_f32 v[52:53], v[52:53], v[244:245] op_sel_hi:[1,0] neg_lo:[0,1] neg_hi:[0,1]
	v_pk_add_f32 v[54:55], v[54:55], v[244:245] op_sel_hi:[1,0] neg_lo:[0,1] neg_hi:[0,1]
	v_pk_add_f32 v[56:57], v[56:57], v[244:245] op_sel_hi:[1,0] neg_lo:[0,1] neg_hi:[0,1]
	v_pk_add_f32 v[58:59], v[58:59], v[244:245] op_sel_hi:[1,0] neg_lo:[0,1] neg_hi:[0,1]
	v_pk_add_f32 v[60:61], v[60:61], v[244:245] op_sel_hi:[1,0] neg_lo:[0,1] neg_hi:[0,1]
	v_pk_add_f32 v[62:63], v[62:63], v[244:245] op_sel_hi:[1,0] neg_lo:[0,1] neg_hi:[0,1]
	v_pk_add_f32 v[64:65], v[64:65], v[244:245] op_sel_hi:[1,0] neg_lo:[0,1] neg_hi:[0,1]
	v_pk_add_f32 v[66:67], v[66:67], v[244:245] op_sel_hi:[1,0] neg_lo:[0,1] neg_hi:[0,1]
	v_pk_add_f32 v[68:69], v[68:69], v[244:245] op_sel_hi:[1,0] neg_lo:[0,1] neg_hi:[0,1]
	v_pk_add_f32 v[70:71], v[70:71], v[244:245] op_sel_hi:[1,0] neg_lo:[0,1] neg_hi:[0,1]
	v_pk_add_f32 v[72:73], v[72:73], v[244:245] op_sel_hi:[1,0] neg_lo:[0,1] neg_hi:[0,1]
	v_pk_add_f32 v[74:75], v[74:75], v[244:245] op_sel_hi:[1,0] neg_lo:[0,1] neg_hi:[0,1]
	v_pk_add_f32 v[76:77], v[76:77], v[244:245] op_sel_hi:[1,0] neg_lo:[0,1] neg_hi:[0,1]
	v_pk_add_f32 v[78:79], v[78:79], v[244:245] op_sel_hi:[1,0] neg_lo:[0,1] neg_hi:[0,1]
	v_pk_add_f32 v[80:81], v[80:81], v[244:245] op_sel_hi:[1,0] neg_lo:[0,1] neg_hi:[0,1]
	v_pk_add_f32 v[82:83], v[82:83], v[244:245] op_sel_hi:[1,0] neg_lo:[0,1] neg_hi:[0,1]
	v_pk_add_f32 v[84:85], v[84:85], v[244:245] op_sel_hi:[1,0] neg_lo:[0,1] neg_hi:[0,1]
; #define LAS __attribute__((address_space(3)))
; __device__ __forceinline__ unsigned pk2(float lo, float hi) { return pg8::cvt_pk_bf16(lo, hi); }
; __device__ __forceinline__ s16x4 vtr(const LAS unsigned char* p) { return __builtin_bit_cast(s16x4, __builtin_amdgcn_ds_read_tr16_b64_v4i16((LAS s16x4*)p)); }
; __device__ __forceinline__ void pv_at(const LAS unsigned char* const (&vp)[4], int off, const f32x4& P0, const f32x4& P1, f32x4 (&O)[4]) {
;     v4u pw; pw.x = pk2(P0[0], P0[1]); pw.y = pk2(P0[2], P0[3]); pw.z = pk2(P1[0], P1[1]); pw.w = pk2(P1[2], P1[3]);
;     const bf16x8 pb = __builtin_bit_cast(bf16x8, pw);
; #pragma unroll
;     for (int db = 0; db < 4; ++db) {
;         const s16x4 lo = vtr(vp[db] + off), hi = vtr(vp[db] + off + 2048);
;         const bf16x8 vt = (bf16x8){lo[0], lo[1], lo[2], lo[3], hi[0], hi[1], hi[2], hi[3]};
;         O[db] = MFMA16(vt, pb, O[db]);
;     }
; }
; __device__ __forceinline__ float xrow16_max(float x) {
;     auto s = __builtin_amdgcn_permlane16_swap(__float_as_uint(x), __float_as_uint(x), false, false);
;     x = fmaxf(__uint_as_float(s[0]), __uint_as_float(s[1]));
;     auto t = __builtin_amdgcn_permlane32_swap(__float_as_uint(x), __float_as_uint(x), false, false);
;     return fmaxf(__uint_as_float(t[0]), __uint_as_float(t[1]));
; }
; __device__ __forceinline__ float xrow16_sum(float x) {
;     auto s = __builtin_amdgcn_permlane16_swap(__float_as_uint(x), __float_as_uint(x), false, false);
;     x = __uint_as_float(s[0]) + __uint_as_float(s[1]);
;     auto t = __builtin_amdgcn_permlane32_swap(__float_as_uint(x), __float_as_uint(x), false, false);
;     return __uint_as_float(t[0]) + __uint_as_float(t[1]);
; }
; __device__ __forceinline__ void softmax_step(f32x4& s0, f32x4& s1, float& m, float& l, f32x4 (&O)[4]) {
;     float t = fmaxf(fmaxf(fmaxf(s0[0], s0[1]), fmaxf(s0[2], s0[3])), fmaxf(fmaxf(s1[0], s1[1]), fmaxf(s1[2], s1[3])));
;     t = xrow16_max(t);
;     const float mn = fmaxf(m, t), alpha = __builtin_amdgcn_exp2f(m - mn);
;     m = mn;
; #pragma unroll
;     for (int k = 0; k < 4; ++k) { s0[k] = __builtin_amdgcn_exp2f(s0[k] - mn); s1[k] = __builtin_amdgcn_exp2f(s1[k] - mn); }
;     l = l * alpha + ((s0[0] + s0[1]) + (s0[2] + s0[3])) + ((s1[0] + s1[1]) + (s1[2] + s1[3]));
; #pragma unroll
;     for (int db = 0; db < 4; ++db) O[db] *= alpha;
; }
	v_pk_add_f32 v[86:87], v[86:87], v[244:245] op_sel_hi:[1,0] neg_lo:[0,1] neg_hi:[0,1]
	v_pk_add_f32 v[88:89], v[88:89], v[244:245] op_sel_hi:[1,0] neg_lo:[0,1] neg_hi:[0,1]
	v_pk_add_f32 v[90:91], v[90:91], v[244:245] op_sel_hi:[1,0] neg_lo:[0,1] neg_hi:[0,1]
	v_pk_add_f32 v[92:93], v[92:93], v[244:245] op_sel_hi:[1,0] neg_lo:[0,1] neg_hi:[0,1]
	v_pk_add_f32 v[94:95], v[94:95], v[244:245] op_sel_hi:[1,0] neg_lo:[0,1] neg_hi:[0,1]
	v_pk_add_f32 v[96:97], v[96:97], v[244:245] op_sel_hi:[1,0] neg_lo:[0,1] neg_hi:[0,1]
	v_pk_add_f32 v[98:99], v[98:99], v[244:245] op_sel_hi:[1,0] neg_lo:[0,1] neg_hi:[0,1]
	v_pk_add_f32 v[100:101], v[100:101], v[244:245] op_sel_hi:[1,0] neg_lo:[0,1] neg_hi:[0,1]
	v_pk_add_f32 v[102:103], v[102:103], v[244:245] op_sel_hi:[1,0] neg_lo:[0,1] neg_hi:[0,1]
	v_pk_add_f32 v[104:105], v[104:105], v[244:245] op_sel_hi:[1,0] neg_lo:[0,1] neg_hi:[0,1]
	v_pk_add_f32 v[106:107], v[106:107], v[244:245] op_sel_hi:[1,0] neg_lo:[0,1] neg_hi:[0,1]
	v_pk_add_f32 v[108:109], v[108:109], v[244:245] op_sel_hi:[1,0] neg_lo:[0,1] neg_hi:[0,1]
	v_pk_add_f32 v[110:111], v[110:111], v[244:245] op_sel_hi:[1,0] neg_lo:[0,1] neg_hi:[0,1]
	v_pk_add_f32 v[112:113], v[112:113], v[244:245] op_sel_hi:[1,0] neg_lo:[0,1] neg_hi:[0,1]
	v_pk_add_f32 v[114:115], v[114:115], v[244:245] op_sel_hi:[1,0] neg_lo:[0,1] neg_hi:[0,1]
	v_pk_add_f32 v[116:117], v[116:117], v[244:245] op_sel_hi:[1,0] neg_lo:[0,1] neg_hi:[0,1]
	v_sub_f32_e32 v219, v145, v178
	v_exp_f32_e32 v50, v50
	v_exp_f32_e32 v51, v51
	v_exp_f32_e32 v52, v52
	v_exp_f32_e32 v53, v53
	v_exp_f32_e32 v54, v54
	v_exp_f32_e32 v55, v55
	v_exp_f32_e32 v56, v56
	v_exp_f32_e32 v57, v57
	v_exp_f32_e32 v58, v58
	v_exp_f32_e32 v59, v59
	v_exp_f32_e32 v60, v60
	v_exp_f32_e32 v61, v61
	v_exp_f32_e32 v62, v62
	v_exp_f32_e32 v63, v63
	v_exp_f32_e32 v64, v64
	v_exp_f32_e32 v65, v65
	v_exp_f32_e32 v66, v66
	v_exp_f32_e32 v67, v67
	v_exp_f32_e32 v68, v68
	v_exp_f32_e32 v69, v69
	v_exp_f32_e32 v70, v70
	v_exp_f32_e32 v71, v71
	v_exp_f32_e32 v72, v72
	v_exp_f32_e32 v73, v73
	v_exp_f32_e32 v74, v74
	v_exp_f32_e32 v75, v75
	v_exp_f32_e32 v76, v76
	v_exp_f32_e32 v77, v77
	v_exp_f32_e32 v78, v78
	v_exp_f32_e32 v79, v79
	v_exp_f32_e32 v80, v80
	v_exp_f32_e32 v81, v81
	v_exp_f32_e32 v82, v82
	v_exp_f32_e32 v83, v83
	v_exp_f32_e32 v84, v84
	v_exp_f32_e32 v85, v85
	v_exp_f32_e32 v86, v86
	v_exp_f32_e32 v87, v87
	v_exp_f32_e32 v88, v88
	v_exp_f32_e32 v89, v89
	v_exp_f32_e32 v90, v90
	v_exp_f32_e32 v91, v91
	v_exp_f32_e32 v92, v92
	v_exp_f32_e32 v93, v93
	v_exp_f32_e32 v94, v94
	v_exp_f32_e32 v95, v95
	v_exp_f32_e32 v96, v96
	v_exp_f32_e32 v97, v97
	v_exp_f32_e32 v98, v98
	v_exp_f32_e32 v99, v99
	v_exp_f32_e32 v100, v100
	v_exp_f32_e32 v101, v101
	v_exp_f32_e32 v102, v102
	v_exp_f32_e32 v103, v103
	v_exp_f32_e32 v104, v104
	v_exp_f32_e32 v105, v105
	v_exp_f32_e32 v106, v106
	v_exp_f32_e32 v107, v107
	v_exp_f32_e32 v108, v108
	v_exp_f32_e32 v109, v109
	v_exp_f32_e32 v110, v110
	v_exp_f32_e32 v111, v111
	v_exp_f32_e32 v112, v112
	v_exp_f32_e32 v113, v113
	v_exp_f32_e32 v114, v114
	v_exp_f32_e32 v115, v115
	v_exp_f32_e32 v116, v116
	v_exp_f32_e32 v117, v117
	v_exp_f32_e32 v219, v219
	v_pk_add_f32 v[236:237], v[50:51], v[52:53]
	v_pk_add_f32 v[238:239], v[54:55], v[56:57]
	v_pk_add_f32 v[240:241], v[58:59], v[60:61]
	v_pk_add_f32 v[242:243], v[62:63], v[64:65]
	v_pk_add_f32 v[236:237], v[236:237], v[66:67]
	v_pk_add_f32 v[238:239], v[238:239], v[70:71]
	v_pk_add_f32 v[240:241], v[240:241], v[74:75]
	v_pk_add_f32 v[242:243], v[242:243], v[78:79]
	v_pk_add_f32 v[236:237], v[236:237], v[68:69]
	v_pk_add_f32 v[238:239], v[238:239], v[72:73]
	v_pk_add_f32 v[240:241], v[240:241], v[76:77]
	v_pk_add_f32 v[242:243], v[242:243], v[80:81]
	v_pk_add_f32 v[236:237], v[236:237], v[82:83]
	v_pk_add_f32 v[238:239], v[238:239], v[86:87]
	v_pk_add_f32 v[240:241], v[240:241], v[90:91]
	v_pk_add_f32 v[242:243], v[242:243], v[94:95]
	v_pk_add_f32 v[236:237], v[236:237], v[84:85]
	v_pk_add_f32 v[238:239], v[238:239], v[88:89]
	v_pk_add_f32 v[240:241], v[240:241], v[92:93]
	v_pk_add_f32 v[242:243], v[242:243], v[96:97]
	v_pk_add_f32 v[236:237], v[236:237], v[98:99]
	v_pk_add_f32 v[238:239], v[238:239], v[102:103]
	v_pk_add_f32 v[240:241], v[240:241], v[106:107]
	v_pk_add_f32 v[242:243], v[242:243], v[110:111]
	v_pk_add_f32 v[236:237], v[236:237], v[100:101]
	v_pk_add_f32 v[238:239], v[238:239], v[104:105]
	v_pk_add_f32 v[240:241], v[240:241], v[108:109]
	v_pk_add_f32 v[242:243], v[242:243], v[112:113]
	v_pk_add_f32 v[236:237], v[236:237], v[114:115]
	v_pk_add_f32 v[236:237], v[236:237], v[116:117]
	v_pk_add_f32 v[236:237], v[236:237], v[238:239]
	v_pk_add_f32 v[240:241], v[240:241], v[242:243]
	v_cndmask_b32_e64 v219, 0, v219, s[74:75]
	v_pk_add_f32 v[236:237], v[236:237], v[240:241]
	v_add_f32_e32 v185, v236, v237
	v_add_f32_e32 v185, v185, v219
	v_cvt_pk_bf16_f32 v236, v50, v51
	v_cvt_pk_bf16_f32 v237, v52, v53
	v_cvt_pk_bf16_f32 v238, v54, v55
	v_cvt_pk_bf16_f32 v239, v56, v57
	s_nop 1
	s_waitcnt lgkmcnt(14)
	v_mfma_f32_16x16x32_bf16 v[210:213], v[186:189], v[236:239], 0
	s_waitcnt lgkmcnt(12)
	v_mfma_f32_16x16x32_bf16 v[214:217], v[190:193], v[236:239], 0
	s_waitcnt lgkmcnt(10)
	v_mfma_f32_16x16x32_bf16 v[220:223], v[194:197], v[236:239], 0
	s_waitcnt lgkmcnt(8)
	v_mfma_f32_16x16x32_bf16 v[224:227], v[198:201], v[236:239], 0
	v_cvt_pk_bf16_f32 v240, v58, v59
	v_cvt_pk_bf16_f32 v241, v60, v61
	v_cvt_pk_bf16_f32 v242, v62, v63
	v_cvt_pk_bf16_f32 v243, v64, v65
	s_waitcnt lgkmcnt(7)
; #define LAS __attribute__((address_space(3)))
; __device__ __forceinline__ unsigned pk2(float lo, float hi) { return pg8::cvt_pk_bf16(lo, hi); }
; __device__ __forceinline__ s16x4 vtr(const LAS unsigned char* p) { return __builtin_bit_cast(s16x4, __builtin_amdgcn_ds_read_tr16_b64_v4i16((LAS s16x4*)p)); }
; #define MFMA16(a, b, c) __builtin_amdgcn_mfma_f32_16x16x32_bf16((a), (b), (c), 0, 0, 0)
; __device__ __forceinline__ void pv_at(const LAS unsigned char* const (&vp)[4], int off, const f32x4& P0, const f32x4& P1, f32x4 (&O)[4]) {
;     v4u pw; pw.x = pk2(P0[0], P0[1]); pw.y = pk2(P0[2], P0[3]); pw.z = pk2(P1[0], P1[1]); pw.w = pk2(P1[2], P1[3]);
;     const bf16x8 pb = __builtin_bit_cast(bf16x8, pw);
; #pragma unroll
;     for (int db = 0; db < 4; ++db) {
;         const s16x4 lo = vtr(vp[db] + off), hi = vtr(vp[db] + off + 2048);
;         const bf16x8 vt = (bf16x8){lo[0], lo[1], lo[2], lo[3], hi[0], hi[1], hi[2], hi[3]};
;         O[db] = MFMA16(vt, pb, O[db]);
;     }
; }
	ds_read_b64_tr_b16 v[186:187], v124 offset:12288
	ds_read_b64_tr_b16 v[188:189], v124 offset:14336
	ds_read_b64_tr_b16 v[190:191], v125 offset:12288
	ds_read_b64_tr_b16 v[192:193], v125 offset:14336
	ds_read_b64_tr_b16 v[194:195], v126 offset:12288
	ds_read_b64_tr_b16 v[196:197], v126 offset:14336
	ds_read_b64_tr_b16 v[198:199], v127 offset:12288
	ds_read_b64_tr_b16 v[200:201], v127 offset:14336
	s_waitcnt lgkmcnt(14)
	v_mfma_f32_16x16x32_bf16 v[210:213], v[202:205], v[240:243], v[210:213]
	s_waitcnt lgkmcnt(12)
	v_mfma_f32_16x16x32_bf16 v[214:217], v[206:209], v[240:243], v[214:217]
	s_waitcnt lgkmcnt(10)
	v_mfma_f32_16x16x32_bf16 v[220:223], v[228:231], v[240:243], v[220:223]
	s_waitcnt lgkmcnt(8)
	v_mfma_f32_16x16x32_bf16 v[224:227], v[232:235], v[240:243], v[224:227]
	v_cvt_pk_bf16_f32 v236, v66, v67
	v_cvt_pk_bf16_f32 v237, v68, v69
	v_cvt_pk_bf16_f32 v238, v70, v71
	v_cvt_pk_bf16_f32 v239, v72, v73
	s_waitcnt lgkmcnt(7)
	ds_read_b64_tr_b16 v[202:203], v124 offset:16384
	ds_read_b64_tr_b16 v[204:205], v124 offset:18432
	ds_read_b64_tr_b16 v[206:207], v125 offset:16384
	ds_read_b64_tr_b16 v[208:209], v125 offset:18432
	ds_read_b64_tr_b16 v[228:229], v126 offset:16384
	ds_read_b64_tr_b16 v[230:231], v126 offset:18432
	ds_read_b64_tr_b16 v[232:233], v127 offset:16384
	ds_read_b64_tr_b16 v[234:235], v127 offset:18432
	s_waitcnt lgkmcnt(14)
	v_mfma_f32_16x16x32_bf16 v[210:213], v[186:189], v[236:239], v[210:213]
	s_waitcnt lgkmcnt(12)
	v_mfma_f32_16x16x32_bf16 v[214:217], v[190:193], v[236:239], v[214:217]
	s_waitcnt lgkmcnt(10)
	v_mfma_f32_16x16x32_bf16 v[220:223], v[194:197], v[236:239], v[220:223]
	s_waitcnt lgkmcnt(8)
	v_mfma_f32_16x16x32_bf16 v[224:227], v[198:201], v[236:239], v[224:227]
	v_cvt_pk_bf16_f32 v240, v74, v75
	v_cvt_pk_bf16_f32 v241, v76, v77
	v_cvt_pk_bf16_f32 v242, v78, v79
	v_cvt_pk_bf16_f32 v243, v80, v81
	s_waitcnt lgkmcnt(7)
	ds_read_b64_tr_b16 v[186:187], v124 offset:20480
	ds_read_b64_tr_b16 v[188:189], v124 offset:22528
	ds_read_b64_tr_b16 v[190:191], v125 offset:20480
	ds_read_b64_tr_b16 v[192:193], v125 offset:22528
	ds_read_b64_tr_b16 v[194:195], v126 offset:20480
	ds_read_b64_tr_b16 v[196:197], v126 offset:22528
	ds_read_b64_tr_b16 v[198:199], v127 offset:20480
	ds_read_b64_tr_b16 v[200:201], v127 offset:22528
	s_waitcnt lgkmcnt(14)
	v_mfma_f32_16x16x32_bf16 v[210:213], v[202:205], v[240:243], v[210:213]
	s_waitcnt lgkmcnt(12)
	v_mfma_f32_16x16x32_bf16 v[214:217], v[206:209], v[240:243], v[214:217]
	s_waitcnt lgkmcnt(10)
	v_mfma_f32_16x16x32_bf16 v[220:223], v[228:231], v[240:243], v[220:223]
	s_waitcnt lgkmcnt(8)
	v_mfma_f32_16x16x32_bf16 v[224:227], v[232:235], v[240:243], v[224:227]
	v_cvt_pk_bf16_f32 v236, v82, v83
	v_cvt_pk_bf16_f32 v237, v84, v85
	v_cvt_pk_bf16_f32 v238, v86, v87
	v_cvt_pk_bf16_f32 v239, v88, v89
	s_waitcnt lgkmcnt(7)
	ds_read_b64_tr_b16 v[202:203], v124 offset:24576
	ds_read_b64_tr_b16 v[204:205], v124 offset:26624
	ds_read_b64_tr_b16 v[206:207], v125 offset:24576
	ds_read_b64_tr_b16 v[208:209], v125 offset:26624
	ds_read_b64_tr_b16 v[228:229], v126 offset:24576
	ds_read_b64_tr_b16 v[230:231], v126 offset:26624
	ds_read_b64_tr_b16 v[232:233], v127 offset:24576
	ds_read_b64_tr_b16 v[234:235], v127 offset:26624
	s_waitcnt lgkmcnt(14)
	v_mfma_f32_16x16x32_bf16 v[210:213], v[186:189], v[236:239], v[210:213]
	s_waitcnt lgkmcnt(12)
	v_mfma_f32_16x16x32_bf16 v[214:217], v[190:193], v[236:239], v[214:217]
	s_waitcnt lgkmcnt(10)
	v_mfma_f32_16x16x32_bf16 v[220:223], v[194:197], v[236:239], v[220:223]
	s_waitcnt lgkmcnt(8)
	v_mfma_f32_16x16x32_bf16 v[224:227], v[198:201], v[236:239], v[224:227]
	v_cvt_pk_bf16_f32 v240, v90, v91
	v_cvt_pk_bf16_f32 v241, v92, v93
	v_cvt_pk_bf16_f32 v242, v94, v95
	v_cvt_pk_bf16_f32 v243, v96, v97
	s_waitcnt lgkmcnt(7)
	ds_read_b64_tr_b16 v[186:187], v124 offset:28672
	ds_read_b64_tr_b16 v[188:189], v124 offset:30720
	ds_read_b64_tr_b16 v[190:191], v125 offset:28672
	ds_read_b64_tr_b16 v[192:193], v125 offset:30720
	ds_read_b64_tr_b16 v[194:195], v126 offset:28672
	ds_read_b64_tr_b16 v[196:197], v126 offset:30720
	ds_read_b64_tr_b16 v[198:199], v127 offset:28672
	ds_read_b64_tr_b16 v[200:201], v127 offset:30720
	s_waitcnt lgkmcnt(14)
	v_mfma_f32_16x16x32_bf16 v[210:213], v[202:205], v[240:243], v[210:213]
	s_waitcnt lgkmcnt(12)
	v_mfma_f32_16x16x32_bf16 v[214:217], v[206:209], v[240:243], v[214:217]
	s_waitcnt lgkmcnt(10)
	v_mfma_f32_16x16x32_bf16 v[220:223], v[228:231], v[240:243], v[220:223]
	s_waitcnt lgkmcnt(8)
	v_mfma_f32_16x16x32_bf16 v[224:227], v[232:235], v[240:243], v[224:227]
	v_cvt_pk_bf16_f32 v236, v98, v99
	v_cvt_pk_bf16_f32 v237, v100, v101
	v_cvt_pk_bf16_f32 v238, v102, v103
	v_cvt_pk_bf16_f32 v239, v104, v105
	s_waitcnt lgkmcnt(7)
	ds_read_b64_tr_b16 v[202:203], v124 offset:32768
	ds_read_b64_tr_b16 v[204:205], v124 offset:34816
	ds_read_b64_tr_b16 v[206:207], v125 offset:32768
	ds_read_b64_tr_b16 v[208:209], v125 offset:34816
	ds_read_b64_tr_b16 v[228:229], v126 offset:32768
	ds_read_b64_tr_b16 v[230:231], v126 offset:34816
	ds_read_b64_tr_b16 v[232:233], v127 offset:32768
	ds_read_b64_tr_b16 v[234:235], v127 offset:34816
	s_waitcnt lgkmcnt(14)
	v_mfma_f32_16x16x32_bf16 v[210:213], v[186:189], v[236:239], v[210:213]
	s_waitcnt lgkmcnt(12)
	v_mfma_f32_16x16x32_bf16 v[214:217], v[190:193], v[236:239], v[214:217]
	s_waitcnt lgkmcnt(10)
	v_mfma_f32_16x16x32_bf16 v[220:223], v[194:197], v[236:239], v[220:223]
	s_waitcnt lgkmcnt(8)
	v_mfma_f32_16x16x32_bf16 v[224:227], v[198:201], v[236:239], v[224:227]
	v_cvt_pk_bf16_f32 v240, v106, v107
	v_cvt_pk_bf16_f32 v241, v108, v109
	v_cvt_pk_bf16_f32 v242, v110, v111
	v_cvt_pk_bf16_f32 v243, v112, v113
	s_waitcnt lgkmcnt(7)
; __device__ __forceinline__ unsigned pk2(float lo, float hi) { return pg8::cvt_pk_bf16(lo, hi); }
; __device__ __forceinline__ void store_o(bf16* yrow, int g, float l, const f32x4 (&O)[4]) {
;     const float inv = 1.0f / xrow16_sum(l);
;     unsigned wx[4], wy[4];
; #pragma unroll
;     for (int db = 0; db < 4; ++db) { wx[db] = pk2(O[db][0] * inv, O[db][1] * inv); wy[db] = pk2(O[db][2] * inv, O[db][3] * inv); }
; #pragma unroll
;     for (int p = 0; p < 2; ++p) {
;         auto rx = __builtin_amdgcn_permlane16_swap(wx[2 * p], wx[2 * p + 1], false, false); wx[2 * p] = rx[0]; wx[2 * p + 1] = rx[1];
;         auto ry = __builtin_amdgcn_permlane16_swap(wy[2 * p], wy[2 * p + 1], false, false); wy[2 * p] = ry[0]; wy[2 * p + 1] = ry[1]; }
; #pragma unroll
;     for (int p = 0; p < 2; ++p) {
;         auto rx = __builtin_amdgcn_permlane32_swap(wx[p], wx[p + 2], false, false); wx[p] = rx[0]; wx[p + 2] = rx[1];
;         auto ry = __builtin_amdgcn_permlane32_swap(wy[p], wy[p + 2], false, false); wy[p] = ry[0]; wy[p + 2] = ry[1]; }
;     v4u lo = {wx[0], wy[0], wx[1], wy[1]}, hi = {wx[2], wy[2], wx[3], wy[3]};
;     *(v4u*)(yrow + 16 * g) = lo; *(v4u*)(yrow + 16 * g + 8) = hi;
; }
; template <bool MASK> __device__ __forceinline__ void a_scores(f32x4& S0, f32x4& S1, float basef, float c1, float slope2, int krow0, int kstart) {
; #pragma unroll
;     for (int r = 0; r < 4; ++r) {
;         const float d0 = fabsf(basef - (float)r), d1 = fabsf(basef - (float)(16 + r));
;         const float v0 = S0[r] - slope2 * d0, v1 = S1[r] - slope2 * d1;
;         if (MASK) { const int p0 = kstart + krow0 + r, p1 = p0 + 16;
;             S0[r] = (d0 <= 128.f && p0 >= 0 && p0 < SEQ) ? v0 : -INFINITY; S1[r] = (d1 <= 128.f && p1 >= 0 && p1 < SEQ) ? v1 : -INFINITY; }
;         else { S0[r] = v0; S1[r] = v1; }
;     }
; }
	ds_read_b64_tr_b16 v[186:187], v124 offset:36864
	ds_read_b64_tr_b16 v[188:189], v124 offset:38912
	ds_read_b64_tr_b16 v[190:191], v125 offset:36864
	ds_read_b64_tr_b16 v[192:193], v125 offset:38912
	ds_read_b64_tr_b16 v[194:195], v126 offset:36864
	ds_read_b64_tr_b16 v[196:197], v126 offset:38912
	ds_read_b64_tr_b16 v[198:199], v127 offset:36864
	ds_read_b64_tr_b16 v[200:201], v127 offset:38912
	s_waitcnt lgkmcnt(14)
	v_mfma_f32_16x16x32_bf16 v[210:213], v[202:205], v[240:243], v[210:213]
	s_waitcnt lgkmcnt(12)
	v_mfma_f32_16x16x32_bf16 v[214:217], v[206:209], v[240:243], v[214:217]
	s_waitcnt lgkmcnt(10)
	v_mfma_f32_16x16x32_bf16 v[220:223], v[228:231], v[240:243], v[220:223]
	s_waitcnt lgkmcnt(8)
	v_mfma_f32_16x16x32_bf16 v[224:227], v[232:235], v[240:243], v[224:227]
	v_cvt_pk_bf16_f32 v236, v114, v115
	v_cvt_pk_bf16_f32 v237, v116, v117
	v_mov_b32_e32 v238, 0
	v_mov_b32_e32 v239, 0
	s_nop 1
	s_waitcnt lgkmcnt(6)
	v_mfma_f32_16x16x32_bf16 v[210:213], v[186:189], v[236:239], v[210:213]
	s_waitcnt lgkmcnt(4)
	v_mfma_f32_16x16x32_bf16 v[214:217], v[190:193], v[236:239], v[214:217]
	s_waitcnt lgkmcnt(2)
	v_mfma_f32_16x16x32_bf16 v[220:223], v[194:197], v[236:239], v[220:223]
	s_waitcnt lgkmcnt(0)
	v_mfma_f32_16x16x32_bf16 v[224:227], v[198:201], v[236:239], v[224:227]
	v_mov_b32_e32 v219, v185
	s_nop 1
	v_permlane16_swap_b32_e32 v185, v219
	v_add_f32_e32 v185, v185, v219
	v_mov_b32_e32 v219, v185
	s_nop 1
	v_permlane32_swap_b32_e32 v185, v219
	v_add_f32_e32 v185, v185, v219
	v_div_scale_f32 v236, s[78:79], v185, v185, 1.0
	v_div_scale_f32 v237, vcc, 1.0, v185, 1.0
	v_rcp_f32_e32 v238, v236
	s_nop 0
	v_fma_f32 v239, -v236, v238, 1.0
	v_fmac_f32_e32 v238, v239, v238
	v_mul_f32_e32 v240, v237, v238
	v_fma_f32 v241, -v236, v240, v237
	v_fmac_f32_e32 v240, v241, v238
	v_fma_f32 v237, -v236, v240, v237
	v_div_fmas_f32 v237, v237, v238, v240
	v_div_fixup_f32 v244, v237, v185, 1.0
	v_mul_f32_e32 v240, v210, v244
	v_mul_f32_e32 v241, v211, v244
	v_mul_f32_e32 v242, v212, v244
	v_mul_f32_e32 v243, v213, v244
	v_cvt_pk_bf16_f32 v186, v240, v241
	v_cvt_pk_bf16_f32 v187, v242, v243
	v_mul_f32_e32 v240, v214, v244
	v_mul_f32_e32 v241, v215, v244
	v_mul_f32_e32 v242, v216, v244
	v_mul_f32_e32 v243, v217, v244
	v_cvt_pk_bf16_f32 v188, v240, v241
	v_cvt_pk_bf16_f32 v189, v242, v243
	v_mul_f32_e32 v240, v220, v244
	v_mul_f32_e32 v241, v221, v244
	v_mul_f32_e32 v242, v222, v244
	v_mul_f32_e32 v243, v223, v244
	v_cvt_pk_bf16_f32 v190, v240, v241
	v_cvt_pk_bf16_f32 v191, v242, v243
	v_mul_f32_e32 v240, v224, v244
	v_mul_f32_e32 v241, v225, v244
	v_mul_f32_e32 v242, v226, v244
	v_mul_f32_e32 v243, v227, v244
	v_cvt_pk_bf16_f32 v192, v240, v241
	v_cvt_pk_bf16_f32 v193, v242, v243
	s_nop 1
	v_permlane16_swap_b32_e32 v186, v188
	v_permlane16_swap_b32_e32 v187, v189
	v_permlane16_swap_b32_e32 v190, v192
	v_permlane16_swap_b32_e32 v191, v193
	s_nop 0
	v_permlane32_swap_b32_e32 v186, v190
	v_permlane32_swap_b32_e32 v187, v191
	v_permlane32_swap_b32_e32 v188, v192
	v_permlane32_swap_b32_e32 v189, v193
	v_add_u32_e32 v219, 0x1000, v128
	global_store_dwordx4 v219, v[186:189], s[82:83] offset:0
	global_store_dwordx4 v219, v[190:193], s[82:83] offset:16
	s_nop 1
	s_bitcmp1_b32 s87, 3
	s_cselect_b32 s21, 0, 0xff800000
	v_add_f32_e32 v120, s21, v132
	v_fmamk_f32 v50, v130, 0x43000000, v120
	v_fmamk_f32 v51, v130, 0x42fe0000, v120
	v_fmamk_f32 v52, v130, 0x42fc0000, v120
	v_fmamk_f32 v53, v130, 0x42fa0000, v120
	s_bitcmp1_b32 s87, 4
	s_cselect_b32 s21, 0, 0xff800000
	v_add_f32_e32 v120, s21, v132
	v_fmamk_f32 v54, v130, 0x42e00000, v120
	v_fmamk_f32 v55, v130, 0x42de0000, v120
	v_fmamk_f32 v56, v130, 0x42dc0000, v120
	v_fmamk_f32 v57, v130, 0x42da0000, v120
	s_bitcmp1_b32 s87, 5
	s_cselect_b32 s21, 0, 0xff800000
	v_add_f32_e32 v120, s21, v132
	v_fmamk_f32 v58, v130, 0x42c00000, v120
	v_fmamk_f32 v59, v130, 0x42be0000, v120
	v_fmamk_f32 v60, v130, 0x42bc0000, v120
	v_fmamk_f32 v61, v130, 0x42ba0000, v120
	s_bitcmp1_b32 s87, 6
	s_cselect_b32 s21, 0, 0xff800000
	v_add_f32_e32 v120, s21, v132
	v_fmamk_f32 v62, v130, 0x42a00000, v120
	v_fmamk_f32 v63, v130, 0x429e0000, v120
	v_fmamk_f32 v64, v130, 0x429c0000, v120
	v_fmamk_f32 v65, v130, 0x429a0000, v120
	s_bitcmp1_b32 s87, 7
	s_cselect_b32 s21, 0, 0xff800000
	v_add_f32_e32 v120, s21, v132
	v_fmamk_f32 v66, v130, 0x42800000, v120
	v_fmamk_f32 v67, v130, 0x427c0000, v120
	v_fmamk_f32 v68, v130, 0x42780000, v120
	v_fmamk_f32 v69, v130, 0x42740000, v120
	s_bitcmp1_b32 s87, 8
	s_cselect_b32 s21, 0, 0xff800000
	v_add_f32_e32 v120, s21, v132
	v_fmamk_f32 v70, v130, 0x42400000, v120
	v_fmamk_f32 v71, v130, 0x423c0000, v120
	v_fmamk_f32 v72, v130, 0x42380000, v120
	v_fmamk_f32 v73, v130, 0x42340000, v120
	s_bitcmp1_b32 s87, 9
	s_cselect_b32 s21, 0, 0xff800000
	v_add_f32_e32 v120, s21, v132
	v_fmamk_f32 v74, v130, 0x42000000, v120
	v_fmamk_f32 v75, v130, 0x41f80000, v120
	v_fmamk_f32 v76, v130, 0x41f00000, v120
	v_fmamk_f32 v77, v130, 0x41e80000, v120
	s_bitcmp1_b32 s87, 10
	s_cselect_b32 s21, 0, 0xff800000
	v_add_f32_e32 v120, s21, v132
	v_fmamk_f32 v78, v130, 0x41800000, v120
	v_fmamk_f32 v79, v130, 0x41700000, v120
	v_fmamk_f32 v80, v130, 0x41600000, v120
	v_fmamk_f32 v81, v130, 0x41500000, v120
	s_bitcmp1_b32 s87, 11
	s_cselect_b32 s21, 0, 0xff800000
	v_add_f32_e32 v219, 0, v129
	v_fma_f32 v82, v130, |v219|, s21
	v_add_f32_e32 v244, 0xbf800000, v129
	v_fma_f32 v83, v130, |v244|, s21
	v_add_f32_e32 v219, 0xc0000000, v129
	v_fma_f32 v84, v130, |v219|, s21
	v_add_f32_e32 v244, 0xc0400000, v129
	v_fma_f32 v85, v130, |v244|, s21
	s_bitcmp1_b32 s87, 12
	s_cselect_b32 s21, 0, 0xff800000
	v_add_f32_e32 v120, s21, v133
; #define LAS __attribute__((address_space(3)))
; #define MFMA16(a, b, c) __builtin_amdgcn_mfma_f32_16x16x32_bf16((a), (b), (c), 0, 0, 0)
; __device__ __forceinline__ void qk_at(const LAS unsigned char* kp0, const LAS unsigned char* kp1, int off, bf16x8 qf0, bf16x8 qf1, f32x4& S0, f32x4& S1) {
;     const bf16x8 k00 = *(const LAS bf16x8*)(kp0 + off), k01 = *(const LAS bf16x8*)(kp1 + off);
;     const bf16x8 k10 = *(const LAS bf16x8*)(kp0 + off + 2048), k11 = *(const LAS bf16x8*)(kp1 + off + 2048);
;     const f32x4 z = {0.f, 0.f, 0.f, 0.f};
;     S0 = MFMA16(k00, qf0, z); S0 = MFMA16(k01, qf1, S0);
;     S1 = MFMA16(k10, qf0, z); S1 = MFMA16(k11, qf1, S1);
; }
; template <bool MASK> __device__ __forceinline__ void a_scores(f32x4& S0, f32x4& S1, float basef, float c1, float slope2, int krow0, int kstart) {
; #pragma unroll
;     for (int r = 0; r < 4; ++r) {
;         const float d0 = fabsf(basef - (float)r), d1 = fabsf(basef - (float)(16 + r));
;         const float v0 = S0[r] - slope2 * d0, v1 = S1[r] - slope2 * d1;
;         if (MASK) { const int p0 = kstart + krow0 + r, p1 = p0 + 16;
;             S0[r] = (d0 <= 128.f && p0 >= 0 && p0 < SEQ) ? v0 : -INFINITY; S1[r] = (d1 <= 128.f && p1 >= 0 && p1 < SEQ) ? v1 : -INFINITY; }
;         else { S0[r] = v0; S1[r] = v1; }
;     }
; }
	v_fmamk_f32 v86, v131, 0xc1800000, v120
	v_fmamk_f32 v87, v131, 0xc1880000, v120
	v_fmamk_f32 v88, v131, 0xc1900000, v120
	v_fmamk_f32 v89, v131, 0xc1980000, v120
	s_bitcmp1_b32 s87, 13
	s_cselect_b32 s21, 0, 0xff800000
	v_add_f32_e32 v120, s21, v133
	v_fmamk_f32 v90, v131, 0xc2000000, v120
	v_fmamk_f32 v91, v131, 0xc2040000, v120
	v_fmamk_f32 v92, v131, 0xc2080000, v120
	v_fmamk_f32 v93, v131, 0xc20c0000, v120
	s_bitcmp1_b32 s87, 14
	s_cselect_b32 s21, 0, 0xff800000
	v_add_f32_e32 v120, s21, v133
	v_fmamk_f32 v94, v131, 0xc2400000, v120
	v_fmamk_f32 v95, v131, 0xc2440000, v120
	v_fmamk_f32 v96, v131, 0xc2480000, v120
	v_fmamk_f32 v97, v131, 0xc24c0000, v120
	s_bitcmp1_b32 s87, 15
	s_cselect_b32 s21, 0, 0xff800000
	v_add_f32_e32 v120, s21, v133
	v_fmamk_f32 v98, v131, 0xc2800000, v120
	v_fmamk_f32 v99, v131, 0xc2820000, v120
	v_fmamk_f32 v100, v131, 0xc2840000, v120
	v_fmamk_f32 v101, v131, 0xc2860000, v120
	s_bitcmp1_b32 s87, 16
	s_cselect_b32 s21, 0, 0xff800000
	v_add_f32_e32 v120, s21, v133
	v_fmamk_f32 v102, v131, 0xc2a00000, v120
	v_fmamk_f32 v103, v131, 0xc2a20000, v120
	v_fmamk_f32 v104, v131, 0xc2a40000, v120
	v_fmamk_f32 v105, v131, 0xc2a60000, v120
	s_bitcmp1_b32 s87, 17
	s_cselect_b32 s21, 0, 0xff800000
	v_add_f32_e32 v120, s21, v133
	v_fmamk_f32 v106, v131, 0xc2c00000, v120
	v_fmamk_f32 v107, v131, 0xc2c20000, v120
	v_fmamk_f32 v108, v131, 0xc2c40000, v120
	v_fmamk_f32 v109, v131, 0xc2c60000, v120
	s_bitcmp1_b32 s87, 18
	s_cselect_b32 s21, 0, 0xff800000
	v_add_f32_e32 v120, s21, v133
	v_fmamk_f32 v110, v131, 0xc2e00000, v120
	v_fmamk_f32 v111, v131, 0xc2e20000, v120
	v_fmamk_f32 v112, v131, 0xc2e40000, v120
	v_fmamk_f32 v113, v131, 0xc2e60000, v120
	s_bitcmp1_b32 s87, 19
	s_cselect_b32 s21, 0, 0xff800000
	v_add_f32_e32 v120, s21, v133
	v_fmamk_f32 v114, v131, 0xc3000000, v120
	v_fmamk_f32 v115, v131, 0xc3010000, v120
	v_fmamk_f32 v116, v131, 0xc3020000, v120
	v_fmamk_f32 v117, v131, 0xc3030000, v120
	v_mov_b32_e32 v245, 0xff800000
	v_cndmask_b32_e64 v50, v245, v50, s[16:17]
	v_cndmask_b32_e64 v51, v245, v51, s[18:19]
	v_cndmask_b32_e64 v52, v245, v52, s[22:23]
	v_cndmask_b32_e64 v53, v245, v53, s[24:25]
	v_cndmask_b32_e64 v114, v245, v114, s[28:29]
	v_cndmask_b32_e64 v115, v245, v115, s[52:53]
	v_cndmask_b32_e64 v116, v245, v116, s[54:55]
	v_cndmask_b32_e64 v117, v245, v117, s[88:89]
	ds_read_b128 v[186:189], v122 offset:6144
	ds_read_b128 v[190:193], v123 offset:6144
	ds_read_b128 v[194:197], v122 offset:8192
	ds_read_b128 v[198:201], v123 offset:8192
	ds_read_b128 v[202:205], v122 offset:10240
	ds_read_b128 v[206:209], v123 offset:10240
	s_waitcnt lgkmcnt(5)
	v_mfma_f32_16x16x32_bf16 v[50:53], v[186:189], v[170:173], v[50:53]
	s_waitcnt lgkmcnt(4)
	v_mfma_f32_16x16x32_bf16 v[50:53], v[190:193], v[174:177], v[50:53]
	ds_read_b128 v[186:189], v122 offset:12288
	ds_read_b128 v[190:193], v123 offset:12288
	s_waitcnt lgkmcnt(5)
	v_mfma_f32_16x16x32_bf16 v[54:57], v[194:197], v[170:173], v[54:57]
	s_waitcnt lgkmcnt(4)
	v_mfma_f32_16x16x32_bf16 v[54:57], v[198:201], v[174:177], v[54:57]
	ds_read_b128 v[194:197], v122 offset:14336
	ds_read_b128 v[198:201], v123 offset:14336
	s_waitcnt lgkmcnt(5)
	v_mfma_f32_16x16x32_bf16 v[58:61], v[202:205], v[170:173], v[58:61]
	s_waitcnt lgkmcnt(4)
	v_mfma_f32_16x16x32_bf16 v[58:61], v[206:209], v[174:177], v[58:61]
	ds_read_b128 v[202:205], v122 offset:16384
	ds_read_b128 v[206:209], v123 offset:16384
	s_waitcnt lgkmcnt(5)
	v_mfma_f32_16x16x32_bf16 v[62:65], v[186:189], v[170:173], v[62:65]
	s_waitcnt lgkmcnt(4)
	v_mfma_f32_16x16x32_bf16 v[62:65], v[190:193], v[174:177], v[62:65]
	ds_read_b128 v[186:189], v122 offset:18432
	ds_read_b128 v[190:193], v123 offset:18432
	s_waitcnt lgkmcnt(5)
	v_mfma_f32_16x16x32_bf16 v[66:69], v[194:197], v[170:173], v[66:69]
	s_waitcnt lgkmcnt(4)
	v_mfma_f32_16x16x32_bf16 v[66:69], v[198:201], v[174:177], v[66:69]
	ds_read_b128 v[194:197], v122 offset:20480
	ds_read_b128 v[198:201], v123 offset:20480
	s_waitcnt lgkmcnt(5)
	v_mfma_f32_16x16x32_bf16 v[70:73], v[202:205], v[170:173], v[70:73]
	s_waitcnt lgkmcnt(4)
	v_mfma_f32_16x16x32_bf16 v[70:73], v[206:209], v[174:177], v[70:73]
	ds_read_b128 v[202:205], v122 offset:22528
	ds_read_b128 v[206:209], v123 offset:22528
	s_waitcnt lgkmcnt(5)
	v_mfma_f32_16x16x32_bf16 v[74:77], v[186:189], v[170:173], v[74:77]
	s_waitcnt lgkmcnt(4)
	v_mfma_f32_16x16x32_bf16 v[74:77], v[190:193], v[174:177], v[74:77]
	ds_read_b128 v[186:189], v122 offset:24576
	ds_read_b128 v[190:193], v123 offset:24576
	s_waitcnt lgkmcnt(5)
	v_mfma_f32_16x16x32_bf16 v[78:81], v[194:197], v[170:173], v[78:81]
	s_waitcnt lgkmcnt(4)
	v_mfma_f32_16x16x32_bf16 v[78:81], v[198:201], v[174:177], v[78:81]
	ds_read_b128 v[194:197], v122 offset:26624
	ds_read_b128 v[198:201], v123 offset:26624
	s_waitcnt lgkmcnt(5)
	v_mfma_f32_16x16x32_bf16 v[82:85], v[202:205], v[170:173], v[82:85]
	s_waitcnt lgkmcnt(4)
	v_mfma_f32_16x16x32_bf16 v[82:85], v[206:209], v[174:177], v[82:85]
	ds_read_b128 v[202:205], v122 offset:28672
	ds_read_b128 v[206:209], v123 offset:28672
	s_waitcnt lgkmcnt(5)
	v_mfma_f32_16x16x32_bf16 v[86:89], v[186:189], v[170:173], v[86:89]
	s_waitcnt lgkmcnt(4)
	v_mfma_f32_16x16x32_bf16 v[86:89], v[190:193], v[174:177], v[86:89]
	ds_read_b128 v[186:189], v122 offset:30720
	ds_read_b128 v[190:193], v123 offset:30720
	s_waitcnt lgkmcnt(5)
	v_mfma_f32_16x16x32_bf16 v[90:93], v[194:197], v[170:173], v[90:93]
	s_waitcnt lgkmcnt(4)
	v_mfma_f32_16x16x32_bf16 v[90:93], v[198:201], v[174:177], v[90:93]
	ds_read_b128 v[194:197], v122 offset:32768
	ds_read_b128 v[198:201], v123 offset:32768
	s_waitcnt lgkmcnt(5)
	v_mfma_f32_16x16x32_bf16 v[94:97], v[202:205], v[170:173], v[94:97]
	s_waitcnt lgkmcnt(4)
; __device__ __forceinline__ void qk_at(const LAS unsigned char* kp0, const LAS unsigned char* kp1, int off, bf16x8 qf0, bf16x8 qf1, f32x4& S0, f32x4& S1) {
;     const bf16x8 k00 = *(const LAS bf16x8*)(kp0 + off), k01 = *(const LAS bf16x8*)(kp1 + off);
;     const bf16x8 k10 = *(const LAS bf16x8*)(kp0 + off + 2048), k11 = *(const LAS bf16x8*)(kp1 + off + 2048);
;     const f32x4 z = {0.f, 0.f, 0.f, 0.f};
;     S0 = MFMA16(k00, qf0, z); S0 = MFMA16(k01, qf1, S0);
;     S1 = MFMA16(k10, qf0, z); S1 = MFMA16(k11, qf1, S1);
; }
; __device__ __forceinline__ void pv_at(const LAS unsigned char* const (&vp)[4], int off, const f32x4& P0, const f32x4& P1, f32x4 (&O)[4]) {
;     v4u pw; pw.x = pk2(P0[0], P0[1]); pw.y = pk2(P0[2], P0[3]); pw.z = pk2(P1[0], P1[1]); pw.w = pk2(P1[2], P1[3]);
;     const bf16x8 pb = __builtin_bit_cast(bf16x8, pw);
; #pragma unroll
;     for (int db = 0; db < 4; ++db) {
;         const s16x4 lo = vtr(vp[db] + off), hi = vtr(vp[db] + off + 2048);
;         const bf16x8 vt = (bf16x8){lo[0], lo[1], lo[2], lo[3], hi[0], hi[1], hi[2], hi[3]};
;         O[db] = MFMA16(vt, pb, O[db]);
;     }
; }
; __device__ __forceinline__ float xrow16_max(float x) {
;     auto s = __builtin_amdgcn_permlane16_swap(__float_as_uint(x), __float_as_uint(x), false, false);
;     x = fmaxf(__uint_as_float(s[0]), __uint_as_float(s[1]));
;     auto t = __builtin_amdgcn_permlane32_swap(__float_as_uint(x), __float_as_uint(x), false, false);
;     return fmaxf(__uint_as_float(t[0]), __uint_as_float(t[1]));
; }
; __device__ __forceinline__ float xrow16_sum(float x) {
;     auto s = __builtin_amdgcn_permlane16_swap(__float_as_uint(x), __float_as_uint(x), false, false);
;     x = __uint_as_float(s[0]) + __uint_as_float(s[1]);
;     auto t = __builtin_amdgcn_permlane32_swap(__float_as_uint(x), __float_as_uint(x), false, false);
;     return __uint_as_float(t[0]) + __uint_as_float(t[1]);
; }
; __device__ __forceinline__ void softmax_step(f32x4& s0, f32x4& s1, float& m, float& l, f32x4 (&O)[4]) {
;     float t = fmaxf(fmaxf(fmaxf(s0[0], s0[1]), fmaxf(s0[2], s0[3])), fmaxf(fmaxf(s1[0], s1[1]), fmaxf(s1[2], s1[3])));
;     t = xrow16_max(t);
;     const float mn = fmaxf(m, t), alpha = __builtin_amdgcn_exp2f(m - mn);
;     m = mn;
; #pragma unroll
;     for (int k = 0; k < 4; ++k) { s0[k] = __builtin_amdgcn_exp2f(s0[k] - mn); s1[k] = __builtin_amdgcn_exp2f(s1[k] - mn); }
	v_mfma_f32_16x16x32_bf16 v[94:97], v[206:209], v[174:177], v[94:97]
	ds_read_b128 v[202:205], v122 offset:34816
	ds_read_b128 v[206:209], v123 offset:34816
	s_waitcnt lgkmcnt(5)
	v_mfma_f32_16x16x32_bf16 v[98:101], v[186:189], v[170:173], v[98:101]
	s_waitcnt lgkmcnt(4)
	v_mfma_f32_16x16x32_bf16 v[98:101], v[190:193], v[174:177], v[98:101]
	ds_read_b128 v[186:189], v122 offset:36864
	ds_read_b128 v[190:193], v123 offset:36864
	s_waitcnt lgkmcnt(5)
	v_mfma_f32_16x16x32_bf16 v[102:105], v[194:197], v[170:173], v[102:105]
	s_waitcnt lgkmcnt(4)
	v_mfma_f32_16x16x32_bf16 v[102:105], v[198:201], v[174:177], v[102:105]
	ds_read_b128 v[194:197], v122 offset:38912
	ds_read_b128 v[198:201], v123 offset:38912
	s_waitcnt lgkmcnt(5)
	v_mfma_f32_16x16x32_bf16 v[106:109], v[202:205], v[170:173], v[106:109]
	s_waitcnt lgkmcnt(4)
	v_mfma_f32_16x16x32_bf16 v[106:109], v[206:209], v[174:177], v[106:109]
	s_waitcnt lgkmcnt(3)
	v_mfma_f32_16x16x32_bf16 v[110:113], v[186:189], v[170:173], v[110:113]
	s_waitcnt lgkmcnt(2)
	v_mfma_f32_16x16x32_bf16 v[110:113], v[190:193], v[174:177], v[110:113]
	s_waitcnt lgkmcnt(1)
	v_mfma_f32_16x16x32_bf16 v[114:117], v[194:197], v[170:173], v[114:117]
	s_waitcnt lgkmcnt(0)
	v_mfma_f32_16x16x32_bf16 v[114:117], v[198:201], v[174:177], v[114:117]
	v_max3_f32 v219, v50, v51, v52
	v_max3_f32 v244, v54, v55, v56
	v_max3_f32 v245, v58, v59, v60
	v_max3_f32 v120, v62, v63, v64
	v_max3_f32 v219, v219, v53, v66
	v_max3_f32 v244, v244, v57, v70
	v_max3_f32 v245, v245, v61, v74
	v_max3_f32 v120, v120, v65, v78
	v_max3_f32 v219, v219, v67, v68
	v_max3_f32 v244, v244, v71, v72
	v_max3_f32 v245, v245, v75, v76
	v_max3_f32 v120, v120, v79, v80
	ds_read_b64_tr_b16 v[186:187], v124 offset:6144
	ds_read_b64_tr_b16 v[188:189], v124 offset:8192
	ds_read_b64_tr_b16 v[190:191], v125 offset:6144
	ds_read_b64_tr_b16 v[192:193], v125 offset:8192
	ds_read_b64_tr_b16 v[194:195], v126 offset:6144
	ds_read_b64_tr_b16 v[196:197], v126 offset:8192
	ds_read_b64_tr_b16 v[198:199], v127 offset:6144
	ds_read_b64_tr_b16 v[200:201], v127 offset:8192
	v_max3_f32 v219, v219, v69, v82
	v_max3_f32 v244, v244, v73, v86
	v_max3_f32 v245, v245, v77, v90
	v_max3_f32 v120, v120, v81, v94
	v_max3_f32 v219, v219, v83, v84
	v_max3_f32 v244, v244, v87, v88
	v_max3_f32 v245, v245, v91, v92
	v_max3_f32 v120, v120, v95, v96
	v_max3_f32 v219, v219, v85, v98
	v_max3_f32 v244, v244, v89, v102
	v_max3_f32 v245, v245, v93, v106
	v_max3_f32 v120, v120, v97, v110
	v_max3_f32 v219, v219, v99, v100
	v_max3_f32 v244, v244, v103, v104
	v_max3_f32 v245, v245, v107, v108
	v_max3_f32 v120, v120, v111, v112
	v_max3_f32 v219, v219, v101, v114
	v_max3_f32 v219, v219, v115, v116
	v_max_f32_e32 v219, v219, v117
	v_max_f32_e32 v244, v244, v105
	v_max_f32_e32 v245, v245, v109
	v_max_f32_e32 v120, v120, v113
	v_max3_f32 v178, v219, v244, v245
	v_max_f32_e32 v178, v178, v120
	v_mov_b32_e32 v219, v178
	s_nop 1
	v_permlane16_swap_b32_e32 v178, v219
	v_max_f32_e32 v178, v178, v219
	v_mov_b32_e32 v219, v178
	s_nop 1
	v_permlane32_swap_b32_e32 v178, v219
	v_max3_f32 v178, v178, v219, v145
	s_waitcnt lgkmcnt(7)
	ds_read_b64_tr_b16 v[202:203], v124 offset:10240
	ds_read_b64_tr_b16 v[204:205], v124 offset:12288
	ds_read_b64_tr_b16 v[206:207], v125 offset:10240
	ds_read_b64_tr_b16 v[208:209], v125 offset:12288
	ds_read_b64_tr_b16 v[228:229], v126 offset:10240
	ds_read_b64_tr_b16 v[230:231], v126 offset:12288
	ds_read_b64_tr_b16 v[232:233], v127 offset:10240
	ds_read_b64_tr_b16 v[234:235], v127 offset:12288
	v_mov_b32_e32 v244, v178
	v_pk_add_f32 v[50:51], v[50:51], v[244:245] op_sel_hi:[1,0] neg_lo:[0,1] neg_hi:[0,1]
	v_pk_add_f32 v[52:53], v[52:53], v[244:245] op_sel_hi:[1,0] neg_lo:[0,1] neg_hi:[0,1]
	v_pk_add_f32 v[54:55], v[54:55], v[244:245] op_sel_hi:[1,0] neg_lo:[0,1] neg_hi:[0,1]
	v_pk_add_f32 v[56:57], v[56:57], v[244:245] op_sel_hi:[1,0] neg_lo:[0,1] neg_hi:[0,1]
	v_pk_add_f32 v[58:59], v[58:59], v[244:245] op_sel_hi:[1,0] neg_lo:[0,1] neg_hi:[0,1]
	v_pk_add_f32 v[60:61], v[60:61], v[244:245] op_sel_hi:[1,0] neg_lo:[0,1] neg_hi:[0,1]
	v_pk_add_f32 v[62:63], v[62:63], v[244:245] op_sel_hi:[1,0] neg_lo:[0,1] neg_hi:[0,1]
	v_pk_add_f32 v[64:65], v[64:65], v[244:245] op_sel_hi:[1,0] neg_lo:[0,1] neg_hi:[0,1]
	v_pk_add_f32 v[66:67], v[66:67], v[244:245] op_sel_hi:[1,0] neg_lo:[0,1] neg_hi:[0,1]
	v_pk_add_f32 v[68:69], v[68:69], v[244:245] op_sel_hi:[1,0] neg_lo:[0,1] neg_hi:[0,1]
	v_pk_add_f32 v[70:71], v[70:71], v[244:245] op_sel_hi:[1,0] neg_lo:[0,1] neg_hi:[0,1]
	v_pk_add_f32 v[72:73], v[72:73], v[244:245] op_sel_hi:[1,0] neg_lo:[0,1] neg_hi:[0,1]
	v_pk_add_f32 v[74:75], v[74:75], v[244:245] op_sel_hi:[1,0] neg_lo:[0,1] neg_hi:[0,1]
	v_pk_add_f32 v[76:77], v[76:77], v[244:245] op_sel_hi:[1,0] neg_lo:[0,1] neg_hi:[0,1]
	v_pk_add_f32 v[78:79], v[78:79], v[244:245] op_sel_hi:[1,0] neg_lo:[0,1] neg_hi:[0,1]
	v_pk_add_f32 v[80:81], v[80:81], v[244:245] op_sel_hi:[1,0] neg_lo:[0,1] neg_hi:[0,1]
	v_pk_add_f32 v[82:83], v[82:83], v[244:245] op_sel_hi:[1,0] neg_lo:[0,1] neg_hi:[0,1]
	v_pk_add_f32 v[84:85], v[84:85], v[244:245] op_sel_hi:[1,0] neg_lo:[0,1] neg_hi:[0,1]
	v_pk_add_f32 v[86:87], v[86:87], v[244:245] op_sel_hi:[1,0] neg_lo:[0,1] neg_hi:[0,1]
	v_pk_add_f32 v[88:89], v[88:89], v[244:245] op_sel_hi:[1,0] neg_lo:[0,1] neg_hi:[0,1]
	v_pk_add_f32 v[90:91], v[90:91], v[244:245] op_sel_hi:[1,0] neg_lo:[0,1] neg_hi:[0,1]
	v_pk_add_f32 v[92:93], v[92:93], v[244:245] op_sel_hi:[1,0] neg_lo:[0,1] neg_hi:[0,1]
	v_pk_add_f32 v[94:95], v[94:95], v[244:245] op_sel_hi:[1,0] neg_lo:[0,1] neg_hi:[0,1]
	v_pk_add_f32 v[96:97], v[96:97], v[244:245] op_sel_hi:[1,0] neg_lo:[0,1] neg_hi:[0,1]
; #define LAS __attribute__((address_space(3)))
; __device__ __forceinline__ unsigned pk2(float lo, float hi) { return pg8::cvt_pk_bf16(lo, hi); }
; __device__ __forceinline__ s16x4 vtr(const LAS unsigned char* p) { return __builtin_bit_cast(s16x4, __builtin_amdgcn_ds_read_tr16_b64_v4i16((LAS s16x4*)p)); }
; __device__ __forceinline__ void pv_at(const LAS unsigned char* const (&vp)[4], int off, const f32x4& P0, const f32x4& P1, f32x4 (&O)[4]) {
;     v4u pw; pw.x = pk2(P0[0], P0[1]); pw.y = pk2(P0[2], P0[3]); pw.z = pk2(P1[0], P1[1]); pw.w = pk2(P1[2], P1[3]);
;     const bf16x8 pb = __builtin_bit_cast(bf16x8, pw);
; #pragma unroll
;     for (int db = 0; db < 4; ++db) {
;         const s16x4 lo = vtr(vp[db] + off), hi = vtr(vp[db] + off + 2048);
;         const bf16x8 vt = (bf16x8){lo[0], lo[1], lo[2], lo[3], hi[0], hi[1], hi[2], hi[3]};
;         O[db] = MFMA16(vt, pb, O[db]);
;     }
; }
; __device__ __forceinline__ float xrow16_max(float x) {
;     auto s = __builtin_amdgcn_permlane16_swap(__float_as_uint(x), __float_as_uint(x), false, false);
;     x = fmaxf(__uint_as_float(s[0]), __uint_as_float(s[1]));
;     auto t = __builtin_amdgcn_permlane32_swap(__float_as_uint(x), __float_as_uint(x), false, false);
;     return fmaxf(__uint_as_float(t[0]), __uint_as_float(t[1]));
; }
; __device__ __forceinline__ float xrow16_sum(float x) {
;     auto s = __builtin_amdgcn_permlane16_swap(__float_as_uint(x), __float_as_uint(x), false, false);
;     x = __uint_as_float(s[0]) + __uint_as_float(s[1]);
;     auto t = __builtin_amdgcn_permlane32_swap(__float_as_uint(x), __float_as_uint(x), false, false);
;     return __uint_as_float(t[0]) + __uint_as_float(t[1]);
; }
; __device__ __forceinline__ void softmax_step(f32x4& s0, f32x4& s1, float& m, float& l, f32x4 (&O)[4]) {
;     float t = fmaxf(fmaxf(fmaxf(s0[0], s0[1]), fmaxf(s0[2], s0[3])), fmaxf(fmaxf(s1[0], s1[1]), fmaxf(s1[2], s1[3])));
;     t = xrow16_max(t);
;     const float mn = fmaxf(m, t), alpha = __builtin_amdgcn_exp2f(m - mn);
;     m = mn;
; #pragma unroll
;     for (int k = 0; k < 4; ++k) { s0[k] = __builtin_amdgcn_exp2f(s0[k] - mn); s1[k] = __builtin_amdgcn_exp2f(s1[k] - mn); }
;     l = l * alpha + ((s0[0] + s0[1]) + (s0[2] + s0[3])) + ((s1[0] + s1[1]) + (s1[2] + s1[3]));
; #pragma unroll
;     for (int db = 0; db < 4; ++db) O[db] *= alpha;
; }
	v_pk_add_f32 v[98:99], v[98:99], v[244:245] op_sel_hi:[1,0] neg_lo:[0,1] neg_hi:[0,1]
	v_pk_add_f32 v[100:101], v[100:101], v[244:245] op_sel_hi:[1,0] neg_lo:[0,1] neg_hi:[0,1]
	v_pk_add_f32 v[102:103], v[102:103], v[244:245] op_sel_hi:[1,0] neg_lo:[0,1] neg_hi:[0,1]
	v_pk_add_f32 v[104:105], v[104:105], v[244:245] op_sel_hi:[1,0] neg_lo:[0,1] neg_hi:[0,1]
	v_pk_add_f32 v[106:107], v[106:107], v[244:245] op_sel_hi:[1,0] neg_lo:[0,1] neg_hi:[0,1]
	v_pk_add_f32 v[108:109], v[108:109], v[244:245] op_sel_hi:[1,0] neg_lo:[0,1] neg_hi:[0,1]
	v_pk_add_f32 v[110:111], v[110:111], v[244:245] op_sel_hi:[1,0] neg_lo:[0,1] neg_hi:[0,1]
	v_pk_add_f32 v[112:113], v[112:113], v[244:245] op_sel_hi:[1,0] neg_lo:[0,1] neg_hi:[0,1]
	v_pk_add_f32 v[114:115], v[114:115], v[244:245] op_sel_hi:[1,0] neg_lo:[0,1] neg_hi:[0,1]
	v_pk_add_f32 v[116:117], v[116:117], v[244:245] op_sel_hi:[1,0] neg_lo:[0,1] neg_hi:[0,1]
	v_sub_f32_e32 v219, v145, v178
	v_exp_f32_e32 v50, v50
	v_exp_f32_e32 v51, v51
	v_exp_f32_e32 v52, v52
	v_exp_f32_e32 v53, v53
	v_exp_f32_e32 v54, v54
	v_exp_f32_e32 v55, v55
	v_exp_f32_e32 v56, v56
	v_exp_f32_e32 v57, v57
	v_exp_f32_e32 v58, v58
	v_exp_f32_e32 v59, v59
	v_exp_f32_e32 v60, v60
	v_exp_f32_e32 v61, v61
	v_exp_f32_e32 v62, v62
	v_exp_f32_e32 v63, v63
	v_exp_f32_e32 v64, v64
	v_exp_f32_e32 v65, v65
	v_exp_f32_e32 v66, v66
	v_exp_f32_e32 v67, v67
	v_exp_f32_e32 v68, v68
	v_exp_f32_e32 v69, v69
	v_exp_f32_e32 v70, v70
	v_exp_f32_e32 v71, v71
	v_exp_f32_e32 v72, v72
	v_exp_f32_e32 v73, v73
	v_exp_f32_e32 v74, v74
	v_exp_f32_e32 v75, v75
	v_exp_f32_e32 v76, v76
	v_exp_f32_e32 v77, v77
	v_exp_f32_e32 v78, v78
	v_exp_f32_e32 v79, v79
	v_exp_f32_e32 v80, v80
	v_exp_f32_e32 v81, v81
	v_exp_f32_e32 v82, v82
	v_exp_f32_e32 v83, v83
	v_exp_f32_e32 v84, v84
	v_exp_f32_e32 v85, v85
	v_exp_f32_e32 v86, v86
	v_exp_f32_e32 v87, v87
	v_exp_f32_e32 v88, v88
	v_exp_f32_e32 v89, v89
	v_exp_f32_e32 v90, v90
	v_exp_f32_e32 v91, v91
	v_exp_f32_e32 v92, v92
	v_exp_f32_e32 v93, v93
	v_exp_f32_e32 v94, v94
	v_exp_f32_e32 v95, v95
	v_exp_f32_e32 v96, v96
	v_exp_f32_e32 v97, v97
	v_exp_f32_e32 v98, v98
	v_exp_f32_e32 v99, v99
	v_exp_f32_e32 v100, v100
	v_exp_f32_e32 v101, v101
	v_exp_f32_e32 v102, v102
	v_exp_f32_e32 v103, v103
	v_exp_f32_e32 v104, v104
	v_exp_f32_e32 v105, v105
	v_exp_f32_e32 v106, v106
	v_exp_f32_e32 v107, v107
	v_exp_f32_e32 v108, v108
	v_exp_f32_e32 v109, v109
	v_exp_f32_e32 v110, v110
	v_exp_f32_e32 v111, v111
	v_exp_f32_e32 v112, v112
	v_exp_f32_e32 v113, v113
	v_exp_f32_e32 v114, v114
	v_exp_f32_e32 v115, v115
	v_exp_f32_e32 v116, v116
	v_exp_f32_e32 v117, v117
	v_exp_f32_e32 v219, v219
	v_pk_add_f32 v[236:237], v[50:51], v[52:53]
	v_pk_add_f32 v[238:239], v[54:55], v[56:57]
	v_pk_add_f32 v[240:241], v[58:59], v[60:61]
	v_pk_add_f32 v[242:243], v[62:63], v[64:65]
	v_pk_add_f32 v[236:237], v[236:237], v[66:67]
	v_pk_add_f32 v[238:239], v[238:239], v[70:71]
	v_pk_add_f32 v[240:241], v[240:241], v[74:75]
	v_pk_add_f32 v[242:243], v[242:243], v[78:79]
	v_pk_add_f32 v[236:237], v[236:237], v[68:69]
	v_pk_add_f32 v[238:239], v[238:239], v[72:73]
	v_pk_add_f32 v[240:241], v[240:241], v[76:77]
	v_pk_add_f32 v[242:243], v[242:243], v[80:81]
	v_pk_add_f32 v[236:237], v[236:237], v[82:83]
	v_pk_add_f32 v[238:239], v[238:239], v[86:87]
	v_pk_add_f32 v[240:241], v[240:241], v[90:91]
	v_pk_add_f32 v[242:243], v[242:243], v[94:95]
	v_pk_add_f32 v[236:237], v[236:237], v[84:85]
	v_pk_add_f32 v[238:239], v[238:239], v[88:89]
	v_pk_add_f32 v[240:241], v[240:241], v[92:93]
	v_pk_add_f32 v[242:243], v[242:243], v[96:97]
	v_pk_add_f32 v[236:237], v[236:237], v[98:99]
	v_pk_add_f32 v[238:239], v[238:239], v[102:103]
	v_pk_add_f32 v[240:241], v[240:241], v[106:107]
	v_pk_add_f32 v[242:243], v[242:243], v[110:111]
	v_pk_add_f32 v[236:237], v[236:237], v[100:101]
	v_pk_add_f32 v[238:239], v[238:239], v[104:105]
	v_pk_add_f32 v[240:241], v[240:241], v[108:109]
	v_pk_add_f32 v[242:243], v[242:243], v[112:113]
	v_pk_add_f32 v[236:237], v[236:237], v[114:115]
	v_pk_add_f32 v[236:237], v[236:237], v[116:117]
	v_pk_add_f32 v[236:237], v[236:237], v[238:239]
	v_pk_add_f32 v[240:241], v[240:241], v[242:243]
	v_cndmask_b32_e64 v219, 0, v219, s[74:75]
	v_pk_add_f32 v[236:237], v[236:237], v[240:241]
	v_add_f32_e32 v185, v236, v237
	v_add_f32_e32 v185, v185, v219
	v_cvt_pk_bf16_f32 v236, v50, v51
	v_cvt_pk_bf16_f32 v237, v52, v53
	v_cvt_pk_bf16_f32 v238, v54, v55
	v_cvt_pk_bf16_f32 v239, v56, v57
	s_nop 1
	s_waitcnt lgkmcnt(14)
	v_mfma_f32_16x16x32_bf16 v[210:213], v[186:189], v[236:239], 0
	s_waitcnt lgkmcnt(12)
	v_mfma_f32_16x16x32_bf16 v[214:217], v[190:193], v[236:239], 0
	s_waitcnt lgkmcnt(10)
	v_mfma_f32_16x16x32_bf16 v[220:223], v[194:197], v[236:239], 0
	s_waitcnt lgkmcnt(8)
	v_mfma_f32_16x16x32_bf16 v[224:227], v[198:201], v[236:239], 0
	v_cvt_pk_bf16_f32 v240, v58, v59
	v_cvt_pk_bf16_f32 v241, v60, v61
	v_cvt_pk_bf16_f32 v242, v62, v63
	v_cvt_pk_bf16_f32 v243, v64, v65
	s_waitcnt lgkmcnt(7)
	ds_read_b64_tr_b16 v[186:187], v124 offset:14336
	ds_read_b64_tr_b16 v[188:189], v124 offset:16384
	ds_read_b64_tr_b16 v[190:191], v125 offset:14336
	ds_read_b64_tr_b16 v[192:193], v125 offset:16384
	ds_read_b64_tr_b16 v[194:195], v126 offset:14336
	ds_read_b64_tr_b16 v[196:197], v126 offset:16384
	ds_read_b64_tr_b16 v[198:199], v127 offset:14336
	ds_read_b64_tr_b16 v[200:201], v127 offset:16384
	s_waitcnt lgkmcnt(14)
	v_mfma_f32_16x16x32_bf16 v[210:213], v[202:205], v[240:243], v[210:213]
	s_waitcnt lgkmcnt(12)
	v_mfma_f32_16x16x32_bf16 v[214:217], v[206:209], v[240:243], v[214:217]
	s_waitcnt lgkmcnt(10)
	v_mfma_f32_16x16x32_bf16 v[220:223], v[228:231], v[240:243], v[220:223]
	s_waitcnt lgkmcnt(8)
; #define LAS __attribute__((address_space(3)))
; __device__ __forceinline__ unsigned pk2(float lo, float hi) { return pg8::cvt_pk_bf16(lo, hi); }
; __device__ __forceinline__ s16x4 vtr(const LAS unsigned char* p) { return __builtin_bit_cast(s16x4, __builtin_amdgcn_ds_read_tr16_b64_v4i16((LAS s16x4*)p)); }
; #define MFMA16(a, b, c) __builtin_amdgcn_mfma_f32_16x16x32_bf16((a), (b), (c), 0, 0, 0)
; __device__ __forceinline__ void pv_at(const LAS unsigned char* const (&vp)[4], int off, const f32x4& P0, const f32x4& P1, f32x4 (&O)[4]) {
;     v4u pw; pw.x = pk2(P0[0], P0[1]); pw.y = pk2(P0[2], P0[3]); pw.z = pk2(P1[0], P1[1]); pw.w = pk2(P1[2], P1[3]);
;     const bf16x8 pb = __builtin_bit_cast(bf16x8, pw);
; #pragma unroll
;     for (int db = 0; db < 4; ++db) {
;         const s16x4 lo = vtr(vp[db] + off), hi = vtr(vp[db] + off + 2048);
;         const bf16x8 vt = (bf16x8){lo[0], lo[1], lo[2], lo[3], hi[0], hi[1], hi[2], hi[3]};
;         O[db] = MFMA16(vt, pb, O[db]);
;     }
; }
	v_mfma_f32_16x16x32_bf16 v[224:227], v[232:235], v[240:243], v[224:227]
	v_cvt_pk_bf16_f32 v236, v66, v67
	v_cvt_pk_bf16_f32 v237, v68, v69
	v_cvt_pk_bf16_f32 v238, v70, v71
	v_cvt_pk_bf16_f32 v239, v72, v73
	s_waitcnt lgkmcnt(7)
	ds_read_b64_tr_b16 v[202:203], v124 offset:18432
	ds_read_b64_tr_b16 v[204:205], v124 offset:20480
	ds_read_b64_tr_b16 v[206:207], v125 offset:18432
	ds_read_b64_tr_b16 v[208:209], v125 offset:20480
	ds_read_b64_tr_b16 v[228:229], v126 offset:18432
	ds_read_b64_tr_b16 v[230:231], v126 offset:20480
	ds_read_b64_tr_b16 v[232:233], v127 offset:18432
	ds_read_b64_tr_b16 v[234:235], v127 offset:20480
	s_waitcnt lgkmcnt(14)
	v_mfma_f32_16x16x32_bf16 v[210:213], v[186:189], v[236:239], v[210:213]
	s_waitcnt lgkmcnt(12)
	v_mfma_f32_16x16x32_bf16 v[214:217], v[190:193], v[236:239], v[214:217]
	s_waitcnt lgkmcnt(10)
	v_mfma_f32_16x16x32_bf16 v[220:223], v[194:197], v[236:239], v[220:223]
	s_waitcnt lgkmcnt(8)
	v_mfma_f32_16x16x32_bf16 v[224:227], v[198:201], v[236:239], v[224:227]
	v_cvt_pk_bf16_f32 v240, v74, v75
	v_cvt_pk_bf16_f32 v241, v76, v77
	v_cvt_pk_bf16_f32 v242, v78, v79
	v_cvt_pk_bf16_f32 v243, v80, v81
	s_waitcnt lgkmcnt(7)
	ds_read_b64_tr_b16 v[186:187], v124 offset:22528
	ds_read_b64_tr_b16 v[188:189], v124 offset:24576
	ds_read_b64_tr_b16 v[190:191], v125 offset:22528
	ds_read_b64_tr_b16 v[192:193], v125 offset:24576
	ds_read_b64_tr_b16 v[194:195], v126 offset:22528
	ds_read_b64_tr_b16 v[196:197], v126 offset:24576
	ds_read_b64_tr_b16 v[198:199], v127 offset:22528
	ds_read_b64_tr_b16 v[200:201], v127 offset:24576
	s_waitcnt lgkmcnt(14)
	v_mfma_f32_16x16x32_bf16 v[210:213], v[202:205], v[240:243], v[210:213]
	s_waitcnt lgkmcnt(12)
	v_mfma_f32_16x16x32_bf16 v[214:217], v[206:209], v[240:243], v[214:217]
	s_waitcnt lgkmcnt(10)
	v_mfma_f32_16x16x32_bf16 v[220:223], v[228:231], v[240:243], v[220:223]
	s_waitcnt lgkmcnt(8)
	v_mfma_f32_16x16x32_bf16 v[224:227], v[232:235], v[240:243], v[224:227]
	v_cvt_pk_bf16_f32 v236, v82, v83
	v_cvt_pk_bf16_f32 v237, v84, v85
	v_cvt_pk_bf16_f32 v238, v86, v87
	v_cvt_pk_bf16_f32 v239, v88, v89
	s_waitcnt lgkmcnt(7)
	ds_read_b64_tr_b16 v[202:203], v124 offset:26624
	ds_read_b64_tr_b16 v[204:205], v124 offset:28672
	ds_read_b64_tr_b16 v[206:207], v125 offset:26624
	ds_read_b64_tr_b16 v[208:209], v125 offset:28672
	ds_read_b64_tr_b16 v[228:229], v126 offset:26624
	ds_read_b64_tr_b16 v[230:231], v126 offset:28672
	ds_read_b64_tr_b16 v[232:233], v127 offset:26624
	ds_read_b64_tr_b16 v[234:235], v127 offset:28672
	s_waitcnt lgkmcnt(14)
	v_mfma_f32_16x16x32_bf16 v[210:213], v[186:189], v[236:239], v[210:213]
	s_waitcnt lgkmcnt(12)
	v_mfma_f32_16x16x32_bf16 v[214:217], v[190:193], v[236:239], v[214:217]
	s_waitcnt lgkmcnt(10)
	v_mfma_f32_16x16x32_bf16 v[220:223], v[194:197], v[236:239], v[220:223]
	s_waitcnt lgkmcnt(8)
	v_mfma_f32_16x16x32_bf16 v[224:227], v[198:201], v[236:239], v[224:227]
	v_cvt_pk_bf16_f32 v240, v90, v91
	v_cvt_pk_bf16_f32 v241, v92, v93
	v_cvt_pk_bf16_f32 v242, v94, v95
	v_cvt_pk_bf16_f32 v243, v96, v97
	s_waitcnt lgkmcnt(7)
	ds_read_b64_tr_b16 v[186:187], v124 offset:30720
	ds_read_b64_tr_b16 v[188:189], v124 offset:32768
	ds_read_b64_tr_b16 v[190:191], v125 offset:30720
	ds_read_b64_tr_b16 v[192:193], v125 offset:32768
	ds_read_b64_tr_b16 v[194:195], v126 offset:30720
	ds_read_b64_tr_b16 v[196:197], v126 offset:32768
	ds_read_b64_tr_b16 v[198:199], v127 offset:30720
	ds_read_b64_tr_b16 v[200:201], v127 offset:32768
	s_waitcnt lgkmcnt(14)
	v_mfma_f32_16x16x32_bf16 v[210:213], v[202:205], v[240:243], v[210:213]
	s_waitcnt lgkmcnt(12)
	v_mfma_f32_16x16x32_bf16 v[214:217], v[206:209], v[240:243], v[214:217]
	s_waitcnt lgkmcnt(10)
	v_mfma_f32_16x16x32_bf16 v[220:223], v[228:231], v[240:243], v[220:223]
	s_waitcnt lgkmcnt(8)
	v_mfma_f32_16x16x32_bf16 v[224:227], v[232:235], v[240:243], v[224:227]
	v_cvt_pk_bf16_f32 v236, v98, v99
	v_cvt_pk_bf16_f32 v237, v100, v101
	v_cvt_pk_bf16_f32 v238, v102, v103
	v_cvt_pk_bf16_f32 v239, v104, v105
	s_waitcnt lgkmcnt(7)
; __device__ __forceinline__ void pv_at(const LAS unsigned char* const (&vp)[4], int off, const f32x4& P0, const f32x4& P1, f32x4 (&O)[4]) {
;     v4u pw; pw.x = pk2(P0[0], P0[1]); pw.y = pk2(P0[2], P0[3]); pw.z = pk2(P1[0], P1[1]); pw.w = pk2(P1[2], P1[3]);
;     const bf16x8 pb = __builtin_bit_cast(bf16x8, pw);
; #pragma unroll
;     for (int db = 0; db < 4; ++db) {
;         const s16x4 lo = vtr(vp[db] + off), hi = vtr(vp[db] + off + 2048);
;         const bf16x8 vt = (bf16x8){lo[0], lo[1], lo[2], lo[3], hi[0], hi[1], hi[2], hi[3]};
;         O[db] = MFMA16(vt, pb, O[db]);
;     }
; }
; __device__ __forceinline__ float xrow16_max(float x) {
;     auto s = __builtin_amdgcn_permlane16_swap(__float_as_uint(x), __float_as_uint(x), false, false);
;     x = fmaxf(__uint_as_float(s[0]), __uint_as_float(s[1]));
;     auto t = __builtin_amdgcn_permlane32_swap(__float_as_uint(x), __float_as_uint(x), false, false);
;     return fmaxf(__uint_as_float(t[0]), __uint_as_float(t[1]));
; }
; __device__ __forceinline__ float xrow16_sum(float x) {
;     auto s = __builtin_amdgcn_permlane16_swap(__float_as_uint(x), __float_as_uint(x), false, false);
;     x = __uint_as_float(s[0]) + __uint_as_float(s[1]);
;     auto t = __builtin_amdgcn_permlane32_swap(__float_as_uint(x), __float_as_uint(x), false, false);
;     return __uint_as_float(t[0]) + __uint_as_float(t[1]);
; }
; __device__ __forceinline__ void softmax_step(f32x4& s0, f32x4& s1, float& m, float& l, f32x4 (&O)[4]) {
;     float t = fmaxf(fmaxf(fmaxf(s0[0], s0[1]), fmaxf(s0[2], s0[3])), fmaxf(fmaxf(s1[0], s1[1]), fmaxf(s1[2], s1[3])));
;     t = xrow16_max(t);
;     const float mn = fmaxf(m, t), alpha = __builtin_amdgcn_exp2f(m - mn);
;     m = mn;
; #pragma unroll
;     for (int k = 0; k < 4; ++k) { s0[k] = __builtin_amdgcn_exp2f(s0[k] - mn); s1[k] = __builtin_amdgcn_exp2f(s1[k] - mn); }
;     l = l * alpha + ((s0[0] + s0[1]) + (s0[2] + s0[3])) + ((s1[0] + s1[1]) + (s1[2] + s1[3]));
; #pragma unroll
;     for (int db = 0; db < 4; ++db) O[db] *= alpha;
; }
; __device__ __forceinline__ void store_o(bf16* yrow, int g, float l, const f32x4 (&O)[4]) {
;     const float inv = 1.0f / xrow16_sum(l);
;     unsigned wx[4], wy[4];
; #pragma unroll
;     for (int db = 0; db < 4; ++db) { wx[db] = pk2(O[db][0] * inv, O[db][1] * inv); wy[db] = pk2(O[db][2] * inv, O[db][3] * inv); }
; #pragma unroll
	ds_read_b64_tr_b16 v[202:203], v124 offset:34816
	ds_read_b64_tr_b16 v[204:205], v124 offset:36864
	ds_read_b64_tr_b16 v[206:207], v125 offset:34816
	ds_read_b64_tr_b16 v[208:209], v125 offset:36864
	ds_read_b64_tr_b16 v[228:229], v126 offset:34816
	ds_read_b64_tr_b16 v[230:231], v126 offset:36864
	ds_read_b64_tr_b16 v[232:233], v127 offset:34816
	ds_read_b64_tr_b16 v[234:235], v127 offset:36864
	s_waitcnt lgkmcnt(14)
	v_mfma_f32_16x16x32_bf16 v[210:213], v[186:189], v[236:239], v[210:213]
	s_waitcnt lgkmcnt(12)
	v_mfma_f32_16x16x32_bf16 v[214:217], v[190:193], v[236:239], v[214:217]
	s_waitcnt lgkmcnt(10)
	v_mfma_f32_16x16x32_bf16 v[220:223], v[194:197], v[236:239], v[220:223]
	s_waitcnt lgkmcnt(8)
	v_mfma_f32_16x16x32_bf16 v[224:227], v[198:201], v[236:239], v[224:227]
	v_cvt_pk_bf16_f32 v240, v106, v107
	v_cvt_pk_bf16_f32 v241, v108, v109
	v_cvt_pk_bf16_f32 v242, v110, v111
	v_cvt_pk_bf16_f32 v243, v112, v113
	s_waitcnt lgkmcnt(7)
	ds_read_b64_tr_b16 v[186:187], v124 offset:38912
	ds_read_b64_tr_b16 v[188:189], v124 offset:40960
	ds_read_b64_tr_b16 v[190:191], v125 offset:38912
	ds_read_b64_tr_b16 v[192:193], v125 offset:40960
	ds_read_b64_tr_b16 v[194:195], v126 offset:38912
	ds_read_b64_tr_b16 v[196:197], v126 offset:40960
	ds_read_b64_tr_b16 v[198:199], v127 offset:38912
	ds_read_b64_tr_b16 v[200:201], v127 offset:40960
	s_waitcnt lgkmcnt(14)
	v_mfma_f32_16x16x32_bf16 v[210:213], v[202:205], v[240:243], v[210:213]
	s_waitcnt lgkmcnt(12)
	v_mfma_f32_16x16x32_bf16 v[214:217], v[206:209], v[240:243], v[214:217]
	s_waitcnt lgkmcnt(10)
	v_mfma_f32_16x16x32_bf16 v[220:223], v[228:231], v[240:243], v[220:223]
	s_waitcnt lgkmcnt(8)
	v_mfma_f32_16x16x32_bf16 v[224:227], v[232:235], v[240:243], v[224:227]
	v_cvt_pk_bf16_f32 v236, v114, v115
	v_cvt_pk_bf16_f32 v237, v116, v117
	v_mov_b32_e32 v238, 0
	v_mov_b32_e32 v239, 0
	s_nop 1
	s_waitcnt lgkmcnt(6)
	v_mfma_f32_16x16x32_bf16 v[210:213], v[186:189], v[236:239], v[210:213]
	s_waitcnt lgkmcnt(4)
	v_mfma_f32_16x16x32_bf16 v[214:217], v[190:193], v[236:239], v[214:217]
	s_waitcnt lgkmcnt(2)
	v_mfma_f32_16x16x32_bf16 v[220:223], v[194:197], v[236:239], v[220:223]
	s_waitcnt lgkmcnt(0)
	v_mfma_f32_16x16x32_bf16 v[224:227], v[198:201], v[236:239], v[224:227]
	v_mov_b32_e32 v219, v185
	s_nop 1
	v_permlane16_swap_b32_e32 v185, v219
	v_add_f32_e32 v185, v185, v219
	v_mov_b32_e32 v219, v185
	s_nop 1
	v_permlane32_swap_b32_e32 v185, v219
	v_add_f32_e32 v185, v185, v219
	v_div_scale_f32 v236, s[78:79], v185, v185, 1.0
	v_div_scale_f32 v237, vcc, 1.0, v185, 1.0
	v_rcp_f32_e32 v238, v236
	s_nop 0
	v_fma_f32 v239, -v236, v238, 1.0
	v_fmac_f32_e32 v238, v239, v238
	v_mul_f32_e32 v240, v237, v238
	v_fma_f32 v241, -v236, v240, v237
	v_fmac_f32_e32 v240, v241, v238
	v_fma_f32 v237, -v236, v240, v237
	v_div_fmas_f32 v237, v237, v238, v240
	v_div_fixup_f32 v244, v237, v185, 1.0
	v_mul_f32_e32 v240, v210, v244
	v_mul_f32_e32 v241, v211, v244
	v_mul_f32_e32 v242, v212, v244
	v_mul_f32_e32 v243, v213, v244
	v_cvt_pk_bf16_f32 v186, v240, v241
	v_cvt_pk_bf16_f32 v187, v242, v243
	v_mul_f32_e32 v240, v214, v244
	v_mul_f32_e32 v241, v215, v244
	v_mul_f32_e32 v242, v216, v244
	v_mul_f32_e32 v243, v217, v244
	v_cvt_pk_bf16_f32 v188, v240, v241
	v_cvt_pk_bf16_f32 v189, v242, v243
	v_mul_f32_e32 v240, v220, v244
	v_mul_f32_e32 v241, v221, v244
	v_mul_f32_e32 v242, v222, v244
	v_mul_f32_e32 v243, v223, v244
	v_cvt_pk_bf16_f32 v190, v240, v241
	v_cvt_pk_bf16_f32 v191, v242, v243
	v_mul_f32_e32 v240, v224, v244
	v_mul_f32_e32 v241, v225, v244
	v_mul_f32_e32 v242, v226, v244
	v_mul_f32_e32 v243, v227, v244
	v_cvt_pk_bf16_f32 v192, v240, v241
	v_cvt_pk_bf16_f32 v193, v242, v243
	s_nop 1
	v_permlane16_swap_b32_e32 v186, v188
	v_permlane16_swap_b32_e32 v187, v189
	v_permlane16_swap_b32_e32 v190, v192
	v_permlane16_swap_b32_e32 v191, v193
	s_nop 0
	v_permlane32_swap_b32_e32 v186, v190
	v_permlane32_swap_b32_e32 v187, v191
	v_permlane32_swap_b32_e32 v188, v192
	v_permlane32_swap_b32_e32 v189, v193
	v_add_u32_e32 v219, 0x1000, v128
	global_store_dwordx4 v219, v[186:189], s[82:83] offset:2048
	global_store_dwordx4 v219, v[190:193], s[82:83] offset:2064
	s_nop 1
	s_branch .LBB0_240
.La_nonext:
	s_waitcnt vmcnt(0)
	s_branch .LBB0_257
.LBB0_267:
	v_readlane_b32 s92, v246, 8
	v_readlane_b32 s93, v246, 9
	v_readlane_b32 s94, v246, 10
	v_readlane_b32 s95, v246, 11
	v_readlane_b32 s96, v246, 12
